# bf16-output GEMMs: wave column blocks made adjacent (B-tile row remap) and the two 64-byte stores per row group regrouped into 8-row full-128-byte-line stores; plus the f32 store regrouping of the res
# speedup vs baseline: 1.0008x; 1.0008x over previous
; #define PG8_LAS __attribute__((address_space(3)))
;     __device__ __forceinline__ void pre_store(const Pre& p, PG8_LAS float* tab, int tid) const {
;         const float tot = ((p.s0[0] + p.s0[1]) + (p.s0[2] + p.s0[3])) + ((p.s1[0] + p.s1[1]) + (p.s1[2] + p.s1[3])) + ((p.s2[0] + p.s2[1]) + (p.s2[2] + p.s2[3])) + ((p.s3[0] + p.s3[1]) + (p.s3[2] + p.s3[3]));
;         if (tid < 256) tab[tid] = rsqrtf(tot * (1.0f / 1024.0f) + 1e-6f);
; template <class Epi, class Sched, bool ALIGN_EPI = false, bool SP2 = false>
; __device__ __forceinline__ void gemm_phase(PG8_LAS unsigned char* lds, const Gemm g, const Sched& S, const Epi& E) {
;     ...
;     const int tid = tid_, wid = __builtin_amdgcn_readfirstlane(tid >> 6), lane = tid & 63, wr = wid >> 2, wc = wid & 3, fr = lane & 15, fq = lane >> 4;
;     const int K = g.K, nt = K / BK;
;     unsigned voffA[2], voffB[2];
; #pragma unroll
;     for (int i = 0; i < 2; ++i) { int R, C; stage_rc(tid * 16 + i * 8192, R, C); const int Rb = Epi::PERM ? ((R & ~31) + perm32(R & 31)) : R;
;         voffA[i] = (unsigned)(R * K + C) * 2u; voffB[i] = (unsigned)(Rb * K + C) * 2u; }
;     const size_t kstep = (size_t)(BK * 2);
;     const size_t hstep = (size_t)HALF * K * 2;
;     const size_t tstep = 2 * hstep;
;     const unsigned ldsw = (unsigned)wid * 1024u;
;     const int aoff = lds_byte(wr * 64 + fr, fq * 8), boff = lds_byte(wc * 32 + fr, fq * 8);
;     ...
;     Unit cur, nxt; int ui = 0;
;     if (!S.next(0, cur)) return;
;     f32x4 acc[2][2][4][2];
; #pragma unroll
;     for (int a = 0; a < 2; ++a)
; #pragma unroll
;         for (int b = 0; b < 2; ++b)
; #pragma unroll
;             for (int m = 0; m < 4; ++m)
; #pragma unroll
;                 for (int n = 0; n < 2; ++n) acc[a][b][m][n] = (f32x4){0.f, 0.f, 0.f, 0.f};
;     bf16x8 At[4][2], B0[2][2], B1[2][2];
;     const char* cA = (const char*)g.A + (size_t)cur.pm * tstep; const char* cB = (const char*)g.Bt + (size_t)cur.pn * tstep;
;     S.a_ready(cur);
;     PG8_LAS float* ptab = (PG8_LAS float*)(lds + STAGE_BYTES);
;     if constexpr (Epi::HAS_PRE) { const auto p0 = E.pre_load(cur.pm, tid); E.pre_store(p0, ptab, tid); }
.LBB0_118:
	s_or_b64 exec, exec, s[0:1]
	s_add_u32 s0, s70, 0x6000000
	s_addc_u32 s1, s71, 0
	v_writelane_b32 v254, s0, 39
	s_nop 1
	v_writelane_b32 v254, s1, 40
	s_add_u32 s0, s70, 0x5600000
	s_addc_u32 s1, s71, 0
	s_add_u32 s92, s70, 0xe000000
	s_addc_u32 s93, s71, 0
	v_writelane_b32 v254, s0, 41
	s_cmp_lt_i32 s96, 2
	s_nop 0
	v_writelane_b32 v254, s1, 42
	s_cselect_b64 s[0:1], -1, 0
	s_cmp_gt_i32 s96, 1
	s_cselect_b64 s[2:3], -1, 0
	s_cmp_lt_i32 s97, 2
	s_cselect_b64 s[4:5], -1, 0
	s_or_b64 s[2:3], s[2:3], s[4:5]
	s_and_b64 vcc, exec, s[2:3]
	s_cbranch_vccnz .LBB0_143
	v_readfirstlane_b32 s100, v166
	s_nop 3
	s_lshr_b32 s98, s100, 8
	s_lshl_b32 s98, s98, 16
	s_add_i32 s99, s98, 0x20000
	s_lshr_b32 s100, s100, 6
	s_and_b32 s100, s100, 3
	s_lshl_b32 s100, s100, 5
	v_mov_b32_e32 v8, v166
	s_cmpk_gt_i32 s75, 0xcff
	v_readfirstlane_b32 s6, v8
	s_cbranch_scc1 .LBB0_143
	s_ashr_i32 s33, s75, 31
	s_lshr_b32 s2, s33, 29
	s_add_i32 s2, s75, s2
	s_ashr_i32 s3, s2, 3
	s_and_b32 s2, s2, -8
	s_sub_i32 s2, s75, s2
	s_cmp_lt_i32 s2, 0
	s_movk_i32 s4, 0x1a1
	s_cselect_b32 s4, s4, 0x1a0
	s_mul_i32 s2, s4, s2
	s_add_i32 s2, s2, s3
	s_mul_hi_i32 s3, s2, 0x4ec4ec4f
	s_lshr_b32 s4, s3, 31
	s_ashr_i32 s3, s3, 5
	s_add_i32 s3, s3, s4
	s_lshl_b32 s4, s3, 3
	s_mulk_i32 s3, 0x68
	s_sub_i32 s2, s2, s3
	s_bfe_i32 s3, s2, 0x80000
	s_bfe_u32 s3, s3, 0x3000c
	s_add_i32 s3, s2, s3
	s_bfe_i32 s5, s3, 0x80000
	s_and_b32 s3, s3, 0xf8
	s_sub_i32 s2, s2, s3
	s_sext_i32_i8 s2, s2
	s_sext_i32_i16 s5, s5
	s_add_i32 s24, s4, s2
	s_movk_i32 s2, 0x100
	s_lshr_b32 s7, s5, 3
	v_and_b32_e32 v164, 0xff, v8
	v_cmp_gt_i32_e64 s[2:3], s2, v8
	s_and_saveexec_b64 s[4:5], s[2:3]
	s_cbranch_execz .LBB0_122
	v_lshl_or_b32 v0, s24, 8, v164
	v_ashrrev_i32_e32 v1, 31, v0
	v_readlane_b32 s8, v254, 41
	v_lshlrev_b64 v[0:1], 6, v[0:1]
	v_readlane_b32 s9, v254, 42
	v_mov_b32_e32 v9, 0x358637bd
	s_nop 0
	v_lshl_add_u64 v[14:15], s[8:9], 0, v[0:1]
	global_load_dwordx4 v[0:3], v[14:15], off
	global_load_dwordx4 v[4:7], v[14:15], off offset:16
	global_load_dwordx4 v[10:13], v[14:15], off offset:32
	s_nop 0
	global_load_dwordx4 v[14:17], v[14:15], off offset:48
	s_mov_b32 s8, 0x800000
	s_waitcnt vmcnt(3)
	v_mov_b32_e32 v18, v1
	v_mov_b32_e32 v19, v2
	v_mov_b32_e32 v1, v3
	s_waitcnt vmcnt(2)
	v_mov_b32_e32 v2, v5
	v_mov_b32_e32 v3, v6
	v_mov_b32_e32 v5, v7
	v_pk_add_f32 v[0:1], v[18:19], v[0:1]
	v_pk_add_f32 v[2:3], v[2:3], v[4:5]
	v_pk_add_f32 v[0:1], v[0:1], v[0:1] op_sel_hi:[0,1]
	v_pk_add_f32 v[2:3], v[2:3], v[2:3] op_sel_hi:[0,1]
	s_waitcnt vmcnt(1)
	v_add_f32_e32 v7, v10, v11
	v_add_f32_e32 v11, v12, v13
	s_waitcnt vmcnt(0)
	v_mov_b32_e32 v6, v14
	v_mov_b32_e32 v10, v15
	v_mov_b32_e32 v2, v16
	v_mov_b32_e32 v0, v17
	v_pk_add_f32 v[4:5], v[6:7], v[10:11]
	v_pk_add_f32 v[0:1], v[2:3], v[0:1]
	s_nop 0
	v_pk_add_f32 v[0:1], v[4:5], v[0:1]
	s_nop 0
	v_add_f32_e32 v0, v0, v1
	v_fmac_f32_e32 v9, 0x3a800000, v0
	v_mul_f32_e32 v0, 0x4b800000, v9
	v_cmp_gt_f32_e32 vcc, s8, v9
	v_lshl_add_u32 v1, v8, 2, 0
	v_add_u32_e32 v1, 0x20000, v1
	v_cndmask_b32_e32 v0, v9, v0, vcc
	v_rsq_f32_e32 v0, v0
	s_nop 0
	v_mul_f32_e32 v2, 0x45800000, v0
	v_cndmask_b32_e32 v0, v0, v2, vcc
	ds_write_b32 v1, v0
; #define PG8_LAS __attribute__((address_space(3)))
; #define PG8_STAGE(bufoff, gbase, voff) do { _Pragma("unroll") for (int _i = 0; _i < 2; ++_i) \
;         __builtin_amdgcn_global_load_lds((const unsigned*)((const char*)(gbase) + (voff)[_i]), (PG8_LAS unsigned*)(lds + (bufoff) + ldsw + _i * 8192), 16, 0, 0); } while (0)
; #define PG8_WAIT_V(n) asm volatile("s_waitcnt vmcnt(" #n ")" ::: "memory")
; #define PG8_BAR __builtin_amdgcn_s_barrier()
; template <class Epi, class Sched, bool ALIGN_EPI = false, bool SP2 = false>
; __device__ __forceinline__ void gemm_phase(PG8_LAS unsigned char* lds, const Gemm g, const Sched& S, const Epi& E) {
;     ...
;     for (int i = 0; i < 2; ++i) { int R, C; stage_rc(tid * 16 + i * 8192, R, C); const int Rb = Epi::PERM ? ((R & ~31) + perm32(R & 31)) : R;
;         voffA[i] = (unsigned)(R * K + C) * 2u; voffB[i] = (unsigned)(Rb * K + C) * 2u; }
;     const size_t kstep = (size_t)(BK * 2);
;     const size_t hstep = (size_t)HALF * K * 2;
;     const size_t tstep = 2 * hstep;
;     const unsigned ldsw = (unsigned)wid * 1024u;
;     const int aoff = lds_byte(wr * 64 + fr, fq * 8), boff = lds_byte(wc * 32 + fr, fq * 8);
;     ...
;     Unit cur, nxt; int ui = 0;
;     if (!S.next(0, cur)) return;
;     f32x4 acc[2][2][4][2];
; #pragma unroll
;     for (int a = 0; a < 2; ++a)
; #pragma unroll
;         for (int b = 0; b < 2; ++b)
; #pragma unroll
;             for (int m = 0; m < 4; ++m)
; #pragma unroll
;                 for (int n = 0; n < 2; ++n) acc[a][b][m][n] = (f32x4){0.f, 0.f, 0.f, 0.f};
;     bf16x8 At[4][2], B0[2][2], B1[2][2];
;     const char* cA = (const char*)g.A + (size_t)cur.pm * tstep; const char* cB = (const char*)g.Bt + (size_t)cur.pn * tstep;
;     S.a_ready(cur);
;     PG8_LAS float* ptab = (PG8_LAS float*)(lds + STAGE_BYTES);
;     if constexpr (Epi::HAS_PRE) { const auto p0 = E.pre_load(cur.pm, tid); E.pre_store(p0, ptab, tid); }
;     if constexpr (SP2) {
;         PG8_STAGE(PG8_SB(0, 0), cB, voffB); PG8_STAGE(PG8_SB(0, 1), cB + hstep, voffB); PG8_STAGE(PG8_SA(0, 0), cA, voffA); PG8_STAGE(PG8_SA(0, 1), cA + hstep, voffA);
;         if (wr == 1) PG8_BAR;
;         PG8_WAIT_V(2); PG8_BAR;
;         PG8_STAGE(PG8_SB(1, 0), cB + kstep, voffB); PG8_STAGE(PG8_SA(1, 0), cA + kstep, voffA); PG8_STAGE(PG8_SB(1, 1), cB + hstep + kstep, voffB);
;         PG8_WAIT_V(6); PG8_BAR;
.LBB0_122:
	s_or_b64 exec, exec, s[4:5]
	v_ashrrev_i32_e32 v1, 31, v8
	v_lshrrev_b32_e32 v1, 26, v1
	v_add_u32_e32 v1, v8, v1
	v_mov_b32_e32 v0, s7
	v_ashrrev_i32_e32 v9, 6, v1
	v_bfe_i32 v1, v8, 27, 1
	v_readfirstlane_b32 s22, v0
	v_lshlrev_b32_e32 v0, 4, v8
	v_lshrrev_b32_e32 v1, 22, v1
	v_add_u32_e32 v1, v0, v1
	v_and_b32_e32 v1, 0xfffffc00, v1
	v_sub_u32_e32 v1, v0, v1
	v_lshrrev_b32_e32 v2, 4, v1
	s_add_u32 s34, s70, 0x100000
	v_bitop3_b32 v1, v2, v1, 32 bitop3:0x6c
	s_addc_u32 s35, s71, 0
	s_ashr_i32 s25, s24, 31
	v_ashrrev_i32_e32 v3, 31, v1
	s_lshl_b64 s[4:5], s[24:25], 19
	v_readlane_b32 s8, v254, 39
	v_lshrrev_b32_e32 v3, 26, v3
	v_readlane_b32 s9, v254, 40
	s_add_u32 s26, s8, s4
	s_mov_b32 s23, 0
	v_add_u32_e32 v3, v1, v3
	s_addc_u32 s27, s9, s5
	s_bfe_i64 s[4:5], s[22:23], 0x80000
	v_lshlrev_b32_e32 v2, 3, v9
	v_ashrrev_i32_e32 v10, 6, v3
	v_and_b32_e32 v3, 0xc0, v3
	s_lshl_b64 s[4:5], s[4:5], 19
	v_and_b32_e32 v2, -16, v2
	v_sub_u32_e32 v1, v1, v3
	v_mov_b32_e32 v3, 1
	s_add_u32 s28, s34, s4
	v_add_u32_e32 v2, v10, v2
	v_ashrrev_i16_sdwa v1, v3, sext(v1) dst_sel:DWORD dst_unused:UNUSED_PAD src0_sel:DWORD src1_sel:BYTE_0
	s_addc_u32 s29, s35, s5
	v_lshlrev_b32_e32 v4, 5, v9
	v_bfe_i32 v11, v1, 0, 16
	v_lshlrev_b32_e32 v1, 1, v2
	v_lshrrev_b32_e32 v5, 2, v2
	v_and_b32_e32 v6, 3, v10
	s_mov_b32 s5, 0x1fffe0
	v_and_b32_e32 v4, 32, v4
	v_and_b32_e32 v1, 24, v1
	v_and_b32_e32 v5, 4, v5
	v_and_or_b32 v6, v2, s5, v6
	v_or3_b32 v1, v6, v5, v1
	v_add_lshl_u32 v4, v4, v11, 1
	v_add_u32_e32 v0, 0x2000, v0
	v_lshl_add_u32 v146, v1, 11, v4
	v_add_u32_e32 v146, s98, v146
	v_ashrrev_i32_e32 v1, 31, v0
	v_lshrrev_b32_e32 v1, 22, v1
	v_add_u32_e32 v1, v0, v1
	v_ashrrev_i32_e32 v12, 10, v1
	v_mul_i32_i24_e32 v1, 0x400, v12
	v_sub_u32_e32 v0, v0, v1
	v_lshrrev_b32_e32 v1, 4, v0
	v_bitop3_b32 v0, v1, v0, 32 bitop3:0x6c
	v_lshl_add_u32 v144, v2, 11, v4
	v_ashrrev_i32_e32 v2, 31, v0
	v_lshrrev_b32_e32 v2, 26, v2
	v_add_u32_e32 v2, v0, v2
	v_lshlrev_b32_e32 v1, 3, v12
	v_ashrrev_i32_e32 v13, 6, v2
	v_and_b32_e32 v2, 0xc0, v2
	v_and_b32_e32 v1, -16, v1
	v_sub_u32_e32 v0, v0, v2
	v_add_u32_e32 v1, v13, v1
	v_ashrrev_i16_sdwa v0, v3, sext(v0) dst_sel:DWORD dst_unused:UNUSED_PAD src0_sel:DWORD src1_sel:BYTE_0
	v_and_b32_e32 v3, 3, v13
	v_and_or_b32 v3, v1, s5, v3
	s_ashr_i32 s5, s6, 6
	s_lshl_b32 s22, s5, 10
	v_lshlrev_b32_e32 v4, 5, v12
	v_bfe_i32 v14, v0, 0, 16
	v_lshlrev_b32_e32 v0, 1, v1
	v_lshrrev_b32_e32 v2, 2, v1
	s_add_i32 s25, s22, 0
	v_and_b32_e32 v4, 32, v4
	v_and_b32_e32 v0, 24, v0
	v_and_b32_e32 v2, 4, v2
	s_add_i32 m0, s25, 0x10000
	s_ashr_i32 s4, s6, 8
	v_or3_b32 v0, v3, v2, v0
	v_add_lshl_u32 v2, v4, v14, 1
	global_load_lds_dwordx4 v146, s[28:29]
	s_add_i32 m0, s25, 0x12000
	v_lshl_add_u32 v150, v0, 11, v2
	v_add_u32_e32 v150, s99, v150
	s_add_u32 s8, s28, 0x10000
	global_load_lds_dwordx4 v150, s[28:29]
	s_addc_u32 s9, s29, 0
	s_add_i32 m0, s25, 0x14000
	s_add_i32 s36, s25, 0x2000
	global_load_lds_dwordx4 v146, s[8:9]
	s_add_i32 m0, s25, 0x16000
	v_lshl_add_u32 v148, v1, 11, v2
	global_load_lds_dwordx4 v150, s[8:9]
	s_mov_b32 m0, s25
	s_add_u32 s8, s26, 0x40000
	global_load_lds_dwordx4 v144, s[26:27]
	s_mov_b32 m0, s36
	s_addc_u32 s9, s27, 0
	s_add_i32 s37, s25, 0x4000
	global_load_lds_dwordx4 v148, s[26:27]
	s_mov_b32 m0, s37
	s_add_i32 s38, s25, 0x6000
	global_load_lds_dwordx4 v144, s[8:9]
	s_mov_b32 m0, s38
	v_mov_b32_e32 v147, 0
	global_load_lds_dwordx4 v148, s[8:9]
	v_mov_b32_e32 v151, v147
	v_mov_b32_e32 v145, v147
	v_mov_b32_e32 v149, v147
	s_cmp_eq_u32 s4, 1
	v_lshl_add_u64 v[6:7], s[28:29], 0, v[146:147]
	v_lshl_add_u64 v[4:5], s[28:29], 0, v[150:151]
	v_lshl_add_u64 v[0:1], s[26:27], 0, v[144:145]
	s_cselect_b64 s[8:9], -1, 0
	s_cmp_lg_u32 s4, 1
	v_lshl_add_u64 v[2:3], s[26:27], 0, v[148:149]
	s_cbranch_scc1 .LBB0_124
	s_barrier
.LBB0_124:
	s_lshl_b32 s5, s5, 5
	s_mov_b64 s[10:11], 0x80
	s_and_b32 s5, s5, 0x60
	s_add_i32 m0, s25, 0x18000
	v_lshl_add_u64 v[6:7], v[6:7], 0, s[10:11]
	s_lshl_b32 s14, s4, 13
	s_lshl_b32 s15, s5, 7
	s_waitcnt vmcnt(2)
	s_barrier
	global_load_lds_dwordx4 v[6:7], off
	v_lshl_add_u64 v[4:5], v[4:5], 0, s[10:11]
	s_add_i32 m0, s25, 0x1a000
	s_add_i32 s39, s25, 0x8000
	s_add_i32 s40, s25, 0xa000
	global_load_lds_dwordx4 v[4:5], off
	v_lshl_add_u64 v[0:1], v[0:1], 0, s[10:11]
	s_mov_b32 m0, s39
	s_add_u32 s12, s28, 0x10080
	global_load_lds_dwordx4 v[0:1], off
	v_lshl_add_u64 v[0:1], v[2:3], 0, s[10:11]
	s_mov_b32 m0, s40
	s_addc_u32 s13, s29, 0
	global_load_lds_dwordx4 v[0:1], off
	s_add_i32 m0, s25, 0x1c000
	v_lshl_add_u64 v[0:1], s[12:13], 0, v[146:147]
	global_load_lds_dwordx4 v[0:1], off
	v_lshl_add_u64 v[0:1], s[12:13], 0, v[150:151]
	s_add_i32 m0, s25, 0x1e000
	v_lshlrev_b32_e32 v4, 2, v8
	global_load_lds_dwordx4 v[0:1], off
	v_lshrrev_b32_e32 v1, 1, v8
	v_and_b32_e32 v0, 15, v8
	v_and_b32_e32 v1, 24, v1
	v_lshl_or_b32 v165, s4, 6, v0
	v_lshlrev_b32_e32 v2, 1, v1
	v_lshl_or_b32 v0, v0, 6, v2
	v_lshlrev_b32_e32 v2, 2, v165
	v_and_b32_e32 v3, 32, v2
	v_and_b32_e32 v5, 32, v4
	v_bitop3_b32 v3, v0, s14, v3 bitop3:0xde
	v_bitop3_b32 v167, v0, s15, v5 bitop3:0xde
	v_lshlrev_b32_e32 v0, 14, v9
	v_and_b32_e32 v0, 0xffff8000, v0
	v_or_b32_e32 v170, s5, v1
	v_lshl_add_u32 v0, v10, 11, v0
	v_and_b32_e32 v1, 1, v9
	v_lshl_or_b32 v0, v1, 6, v0
	v_lshl_add_u32 v152, v11, 1, v0
	v_lshlrev_b32_e32 v0, 14, v12
	s_add_i32 s4, 0, 0x20000
	v_and_b32_e32 v0, 0xffff8000, v0
	s_waitcnt vmcnt(6)
	s_cmpk_lt_u32 s6, 0x100
	v_lshl_add_u32 v0, v13, 11, v0
	v_and_b32_e32 v1, 1, v12
	s_cselect_b64 s[12:13], -1, 0
	v_lshl_or_b32 v0, v1, 6, v0
	s_add_i32 s44, 0, 0x10000
	s_add_i32 s45, 0, 0x14000
	s_sext_i32_i8 s49, s7
	v_add_u32_e32 v168, s4, v2
	v_add_u32_e32 v169, s4, v4
	s_ashr_i32 s41, s94, 31
	s_mov_b32 s42, s94
	v_mov_b32_e32 v153, v147
	v_lshl_add_u32 v154, v14, 1, v0
	v_mov_b32_e32 v155, v147
	v_mov_b64_e32 v[156:157], 0xd00
	v_mov_b64_e32 v[158:159], 0xcff
	s_movk_i32 s43, 0x1a1
	v_add_u32_e32 v171, s44, v167
	v_add_u32_e32 v172, s45, v167
	v_add_u32_e32 v173, 0, v3
	s_movk_i32 s46, 0x1a00
	v_mov_b32_e32 v174, 0x358637bd
	s_mov_b32 s47, 0x800000
	s_barrier
	s_branch .LBB0_127

; #define PG8_STAGE(bufoff, gbase, voff) do { _Pragma("unroll") for (int _i = 0; _i < 2; ++_i) \
;         __builtin_amdgcn_global_load_lds((const unsigned*)((const char*)(gbase) + (voff)[_i]), (PG8_LAS unsigned*)(lds + (bufoff) + ldsw + _i * 8192), 16, 0, 0); } while (0)
; #define PG8_LDA(dst, b, h) do { _Pragma("unroll") for (int m = 0; m < 4; ++m) _Pragma("unroll") for (int k = 0; k < 2; ++k) dst[m][k] = *(const PG8_LAS bf16x8*)(lds + PG8_SA(b, h) + aoff + m * 2048 + k * 1024); } while (0)
; #define PG8_LDB(dst, b, h) do { _Pragma("unroll") for (int n = 0; n < 2; ++n) _Pragma("unroll") for (int k = 0; k < 2; ++k) dst[n][k] = *(const PG8_LAS bf16x8*)(lds + PG8_SB(b, h) + boff + n * 2048 + k * 1024); } while (0)
; #define PG8_MMA(ai, bj, At, Bt) do { __builtin_amdgcn_s_setprio(1); _Pragma("unroll") for (int m = 0; m < 4; ++m) _Pragma("unroll") for (int n = 0; n < 2; ++n) _Pragma("unroll") for (int k = 0; k < 2; ++k) \
;         acc[ai][bj][m][n] = __builtin_amdgcn_mfma_f32_16x16x32_bf16(Bt[n][k], At[m][k], acc[ai][bj][m][n], 0, 0, 0); __builtin_amdgcn_s_setprio(0); } while (0)
; #define PG8_WAIT_V(n) asm volatile("s_waitcnt vmcnt(" #n ")" ::: "memory")
; #define PG8_WAIT_L(n) asm volatile("s_waitcnt lgkmcnt(" #n ")" ::: "memory")
; #define PG8_BAR __builtin_amdgcn_s_barrier()
; #define PG8_SCHED __builtin_amdgcn_sched_barrier(0)
; template <class Epi, class Sched, bool ALIGN_EPI = false, bool SP2 = false>
; __device__ __forceinline__ void gemm_phase(PG8_LAS unsigned char* lds, const Gemm g, const Sched& S, const Epi& E) {
;     ...
;             PG8_LDB(B0, 0, 0); PG8_LDB(B1, 0, 1); PG8_SCHED; PG8_LDA(At, 0, 0); PG8_STAGE(PG8_SA(1, 1), a1 + hstep, voffA);
;             PG8_WAIT_V(8); PG8_WAIT_L(0); PG8_BAR; PG8_MMA(0, 0, At, B0); PG8_MMA(0, 1, At, B1); PG8_BAR; PG8_SCHED;
;             PG8_LDA(At, 0, 1); PG8_STAGE(PG8_SB(0, 0), b2, voffB); PG8_STAGE(PG8_SB(0, 1), b2 + hstep, voffB); PG8_STAGE(PG8_SA(0, 0), a2, voffA);
;             PG8_WAIT_V(8); PG8_WAIT_L(0); PG8_BAR; PG8_MMA(1, 0, At, B0); PG8_MMA(1, 1, At, B1); PG8_BAR; PG8_SCHED;
.LBB0_130:
	s_nop 0
	ds_read_b128 v[128:131], v171
	ds_read_b128 v[132:135], v171 offset:1024
	ds_read_b128 v[136:139], v171 offset:2048
	ds_read_b128 v[140:143], v171 offset:3072
	ds_read_b128 v[160:163], v172
	ds_read_b128 v[176:179], v172 offset:1024
	ds_read_b128 v[180:183], v172 offset:2048
	ds_read_b128 v[184:187], v172 offset:3072
	s_add_u32 s28, s26, 0xfffc0080
	s_addc_u32 s29, s27, -1
	s_cmp_eq_u32 s54, 12
	s_cselect_b32 s31, s17, s29
	s_cselect_b32 s30, s50, s28
	s_cselect_b32 s29, s15, s53
	s_cselect_b32 s28, s51, s52
	v_lshl_add_u64 v[220:221], s[26:27], 0, v[152:153]
	s_add_i32 m0, s25, 0xc000
	ds_read_b128 v[188:191], v173
	ds_read_b128 v[192:195], v173 offset:1024
	ds_read_b128 v[196:199], v173 offset:2048
	ds_read_b128 v[200:203], v173 offset:3072
	ds_read_b128 v[204:207], v173 offset:4096
	ds_read_b128 v[208:211], v173 offset:5120
	ds_read_b128 v[212:215], v173 offset:6144
	ds_read_b128 v[216:219], v173 offset:7168
	global_load_lds_dwordx4 v[220:221], off
	v_lshl_add_u64 v[220:221], s[26:27], 0, v[154:155]
	s_add_i32 m0, s25, 0xe000
	s_nop 0
	global_load_lds_dwordx4 v[220:221], off
	s_waitcnt vmcnt(8)
	s_waitcnt lgkmcnt(0)
	s_barrier
	s_setprio 1
	s_waitcnt lgkmcnt(0)
	v_mfma_f32_16x16x32_bf16 v[124:127], v[128:131], v[188:191], v[124:127]
	v_mfma_f32_16x16x32_bf16 v[120:123], v[136:139], v[188:191], v[120:123]
	v_mfma_f32_16x16x32_bf16 v[116:119], v[128:131], v[196:199], v[116:119]
	v_mfma_f32_16x16x32_bf16 v[108:111], v[136:139], v[196:199], v[108:111]
	v_mfma_f32_16x16x32_bf16 v[96:99], v[128:131], v[204:207], v[96:99]
	v_mfma_f32_16x16x32_bf16 v[88:91], v[136:139], v[204:207], v[88:91]
	v_mfma_f32_16x16x32_bf16 v[84:87], v[128:131], v[212:215], v[84:87]
	v_mfma_f32_16x16x32_bf16 v[76:79], v[136:139], v[212:215], v[76:79]
	v_mfma_f32_16x16x32_bf16 v[124:127], v[132:135], v[192:195], v[124:127]
	v_mfma_f32_16x16x32_bf16 v[120:123], v[140:143], v[192:195], v[120:123]
	v_mfma_f32_16x16x32_bf16 v[116:119], v[132:135], v[200:203], v[116:119]
	v_mfma_f32_16x16x32_bf16 v[108:111], v[140:143], v[200:203], v[108:111]
	v_mfma_f32_16x16x32_bf16 v[96:99], v[132:135], v[208:211], v[96:99]
	v_mfma_f32_16x16x32_bf16 v[88:91], v[140:143], v[208:211], v[88:91]
	v_mfma_f32_16x16x32_bf16 v[84:87], v[132:135], v[216:219], v[84:87]
	v_mfma_f32_16x16x32_bf16 v[76:79], v[140:143], v[216:219], v[76:79]
	s_setprio 0
	s_setprio 1
	v_mfma_f32_16x16x32_bf16 v[112:115], v[160:163], v[188:191], v[112:115]
	v_mfma_f32_16x16x32_bf16 v[104:107], v[180:183], v[188:191], v[104:107]
	v_mfma_f32_16x16x32_bf16 v[100:103], v[160:163], v[196:199], v[100:103]
	v_mfma_f32_16x16x32_bf16 v[92:95], v[180:183], v[196:199], v[92:95]
	v_mfma_f32_16x16x32_bf16 v[80:83], v[160:163], v[204:207], v[80:83]
	v_mfma_f32_16x16x32_bf16 v[72:75], v[180:183], v[204:207], v[72:75]
	v_mfma_f32_16x16x32_bf16 v[68:71], v[160:163], v[212:215], v[68:71]
	v_mfma_f32_16x16x32_bf16 v[64:67], v[180:183], v[212:215], v[64:67]
	v_mfma_f32_16x16x32_bf16 v[112:115], v[176:179], v[192:195], v[112:115]
	v_mfma_f32_16x16x32_bf16 v[104:107], v[184:187], v[192:195], v[104:107]
	v_mfma_f32_16x16x32_bf16 v[100:103], v[176:179], v[200:203], v[100:103]
	v_mfma_f32_16x16x32_bf16 v[92:95], v[184:187], v[200:203], v[92:95]
	v_mfma_f32_16x16x32_bf16 v[80:83], v[176:179], v[208:211], v[80:83]
	v_mfma_f32_16x16x32_bf16 v[72:75], v[184:187], v[208:211], v[72:75]
	v_mfma_f32_16x16x32_bf16 v[68:71], v[176:179], v[216:219], v[68:71]
	v_mfma_f32_16x16x32_bf16 v[64:67], v[184:187], v[216:219], v[64:67]
	s_setprio 0
	s_barrier
	s_add_i32 s55, s44, s22
	v_lshl_add_u64 v[220:221], s[28:29], 0, v[146:147]
	s_mov_b32 m0, s55
	ds_read_b128 v[188:191], v173 offset:16384
	ds_read_b128 v[192:195], v173 offset:17408
	ds_read_b128 v[196:199], v173 offset:18432
	ds_read_b128 v[200:203], v173 offset:19456
	ds_read_b128 v[204:207], v173 offset:20480
	ds_read_b128 v[208:211], v173 offset:21504
	ds_read_b128 v[212:215], v173 offset:22528
	ds_read_b128 v[216:219], v173 offset:23552
	global_load_lds_dwordx4 v[220:221], off
	s_add_i32 m0, s55, 0x2000
	s_add_u32 s56, s28, 0x10000
	v_lshl_add_u64 v[222:223], s[28:29], 0, v[150:151]
	s_addc_u32 s57, s29, 0
	s_add_i32 s55, s45, s22
	global_load_lds_dwordx4 v[222:223], off
	v_lshl_add_u64 v[224:225], s[56:57], 0, v[146:147]
	s_mov_b32 m0, s55
	v_lshl_add_u64 v[226:227], s[30:31], 0, v[148:149]
	global_load_lds_dwordx4 v[224:225], off
	v_lshl_add_u64 v[224:225], s[56:57], 0, v[150:151]
	s_add_i32 m0, s55, 0x2000
	s_nop 0
	global_load_lds_dwordx4 v[224:225], off
	v_lshl_add_u64 v[224:225], s[30:31], 0, v[144:145]
	s_mov_b32 m0, s25
	s_nop 0
	global_load_lds_dwordx4 v[224:225], off
	s_mov_b32 m0, s36
	s_nop 0
	global_load_lds_dwordx4 v[226:227], off
	s_waitcnt vmcnt(8)
	s_waitcnt lgkmcnt(0)
	s_barrier
; #define PG8_STAGE(bufoff, gbase, voff) do { _Pragma("unroll") for (int _i = 0; _i < 2; ++_i) \
;         __builtin_amdgcn_global_load_lds((const unsigned*)((const char*)(gbase) + (voff)[_i]), (PG8_LAS unsigned*)(lds + (bufoff) + ldsw + _i * 8192), 16, 0, 0); } while (0)
; #define PG8_LDA(dst, b, h) do { _Pragma("unroll") for (int m = 0; m < 4; ++m) _Pragma("unroll") for (int k = 0; k < 2; ++k) dst[m][k] = *(const PG8_LAS bf16x8*)(lds + PG8_SA(b, h) + aoff + m * 2048 + k * 1024); } while (0)
; #define PG8_LDB(dst, b, h) do { _Pragma("unroll") for (int n = 0; n < 2; ++n) _Pragma("unroll") for (int k = 0; k < 2; ++k) dst[n][k] = *(const PG8_LAS bf16x8*)(lds + PG8_SB(b, h) + boff + n * 2048 + k * 1024); } while (0)
; #define PG8_MMA(ai, bj, At, Bt) do { __builtin_amdgcn_s_setprio(1); _Pragma("unroll") for (int m = 0; m < 4; ++m) _Pragma("unroll") for (int n = 0; n < 2; ++n) _Pragma("unroll") for (int k = 0; k < 2; ++k) \
;         acc[ai][bj][m][n] = __builtin_amdgcn_mfma_f32_16x16x32_bf16(Bt[n][k], At[m][k], acc[ai][bj][m][n], 0, 0, 0); __builtin_amdgcn_s_setprio(0); } while (0)
; #define PG8_WAIT_V(n) asm volatile("s_waitcnt vmcnt(" #n ")" ::: "memory")
; #define PG8_WAIT_L(n) asm volatile("s_waitcnt lgkmcnt(" #n ")" ::: "memory")
; #define PG8_BAR __builtin_amdgcn_s_barrier()
; #define PG8_SCHED __builtin_amdgcn_sched_barrier(0)
; template <class Epi, class Sched, bool ALIGN_EPI = false, bool SP2 = false>
; __device__ __forceinline__ void gemm_phase(PG8_LAS unsigned char* lds, const Gemm g, const Sched& S, const Epi& E) {
;     ...
;             PG8_WAIT_V(8); PG8_WAIT_L(0); PG8_BAR; PG8_MMA(1, 0, At, B0); PG8_MMA(1, 1, At, B1); PG8_BAR; PG8_SCHED;
;             PG8_LDB(B0, 1, 0); PG8_LDB(B1, 1, 1); PG8_SCHED; PG8_LDA(At, 1, 0); PG8_STAGE(PG8_SA(0, 1), a2 + hstep, voffA);
;             PG8_WAIT_V(8); PG8_WAIT_L(0); PG8_BAR; PG8_MMA(0, 0, At, B0); PG8_MMA(0, 1, At, B1); PG8_BAR; PG8_SCHED;
	s_setprio 1
	s_waitcnt lgkmcnt(0)
	v_mfma_f32_16x16x32_bf16 v[60:63], v[128:131], v[188:191], v[60:63]
	v_mfma_f32_16x16x32_bf16 v[56:59], v[136:139], v[188:191], v[56:59]
	v_mfma_f32_16x16x32_bf16 v[52:55], v[128:131], v[196:199], v[52:55]
	v_mfma_f32_16x16x32_bf16 v[44:47], v[136:139], v[196:199], v[44:47]
	v_mfma_f32_16x16x32_bf16 v[32:35], v[128:131], v[204:207], v[32:35]
	v_mfma_f32_16x16x32_bf16 v[24:27], v[136:139], v[204:207], v[24:27]
	v_mfma_f32_16x16x32_bf16 v[20:23], v[128:131], v[212:215], v[20:23]
	v_mfma_f32_16x16x32_bf16 v[12:15], v[136:139], v[212:215], v[12:15]
	v_mfma_f32_16x16x32_bf16 v[60:63], v[132:135], v[192:195], v[60:63]
	v_mfma_f32_16x16x32_bf16 v[56:59], v[140:143], v[192:195], v[56:59]
	v_mfma_f32_16x16x32_bf16 v[52:55], v[132:135], v[200:203], v[52:55]
	v_mfma_f32_16x16x32_bf16 v[44:47], v[140:143], v[200:203], v[44:47]
	v_mfma_f32_16x16x32_bf16 v[32:35], v[132:135], v[208:211], v[32:35]
	v_mfma_f32_16x16x32_bf16 v[24:27], v[140:143], v[208:211], v[24:27]
	v_mfma_f32_16x16x32_bf16 v[20:23], v[132:135], v[216:219], v[20:23]
	v_mfma_f32_16x16x32_bf16 v[12:15], v[140:143], v[216:219], v[12:15]
	s_setprio 0
	s_setprio 1
	v_mfma_f32_16x16x32_bf16 v[48:51], v[160:163], v[188:191], v[48:51]
	v_mfma_f32_16x16x32_bf16 v[40:43], v[180:183], v[188:191], v[40:43]
	v_mfma_f32_16x16x32_bf16 v[36:39], v[160:163], v[196:199], v[36:39]
	v_mfma_f32_16x16x32_bf16 v[28:31], v[180:183], v[196:199], v[28:31]
	v_mfma_f32_16x16x32_bf16 v[16:19], v[160:163], v[204:207], v[16:19]
	v_mfma_f32_16x16x32_bf16 v[8:11], v[180:183], v[204:207], v[8:11]
	v_mfma_f32_16x16x32_bf16 v[4:7], v[160:163], v[212:215], v[4:7]
	v_mfma_f32_16x16x32_bf16 v[0:3], v[180:183], v[212:215], v[0:3]
	v_mfma_f32_16x16x32_bf16 v[48:51], v[176:179], v[192:195], v[48:51]
	v_mfma_f32_16x16x32_bf16 v[40:43], v[184:187], v[192:195], v[40:43]
	v_mfma_f32_16x16x32_bf16 v[36:39], v[176:179], v[200:203], v[36:39]
	v_mfma_f32_16x16x32_bf16 v[28:31], v[184:187], v[200:203], v[28:31]
	v_mfma_f32_16x16x32_bf16 v[16:19], v[176:179], v[208:211], v[16:19]
	v_mfma_f32_16x16x32_bf16 v[8:11], v[184:187], v[208:211], v[8:11]
	v_mfma_f32_16x16x32_bf16 v[4:7], v[176:179], v[216:219], v[4:7]
	v_mfma_f32_16x16x32_bf16 v[0:3], v[184:187], v[216:219], v[0:3]
	s_setprio 0
	s_barrier
	s_add_i32 s55, 0, 0x18000
	s_add_i32 s56, 0, 0x1c000
	v_add_u32_e32 v140, s55, v167
	v_add_u32_e32 v175, s56, v167
	ds_read_b128 v[128:131], v140
	ds_read_b128 v[132:135], v140 offset:1024
	ds_read_b128 v[136:139], v140 offset:2048
	ds_read_b128 v[140:143], v140 offset:3072
	ds_read_b128 v[160:163], v175
	ds_read_b128 v[176:179], v175 offset:1024
	ds_read_b128 v[180:183], v175 offset:2048
	ds_read_b128 v[184:187], v175 offset:3072
	s_add_u32 s30, s30, 0x40000
	s_addc_u32 s31, s31, 0
	s_mov_b32 m0, s37
	v_lshl_add_u64 v[228:229], s[30:31], 0, v[144:145]
	ds_read_b128 v[188:191], v173 offset:32768
	ds_read_b128 v[192:195], v173 offset:33792
	ds_read_b128 v[196:199], v173 offset:34816
	ds_read_b128 v[200:203], v173 offset:35840
	ds_read_b128 v[204:207], v173 offset:36864
	ds_read_b128 v[208:211], v173 offset:37888
	ds_read_b128 v[212:215], v173 offset:38912
	ds_read_b128 v[216:219], v173 offset:39936
	global_load_lds_dwordx4 v[228:229], off
	v_lshl_add_u64 v[228:229], s[30:31], 0, v[148:149]
	s_mov_b32 m0, s38
	s_nop 0
	global_load_lds_dwordx4 v[228:229], off
	s_waitcnt vmcnt(8)
	s_waitcnt lgkmcnt(0)
	s_barrier
	s_setprio 1
	s_waitcnt lgkmcnt(0)
	v_mfma_f32_16x16x32_bf16 v[124:127], v[128:131], v[188:191], v[124:127]
	v_mfma_f32_16x16x32_bf16 v[120:123], v[136:139], v[188:191], v[120:123]
	v_mfma_f32_16x16x32_bf16 v[116:119], v[128:131], v[196:199], v[116:119]
	v_mfma_f32_16x16x32_bf16 v[108:111], v[136:139], v[196:199], v[108:111]
	v_mfma_f32_16x16x32_bf16 v[96:99], v[128:131], v[204:207], v[96:99]
	v_mfma_f32_16x16x32_bf16 v[88:91], v[136:139], v[204:207], v[88:91]
	v_mfma_f32_16x16x32_bf16 v[84:87], v[128:131], v[212:215], v[84:87]
	v_mfma_f32_16x16x32_bf16 v[76:79], v[136:139], v[212:215], v[76:79]
	v_mfma_f32_16x16x32_bf16 v[124:127], v[132:135], v[192:195], v[124:127]
	v_mfma_f32_16x16x32_bf16 v[120:123], v[140:143], v[192:195], v[120:123]
	v_mfma_f32_16x16x32_bf16 v[116:119], v[132:135], v[200:203], v[116:119]
	v_mfma_f32_16x16x32_bf16 v[108:111], v[140:143], v[200:203], v[108:111]
	v_mfma_f32_16x16x32_bf16 v[96:99], v[132:135], v[208:211], v[96:99]
	v_mfma_f32_16x16x32_bf16 v[88:91], v[140:143], v[208:211], v[88:91]
	v_mfma_f32_16x16x32_bf16 v[84:87], v[132:135], v[216:219], v[84:87]
	v_mfma_f32_16x16x32_bf16 v[76:79], v[140:143], v[216:219], v[76:79]
	s_setprio 0
	s_setprio 1
	v_mfma_f32_16x16x32_bf16 v[112:115], v[160:163], v[188:191], v[112:115]
	v_mfma_f32_16x16x32_bf16 v[104:107], v[180:183], v[188:191], v[104:107]
	v_mfma_f32_16x16x32_bf16 v[100:103], v[160:163], v[196:199], v[100:103]
	v_mfma_f32_16x16x32_bf16 v[92:95], v[180:183], v[196:199], v[92:95]
	v_mfma_f32_16x16x32_bf16 v[80:83], v[160:163], v[204:207], v[80:83]
	v_mfma_f32_16x16x32_bf16 v[72:75], v[180:183], v[204:207], v[72:75]
	v_mfma_f32_16x16x32_bf16 v[68:71], v[160:163], v[212:215], v[68:71]
	v_mfma_f32_16x16x32_bf16 v[64:67], v[180:183], v[212:215], v[64:67]
	v_mfma_f32_16x16x32_bf16 v[112:115], v[176:179], v[192:195], v[112:115]
	v_mfma_f32_16x16x32_bf16 v[104:107], v[184:187], v[192:195], v[104:107]
	v_mfma_f32_16x16x32_bf16 v[100:103], v[176:179], v[200:203], v[100:103]
	v_mfma_f32_16x16x32_bf16 v[92:95], v[184:187], v[200:203], v[92:95]
	v_mfma_f32_16x16x32_bf16 v[80:83], v[176:179], v[208:211], v[80:83]
	v_mfma_f32_16x16x32_bf16 v[72:75], v[184:187], v[208:211], v[72:75]
	v_mfma_f32_16x16x32_bf16 v[68:71], v[176:179], v[216:219], v[68:71]
	v_mfma_f32_16x16x32_bf16 v[64:67], v[184:187], v[216:219], v[64:67]
	s_setprio 0
	s_barrier
; #define PG8_STAGE(bufoff, gbase, voff) do { _Pragma("unroll") for (int _i = 0; _i < 2; ++_i) \
;         __builtin_amdgcn_global_load_lds((const unsigned*)((const char*)(gbase) + (voff)[_i]), (PG8_LAS unsigned*)(lds + (bufoff) + ldsw + _i * 8192), 16, 0, 0); } while (0)
; #define PG8_WAIT_V(n) asm volatile("s_waitcnt vmcnt(" #n ")" ::: "memory")
; template <class Epi, class Sched, bool ALIGN_EPI = false, bool SP2 = false>
; __device__ __forceinline__ void gemm_phase(PG8_LAS unsigned char* lds, const Gemm g, const Sched& S, const Epi& E) {
;     ...
;             PG8_LDA(At, 1, 1); PG8_STAGE(PG8_SB(1, 0), b3, voffB); PG8_STAGE(PG8_SB(1, 1), b3 + hstep, voffB); PG8_STAGE(PG8_SA(1, 0), a3, voffA);
;             PG8_WAIT_V(8); PG8_WAIT_L(0); PG8_BAR; PG8_MMA(1, 0, At, B0); PG8_MMA(1, 1, At, B1); PG8_BAR; PG8_SCHED;
;             } else {
;             PG8_LDB(B0, 0, 0); PG8_SCHED; PG8_LDA(At, 0, 0); PG8_STAGE(PG8_SA(1, 1), a1 + hstep, voffA);
;             PG8_WAIT_L(8); PG8_BAR; PG8_WAIT_L(0); PG8_MMA(0, 0, At, B0); PG8_BAR; PG8_SCHED;
;             PG8_LDB(B1, 0, 1); PG8_STAGE(PG8_SB(0, 0), b2, voffB);
;             PG8_BAR; PG8_WAIT_L(0); PG8_MMA(0, 1, At, B1); PG8_BAR;
;             PG8_LDA(At, 0, 1); PG8_STAGE(PG8_SA(0, 0), a2, voffA);
;             PG8_BAR; PG8_WAIT_L(0); PG8_MMA(1, 0, At, B0); PG8_BAR; PG8_SCHED;
;             PG8_STAGE(PG8_SB(0, 1), b2 + hstep, voffB);
;             PG8_WAIT_V(6); PG8_BAR; PG8_MMA(1, 1, At, B1); PG8_BAR;
;             PG8_LDB(B0, 1, 0); PG8_SCHED; PG8_LDA(At, 1, 0); PG8_STAGE(PG8_SA(0, 1), a2 + hstep, voffA);
;             PG8_WAIT_L(8); PG8_BAR; PG8_WAIT_L(0); PG8_MMA(0, 0, At, B0); PG8_BAR; PG8_SCHED;
;             PG8_LDB(B1, 1, 1); PG8_STAGE(PG8_SB(1, 0), b3, voffB);
;             PG8_BAR; PG8_WAIT_L(0); PG8_MMA(0, 1, At, B1); PG8_BAR;
;             PG8_LDA(At, 1, 1); PG8_STAGE(PG8_SA(1, 0), a3, voffA);
;             PG8_BAR; PG8_WAIT_L(0); PG8_MMA(1, 0, At, B0); PG8_BAR; PG8_SCHED;
;             PG8_STAGE(PG8_SB(1, 1), b3 + hstep, voffB);
;             PG8_WAIT_V(6); PG8_BAR; PG8_MMA(1, 1, At, B1); PG8_BAR;
;             }
;         }
;         if constexpr (ALIGN_EPI) { if (wr == 0) PG8_BAR; }
;         if constexpr (Epi::HAS_PRE) {
;             if (has_next) { const auto pn_ = E.pre_load(nxt.pm, tid); E(acc, cur, wr, wc, fr, fq, ptab + (ui & 1) * 256); E.pre_store(pn_, ptab + ((ui + 1) & 1) * 256, tid); }
	s_add_i32 s30, s55, s22
	v_lshl_add_u64 v[220:221], v[220:221], 0, s[10:11]
	s_mov_b32 m0, s30
	ds_read_b128 v[188:191], v173 offset:49152
	ds_read_b128 v[192:195], v173 offset:50176
	ds_read_b128 v[196:199], v173 offset:51200
	ds_read_b128 v[200:203], v173 offset:52224
	ds_read_b128 v[204:207], v173 offset:53248
	ds_read_b128 v[208:211], v173 offset:54272
	ds_read_b128 v[212:215], v173 offset:55296
	ds_read_b128 v[216:219], v173 offset:56320
	global_load_lds_dwordx4 v[220:221], off
	s_add_i32 m0, s30, 0x2000
	s_add_u32 s28, s28, 0x10080
	v_lshl_add_u64 v[220:221], v[222:223], 0, s[10:11]
	s_addc_u32 s29, s29, 0
	s_add_i32 s30, s56, s22
	global_load_lds_dwordx4 v[220:221], off
	v_lshl_add_u64 v[220:221], s[28:29], 0, v[146:147]
	s_mov_b32 m0, s30
	s_nop 0
	global_load_lds_dwordx4 v[220:221], off
	v_lshl_add_u64 v[220:221], s[28:29], 0, v[150:151]
	s_add_i32 m0, s30, 0x2000
	s_nop 0
	global_load_lds_dwordx4 v[220:221], off
	v_lshl_add_u64 v[220:221], v[224:225], 0, s[10:11]
	s_mov_b32 m0, s39
	s_nop 0
	global_load_lds_dwordx4 v[220:221], off
	v_lshl_add_u64 v[220:221], v[226:227], 0, s[10:11]
	s_mov_b32 m0, s40
	s_nop 0
	global_load_lds_dwordx4 v[220:221], off
	s_waitcnt vmcnt(8)
	s_waitcnt lgkmcnt(0)
	s_barrier
	s_setprio 1
	s_waitcnt lgkmcnt(0)
	v_mfma_f32_16x16x32_bf16 v[60:63], v[128:131], v[188:191], v[60:63]
	v_mfma_f32_16x16x32_bf16 v[56:59], v[136:139], v[188:191], v[56:59]
	v_mfma_f32_16x16x32_bf16 v[52:55], v[128:131], v[196:199], v[52:55]
	v_mfma_f32_16x16x32_bf16 v[44:47], v[136:139], v[196:199], v[44:47]
	v_mfma_f32_16x16x32_bf16 v[32:35], v[128:131], v[204:207], v[32:35]
	v_mfma_f32_16x16x32_bf16 v[24:27], v[136:139], v[204:207], v[24:27]
	v_mfma_f32_16x16x32_bf16 v[20:23], v[128:131], v[212:215], v[20:23]
	v_mfma_f32_16x16x32_bf16 v[12:15], v[136:139], v[212:215], v[12:15]
	v_mfma_f32_16x16x32_bf16 v[60:63], v[132:135], v[192:195], v[60:63]
	v_mfma_f32_16x16x32_bf16 v[56:59], v[140:143], v[192:195], v[56:59]
	v_mfma_f32_16x16x32_bf16 v[52:55], v[132:135], v[200:203], v[52:55]
	v_mfma_f32_16x16x32_bf16 v[44:47], v[140:143], v[200:203], v[44:47]
	v_mfma_f32_16x16x32_bf16 v[32:35], v[132:135], v[208:211], v[32:35]
	v_mfma_f32_16x16x32_bf16 v[24:27], v[140:143], v[208:211], v[24:27]
	v_mfma_f32_16x16x32_bf16 v[20:23], v[132:135], v[216:219], v[20:23]
	v_mfma_f32_16x16x32_bf16 v[12:15], v[140:143], v[216:219], v[12:15]
	s_setprio 0
	s_setprio 1
	v_mfma_f32_16x16x32_bf16 v[48:51], v[160:163], v[188:191], v[48:51]
	v_mfma_f32_16x16x32_bf16 v[40:43], v[180:183], v[188:191], v[40:43]
	v_mfma_f32_16x16x32_bf16 v[36:39], v[160:163], v[196:199], v[36:39]
	v_mfma_f32_16x16x32_bf16 v[28:31], v[180:183], v[196:199], v[28:31]
	v_mfma_f32_16x16x32_bf16 v[16:19], v[160:163], v[204:207], v[16:19]
	v_mfma_f32_16x16x32_bf16 v[8:11], v[180:183], v[204:207], v[8:11]
	v_mfma_f32_16x16x32_bf16 v[4:7], v[160:163], v[212:215], v[4:7]
	v_mfma_f32_16x16x32_bf16 v[0:3], v[180:183], v[212:215], v[0:3]
	v_mfma_f32_16x16x32_bf16 v[48:51], v[176:179], v[192:195], v[48:51]
	v_mfma_f32_16x16x32_bf16 v[40:43], v[184:187], v[192:195], v[40:43]
	v_mfma_f32_16x16x32_bf16 v[36:39], v[176:179], v[200:203], v[36:39]
	v_mfma_f32_16x16x32_bf16 v[28:31], v[184:187], v[200:203], v[28:31]
	v_mfma_f32_16x16x32_bf16 v[16:19], v[176:179], v[208:211], v[16:19]
	v_mfma_f32_16x16x32_bf16 v[8:11], v[184:187], v[208:211], v[8:11]
	v_mfma_f32_16x16x32_bf16 v[4:7], v[176:179], v[216:219], v[4:7]
	v_mfma_f32_16x16x32_bf16 v[0:3], v[184:187], v[216:219], v[0:3]
	s_setprio 0
	s_barrier
	s_add_i32 s54, s54, 2
	s_add_u32 s26, s26, 0x100
	s_addc_u32 s27, s27, 0
	s_add_u32 s52, s52, 0x100
	s_addc_u32 s53, s53, 0
	s_cmp_gt_u32 s54, 13
	s_cbranch_scc0 .LBB0_130
	v_mbcnt_lo_u32_b32 v234, -1, 0
	v_mbcnt_hi_u32_b32 v234, -1, v234
	v_bfe_u32 v234, v234, 3, 1
	v_sub_u32_e32 v249, 0, v234
	v_and_b32_e32 v248, 0xffff3040, v249
	v_and_b32_e32 v235, 0xcfc0, v249
	v_sub_u32_e32 v250, 0xd000, v235
	v_mov_b32_e32 v251, 0
	s_mov_b32 s98, 0xff00ff
	s_mov_b32 s99, 0xff00ff
	s_and_b64 vcc, exec, s[12:13]
	s_cbranch_vccz .LBB0_133
	s_barrier
.LBB0_133:
	s_mov_b64 s[26:27], -1
	s_and_b64 vcc, exec, s[6:7]
	v_lshl_add_u32 v175, s24, 8, v165
	v_lshl_or_b32 v160, s49, 8, v170
	v_add_u32_e32 v160, s100, v160
	s_cbranch_vccnz .LBB0_136
	s_andn2_b64 vcc, exec, s[26:27]
	s_cbranch_vccz .LBB0_137

; #define PG8_LAS __attribute__((address_space(3)))
; __device__ __forceinline__ unsigned cvt_pk_bf16(float lo, float hi) { const f32x2_t v = {lo, hi}; const bf16x2_t b = __builtin_convertvector(v, bf16x2_t); return __builtin_bit_cast(unsigned, b); }
;     __device__ __forceinline__ void operator()(const f32x4 (&acc)[2][2][4][2], const Unit& u, int wr, int wc, int fr, int fq, const PG8_LAS float* tab) const {
;         const int rl0 = wr * 64 + fr; const int row0 = u.pm * BM + rl0; const int col0 = u.pn * BM + wc * 32 + 8 * fq;
; #pragma unroll
;         for (int ai = 0; ai < 2; ++ai)
; #pragma unroll
;             for (int m = 0; m < 4; ++m) { const int row = row0 + ai * HALF + m * 16; bf16_t* rowp = O + (size_t)row * ldc + col0;
;                 const float rstd = tab[rl0 + ai * HALF + m * 16];
; #pragma unroll
;                 for (int bj = 0; bj < 2; ++bj) { f32x4 v0 = acc[ai][bj][m][0] * rstd, v1 = acc[ai][bj][m][1] * rstd;
;                     if (ACT == 1) {
; #pragma unroll
;                         for (int e = 0; e < 4; ++e) { float a = v0[e] > 0.f ? v0[e] : 0.f; v0[e] = a * a; float b = v1[e] > 0.f ? v1[e] : 0.f; v1[e] = b * b; } }
;                     u32x4 w; w.x = cvt_pk_bf16(v0[0], v0[1]); w.y = cvt_pk_bf16(v0[2], v0[3]); w.z = cvt_pk_bf16(v1[0], v1[1]); w.w = cvt_pk_bf16(v1[2], v1[3]);
;                     *(u32x4*)(rowp + bj * HALF) = w; } }
.LBB0_136:
	s_lshl_b32 s6, s23, 10
	s_and_b32 s6, s6, 0x400
	v_add_u32_e32 v162, s6, v168
	ds_read2_b32 v[136:137], v162 offset1:16
	v_ashrrev_i32_e32 v161, 31, v160
	v_mov_b64_e32 v[128:129], s[92:93]
	v_mad_i64_i32 v[132:133], s[6:7], v175, s46, v[128:129]
	v_lshlrev_b64 v[130:131], 1, v[160:161]
	v_lshl_add_u64 v[138:139], v[132:133], 0, v[130:131]
	s_waitcnt lgkmcnt(0)
	v_pk_mul_f32 v[134:135], v[126:127], v[136:137] op_sel_hi:[1,0]
	v_pk_mul_f32 v[132:133], v[124:125], v[136:137] op_sel_hi:[1,0]
	v_pk_mul_f32 v[140:141], v[122:123], v[136:137] op_sel_hi:[1,0]
	v_pk_mul_f32 v[142:143], v[120:121], v[136:137] op_sel_hi:[1,0]
	v_cvt_pk_bf16_f32 v132, v132, v133
	v_cvt_pk_bf16_f32 v133, v134, v135
	v_cvt_pk_bf16_f32 v134, v142, v143
	v_cvt_pk_bf16_f32 v135, v140, v141
	v_mov_b32_e32 v236, v132
	v_mov_b32_e32 v237, v133
	v_mov_b32_e32 v238, v134
	v_mov_b32_e32 v239, v135
	v_lshl_add_u64 v[230:231], v[138:139], 0, v[248:249]
	v_lshl_add_u64 v[232:233], v[138:139], 0, v[250:251]
	v_pk_mul_f32 v[140:141], v[106:107], v[136:137] op_sel_hi:[1,0]
	v_pk_mul_f32 v[142:143], v[104:105], v[136:137] op_sel_hi:[1,0]
	v_pk_mul_f32 v[134:135], v[114:115], v[136:137] op_sel_hi:[1,0]
	v_pk_mul_f32 v[132:133], v[112:113], v[136:137] op_sel_hi:[1,0]
	v_mov_b32_e32 v136, v137
	v_cvt_pk_bf16_f32 v132, v132, v133
	v_cvt_pk_bf16_f32 v133, v134, v135
	v_cvt_pk_bf16_f32 v134, v142, v143
	v_cvt_pk_bf16_f32 v135, v140, v141
	ds_swizzle_b32 v240, v132 offset:swizzle(SWAP,8)
	ds_swizzle_b32 v241, v133 offset:swizzle(SWAP,8)
	ds_swizzle_b32 v242, v134 offset:swizzle(SWAP,8)
	ds_swizzle_b32 v243, v135 offset:swizzle(SWAP,8)
	ds_swizzle_b32 v244, v236 offset:swizzle(SWAP,8)
	ds_swizzle_b32 v245, v237 offset:swizzle(SWAP,8)
	ds_swizzle_b32 v246, v238 offset:swizzle(SWAP,8)
	ds_swizzle_b32 v247, v239 offset:swizzle(SWAP,8)
	s_waitcnt lgkmcnt(0)
	v_cndmask_b32_e64 v240, v240, v236, s[98:99]
	v_cndmask_b32_e64 v241, v241, v237, s[98:99]
	v_cndmask_b32_e64 v242, v242, v238, s[98:99]
	v_cndmask_b32_e64 v243, v243, v239, s[98:99]
	v_cndmask_b32_e64 v244, v132, v244, s[98:99]
	v_cndmask_b32_e64 v245, v133, v245, s[98:99]
	v_cndmask_b32_e64 v246, v134, v246, s[98:99]
	v_cndmask_b32_e64 v247, v135, v247, s[98:99]
	global_store_dwordx4 v[230:231], v[240:243], off
	global_store_dwordx4 v[232:233], v[244:247], off
	v_pk_mul_f32 v[140:141], v[110:111], v[136:137] op_sel_hi:[1,0]
	v_pk_mul_f32 v[142:143], v[108:109], v[136:137] op_sel_hi:[1,0]
	v_or_b32_e32 v132, 16, v175
	v_mad_i64_i32 v[132:133], s[6:7], v132, s46, v[128:129]
	v_lshl_add_u64 v[138:139], v[132:133], 0, v[130:131]
	v_pk_mul_f32 v[134:135], v[118:119], v[136:137] op_sel_hi:[1,0]
	v_pk_mul_f32 v[132:133], v[116:117], v[136:137] op_sel_hi:[1,0]
	s_nop 0
	v_cvt_pk_bf16_f32 v132, v132, v133
	v_cvt_pk_bf16_f32 v133, v134, v135
	v_cvt_pk_bf16_f32 v134, v142, v143
	v_cvt_pk_bf16_f32 v135, v140, v141
	v_mov_b32_e32 v236, v132
	v_mov_b32_e32 v237, v133
	v_mov_b32_e32 v238, v134
	v_mov_b32_e32 v239, v135
	v_lshl_add_u64 v[230:231], v[138:139], 0, v[248:249]
	v_lshl_add_u64 v[232:233], v[138:139], 0, v[250:251]
	v_pk_mul_f32 v[140:141], v[94:95], v[136:137] op_sel_hi:[1,0]
	s_nop 0
	v_pk_mul_f32 v[134:135], v[102:103], v[136:137] op_sel_hi:[1,0]
	v_pk_mul_f32 v[132:133], v[100:101], v[136:137] op_sel_hi:[1,0]
	v_pk_mul_f32 v[136:137], v[92:93], v[136:137] op_sel_hi:[1,0]
	v_cvt_pk_bf16_f32 v132, v132, v133
	v_cvt_pk_bf16_f32 v133, v134, v135
	v_cvt_pk_bf16_f32 v134, v136, v137
	ds_read2_b32 v[136:137], v162 offset0:32 offset1:48
	v_cvt_pk_bf16_f32 v135, v140, v141
	ds_swizzle_b32 v240, v132 offset:swizzle(SWAP,8)
	ds_swizzle_b32 v241, v133 offset:swizzle(SWAP,8)
	ds_swizzle_b32 v242, v134 offset:swizzle(SWAP,8)
	ds_swizzle_b32 v243, v135 offset:swizzle(SWAP,8)
	ds_swizzle_b32 v244, v236 offset:swizzle(SWAP,8)
	ds_swizzle_b32 v245, v237 offset:swizzle(SWAP,8)
	ds_swizzle_b32 v246, v238 offset:swizzle(SWAP,8)
	ds_swizzle_b32 v247, v239 offset:swizzle(SWAP,8)
	s_waitcnt lgkmcnt(0)
	v_cndmask_b32_e64 v240, v240, v236, s[98:99]
	v_cndmask_b32_e64 v241, v241, v237, s[98:99]
	v_cndmask_b32_e64 v242, v242, v238, s[98:99]
	v_cndmask_b32_e64 v243, v243, v239, s[98:99]
	v_cndmask_b32_e64 v244, v132, v244, s[98:99]
	v_cndmask_b32_e64 v245, v133, v245, s[98:99]
	v_cndmask_b32_e64 v246, v134, v246, s[98:99]
	v_cndmask_b32_e64 v247, v135, v247, s[98:99]
	global_store_dwordx4 v[230:231], v[240:243], off
	global_store_dwordx4 v[232:233], v[244:247], off
	s_waitcnt lgkmcnt(0)
	v_pk_mul_f32 v[140:141], v[90:91], v[136:137] op_sel_hi:[1,0]
	v_or_b32_e32 v132, 32, v175
	v_mad_i64_i32 v[132:133], s[6:7], v132, s46, v[128:129]
	v_lshl_add_u64 v[138:139], v[132:133], 0, v[130:131]
	v_pk_mul_f32 v[134:135], v[98:99], v[136:137] op_sel_hi:[1,0]
	v_pk_mul_f32 v[132:133], v[96:97], v[136:137] op_sel_hi:[1,0]
	v_pk_mul_f32 v[142:143], v[88:89], v[136:137] op_sel_hi:[1,0]
	v_cvt_pk_bf16_f32 v132, v132, v133
	v_cvt_pk_bf16_f32 v133, v134, v135
	v_cvt_pk_bf16_f32 v134, v142, v143
	v_cvt_pk_bf16_f32 v135, v140, v141
	v_mov_b32_e32 v236, v132
	v_mov_b32_e32 v237, v133
	v_mov_b32_e32 v238, v134
	v_mov_b32_e32 v239, v135
	v_lshl_add_u64 v[230:231], v[138:139], 0, v[248:249]
	v_lshl_add_u64 v[232:233], v[138:139], 0, v[250:251]
	v_pk_mul_f32 v[140:141], v[74:75], v[136:137] op_sel_hi:[1,0]
	v_pk_mul_f32 v[142:143], v[72:73], v[136:137] op_sel_hi:[1,0]
	v_pk_mul_f32 v[134:135], v[82:83], v[136:137] op_sel_hi:[1,0]
	v_pk_mul_f32 v[132:133], v[80:81], v[136:137] op_sel_hi:[1,0]
	v_mov_b32_e32 v136, v137
	v_cvt_pk_bf16_f32 v132, v132, v133
	v_cvt_pk_bf16_f32 v133, v134, v135
	v_cvt_pk_bf16_f32 v134, v142, v143
	v_cvt_pk_bf16_f32 v135, v140, v141
	ds_swizzle_b32 v240, v132 offset:swizzle(SWAP,8)
	ds_swizzle_b32 v241, v133 offset:swizzle(SWAP,8)
	ds_swizzle_b32 v242, v134 offset:swizzle(SWAP,8)
	ds_swizzle_b32 v243, v135 offset:swizzle(SWAP,8)
	ds_swizzle_b32 v244, v236 offset:swizzle(SWAP,8)
	ds_swizzle_b32 v245, v237 offset:swizzle(SWAP,8)
	ds_swizzle_b32 v246, v238 offset:swizzle(SWAP,8)
	ds_swizzle_b32 v247, v239 offset:swizzle(SWAP,8)
	s_waitcnt lgkmcnt(0)
; __device__ __forceinline__ unsigned cvt_pk_bf16(float lo, float hi) { const f32x2_t v = {lo, hi}; const bf16x2_t b = __builtin_convertvector(v, bf16x2_t); return __builtin_bit_cast(unsigned, b); }
;     __device__ __forceinline__ void operator()(const f32x4 (&acc)[2][2][4][2], const Unit& u, int wr, int wc, int fr, int fq, const PG8_LAS float* tab) const {
;     ...
;             for (int m = 0; m < 4; ++m) { const int row = row0 + ai * HALF + m * 16; bf16_t* rowp = O + (size_t)row * ldc + col0;
;                 const float rstd = tab[rl0 + ai * HALF + m * 16];
; #pragma unroll
;                 for (int bj = 0; bj < 2; ++bj) { f32x4 v0 = acc[ai][bj][m][0] * rstd, v1 = acc[ai][bj][m][1] * rstd;
;                     if (ACT == 1) {
; #pragma unroll
;                         for (int e = 0; e < 4; ++e) { float a = v0[e] > 0.f ? v0[e] : 0.f; v0[e] = a * a; float b = v1[e] > 0.f ? v1[e] : 0.f; v1[e] = b * b; } }
;                     u32x4 w; w.x = cvt_pk_bf16(v0[0], v0[1]); w.y = cvt_pk_bf16(v0[2], v0[3]); w.z = cvt_pk_bf16(v1[0], v1[1]); w.w = cvt_pk_bf16(v1[2], v1[3]);
;                     *(u32x4*)(rowp + bj * HALF) = w; } }
	v_cndmask_b32_e64 v240, v240, v236, s[98:99]
	v_cndmask_b32_e64 v241, v241, v237, s[98:99]
	v_cndmask_b32_e64 v242, v242, v238, s[98:99]
	v_cndmask_b32_e64 v243, v243, v239, s[98:99]
	v_cndmask_b32_e64 v244, v132, v244, s[98:99]
	v_cndmask_b32_e64 v245, v133, v245, s[98:99]
	v_cndmask_b32_e64 v246, v134, v246, s[98:99]
	v_cndmask_b32_e64 v247, v135, v247, s[98:99]
	global_store_dwordx4 v[230:231], v[240:243], off
	global_store_dwordx4 v[232:233], v[244:247], off
	v_pk_mul_f32 v[140:141], v[78:79], v[136:137] op_sel_hi:[1,0]
	v_pk_mul_f32 v[142:143], v[76:77], v[136:137] op_sel_hi:[1,0]
	v_or_b32_e32 v132, 48, v175
	v_mad_i64_i32 v[132:133], s[6:7], v132, s46, v[128:129]
	v_lshl_add_u64 v[138:139], v[132:133], 0, v[130:131]
	v_pk_mul_f32 v[134:135], v[86:87], v[136:137] op_sel_hi:[1,0]
	v_pk_mul_f32 v[132:133], v[84:85], v[136:137] op_sel_hi:[1,0]
	s_nop 0
	v_cvt_pk_bf16_f32 v132, v132, v133
	v_cvt_pk_bf16_f32 v133, v134, v135
	v_cvt_pk_bf16_f32 v134, v142, v143
	v_cvt_pk_bf16_f32 v135, v140, v141
	v_mov_b32_e32 v236, v132
	v_mov_b32_e32 v237, v133
	v_mov_b32_e32 v238, v134
	v_mov_b32_e32 v239, v135
	v_lshl_add_u64 v[230:231], v[138:139], 0, v[248:249]
	v_lshl_add_u64 v[232:233], v[138:139], 0, v[250:251]
	v_pk_mul_f32 v[140:141], v[66:67], v[136:137] op_sel_hi:[1,0]
	s_nop 0
	v_pk_mul_f32 v[134:135], v[70:71], v[136:137] op_sel_hi:[1,0]
	v_pk_mul_f32 v[132:133], v[68:69], v[136:137] op_sel_hi:[1,0]
	v_pk_mul_f32 v[136:137], v[64:65], v[136:137] op_sel_hi:[1,0]
	v_cvt_pk_bf16_f32 v132, v132, v133
	v_cvt_pk_bf16_f32 v133, v134, v135
	v_cvt_pk_bf16_f32 v134, v136, v137
	ds_read2_b32 v[136:137], v162 offset0:128 offset1:144
	v_cvt_pk_bf16_f32 v135, v140, v141
	ds_swizzle_b32 v240, v132 offset:swizzle(SWAP,8)
	ds_swizzle_b32 v241, v133 offset:swizzle(SWAP,8)
	ds_swizzle_b32 v242, v134 offset:swizzle(SWAP,8)
	ds_swizzle_b32 v243, v135 offset:swizzle(SWAP,8)
	ds_swizzle_b32 v244, v236 offset:swizzle(SWAP,8)
	ds_swizzle_b32 v245, v237 offset:swizzle(SWAP,8)
	ds_swizzle_b32 v246, v238 offset:swizzle(SWAP,8)
	ds_swizzle_b32 v247, v239 offset:swizzle(SWAP,8)
	s_waitcnt lgkmcnt(0)
	v_cndmask_b32_e64 v240, v240, v236, s[98:99]
	v_cndmask_b32_e64 v241, v241, v237, s[98:99]
	v_cndmask_b32_e64 v242, v242, v238, s[98:99]
	v_cndmask_b32_e64 v243, v243, v239, s[98:99]
	v_cndmask_b32_e64 v244, v132, v244, s[98:99]
	v_cndmask_b32_e64 v245, v133, v245, s[98:99]
	v_cndmask_b32_e64 v246, v134, v246, s[98:99]
	v_cndmask_b32_e64 v247, v135, v247, s[98:99]
	global_store_dwordx4 v[230:231], v[240:243], off
	global_store_dwordx4 v[232:233], v[244:247], off
	s_waitcnt lgkmcnt(0)
	v_pk_mul_f32 v[140:141], v[58:59], v[136:137] op_sel_hi:[1,0]
	v_add_u32_e32 v132, 0x80, v175
	v_mad_i64_i32 v[132:133], s[6:7], v132, s46, v[128:129]
	v_lshl_add_u64 v[138:139], v[132:133], 0, v[130:131]
	v_pk_mul_f32 v[134:135], v[62:63], v[136:137] op_sel_hi:[1,0]
	v_pk_mul_f32 v[132:133], v[60:61], v[136:137] op_sel_hi:[1,0]
	v_pk_mul_f32 v[142:143], v[56:57], v[136:137] op_sel_hi:[1,0]
	v_cvt_pk_bf16_f32 v132, v132, v133
	v_cvt_pk_bf16_f32 v133, v134, v135
	v_cvt_pk_bf16_f32 v134, v142, v143
	v_cvt_pk_bf16_f32 v135, v140, v141
	v_mov_b32_e32 v236, v132
	v_mov_b32_e32 v237, v133
	v_mov_b32_e32 v238, v134
	v_mov_b32_e32 v239, v135
	v_lshl_add_u64 v[230:231], v[138:139], 0, v[248:249]
	v_lshl_add_u64 v[232:233], v[138:139], 0, v[250:251]
	v_pk_mul_f32 v[140:141], v[42:43], v[136:137] op_sel_hi:[1,0]
	v_pk_mul_f32 v[142:143], v[40:41], v[136:137] op_sel_hi:[1,0]
	v_pk_mul_f32 v[134:135], v[50:51], v[136:137] op_sel_hi:[1,0]
	v_pk_mul_f32 v[132:133], v[48:49], v[136:137] op_sel_hi:[1,0]
	v_mov_b32_e32 v136, v137
	v_cvt_pk_bf16_f32 v132, v132, v133
	v_cvt_pk_bf16_f32 v133, v134, v135
	v_cvt_pk_bf16_f32 v134, v142, v143
	v_cvt_pk_bf16_f32 v135, v140, v141
	ds_swizzle_b32 v240, v132 offset:swizzle(SWAP,8)
	ds_swizzle_b32 v241, v133 offset:swizzle(SWAP,8)
	ds_swizzle_b32 v242, v134 offset:swizzle(SWAP,8)
	ds_swizzle_b32 v243, v135 offset:swizzle(SWAP,8)
	ds_swizzle_b32 v244, v236 offset:swizzle(SWAP,8)
	ds_swizzle_b32 v245, v237 offset:swizzle(SWAP,8)
	ds_swizzle_b32 v246, v238 offset:swizzle(SWAP,8)
	ds_swizzle_b32 v247, v239 offset:swizzle(SWAP,8)
	s_waitcnt lgkmcnt(0)
	v_cndmask_b32_e64 v240, v240, v236, s[98:99]
	v_cndmask_b32_e64 v241, v241, v237, s[98:99]
	v_cndmask_b32_e64 v242, v242, v238, s[98:99]
	v_cndmask_b32_e64 v243, v243, v239, s[98:99]
	v_cndmask_b32_e64 v244, v132, v244, s[98:99]
	v_cndmask_b32_e64 v245, v133, v245, s[98:99]
	v_cndmask_b32_e64 v246, v134, v246, s[98:99]
	v_cndmask_b32_e64 v247, v135, v247, s[98:99]
	global_store_dwordx4 v[230:231], v[240:243], off
	global_store_dwordx4 v[232:233], v[244:247], off
	v_pk_mul_f32 v[140:141], v[46:47], v[136:137] op_sel_hi:[1,0]
	v_pk_mul_f32 v[142:143], v[44:45], v[136:137] op_sel_hi:[1,0]
	v_add_u32_e32 v132, 0x90, v175
	v_mad_i64_i32 v[132:133], s[6:7], v132, s46, v[128:129]
	v_lshl_add_u64 v[138:139], v[132:133], 0, v[130:131]
	v_pk_mul_f32 v[134:135], v[54:55], v[136:137] op_sel_hi:[1,0]
	v_pk_mul_f32 v[132:133], v[52:53], v[136:137] op_sel_hi:[1,0]
	s_nop 0
	v_cvt_pk_bf16_f32 v132, v132, v133
	v_cvt_pk_bf16_f32 v133, v134, v135
	v_cvt_pk_bf16_f32 v134, v142, v143
	v_cvt_pk_bf16_f32 v135, v140, v141
	v_mov_b32_e32 v236, v132
	v_mov_b32_e32 v237, v133
	v_mov_b32_e32 v238, v134
	v_mov_b32_e32 v239, v135
	v_lshl_add_u64 v[230:231], v[138:139], 0, v[248:249]
	v_lshl_add_u64 v[232:233], v[138:139], 0, v[250:251]
	v_pk_mul_f32 v[140:141], v[30:31], v[136:137] op_sel_hi:[1,0]
	s_nop 0
	v_pk_mul_f32 v[134:135], v[38:39], v[136:137] op_sel_hi:[1,0]
	v_pk_mul_f32 v[132:133], v[36:37], v[136:137] op_sel_hi:[1,0]
	v_pk_mul_f32 v[136:137], v[28:29], v[136:137] op_sel_hi:[1,0]
	v_cvt_pk_bf16_f32 v132, v132, v133
	v_cvt_pk_bf16_f32 v133, v134, v135
	v_cvt_pk_bf16_f32 v134, v136, v137
	ds_read2_b32 v[136:137], v162 offset0:160 offset1:176
	v_cvt_pk_bf16_f32 v135, v140, v141
	ds_swizzle_b32 v240, v132 offset:swizzle(SWAP,8)
	ds_swizzle_b32 v241, v133 offset:swizzle(SWAP,8)
	ds_swizzle_b32 v242, v134 offset:swizzle(SWAP,8)
	ds_swizzle_b32 v243, v135 offset:swizzle(SWAP,8)
	ds_swizzle_b32 v244, v236 offset:swizzle(SWAP,8)
	ds_swizzle_b32 v245, v237 offset:swizzle(SWAP,8)
	ds_swizzle_b32 v246, v238 offset:swizzle(SWAP,8)
	ds_swizzle_b32 v247, v239 offset:swizzle(SWAP,8)
	s_waitcnt lgkmcnt(0)
; __device__ __forceinline__ unsigned cvt_pk_bf16(float lo, float hi) { const f32x2_t v = {lo, hi}; const bf16x2_t b = __builtin_convertvector(v, bf16x2_t); return __builtin_bit_cast(unsigned, b); }
;     __device__ __forceinline__ void operator()(const f32x4 (&acc)[2][2][4][2], const Unit& u, int wr, int wc, int fr, int fq, const PG8_LAS float* tab) const {
;     ...
;             for (int m = 0; m < 4; ++m) { const int row = row0 + ai * HALF + m * 16; bf16_t* rowp = O + (size_t)row * ldc + col0;
;                 const float rstd = tab[rl0 + ai * HALF + m * 16];
; #pragma unroll
;                 for (int bj = 0; bj < 2; ++bj) { f32x4 v0 = acc[ai][bj][m][0] * rstd, v1 = acc[ai][bj][m][1] * rstd;
;                     if (ACT == 1) {
; #pragma unroll
;                         for (int e = 0; e < 4; ++e) { float a = v0[e] > 0.f ? v0[e] : 0.f; v0[e] = a * a; float b = v1[e] > 0.f ? v1[e] : 0.f; v1[e] = b * b; } }
;                     u32x4 w; w.x = cvt_pk_bf16(v0[0], v0[1]); w.y = cvt_pk_bf16(v0[2], v0[3]); w.z = cvt_pk_bf16(v1[0], v1[1]); w.w = cvt_pk_bf16(v1[2], v1[3]);
;                     *(u32x4*)(rowp + bj * HALF) = w; } }
	v_cndmask_b32_e64 v240, v240, v236, s[98:99]
	v_cndmask_b32_e64 v241, v241, v237, s[98:99]
	v_cndmask_b32_e64 v242, v242, v238, s[98:99]
	v_cndmask_b32_e64 v243, v243, v239, s[98:99]
	v_cndmask_b32_e64 v244, v132, v244, s[98:99]
	v_cndmask_b32_e64 v245, v133, v245, s[98:99]
	v_cndmask_b32_e64 v246, v134, v246, s[98:99]
	v_cndmask_b32_e64 v247, v135, v247, s[98:99]
	global_store_dwordx4 v[230:231], v[240:243], off
	global_store_dwordx4 v[232:233], v[244:247], off
	s_waitcnt lgkmcnt(0)
	v_pk_mul_f32 v[140:141], v[26:27], v[136:137] op_sel_hi:[1,0]
	v_add_u32_e32 v132, 0xa0, v175
	v_mad_i64_i32 v[132:133], s[6:7], v132, s46, v[128:129]
	v_lshl_add_u64 v[138:139], v[132:133], 0, v[130:131]
	v_pk_mul_f32 v[134:135], v[34:35], v[136:137] op_sel_hi:[1,0]
	v_pk_mul_f32 v[132:133], v[32:33], v[136:137] op_sel_hi:[1,0]
	v_pk_mul_f32 v[142:143], v[24:25], v[136:137] op_sel_hi:[1,0]
	v_cvt_pk_bf16_f32 v132, v132, v133
	v_cvt_pk_bf16_f32 v133, v134, v135
	v_cvt_pk_bf16_f32 v134, v142, v143
	v_cvt_pk_bf16_f32 v135, v140, v141
	v_mov_b32_e32 v236, v132
	v_mov_b32_e32 v237, v133
	v_mov_b32_e32 v238, v134
	v_mov_b32_e32 v239, v135
	v_lshl_add_u64 v[230:231], v[138:139], 0, v[248:249]
	v_lshl_add_u64 v[232:233], v[138:139], 0, v[250:251]
	v_pk_mul_f32 v[140:141], v[10:11], v[136:137] op_sel_hi:[1,0]
	v_pk_mul_f32 v[142:143], v[8:9], v[136:137] op_sel_hi:[1,0]
	v_pk_mul_f32 v[134:135], v[18:19], v[136:137] op_sel_hi:[1,0]
	v_pk_mul_f32 v[132:133], v[16:17], v[136:137] op_sel_hi:[1,0]
	s_nop 0
	v_cvt_pk_bf16_f32 v132, v132, v133
	v_cvt_pk_bf16_f32 v133, v134, v135
	v_cvt_pk_bf16_f32 v134, v142, v143
	v_cvt_pk_bf16_f32 v135, v140, v141
	ds_swizzle_b32 v240, v132 offset:swizzle(SWAP,8)
	ds_swizzle_b32 v241, v133 offset:swizzle(SWAP,8)
	ds_swizzle_b32 v242, v134 offset:swizzle(SWAP,8)
	ds_swizzle_b32 v243, v135 offset:swizzle(SWAP,8)
	ds_swizzle_b32 v244, v236 offset:swizzle(SWAP,8)
	ds_swizzle_b32 v245, v237 offset:swizzle(SWAP,8)
	ds_swizzle_b32 v246, v238 offset:swizzle(SWAP,8)
	ds_swizzle_b32 v247, v239 offset:swizzle(SWAP,8)
	s_waitcnt lgkmcnt(0)
	v_cndmask_b32_e64 v240, v240, v236, s[98:99]
	v_cndmask_b32_e64 v241, v241, v237, s[98:99]
	v_cndmask_b32_e64 v242, v242, v238, s[98:99]
	v_cndmask_b32_e64 v243, v243, v239, s[98:99]
	v_cndmask_b32_e64 v244, v132, v244, s[98:99]
	v_cndmask_b32_e64 v245, v133, v245, s[98:99]
	v_cndmask_b32_e64 v246, v134, v246, s[98:99]
	v_cndmask_b32_e64 v247, v135, v247, s[98:99]
	global_store_dwordx4 v[230:231], v[240:243], off
	global_store_dwordx4 v[232:233], v[244:247], off
	s_nop 1
	v_add_u32_e32 v132, 0xb0, v175
	v_mad_i64_i32 v[128:129], s[6:7], v132, s46, v[128:129]
	v_mov_b32_e32 v134, v137
	v_lshl_add_u64 v[132:133], v[128:129], 0, v[130:131]
	v_pk_mul_f32 v[130:131], v[22:23], v[134:135] op_sel_hi:[1,0]
	v_pk_mul_f32 v[128:129], v[20:21], v[134:135] op_sel_hi:[1,0]
	v_pk_mul_f32 v[136:137], v[14:15], v[134:135] op_sel_hi:[1,0]
	v_pk_mul_f32 v[138:139], v[12:13], v[134:135] op_sel_hi:[1,0]
	v_cvt_pk_bf16_f32 v128, v128, v129
	v_cvt_pk_bf16_f32 v129, v130, v131
	v_cvt_pk_bf16_f32 v130, v138, v139
	v_cvt_pk_bf16_f32 v131, v136, v137
	v_mov_b32_e32 v236, v128
	v_mov_b32_e32 v237, v129
	v_mov_b32_e32 v238, v130
	v_mov_b32_e32 v239, v131
	v_lshl_add_u64 v[230:231], v[132:133], 0, v[248:249]
	v_lshl_add_u64 v[232:233], v[132:133], 0, v[250:251]
	v_pk_mul_f32 v[136:137], v[2:3], v[134:135] op_sel_hi:[1,0]
	s_nop 0
	v_pk_mul_f32 v[130:131], v[6:7], v[134:135] op_sel_hi:[1,0]
	v_pk_mul_f32 v[128:129], v[4:5], v[134:135] op_sel_hi:[1,0]
	v_pk_mul_f32 v[134:135], v[0:1], v[134:135] op_sel_hi:[1,0]
	v_cvt_pk_bf16_f32 v128, v128, v129
	v_cvt_pk_bf16_f32 v129, v130, v131
	v_cvt_pk_bf16_f32 v130, v134, v135
	v_cvt_pk_bf16_f32 v131, v136, v137
	ds_swizzle_b32 v240, v128 offset:swizzle(SWAP,8)
	ds_swizzle_b32 v241, v129 offset:swizzle(SWAP,8)
	ds_swizzle_b32 v242, v130 offset:swizzle(SWAP,8)
	ds_swizzle_b32 v243, v131 offset:swizzle(SWAP,8)
	ds_swizzle_b32 v244, v236 offset:swizzle(SWAP,8)
	ds_swizzle_b32 v245, v237 offset:swizzle(SWAP,8)
	ds_swizzle_b32 v246, v238 offset:swizzle(SWAP,8)
	ds_swizzle_b32 v247, v239 offset:swizzle(SWAP,8)
	s_waitcnt lgkmcnt(0)
	v_cndmask_b32_e64 v240, v240, v236, s[98:99]
	v_cndmask_b32_e64 v241, v241, v237, s[98:99]
	v_cndmask_b32_e64 v242, v242, v238, s[98:99]
	v_cndmask_b32_e64 v243, v243, v239, s[98:99]
	v_cndmask_b32_e64 v244, v128, v244, s[98:99]
	v_cndmask_b32_e64 v245, v129, v245, s[98:99]
	v_cndmask_b32_e64 v246, v130, v246, s[98:99]
	v_cndmask_b32_e64 v247, v131, v247, s[98:99]
	global_store_dwordx4 v[230:231], v[240:243], off
	global_store_dwordx4 v[232:233], v[244:247], off
	s_cbranch_execnz .LBB0_135
; #define PG8_LAS __attribute__((address_space(3)))
; __device__ __forceinline__ unsigned cvt_pk_bf16(float lo, float hi) { const f32x2_t v = {lo, hi}; const bf16x2_t b = __builtin_convertvector(v, bf16x2_t); return __builtin_bit_cast(unsigned, b); }
;     __device__ __forceinline__ void pre_store(const Pre& p, PG8_LAS float* tab, int tid) const {
;         const float tot = ((p.s0[0] + p.s0[1]) + (p.s0[2] + p.s0[3])) + ((p.s1[0] + p.s1[1]) + (p.s1[2] + p.s1[3])) + ((p.s2[0] + p.s2[1]) + (p.s2[2] + p.s2[3])) + ((p.s3[0] + p.s3[1]) + (p.s3[2] + p.s3[3]));
;         if (tid < 256) tab[tid] = rsqrtf(tot * (1.0f / 1024.0f) + 1e-6f);
;     }
;     __device__ __forceinline__ void operator()(const f32x4 (&acc)[2][2][4][2], const Unit& u, int wr, int wc, int fr, int fq, const PG8_LAS float* tab) const {
;         const int rl0 = wr * 64 + fr; const int row0 = u.pm * BM + rl0; const int col0 = u.pn * BM + wc * 32 + 8 * fq;
; #pragma unroll
;         for (int ai = 0; ai < 2; ++ai)
; #pragma unroll
;             for (int m = 0; m < 4; ++m) { const int row = row0 + ai * HALF + m * 16; bf16_t* rowp = O + (size_t)row * ldc + col0;
;                 const float rstd = tab[rl0 + ai * HALF + m * 16];
; #pragma unroll
;                 for (int bj = 0; bj < 2; ++bj) { f32x4 v0 = acc[ai][bj][m][0] * rstd, v1 = acc[ai][bj][m][1] * rstd;
;                     if (ACT == 1) {
; #pragma unroll
;                         for (int e = 0; e < 4; ++e) { float a = v0[e] > 0.f ? v0[e] : 0.f; v0[e] = a * a; float b = v1[e] > 0.f ? v1[e] : 0.f; v1[e] = b * b; } }
;                     u32x4 w; w.x = cvt_pk_bf16(v0[0], v0[1]); w.y = cvt_pk_bf16(v0[2], v0[3]); w.z = cvt_pk_bf16(v1[0], v1[1]); w.w = cvt_pk_bf16(v1[2], v1[3]);
;                     *(u32x4*)(rowp + bj * HALF) = w; } }
.LBB0_137:
	s_nop 0
	v_lshl_or_b32 v128, s16, 8, v164
	v_ashrrev_i32_e32 v129, 31, v128
	v_readlane_b32 s6, v254, 41
	v_lshlrev_b64 v[128:129], 6, v[128:129]
	v_readlane_b32 s7, v254, 42
	v_ashrrev_i32_e32 v161, 31, v160
	v_mov_b64_e32 v[162:163], s[92:93]
	v_lshl_add_u64 v[140:141], s[6:7], 0, v[128:129]
	global_load_dwordx4 v[128:131], v[140:141], off offset:48
	global_load_dwordx4 v[132:135], v[140:141], off offset:32
	global_load_dwordx4 v[136:139], v[140:141], off offset:16
	s_nop 0
	global_load_dwordx4 v[140:143], v[140:141], off
	s_lshl_b32 s6, s23, 10
	s_and_b32 s6, s6, 0x400
	v_add_u32_e32 v182, s6, v168
	ds_read2_b32 v[176:177], v182 offset1:16
	v_mad_i64_i32 v[178:179], s[6:7], v175, s46, v[162:163]
	v_lshlrev_b64 v[160:161], 1, v[160:161]
	v_lshl_add_u64 v[178:179], v[178:179], 0, v[160:161]
	s_waitcnt lgkmcnt(0)
	v_pk_mul_f32 v[126:127], v[126:127], v[176:177] op_sel_hi:[1,0]
	v_pk_mul_f32 v[124:125], v[124:125], v[176:177] op_sel_hi:[1,0]
	v_pk_mul_f32 v[180:181], v[122:123], v[176:177] op_sel_hi:[1,0]
	v_pk_mul_f32 v[122:123], v[120:121], v[176:177] op_sel_hi:[1,0]
	v_cvt_pk_bf16_f32 v120, v124, v125
	v_cvt_pk_bf16_f32 v121, v126, v127
	v_cvt_pk_bf16_f32 v122, v122, v123
	v_cvt_pk_bf16_f32 v123, v180, v181
	v_mov_b32_e32 v236, v120
	v_mov_b32_e32 v237, v121
	v_mov_b32_e32 v238, v122
	v_mov_b32_e32 v239, v123
	v_lshl_add_u64 v[230:231], v[178:179], 0, v[248:249]
	v_lshl_add_u64 v[232:233], v[178:179], 0, v[250:251]
	v_pk_mul_f32 v[114:115], v[114:115], v[176:177] op_sel_hi:[1,0]
	v_pk_mul_f32 v[112:113], v[112:113], v[176:177] op_sel_hi:[1,0]
	v_pk_mul_f32 v[120:121], v[106:107], v[176:177] op_sel_hi:[1,0]
	v_pk_mul_f32 v[106:107], v[104:105], v[176:177] op_sel_hi:[1,0]
	v_cvt_pk_bf16_f32 v104, v112, v113
	v_cvt_pk_bf16_f32 v105, v114, v115
	v_cvt_pk_bf16_f32 v106, v106, v107
	v_cvt_pk_bf16_f32 v107, v120, v121
	ds_swizzle_b32 v240, v104 offset:swizzle(SWAP,8)
	ds_swizzle_b32 v241, v105 offset:swizzle(SWAP,8)
	ds_swizzle_b32 v242, v106 offset:swizzle(SWAP,8)
	ds_swizzle_b32 v243, v107 offset:swizzle(SWAP,8)
	ds_swizzle_b32 v244, v236 offset:swizzle(SWAP,8)
	ds_swizzle_b32 v245, v237 offset:swizzle(SWAP,8)
	ds_swizzle_b32 v246, v238 offset:swizzle(SWAP,8)
	ds_swizzle_b32 v247, v239 offset:swizzle(SWAP,8)
	s_waitcnt lgkmcnt(0)
	v_cndmask_b32_e64 v240, v240, v236, s[98:99]
	v_cndmask_b32_e64 v241, v241, v237, s[98:99]
	v_cndmask_b32_e64 v242, v242, v238, s[98:99]
	v_cndmask_b32_e64 v243, v243, v239, s[98:99]
	v_cndmask_b32_e64 v244, v104, v244, s[98:99]
	v_cndmask_b32_e64 v245, v105, v245, s[98:99]
	v_cndmask_b32_e64 v246, v106, v246, s[98:99]
	v_cndmask_b32_e64 v247, v107, v247, s[98:99]
	global_store_dwordx4 v[230:231], v[240:243], off
	global_store_dwordx4 v[232:233], v[244:247], off
	v_mov_b32_e32 v114, v177
	v_pk_mul_f32 v[110:111], v[110:111], v[114:115] op_sel_hi:[1,0]
	v_or_b32_e32 v104, 16, v175
	v_mad_i64_i32 v[104:105], s[6:7], v104, s46, v[162:163]
	v_lshl_add_u64 v[112:113], v[104:105], 0, v[160:161]
	v_pk_mul_f32 v[106:107], v[118:119], v[114:115] op_sel_hi:[1,0]
	v_pk_mul_f32 v[104:105], v[116:117], v[114:115] op_sel_hi:[1,0]
	v_pk_mul_f32 v[108:109], v[108:109], v[114:115] op_sel_hi:[1,0]
	v_cvt_pk_bf16_f32 v104, v104, v105
	v_cvt_pk_bf16_f32 v105, v106, v107
	v_cvt_pk_bf16_f32 v106, v108, v109
	v_cvt_pk_bf16_f32 v107, v110, v111
	v_mov_b32_e32 v236, v104
	v_mov_b32_e32 v237, v105
	v_mov_b32_e32 v238, v106
	v_mov_b32_e32 v239, v107
	v_lshl_add_u64 v[230:231], v[112:113], 0, v[248:249]
	v_lshl_add_u64 v[232:233], v[112:113], 0, v[250:251]
	v_pk_mul_f32 v[102:103], v[102:103], v[114:115] op_sel_hi:[1,0]
	v_pk_mul_f32 v[100:101], v[100:101], v[114:115] op_sel_hi:[1,0]
	v_pk_mul_f32 v[104:105], v[94:95], v[114:115] op_sel_hi:[1,0]
	v_pk_mul_f32 v[94:95], v[92:93], v[114:115] op_sel_hi:[1,0]
	v_cvt_pk_bf16_f32 v92, v100, v101
	v_cvt_pk_bf16_f32 v93, v102, v103
	v_cvt_pk_bf16_f32 v94, v94, v95
	v_cvt_pk_bf16_f32 v95, v104, v105
	ds_swizzle_b32 v240, v92 offset:swizzle(SWAP,8)
	ds_swizzle_b32 v241, v93 offset:swizzle(SWAP,8)
	ds_swizzle_b32 v242, v94 offset:swizzle(SWAP,8)
	ds_swizzle_b32 v243, v95 offset:swizzle(SWAP,8)
	ds_swizzle_b32 v244, v236 offset:swizzle(SWAP,8)
	ds_swizzle_b32 v245, v237 offset:swizzle(SWAP,8)
	ds_swizzle_b32 v246, v238 offset:swizzle(SWAP,8)
	ds_swizzle_b32 v247, v239 offset:swizzle(SWAP,8)
	s_waitcnt lgkmcnt(0)
	v_cndmask_b32_e64 v240, v240, v236, s[98:99]
	v_cndmask_b32_e64 v241, v241, v237, s[98:99]
	v_cndmask_b32_e64 v242, v242, v238, s[98:99]
	v_cndmask_b32_e64 v243, v243, v239, s[98:99]
	v_cndmask_b32_e64 v244, v92, v244, s[98:99]
	v_cndmask_b32_e64 v245, v93, v245, s[98:99]
	v_cndmask_b32_e64 v246, v94, v246, s[98:99]
	v_cndmask_b32_e64 v247, v95, v247, s[98:99]
	global_store_dwordx4 v[230:231], v[240:243], off
	global_store_dwordx4 v[232:233], v[244:247], off
	ds_read2_b32 v[92:93], v182 offset0:32 offset1:48
	s_waitcnt lgkmcnt(0)
	v_pk_mul_f32 v[98:99], v[98:99], v[92:93] op_sel_hi:[1,0]
	v_or_b32_e32 v94, 32, v175
	v_mad_i64_i32 v[94:95], s[6:7], v94, s46, v[162:163]
	v_pk_mul_f32 v[96:97], v[96:97], v[92:93] op_sel_hi:[1,0]
	v_pk_mul_f32 v[100:101], v[90:91], v[92:93] op_sel_hi:[1,0]
	v_pk_mul_f32 v[90:91], v[88:89], v[92:93] op_sel_hi:[1,0]
	v_lshl_add_u64 v[94:95], v[94:95], 0, v[160:161]
	v_cvt_pk_bf16_f32 v88, v96, v97
	v_cvt_pk_bf16_f32 v89, v98, v99
	v_cvt_pk_bf16_f32 v90, v90, v91
	v_cvt_pk_bf16_f32 v91, v100, v101
	v_mov_b32_e32 v236, v88
	v_mov_b32_e32 v237, v89
	v_mov_b32_e32 v238, v90
	v_mov_b32_e32 v239, v91
	v_lshl_add_u64 v[230:231], v[94:95], 0, v[248:249]
	v_lshl_add_u64 v[232:233], v[94:95], 0, v[250:251]
	v_pk_mul_f32 v[82:83], v[82:83], v[92:93] op_sel_hi:[1,0]
	v_pk_mul_f32 v[80:81], v[80:81], v[92:93] op_sel_hi:[1,0]
	v_pk_mul_f32 v[88:89], v[74:75], v[92:93] op_sel_hi:[1,0]
	v_pk_mul_f32 v[74:75], v[72:73], v[92:93] op_sel_hi:[1,0]
	v_cvt_pk_bf16_f32 v72, v80, v81
	v_cvt_pk_bf16_f32 v73, v82, v83
	v_cvt_pk_bf16_f32 v74, v74, v75
	v_cvt_pk_bf16_f32 v75, v88, v89
	ds_swizzle_b32 v240, v72 offset:swizzle(SWAP,8)
	ds_swizzle_b32 v241, v73 offset:swizzle(SWAP,8)
	ds_swizzle_b32 v242, v74 offset:swizzle(SWAP,8)
	ds_swizzle_b32 v243, v75 offset:swizzle(SWAP,8)
	ds_swizzle_b32 v244, v236 offset:swizzle(SWAP,8)
	ds_swizzle_b32 v245, v237 offset:swizzle(SWAP,8)
	ds_swizzle_b32 v246, v238 offset:swizzle(SWAP,8)
	ds_swizzle_b32 v247, v239 offset:swizzle(SWAP,8)
	s_waitcnt lgkmcnt(0)
; __device__ __forceinline__ unsigned cvt_pk_bf16(float lo, float hi) { const f32x2_t v = {lo, hi}; const bf16x2_t b = __builtin_convertvector(v, bf16x2_t); return __builtin_bit_cast(unsigned, b); }
;     __device__ __forceinline__ void operator()(const f32x4 (&acc)[2][2][4][2], const Unit& u, int wr, int wc, int fr, int fq, const PG8_LAS float* tab) const {
;     ...
;             for (int m = 0; m < 4; ++m) { const int row = row0 + ai * HALF + m * 16; bf16_t* rowp = O + (size_t)row * ldc + col0;
;                 const float rstd = tab[rl0 + ai * HALF + m * 16];
; #pragma unroll
;                 for (int bj = 0; bj < 2; ++bj) { f32x4 v0 = acc[ai][bj][m][0] * rstd, v1 = acc[ai][bj][m][1] * rstd;
;                     if (ACT == 1) {
; #pragma unroll
;                         for (int e = 0; e < 4; ++e) { float a = v0[e] > 0.f ? v0[e] : 0.f; v0[e] = a * a; float b = v1[e] > 0.f ? v1[e] : 0.f; v1[e] = b * b; } }
;                     u32x4 w; w.x = cvt_pk_bf16(v0[0], v0[1]); w.y = cvt_pk_bf16(v0[2], v0[3]); w.z = cvt_pk_bf16(v1[0], v1[1]); w.w = cvt_pk_bf16(v1[2], v1[3]);
;                     *(u32x4*)(rowp + bj * HALF) = w; } }
	v_cndmask_b32_e64 v240, v240, v236, s[98:99]
	v_cndmask_b32_e64 v241, v241, v237, s[98:99]
	v_cndmask_b32_e64 v242, v242, v238, s[98:99]
	v_cndmask_b32_e64 v243, v243, v239, s[98:99]
	v_cndmask_b32_e64 v244, v72, v244, s[98:99]
	v_cndmask_b32_e64 v245, v73, v245, s[98:99]
	v_cndmask_b32_e64 v246, v74, v246, s[98:99]
	v_cndmask_b32_e64 v247, v75, v247, s[98:99]
	global_store_dwordx4 v[230:231], v[240:243], off
	global_store_dwordx4 v[232:233], v[244:247], off
	v_mov_b32_e32 v82, v93
	v_pk_mul_f32 v[78:79], v[78:79], v[82:83] op_sel_hi:[1,0]
	v_or_b32_e32 v72, 48, v175
	v_mad_i64_i32 v[72:73], s[6:7], v72, s46, v[162:163]
	v_lshl_add_u64 v[80:81], v[72:73], 0, v[160:161]
	v_pk_mul_f32 v[74:75], v[86:87], v[82:83] op_sel_hi:[1,0]
	v_pk_mul_f32 v[72:73], v[84:85], v[82:83] op_sel_hi:[1,0]
	v_pk_mul_f32 v[76:77], v[76:77], v[82:83] op_sel_hi:[1,0]
	v_cvt_pk_bf16_f32 v72, v72, v73
	v_cvt_pk_bf16_f32 v73, v74, v75
	v_cvt_pk_bf16_f32 v74, v76, v77
	v_cvt_pk_bf16_f32 v75, v78, v79
	v_mov_b32_e32 v236, v72
	v_mov_b32_e32 v237, v73
	v_mov_b32_e32 v238, v74
	v_mov_b32_e32 v239, v75
	v_lshl_add_u64 v[230:231], v[80:81], 0, v[248:249]
	v_lshl_add_u64 v[232:233], v[80:81], 0, v[250:251]
	v_pk_mul_f32 v[70:71], v[70:71], v[82:83] op_sel_hi:[1,0]
	v_pk_mul_f32 v[68:69], v[68:69], v[82:83] op_sel_hi:[1,0]
	v_pk_mul_f32 v[72:73], v[66:67], v[82:83] op_sel_hi:[1,0]
	v_pk_mul_f32 v[66:67], v[64:65], v[82:83] op_sel_hi:[1,0]
	v_cvt_pk_bf16_f32 v64, v68, v69
	v_cvt_pk_bf16_f32 v65, v70, v71
	v_cvt_pk_bf16_f32 v66, v66, v67
	v_cvt_pk_bf16_f32 v67, v72, v73
	ds_swizzle_b32 v240, v64 offset:swizzle(SWAP,8)
	ds_swizzle_b32 v241, v65 offset:swizzle(SWAP,8)
	ds_swizzle_b32 v242, v66 offset:swizzle(SWAP,8)
	ds_swizzle_b32 v243, v67 offset:swizzle(SWAP,8)
	ds_swizzle_b32 v244, v236 offset:swizzle(SWAP,8)
	ds_swizzle_b32 v245, v237 offset:swizzle(SWAP,8)
	ds_swizzle_b32 v246, v238 offset:swizzle(SWAP,8)
	ds_swizzle_b32 v247, v239 offset:swizzle(SWAP,8)
	s_waitcnt lgkmcnt(0)
	v_cndmask_b32_e64 v240, v240, v236, s[98:99]
	v_cndmask_b32_e64 v241, v241, v237, s[98:99]
	v_cndmask_b32_e64 v242, v242, v238, s[98:99]
	v_cndmask_b32_e64 v243, v243, v239, s[98:99]
	v_cndmask_b32_e64 v244, v64, v244, s[98:99]
	v_cndmask_b32_e64 v245, v65, v245, s[98:99]
	v_cndmask_b32_e64 v246, v66, v246, s[98:99]
	v_cndmask_b32_e64 v247, v67, v247, s[98:99]
	global_store_dwordx4 v[230:231], v[240:243], off
	global_store_dwordx4 v[232:233], v[244:247], off
	ds_read2_b32 v[64:65], v182 offset0:128 offset1:144
	s_waitcnt lgkmcnt(0)
	v_pk_mul_f32 v[62:63], v[62:63], v[64:65] op_sel_hi:[1,0]
	v_add_u32_e32 v66, 0x80, v175
	v_mad_i64_i32 v[66:67], s[6:7], v66, s46, v[162:163]
	v_pk_mul_f32 v[60:61], v[60:61], v[64:65] op_sel_hi:[1,0]
	v_pk_mul_f32 v[68:69], v[58:59], v[64:65] op_sel_hi:[1,0]
	v_pk_mul_f32 v[58:59], v[56:57], v[64:65] op_sel_hi:[1,0]
	v_lshl_add_u64 v[66:67], v[66:67], 0, v[160:161]
	v_cvt_pk_bf16_f32 v56, v60, v61
	v_cvt_pk_bf16_f32 v57, v62, v63
	v_cvt_pk_bf16_f32 v58, v58, v59
	v_cvt_pk_bf16_f32 v59, v68, v69
	v_mov_b32_e32 v236, v56
	v_mov_b32_e32 v237, v57
	v_mov_b32_e32 v238, v58
	v_mov_b32_e32 v239, v59
	v_lshl_add_u64 v[230:231], v[66:67], 0, v[248:249]
	v_lshl_add_u64 v[232:233], v[66:67], 0, v[250:251]
	v_pk_mul_f32 v[50:51], v[50:51], v[64:65] op_sel_hi:[1,0]
	v_pk_mul_f32 v[48:49], v[48:49], v[64:65] op_sel_hi:[1,0]
	v_pk_mul_f32 v[56:57], v[42:43], v[64:65] op_sel_hi:[1,0]
	v_pk_mul_f32 v[42:43], v[40:41], v[64:65] op_sel_hi:[1,0]
	v_cvt_pk_bf16_f32 v40, v48, v49
	v_cvt_pk_bf16_f32 v41, v50, v51
	v_cvt_pk_bf16_f32 v42, v42, v43
	v_cvt_pk_bf16_f32 v43, v56, v57
	ds_swizzle_b32 v240, v40 offset:swizzle(SWAP,8)
	ds_swizzle_b32 v241, v41 offset:swizzle(SWAP,8)
	ds_swizzle_b32 v242, v42 offset:swizzle(SWAP,8)
	ds_swizzle_b32 v243, v43 offset:swizzle(SWAP,8)
	ds_swizzle_b32 v244, v236 offset:swizzle(SWAP,8)
	ds_swizzle_b32 v245, v237 offset:swizzle(SWAP,8)
	ds_swizzle_b32 v246, v238 offset:swizzle(SWAP,8)
	ds_swizzle_b32 v247, v239 offset:swizzle(SWAP,8)
	s_waitcnt lgkmcnt(0)
	v_cndmask_b32_e64 v240, v240, v236, s[98:99]
	v_cndmask_b32_e64 v241, v241, v237, s[98:99]
	v_cndmask_b32_e64 v242, v242, v238, s[98:99]
	v_cndmask_b32_e64 v243, v243, v239, s[98:99]
	v_cndmask_b32_e64 v244, v40, v244, s[98:99]
	v_cndmask_b32_e64 v245, v41, v245, s[98:99]
	v_cndmask_b32_e64 v246, v42, v246, s[98:99]
	v_cndmask_b32_e64 v247, v43, v247, s[98:99]
	global_store_dwordx4 v[230:231], v[240:243], off
	global_store_dwordx4 v[232:233], v[244:247], off
	v_mov_b32_e32 v50, v65
	v_pk_mul_f32 v[46:47], v[46:47], v[50:51] op_sel_hi:[1,0]
	v_add_u32_e32 v40, 0x90, v175
	v_mad_i64_i32 v[40:41], s[6:7], v40, s46, v[162:163]
	v_lshl_add_u64 v[48:49], v[40:41], 0, v[160:161]
	v_pk_mul_f32 v[42:43], v[54:55], v[50:51] op_sel_hi:[1,0]
	v_pk_mul_f32 v[40:41], v[52:53], v[50:51] op_sel_hi:[1,0]
	v_pk_mul_f32 v[44:45], v[44:45], v[50:51] op_sel_hi:[1,0]
	v_cvt_pk_bf16_f32 v40, v40, v41
	v_cvt_pk_bf16_f32 v41, v42, v43
	v_cvt_pk_bf16_f32 v42, v44, v45
	v_cvt_pk_bf16_f32 v43, v46, v47
	v_mov_b32_e32 v236, v40
	v_mov_b32_e32 v237, v41
	v_mov_b32_e32 v238, v42
	v_mov_b32_e32 v239, v43
	v_lshl_add_u64 v[230:231], v[48:49], 0, v[248:249]
	v_lshl_add_u64 v[232:233], v[48:49], 0, v[250:251]
	v_pk_mul_f32 v[38:39], v[38:39], v[50:51] op_sel_hi:[1,0]
	v_pk_mul_f32 v[36:37], v[36:37], v[50:51] op_sel_hi:[1,0]
	v_pk_mul_f32 v[40:41], v[30:31], v[50:51] op_sel_hi:[1,0]
	v_pk_mul_f32 v[30:31], v[28:29], v[50:51] op_sel_hi:[1,0]
	v_cvt_pk_bf16_f32 v28, v36, v37
	v_cvt_pk_bf16_f32 v29, v38, v39
	v_cvt_pk_bf16_f32 v30, v30, v31
	v_cvt_pk_bf16_f32 v31, v40, v41
	ds_swizzle_b32 v240, v28 offset:swizzle(SWAP,8)
	ds_swizzle_b32 v241, v29 offset:swizzle(SWAP,8)
	ds_swizzle_b32 v242, v30 offset:swizzle(SWAP,8)
	ds_swizzle_b32 v243, v31 offset:swizzle(SWAP,8)
	ds_swizzle_b32 v244, v236 offset:swizzle(SWAP,8)
	ds_swizzle_b32 v245, v237 offset:swizzle(SWAP,8)
	ds_swizzle_b32 v246, v238 offset:swizzle(SWAP,8)
	ds_swizzle_b32 v247, v239 offset:swizzle(SWAP,8)
	s_waitcnt lgkmcnt(0)
; #define PG8_LAS __attribute__((address_space(3)))
; __device__ __forceinline__ unsigned cvt_pk_bf16(float lo, float hi) { const f32x2_t v = {lo, hi}; const bf16x2_t b = __builtin_convertvector(v, bf16x2_t); return __builtin_bit_cast(unsigned, b); }
;     __device__ __forceinline__ void pre_store(const Pre& p, PG8_LAS float* tab, int tid) const {
;         const float tot = ((p.s0[0] + p.s0[1]) + (p.s0[2] + p.s0[3])) + ((p.s1[0] + p.s1[1]) + (p.s1[2] + p.s1[3])) + ((p.s2[0] + p.s2[1]) + (p.s2[2] + p.s2[3])) + ((p.s3[0] + p.s3[1]) + (p.s3[2] + p.s3[3]));
;         if (tid < 256) tab[tid] = rsqrtf(tot * (1.0f / 1024.0f) + 1e-6f);
;     }
;     __device__ __forceinline__ void operator()(const f32x4 (&acc)[2][2][4][2], const Unit& u, int wr, int wc, int fr, int fq, const PG8_LAS float* tab) const {
;         const int rl0 = wr * 64 + fr; const int row0 = u.pm * BM + rl0; const int col0 = u.pn * BM + wc * 32 + 8 * fq;
; #pragma unroll
;         for (int ai = 0; ai < 2; ++ai)
; #pragma unroll
;             for (int m = 0; m < 4; ++m) { const int row = row0 + ai * HALF + m * 16; bf16_t* rowp = O + (size_t)row * ldc + col0;
;                 const float rstd = tab[rl0 + ai * HALF + m * 16];
; #pragma unroll
;                 for (int bj = 0; bj < 2; ++bj) { f32x4 v0 = acc[ai][bj][m][0] * rstd, v1 = acc[ai][bj][m][1] * rstd;
;                     if (ACT == 1) {
; #pragma unroll
;                         for (int e = 0; e < 4; ++e) { float a = v0[e] > 0.f ? v0[e] : 0.f; v0[e] = a * a; float b = v1[e] > 0.f ? v1[e] : 0.f; v1[e] = b * b; } }
;                     u32x4 w; w.x = cvt_pk_bf16(v0[0], v0[1]); w.y = cvt_pk_bf16(v0[2], v0[3]); w.z = cvt_pk_bf16(v1[0], v1[1]); w.w = cvt_pk_bf16(v1[2], v1[3]);
;                     *(u32x4*)(rowp + bj * HALF) = w; } }
	v_cndmask_b32_e64 v240, v240, v236, s[98:99]
	v_cndmask_b32_e64 v241, v241, v237, s[98:99]
	v_cndmask_b32_e64 v242, v242, v238, s[98:99]
	v_cndmask_b32_e64 v243, v243, v239, s[98:99]
	v_cndmask_b32_e64 v244, v28, v244, s[98:99]
	v_cndmask_b32_e64 v245, v29, v245, s[98:99]
	v_cndmask_b32_e64 v246, v30, v246, s[98:99]
	v_cndmask_b32_e64 v247, v31, v247, s[98:99]
	global_store_dwordx4 v[230:231], v[240:243], off
	global_store_dwordx4 v[232:233], v[244:247], off
	ds_read2_b32 v[28:29], v182 offset0:160 offset1:176
	s_waitcnt lgkmcnt(0)
	v_pk_mul_f32 v[34:35], v[34:35], v[28:29] op_sel_hi:[1,0]
	v_add_u32_e32 v30, 0xa0, v175
	v_mad_i64_i32 v[30:31], s[6:7], v30, s46, v[162:163]
	v_pk_mul_f32 v[32:33], v[32:33], v[28:29] op_sel_hi:[1,0]
	v_pk_mul_f32 v[36:37], v[26:27], v[28:29] op_sel_hi:[1,0]
	v_pk_mul_f32 v[26:27], v[24:25], v[28:29] op_sel_hi:[1,0]
	v_lshl_add_u64 v[30:31], v[30:31], 0, v[160:161]
	v_cvt_pk_bf16_f32 v24, v32, v33
	v_cvt_pk_bf16_f32 v25, v34, v35
	v_cvt_pk_bf16_f32 v26, v26, v27
	v_cvt_pk_bf16_f32 v27, v36, v37
	v_mov_b32_e32 v236, v24
	v_mov_b32_e32 v237, v25
	v_mov_b32_e32 v238, v26
	v_mov_b32_e32 v239, v27
	v_lshl_add_u64 v[230:231], v[30:31], 0, v[248:249]
	v_lshl_add_u64 v[232:233], v[30:31], 0, v[250:251]
	v_pk_mul_f32 v[18:19], v[18:19], v[28:29] op_sel_hi:[1,0]
	v_pk_mul_f32 v[16:17], v[16:17], v[28:29] op_sel_hi:[1,0]
	v_pk_mul_f32 v[24:25], v[10:11], v[28:29] op_sel_hi:[1,0]
	v_pk_mul_f32 v[10:11], v[8:9], v[28:29] op_sel_hi:[1,0]
	v_cvt_pk_bf16_f32 v8, v16, v17
	v_cvt_pk_bf16_f32 v9, v18, v19
	v_cvt_pk_bf16_f32 v10, v10, v11
	v_cvt_pk_bf16_f32 v11, v24, v25
	ds_swizzle_b32 v240, v8 offset:swizzle(SWAP,8)
	ds_swizzle_b32 v241, v9 offset:swizzle(SWAP,8)
	ds_swizzle_b32 v242, v10 offset:swizzle(SWAP,8)
	ds_swizzle_b32 v243, v11 offset:swizzle(SWAP,8)
	ds_swizzle_b32 v244, v236 offset:swizzle(SWAP,8)
	ds_swizzle_b32 v245, v237 offset:swizzle(SWAP,8)
	ds_swizzle_b32 v246, v238 offset:swizzle(SWAP,8)
	ds_swizzle_b32 v247, v239 offset:swizzle(SWAP,8)
	s_waitcnt lgkmcnt(0)
	v_cndmask_b32_e64 v240, v240, v236, s[98:99]
	v_cndmask_b32_e64 v241, v241, v237, s[98:99]
	v_cndmask_b32_e64 v242, v242, v238, s[98:99]
	v_cndmask_b32_e64 v243, v243, v239, s[98:99]
	v_cndmask_b32_e64 v244, v8, v244, s[98:99]
	v_cndmask_b32_e64 v245, v9, v245, s[98:99]
	v_cndmask_b32_e64 v246, v10, v246, s[98:99]
	v_cndmask_b32_e64 v247, v11, v247, s[98:99]
	global_store_dwordx4 v[230:231], v[240:243], off
	global_store_dwordx4 v[232:233], v[244:247], off
	v_mov_b32_e32 v18, v29
	v_pk_mul_f32 v[14:15], v[14:15], v[18:19] op_sel_hi:[1,0]
	v_add_u32_e32 v8, 0xb0, v175
	v_mad_i64_i32 v[8:9], s[6:7], v8, s46, v[162:163]
	v_lshl_add_u64 v[16:17], v[8:9], 0, v[160:161]
	v_pk_mul_f32 v[10:11], v[22:23], v[18:19] op_sel_hi:[1,0]
	v_pk_mul_f32 v[8:9], v[20:21], v[18:19] op_sel_hi:[1,0]
	v_pk_mul_f32 v[12:13], v[12:13], v[18:19] op_sel_hi:[1,0]
	v_cvt_pk_bf16_f32 v8, v8, v9
	v_cvt_pk_bf16_f32 v9, v10, v11
	v_cvt_pk_bf16_f32 v10, v12, v13
	v_cvt_pk_bf16_f32 v11, v14, v15
	v_mov_b32_e32 v236, v8
	v_mov_b32_e32 v237, v9
	v_mov_b32_e32 v238, v10
	v_mov_b32_e32 v239, v11
	v_lshl_add_u64 v[230:231], v[16:17], 0, v[248:249]
	v_lshl_add_u64 v[232:233], v[16:17], 0, v[250:251]
	v_pk_mul_f32 v[6:7], v[6:7], v[18:19] op_sel_hi:[1,0]
	v_pk_mul_f32 v[4:5], v[4:5], v[18:19] op_sel_hi:[1,0]
	v_pk_mul_f32 v[8:9], v[2:3], v[18:19] op_sel_hi:[1,0]
	v_pk_mul_f32 v[2:3], v[0:1], v[18:19] op_sel_hi:[1,0]
	v_cvt_pk_bf16_f32 v0, v4, v5
	v_cvt_pk_bf16_f32 v1, v6, v7
	v_cvt_pk_bf16_f32 v2, v2, v3
	v_cvt_pk_bf16_f32 v3, v8, v9
	ds_swizzle_b32 v240, v0 offset:swizzle(SWAP,8)
	ds_swizzle_b32 v241, v1 offset:swizzle(SWAP,8)
	ds_swizzle_b32 v242, v2 offset:swizzle(SWAP,8)
	ds_swizzle_b32 v243, v3 offset:swizzle(SWAP,8)
	ds_swizzle_b32 v244, v236 offset:swizzle(SWAP,8)
	ds_swizzle_b32 v245, v237 offset:swizzle(SWAP,8)
	ds_swizzle_b32 v246, v238 offset:swizzle(SWAP,8)
	ds_swizzle_b32 v247, v239 offset:swizzle(SWAP,8)
	s_waitcnt lgkmcnt(0)
	v_cndmask_b32_e64 v240, v240, v236, s[98:99]
	v_cndmask_b32_e64 v241, v241, v237, s[98:99]
	v_cndmask_b32_e64 v242, v242, v238, s[98:99]
	v_cndmask_b32_e64 v243, v243, v239, s[98:99]
	v_cndmask_b32_e64 v244, v0, v244, s[98:99]
	v_cndmask_b32_e64 v245, v1, v245, s[98:99]
	v_cndmask_b32_e64 v246, v2, v246, s[98:99]
	v_cndmask_b32_e64 v247, v3, v247, s[98:99]
	global_store_dwordx4 v[230:231], v[240:243], off
	global_store_dwordx4 v[232:233], v[244:247], off
	s_and_saveexec_b64 s[6:7], s[2:3]
	s_cbranch_execz .LBB0_139
	s_waitcnt vmcnt(0)
	v_mov_b32_e32 v0, v141
	v_mov_b32_e32 v1, v142
	v_mov_b32_e32 v141, v143
	v_mov_b32_e32 v2, v137
	v_mov_b32_e32 v3, v138
	v_mov_b32_e32 v137, v139
	v_pk_add_f32 v[0:1], v[0:1], v[140:141]
	v_pk_add_f32 v[2:3], v[2:3], v[136:137]
	v_pk_add_f32 v[0:1], v[0:1], v[0:1] op_sel:[0,1] op_sel_hi:[1,0]
	v_pk_add_f32 v[2:3], v[2:3], v[2:3] op_sel:[0,1] op_sel_hi:[1,0]
	v_add_f32_e32 v4, v132, v133
	v_add_f32_e32 v6, v134, v135
	v_mov_b32_e32 v1, v128
	v_mov_b32_e32 v3, v129
	v_mov_b32_e32 v5, v130
	v_mov_b32_e32 v7, v131
	v_pk_add_f32 v[0:1], v[0:1], v[2:3]
	v_pk_add_f32 v[2:3], v[4:5], v[6:7]
	s_lshl_b32 s15, s48, 10
	v_pk_add_f32 v[0:1], v[0:1], v[2:3]
	s_and_b32 s15, s15, 0x400
	v_add_f32_e32 v0, v0, v1
	v_fmamk_f32 v0, v0, 0x3a800000, v174
	v_mul_f32_e32 v1, 0x4b800000, v0
	v_cmp_gt_f32_e32 vcc, s47, v0
	s_nop 1
	v_cndmask_b32_e32 v0, v0, v1, vcc
	v_rsq_f32_e32 v0, v0
	s_nop 0
	v_mul_f32_e32 v1, 0x45800000, v0
	v_cndmask_b32_e32 v0, v0, v1, vcc
	v_add_u32_e32 v1, s15, v169
	ds_write_b32 v1, v0

; template <class Epi, class Sched, bool ALIGN_EPI = false, bool SP2 = false>
; __device__ __forceinline__ void gemm_phase(PG8_LAS unsigned char* lds, const Gemm g, const Sched& S, const Epi& E) {
;     ...
;     const int tid = tid_, wid = __builtin_amdgcn_readfirstlane(tid >> 6), lane = tid & 63, wr = wid >> 2, wc = wid & 3, fr = lane & 15, fq = lane >> 4;
;     const int K = g.K, nt = K / BK;
;     unsigned voffA[2], voffB[2];
; #pragma unroll
;     for (int i = 0; i < 2; ++i) { int R, C; stage_rc(tid * 16 + i * 8192, R, C); const int Rb = Epi::PERM ? ((R & ~31) + perm32(R & 31)) : R;
;         voffA[i] = (unsigned)(R * K + C) * 2u; voffB[i] = (unsigned)(Rb * K + C) * 2u; }
;     const size_t kstep = (size_t)(BK * 2);
;     const size_t hstep = (size_t)HALF * K * 2;
;     const size_t tstep = 2 * hstep;
;     const unsigned ldsw = (unsigned)wid * 1024u;
;     const int aoff = lds_byte(wr * 64 + fr, fq * 8), boff = lds_byte(wc * 32 + fr, fq * 8);
;     ...
;     Unit cur, nxt; int ui = 0;
;     if (!S.next(0, cur)) return;
; template <int L> __device__ __forceinline__ void layer_phases(const KArgs& a, LAS unsigned char* lds, const XcdBarrier& xbar, int lo, int hi) {
;     ...
;     if (PH_IN(P0 + 4)) {
;         pg8::Gemm g{XB, (const bf16_t*)(ws + WS_WUP) + (size_t)l * FF * DM, MTOK, FF, DM}; pg8::StaticOrder S; S.init(MTOK, FF, G, (int)blockIdx.x);
;         pg8::EpiBf16<1> E{Hb, FF, SSQ};
;         pg8::gemm_phase<pg8::EpiBf16<1>, pg8::StaticOrder, true, true>(lds, g, S, E);
.LBB0_735:
	s_cmp_lt_i32 s96, 6
	s_cselect_b64 s[0:1], -1, 0
	s_and_b64 s[2:3], s[0:1], s[2:3]
	s_andn2_b64 vcc, exec, s[2:3]
	s_cbranch_vccnz .LBB0_768
	v_readfirstlane_b32 s100, v166
	s_nop 3
	s_lshr_b32 s98, s100, 8
	s_lshl_b32 s98, s98, 16
	s_add_i32 s99, s98, 0x20000
	s_lshr_b32 s100, s100, 6
	s_and_b32 s100, s100, 3
	s_lshl_b32 s100, s100, 5
	v_mov_b32_e32 v8, v166
	s_cmpk_gt_i32 s75, 0xfff
	v_readfirstlane_b32 s6, v8
	s_cbranch_scc1 .LBB0_768
	s_ashr_i32 s33, s75, 31
	s_lshr_b32 s2, s33, 29
	s_add_i32 s4, s75, s2
	s_and_b32 s2, s4, -8
	s_sub_i32 s5, s75, s2
	s_cmp_gt_i32 s5, -1
	s_cbranch_scc0 .LBB0_739
	s_lshl_b32 s7, s5, 9
	s_cbranch_execz .LBB0_740
	s_branch .LBB0_741

; #define PG8_LAS __attribute__((address_space(3)))
; #define PG8_STAGE(bufoff, gbase, voff) do { _Pragma("unroll") for (int _i = 0; _i < 2; ++_i) \
;         __builtin_amdgcn_global_load_lds((const unsigned*)((const char*)(gbase) + (voff)[_i]), (PG8_LAS unsigned*)(lds + (bufoff) + ldsw + _i * 8192), 16, 0, 0); } while (0)
; #define PG8_WAIT_V(n) asm volatile("s_waitcnt vmcnt(" #n ")" ::: "memory")
; #define PG8_BAR __builtin_amdgcn_s_barrier()
; template <class Epi, class Sched, bool ALIGN_EPI = false, bool SP2 = false>
; __device__ __forceinline__ void gemm_phase(PG8_LAS unsigned char* lds, const Gemm g, const Sched& S, const Epi& E) {
;     ...
;     for (int i = 0; i < 2; ++i) { int R, C; stage_rc(tid * 16 + i * 8192, R, C); const int Rb = Epi::PERM ? ((R & ~31) + perm32(R & 31)) : R;
;         voffA[i] = (unsigned)(R * K + C) * 2u; voffB[i] = (unsigned)(Rb * K + C) * 2u; }
;     const size_t kstep = (size_t)(BK * 2);
;     const size_t hstep = (size_t)HALF * K * 2;
;     const size_t tstep = 2 * hstep;
;     const unsigned ldsw = (unsigned)wid * 1024u;
;     const int aoff = lds_byte(wr * 64 + fr, fq * 8), boff = lds_byte(wc * 32 + fr, fq * 8);
;     ...
;     Unit cur, nxt; int ui = 0;
;     if (!S.next(0, cur)) return;
;     f32x4 acc[2][2][4][2];
; #pragma unroll
;     for (int a = 0; a < 2; ++a)
; #pragma unroll
;         for (int b = 0; b < 2; ++b)
; #pragma unroll
;             for (int m = 0; m < 4; ++m)
; #pragma unroll
;                 for (int n = 0; n < 2; ++n) acc[a][b][m][n] = (f32x4){0.f, 0.f, 0.f, 0.f};
;     bf16x8 At[4][2], B0[2][2], B1[2][2];
;     const char* cA = (const char*)g.A + (size_t)cur.pm * tstep; const char* cB = (const char*)g.Bt + (size_t)cur.pn * tstep;
;     S.a_ready(cur);
;     PG8_LAS float* ptab = (PG8_LAS float*)(lds + STAGE_BYTES);
;     if constexpr (Epi::HAS_PRE) { const auto p0 = E.pre_load(cur.pm, tid); E.pre_store(p0, ptab, tid); }
;     if constexpr (SP2) {
;         PG8_STAGE(PG8_SB(0, 0), cB, voffB); PG8_STAGE(PG8_SB(0, 1), cB + hstep, voffB); PG8_STAGE(PG8_SA(0, 0), cA, voffA); PG8_STAGE(PG8_SA(0, 1), cA + hstep, voffA);
;         if (wr == 1) PG8_BAR;
;         PG8_WAIT_V(2); PG8_BAR;
;         PG8_STAGE(PG8_SB(1, 0), cB + kstep, voffB); PG8_STAGE(PG8_SA(1, 0), cA + kstep, voffA); PG8_STAGE(PG8_SB(1, 1), cB + hstep + kstep, voffB);
;         PG8_WAIT_V(6); PG8_BAR;
.LBB0_743:
	s_or_b64 exec, exec, s[4:5]
	s_waitcnt lgkmcnt(0)
	v_ashrrev_i32_e32 v1, 31, v8
	v_lshrrev_b32_e32 v1, 26, v1
	v_add_u32_e32 v1, v8, v1
	v_mov_b32_e32 v0, s7
	v_ashrrev_i32_e32 v9, 6, v1
	v_bfe_i32 v1, v8, 27, 1
	v_readfirstlane_b32 s30, v0
	v_lshlrev_b32_e32 v0, 4, v8
	v_lshrrev_b32_e32 v1, 22, v1
	v_add_u32_e32 v1, v0, v1
	v_and_b32_e32 v1, 0xfffffc00, v1
	v_sub_u32_e32 v1, v0, v1
	v_lshrrev_b32_e32 v2, 4, v1
	s_add_u32 s42, s70, 0x1200000
	v_bitop3_b32 v1, v2, v1, 32 bitop3:0x6c
	s_addc_u32 s43, s71, 0
	s_ashr_i32 s35, s34, 31
	v_ashrrev_i32_e32 v3, 31, v1
	s_lshl_b64 s[4:5], s[34:35], 19
	v_readlane_b32 s8, v254, 39
	v_lshrrev_b32_e32 v3, 26, v3
	v_readlane_b32 s9, v254, 40
	s_add_u32 s36, s8, s4
	s_mov_b32 s31, 0
	v_add_u32_e32 v3, v1, v3
	s_addc_u32 s37, s9, s5
	s_bfe_i64 s[4:5], s[30:31], 0x80000
	v_lshlrev_b32_e32 v2, 3, v9
	v_ashrrev_i32_e32 v10, 6, v3
	v_and_b32_e32 v3, 0xc0, v3
	s_lshl_b64 s[4:5], s[4:5], 19
	v_and_b32_e32 v2, -16, v2
	v_sub_u32_e32 v1, v1, v3
	v_mov_b32_e32 v3, 1
	s_add_u32 s38, s42, s4
	v_add_u32_e32 v2, v10, v2
	v_ashrrev_i16_sdwa v1, v3, sext(v1) dst_sel:DWORD dst_unused:UNUSED_PAD src0_sel:DWORD src1_sel:BYTE_0
	s_addc_u32 s39, s43, s5
	v_lshlrev_b32_e32 v4, 5, v9
	v_bfe_i32 v11, v1, 0, 16
	v_lshlrev_b32_e32 v1, 1, v2
	v_lshrrev_b32_e32 v5, 2, v2
	v_and_b32_e32 v6, 3, v10
	s_mov_b32 s5, 0x1fffe0
	v_and_b32_e32 v4, 32, v4
	v_and_b32_e32 v1, 24, v1
	v_and_b32_e32 v5, 4, v5
	v_and_or_b32 v6, v2, s5, v6
	v_or3_b32 v1, v6, v5, v1
	v_add_lshl_u32 v4, v4, v11, 1
	v_add_u32_e32 v0, 0x2000, v0
	v_lshl_add_u32 v146, v1, 11, v4
	v_add_u32_e32 v146, s98, v146
	v_ashrrev_i32_e32 v1, 31, v0
	v_lshrrev_b32_e32 v1, 22, v1
	v_add_u32_e32 v1, v0, v1
	v_ashrrev_i32_e32 v12, 10, v1
	v_mul_i32_i24_e32 v1, 0x400, v12
	v_sub_u32_e32 v0, v0, v1
	v_lshrrev_b32_e32 v1, 4, v0
	v_bitop3_b32 v0, v1, v0, 32 bitop3:0x6c
	v_lshl_add_u32 v144, v2, 11, v4
	v_ashrrev_i32_e32 v2, 31, v0
	v_lshrrev_b32_e32 v2, 26, v2
	v_add_u32_e32 v2, v0, v2
	v_lshlrev_b32_e32 v1, 3, v12
	v_ashrrev_i32_e32 v13, 6, v2
	v_and_b32_e32 v2, 0xc0, v2
	v_and_b32_e32 v1, -16, v1
	v_sub_u32_e32 v0, v0, v2
	v_add_u32_e32 v1, v13, v1
	v_ashrrev_i16_sdwa v0, v3, sext(v0) dst_sel:DWORD dst_unused:UNUSED_PAD src0_sel:DWORD src1_sel:BYTE_0
	v_and_b32_e32 v3, 3, v13
	v_and_or_b32 v3, v1, s5, v3
	s_ashr_i32 s5, s6, 6
	s_lshl_b32 s30, s5, 10
	v_lshlrev_b32_e32 v4, 5, v12
	v_bfe_i32 v14, v0, 0, 16
	v_lshlrev_b32_e32 v0, 1, v1
	v_lshrrev_b32_e32 v2, 2, v1
	s_add_i32 s35, s30, 0
	v_and_b32_e32 v4, 32, v4
	v_and_b32_e32 v0, 24, v0
	v_and_b32_e32 v2, 4, v2
	s_add_i32 m0, s35, 0x10000
	s_ashr_i32 s4, s6, 8
	v_or3_b32 v0, v3, v2, v0
	v_add_lshl_u32 v2, v4, v14, 1
	global_load_lds_dwordx4 v146, s[38:39]
	s_add_i32 m0, s35, 0x12000
	v_lshl_add_u32 v150, v0, 11, v2
	v_add_u32_e32 v150, s99, v150
	s_add_u32 s8, s38, 0x10000
	global_load_lds_dwordx4 v150, s[38:39]
	s_addc_u32 s9, s39, 0
	s_add_i32 m0, s35, 0x14000
	s_add_i32 s44, s35, 0x2000
	global_load_lds_dwordx4 v146, s[8:9]
	s_add_i32 m0, s35, 0x16000
	v_lshl_add_u32 v148, v1, 11, v2
	global_load_lds_dwordx4 v150, s[8:9]
	s_mov_b32 m0, s35
	s_add_u32 s8, s36, 0x40000
	global_load_lds_dwordx4 v144, s[36:37]
	s_mov_b32 m0, s44
	s_addc_u32 s9, s37, 0
	s_add_i32 s45, s35, 0x4000
	global_load_lds_dwordx4 v148, s[36:37]
	s_mov_b32 m0, s45
	s_add_i32 s46, s35, 0x6000
	global_load_lds_dwordx4 v144, s[8:9]
	s_mov_b32 m0, s46
	v_mov_b32_e32 v147, 0
	global_load_lds_dwordx4 v148, s[8:9]
	v_mov_b32_e32 v151, v147
	v_mov_b32_e32 v145, v147
	v_mov_b32_e32 v149, v147
	s_cmp_eq_u32 s4, 1
	v_lshl_add_u64 v[6:7], s[38:39], 0, v[146:147]
	v_lshl_add_u64 v[4:5], s[38:39], 0, v[150:151]
	v_lshl_add_u64 v[0:1], s[36:37], 0, v[144:145]
	s_cselect_b64 s[8:9], -1, 0
	s_cmp_lg_u32 s4, 1
	v_lshl_add_u64 v[2:3], s[36:37], 0, v[148:149]
	s_cbranch_scc1 .LBB0_745
	s_barrier
.LBB0_745:
	s_lshl_b32 s5, s5, 5
	s_mov_b64 s[10:11], 0x80
	s_and_b32 s5, s5, 0x60
	s_add_i32 m0, s35, 0x18000
	v_lshl_add_u64 v[6:7], v[6:7], 0, s[10:11]
	s_lshl_b32 s14, s4, 13
	s_lshl_b32 s15, s5, 7
	s_waitcnt vmcnt(2)
	s_barrier
	global_load_lds_dwordx4 v[6:7], off
	v_lshl_add_u64 v[4:5], v[4:5], 0, s[10:11]
	s_add_i32 m0, s35, 0x1a000
	s_add_i32 s47, s35, 0x8000
	s_add_i32 s48, s35, 0xa000
	global_load_lds_dwordx4 v[4:5], off
	v_lshl_add_u64 v[0:1], v[0:1], 0, s[10:11]
	s_mov_b32 m0, s47
	s_add_u32 s12, s38, 0x10080
	global_load_lds_dwordx4 v[0:1], off
	v_lshl_add_u64 v[0:1], v[2:3], 0, s[10:11]
	s_mov_b32 m0, s48
	s_addc_u32 s13, s39, 0
	global_load_lds_dwordx4 v[0:1], off
	s_add_i32 m0, s35, 0x1c000
	v_lshl_add_u64 v[0:1], s[12:13], 0, v[146:147]
	global_load_lds_dwordx4 v[0:1], off
	v_lshl_add_u64 v[0:1], s[12:13], 0, v[150:151]
	s_add_i32 m0, s35, 0x1e000
	v_lshlrev_b32_e32 v4, 2, v8
	global_load_lds_dwordx4 v[0:1], off
	v_lshrrev_b32_e32 v1, 1, v8
	v_and_b32_e32 v0, 15, v8
	v_and_b32_e32 v1, 24, v1
	v_lshl_or_b32 v168, s4, 6, v0
	v_lshlrev_b32_e32 v2, 1, v1
	v_lshl_or_b32 v0, v0, 6, v2
	v_lshlrev_b32_e32 v2, 2, v168
	v_and_b32_e32 v3, 32, v2
	v_and_b32_e32 v5, 32, v4
	v_bitop3_b32 v3, v0, s14, v3 bitop3:0xde
	v_bitop3_b32 v169, v0, s15, v5 bitop3:0xde
	v_lshlrev_b32_e32 v0, 14, v9
	v_and_b32_e32 v0, 0xffff8000, v0
	v_or_b32_e32 v172, s5, v1
	v_lshl_add_u32 v0, v10, 11, v0
	v_and_b32_e32 v1, 1, v9
	v_lshl_or_b32 v0, v1, 6, v0
	v_lshl_add_u32 v152, v11, 1, v0
	v_lshlrev_b32_e32 v0, 14, v12
	s_add_i32 s4, 0, 0x20000
	v_and_b32_e32 v0, 0xffff8000, v0
	s_waitcnt vmcnt(6)
	s_cmpk_lt_u32 s6, 0x100
	v_lshl_add_u32 v0, v13, 11, v0
	v_and_b32_e32 v1, 1, v12
	s_cselect_b64 s[12:13], -1, 0
	v_lshl_or_b32 v0, v1, 6, v0
	s_add_i32 s51, 0, 0x10000
	s_add_i32 s52, 0, 0x14000
	s_sext_i32_i8 s58, s7
	v_add_u32_e32 v170, s4, v2
	v_add_u32_e32 v171, s4, v4
	s_ashr_i32 s49, s94, 31
	s_mov_b32 s50, s94
	v_mov_b32_e32 v153, v147
	v_lshl_add_u32 v154, v14, 1, v0
	v_mov_b32_e32 v155, v147
	v_mov_b64_e32 v[156:157], 0x1000
	v_mov_b64_e32 v[158:159], 0xfff
	v_add_u32_e32 v173, s51, v169
	v_add_u32_e32 v174, s52, v169
	v_add_u32_e32 v175, 0, v3
	s_mov_b64 s[14:15], 0x100000
	s_mov_b32 s53, 0x100000
	s_mov_b64 s[16:17], 0x120000
	s_mov_b32 s54, 0x120000
	s_mov_b64 s[18:19], 0x140000
	s_mov_b32 s55, 0x140000
	s_mov_b64 s[20:21], 0x160000
	s_mov_b32 s56, 0x160000
	v_mov_b32_e32 v176, 0x358637bd
	s_barrier
	s_branch .LBB0_748

; #define PG8_STAGE(bufoff, gbase, voff) do { _Pragma("unroll") for (int _i = 0; _i < 2; ++_i) \
;         __builtin_amdgcn_global_load_lds((const unsigned*)((const char*)(gbase) + (voff)[_i]), (PG8_LAS unsigned*)(lds + (bufoff) + ldsw + _i * 8192), 16, 0, 0); } while (0)
; #define PG8_LDA(dst, b, h) do { _Pragma("unroll") for (int m = 0; m < 4; ++m) _Pragma("unroll") for (int k = 0; k < 2; ++k) dst[m][k] = *(const PG8_LAS bf16x8*)(lds + PG8_SA(b, h) + aoff + m * 2048 + k * 1024); } while (0)
; #define PG8_LDB(dst, b, h) do { _Pragma("unroll") for (int n = 0; n < 2; ++n) _Pragma("unroll") for (int k = 0; k < 2; ++k) dst[n][k] = *(const PG8_LAS bf16x8*)(lds + PG8_SB(b, h) + boff + n * 2048 + k * 1024); } while (0)
; #define PG8_MMA(ai, bj, At, Bt) do { __builtin_amdgcn_s_setprio(1); _Pragma("unroll") for (int m = 0; m < 4; ++m) _Pragma("unroll") for (int n = 0; n < 2; ++n) _Pragma("unroll") for (int k = 0; k < 2; ++k) \
;         acc[ai][bj][m][n] = __builtin_amdgcn_mfma_f32_16x16x32_bf16(Bt[n][k], At[m][k], acc[ai][bj][m][n], 0, 0, 0); __builtin_amdgcn_s_setprio(0); } while (0)
; #define PG8_WAIT_V(n) asm volatile("s_waitcnt vmcnt(" #n ")" ::: "memory")
; #define PG8_WAIT_L(n) asm volatile("s_waitcnt lgkmcnt(" #n ")" ::: "memory")
; #define PG8_BAR __builtin_amdgcn_s_barrier()
; #define PG8_SCHED __builtin_amdgcn_sched_barrier(0)
; template <class Epi, class Sched, bool ALIGN_EPI = false, bool SP2 = false>
; __device__ __forceinline__ void gemm_phase(PG8_LAS unsigned char* lds, const Gemm g, const Sched& S, const Epi& E) {
;     ...
;             PG8_LDB(B0, 0, 0); PG8_LDB(B1, 0, 1); PG8_SCHED; PG8_LDA(At, 0, 0); PG8_STAGE(PG8_SA(1, 1), a1 + hstep, voffA);
;             PG8_WAIT_V(8); PG8_WAIT_L(0); PG8_BAR; PG8_MMA(0, 0, At, B0); PG8_MMA(0, 1, At, B1); PG8_BAR; PG8_SCHED;
;             PG8_LDA(At, 0, 1); PG8_STAGE(PG8_SB(0, 0), b2, voffB); PG8_STAGE(PG8_SB(0, 1), b2 + hstep, voffB); PG8_STAGE(PG8_SA(0, 0), a2, voffA);
;             PG8_WAIT_V(8); PG8_WAIT_L(0); PG8_BAR; PG8_MMA(1, 0, At, B0); PG8_MMA(1, 1, At, B1); PG8_BAR; PG8_SCHED;
.LBB0_755:
	ds_read_b128 v[128:131], v173
	ds_read_b128 v[132:135], v173 offset:1024
	ds_read_b128 v[136:139], v173 offset:2048
	ds_read_b128 v[140:143], v173 offset:3072
	ds_read_b128 v[160:163], v174
	ds_read_b128 v[178:181], v174 offset:1024
	ds_read_b128 v[182:185], v174 offset:2048
	ds_read_b128 v[186:189], v174 offset:3072
	s_add_u32 s38, s36, 0xfffc0080
	s_addc_u32 s39, s37, -1
	s_cmp_eq_u32 s63, 12
	s_cselect_b32 s41, s25, s39
	s_cselect_b32 s40, s59, s38
	s_cselect_b32 s39, s23, s62
	s_cselect_b32 s38, s60, s61
	v_lshl_add_u64 v[164:165], s[36:37], 0, v[152:153]
	s_add_i32 m0, s35, 0xc000
	ds_read_b128 v[190:193], v175
	ds_read_b128 v[194:197], v175 offset:1024
	ds_read_b128 v[198:201], v175 offset:2048
	ds_read_b128 v[202:205], v175 offset:3072
	ds_read_b128 v[206:209], v175 offset:4096
	ds_read_b128 v[210:213], v175 offset:5120
	ds_read_b128 v[214:217], v175 offset:6144
	ds_read_b128 v[218:221], v175 offset:7168
	global_load_lds_dwordx4 v[164:165], off
	v_lshl_add_u64 v[164:165], s[36:37], 0, v[154:155]
	s_add_i32 m0, s35, 0xe000
	s_nop 0
	global_load_lds_dwordx4 v[164:165], off
	s_waitcnt vmcnt(8)
	s_waitcnt lgkmcnt(0)
	s_barrier
	s_setprio 1
	s_waitcnt lgkmcnt(0)
	v_mfma_f32_16x16x32_bf16 v[124:127], v[128:131], v[190:193], v[124:127]
	v_mfma_f32_16x16x32_bf16 v[120:123], v[136:139], v[190:193], v[120:123]
	v_mfma_f32_16x16x32_bf16 v[108:111], v[128:131], v[198:201], v[108:111]
	v_mfma_f32_16x16x32_bf16 v[104:107], v[136:139], v[198:201], v[104:107]
	v_mfma_f32_16x16x32_bf16 v[92:95], v[128:131], v[206:209], v[92:95]
	v_mfma_f32_16x16x32_bf16 v[88:91], v[136:139], v[206:209], v[88:91]
	v_mfma_f32_16x16x32_bf16 v[76:79], v[128:131], v[214:217], v[76:79]
	v_mfma_f32_16x16x32_bf16 v[72:75], v[136:139], v[214:217], v[72:75]
	v_mfma_f32_16x16x32_bf16 v[124:127], v[132:135], v[194:197], v[124:127]
	v_mfma_f32_16x16x32_bf16 v[120:123], v[140:143], v[194:197], v[120:123]
	v_mfma_f32_16x16x32_bf16 v[108:111], v[132:135], v[202:205], v[108:111]
	v_mfma_f32_16x16x32_bf16 v[104:107], v[140:143], v[202:205], v[104:107]
	v_mfma_f32_16x16x32_bf16 v[92:95], v[132:135], v[210:213], v[92:95]
	v_mfma_f32_16x16x32_bf16 v[88:91], v[140:143], v[210:213], v[88:91]
	v_mfma_f32_16x16x32_bf16 v[76:79], v[132:135], v[218:221], v[76:79]
	v_mfma_f32_16x16x32_bf16 v[72:75], v[140:143], v[218:221], v[72:75]
	s_setprio 0
	s_setprio 1
	v_mfma_f32_16x16x32_bf16 v[116:119], v[160:163], v[190:193], v[116:119]
	v_mfma_f32_16x16x32_bf16 v[112:115], v[182:185], v[190:193], v[112:115]
	v_mfma_f32_16x16x32_bf16 v[100:103], v[160:163], v[198:201], v[100:103]
	v_mfma_f32_16x16x32_bf16 v[96:99], v[182:185], v[198:201], v[96:99]
	v_mfma_f32_16x16x32_bf16 v[84:87], v[160:163], v[206:209], v[84:87]
	v_mfma_f32_16x16x32_bf16 v[80:83], v[182:185], v[206:209], v[80:83]
	v_mfma_f32_16x16x32_bf16 v[68:71], v[160:163], v[214:217], v[68:71]
	v_mfma_f32_16x16x32_bf16 v[64:67], v[182:185], v[214:217], v[64:67]
	v_mfma_f32_16x16x32_bf16 v[116:119], v[178:181], v[194:197], v[116:119]
	v_mfma_f32_16x16x32_bf16 v[112:115], v[186:189], v[194:197], v[112:115]
	v_mfma_f32_16x16x32_bf16 v[100:103], v[178:181], v[202:205], v[100:103]
	v_mfma_f32_16x16x32_bf16 v[96:99], v[186:189], v[202:205], v[96:99]
	v_mfma_f32_16x16x32_bf16 v[84:87], v[178:181], v[210:213], v[84:87]
	v_mfma_f32_16x16x32_bf16 v[80:83], v[186:189], v[210:213], v[80:83]
	v_mfma_f32_16x16x32_bf16 v[68:71], v[178:181], v[218:221], v[68:71]
	v_mfma_f32_16x16x32_bf16 v[64:67], v[186:189], v[218:221], v[64:67]
	s_setprio 0
	s_barrier
	s_add_i32 s64, s51, s30
	v_lshl_add_u64 v[164:165], s[38:39], 0, v[146:147]
	s_mov_b32 m0, s64
	ds_read_b128 v[190:193], v175 offset:16384
	ds_read_b128 v[194:197], v175 offset:17408
	ds_read_b128 v[198:201], v175 offset:18432
	ds_read_b128 v[202:205], v175 offset:19456
	ds_read_b128 v[206:209], v175 offset:20480
	ds_read_b128 v[210:213], v175 offset:21504
	ds_read_b128 v[214:217], v175 offset:22528
	ds_read_b128 v[218:221], v175 offset:23552
	global_load_lds_dwordx4 v[164:165], off
	s_add_i32 m0, s64, 0x2000
	s_add_u32 s64, s38, 0x10000
	v_lshl_add_u64 v[222:223], s[38:39], 0, v[150:151]
	s_addc_u32 s65, s39, 0
	s_add_i32 s66, s52, s30
	global_load_lds_dwordx4 v[222:223], off
	v_lshl_add_u64 v[224:225], s[64:65], 0, v[146:147]
	s_mov_b32 m0, s66
	v_lshl_add_u64 v[226:227], s[40:41], 0, v[148:149]
	global_load_lds_dwordx4 v[224:225], off
	v_lshl_add_u64 v[224:225], s[64:65], 0, v[150:151]
	s_add_i32 m0, s66, 0x2000
	s_nop 0
	global_load_lds_dwordx4 v[224:225], off
	v_lshl_add_u64 v[224:225], s[40:41], 0, v[144:145]
	s_mov_b32 m0, s35
	s_nop 0
	global_load_lds_dwordx4 v[224:225], off
	s_mov_b32 m0, s44
	s_nop 0
	global_load_lds_dwordx4 v[226:227], off
	s_waitcnt vmcnt(8)
	s_waitcnt lgkmcnt(0)
	s_barrier
; #define PG8_STAGE(bufoff, gbase, voff) do { _Pragma("unroll") for (int _i = 0; _i < 2; ++_i) \
;         __builtin_amdgcn_global_load_lds((const unsigned*)((const char*)(gbase) + (voff)[_i]), (PG8_LAS unsigned*)(lds + (bufoff) + ldsw + _i * 8192), 16, 0, 0); } while (0)
; #define PG8_LDA(dst, b, h) do { _Pragma("unroll") for (int m = 0; m < 4; ++m) _Pragma("unroll") for (int k = 0; k < 2; ++k) dst[m][k] = *(const PG8_LAS bf16x8*)(lds + PG8_SA(b, h) + aoff + m * 2048 + k * 1024); } while (0)
; #define PG8_LDB(dst, b, h) do { _Pragma("unroll") for (int n = 0; n < 2; ++n) _Pragma("unroll") for (int k = 0; k < 2; ++k) dst[n][k] = *(const PG8_LAS bf16x8*)(lds + PG8_SB(b, h) + boff + n * 2048 + k * 1024); } while (0)
; #define PG8_MMA(ai, bj, At, Bt) do { __builtin_amdgcn_s_setprio(1); _Pragma("unroll") for (int m = 0; m < 4; ++m) _Pragma("unroll") for (int n = 0; n < 2; ++n) _Pragma("unroll") for (int k = 0; k < 2; ++k) \
;         acc[ai][bj][m][n] = __builtin_amdgcn_mfma_f32_16x16x32_bf16(Bt[n][k], At[m][k], acc[ai][bj][m][n], 0, 0, 0); __builtin_amdgcn_s_setprio(0); } while (0)
; #define PG8_WAIT_V(n) asm volatile("s_waitcnt vmcnt(" #n ")" ::: "memory")
; #define PG8_WAIT_L(n) asm volatile("s_waitcnt lgkmcnt(" #n ")" ::: "memory")
; #define PG8_BAR __builtin_amdgcn_s_barrier()
; #define PG8_SCHED __builtin_amdgcn_sched_barrier(0)
; template <class Epi, class Sched, bool ALIGN_EPI = false, bool SP2 = false>
; __device__ __forceinline__ void gemm_phase(PG8_LAS unsigned char* lds, const Gemm g, const Sched& S, const Epi& E) {
;     ...
;             PG8_WAIT_V(8); PG8_WAIT_L(0); PG8_BAR; PG8_MMA(1, 0, At, B0); PG8_MMA(1, 1, At, B1); PG8_BAR; PG8_SCHED;
;             PG8_LDB(B0, 1, 0); PG8_LDB(B1, 1, 1); PG8_SCHED; PG8_LDA(At, 1, 0); PG8_STAGE(PG8_SA(0, 1), a2 + hstep, voffA);
;             PG8_WAIT_V(8); PG8_WAIT_L(0); PG8_BAR; PG8_MMA(0, 0, At, B0); PG8_MMA(0, 1, At, B1); PG8_BAR; PG8_SCHED;
	s_setprio 1
	s_waitcnt lgkmcnt(0)
	v_mfma_f32_16x16x32_bf16 v[60:63], v[128:131], v[190:193], v[60:63]
	v_mfma_f32_16x16x32_bf16 v[56:59], v[136:139], v[190:193], v[56:59]
	v_mfma_f32_16x16x32_bf16 v[44:47], v[128:131], v[198:201], v[44:47]
	v_mfma_f32_16x16x32_bf16 v[40:43], v[136:139], v[198:201], v[40:43]
	v_mfma_f32_16x16x32_bf16 v[28:31], v[128:131], v[206:209], v[28:31]
	v_mfma_f32_16x16x32_bf16 v[24:27], v[136:139], v[206:209], v[24:27]
	v_mfma_f32_16x16x32_bf16 v[12:15], v[128:131], v[214:217], v[12:15]
	v_mfma_f32_16x16x32_bf16 v[8:11], v[136:139], v[214:217], v[8:11]
	v_mfma_f32_16x16x32_bf16 v[60:63], v[132:135], v[194:197], v[60:63]
	v_mfma_f32_16x16x32_bf16 v[56:59], v[140:143], v[194:197], v[56:59]
	v_mfma_f32_16x16x32_bf16 v[44:47], v[132:135], v[202:205], v[44:47]
	v_mfma_f32_16x16x32_bf16 v[40:43], v[140:143], v[202:205], v[40:43]
	v_mfma_f32_16x16x32_bf16 v[28:31], v[132:135], v[210:213], v[28:31]
	v_mfma_f32_16x16x32_bf16 v[24:27], v[140:143], v[210:213], v[24:27]
	v_mfma_f32_16x16x32_bf16 v[12:15], v[132:135], v[218:221], v[12:15]
	v_mfma_f32_16x16x32_bf16 v[8:11], v[140:143], v[218:221], v[8:11]
	s_setprio 0
	s_setprio 1
	v_mfma_f32_16x16x32_bf16 v[52:55], v[160:163], v[190:193], v[52:55]
	v_mfma_f32_16x16x32_bf16 v[48:51], v[182:185], v[190:193], v[48:51]
	v_mfma_f32_16x16x32_bf16 v[36:39], v[160:163], v[198:201], v[36:39]
	v_mfma_f32_16x16x32_bf16 v[32:35], v[182:185], v[198:201], v[32:35]
	v_mfma_f32_16x16x32_bf16 v[20:23], v[160:163], v[206:209], v[20:23]
	v_mfma_f32_16x16x32_bf16 v[16:19], v[182:185], v[206:209], v[16:19]
	v_mfma_f32_16x16x32_bf16 v[4:7], v[160:163], v[214:217], v[4:7]
	v_mfma_f32_16x16x32_bf16 v[0:3], v[182:185], v[214:217], v[0:3]
	v_mfma_f32_16x16x32_bf16 v[52:55], v[178:181], v[194:197], v[52:55]
	v_mfma_f32_16x16x32_bf16 v[48:51], v[186:189], v[194:197], v[48:51]
	v_mfma_f32_16x16x32_bf16 v[36:39], v[178:181], v[202:205], v[36:39]
	v_mfma_f32_16x16x32_bf16 v[32:35], v[186:189], v[202:205], v[32:35]
	v_mfma_f32_16x16x32_bf16 v[20:23], v[178:181], v[210:213], v[20:23]
	v_mfma_f32_16x16x32_bf16 v[16:19], v[186:189], v[210:213], v[16:19]
	v_mfma_f32_16x16x32_bf16 v[4:7], v[178:181], v[218:221], v[4:7]
	v_mfma_f32_16x16x32_bf16 v[0:3], v[186:189], v[218:221], v[0:3]
	s_setprio 0
	s_barrier
	s_add_i32 s64, 0, 0x18000
	s_add_i32 s65, 0, 0x1c000
	v_add_u32_e32 v140, s64, v169
	v_add_u32_e32 v177, s65, v169
	ds_read_b128 v[128:131], v140
	ds_read_b128 v[132:135], v140 offset:1024
	ds_read_b128 v[136:139], v140 offset:2048
	ds_read_b128 v[140:143], v140 offset:3072
	ds_read_b128 v[160:163], v177
	ds_read_b128 v[178:181], v177 offset:1024
	ds_read_b128 v[182:185], v177 offset:2048
	ds_read_b128 v[186:189], v177 offset:3072
	s_add_u32 s40, s40, 0x40000
	s_addc_u32 s41, s41, 0
	s_mov_b32 m0, s45
	v_lshl_add_u64 v[228:229], s[40:41], 0, v[144:145]
	ds_read_b128 v[190:193], v175 offset:32768
	ds_read_b128 v[194:197], v175 offset:33792
	ds_read_b128 v[198:201], v175 offset:34816
	ds_read_b128 v[202:205], v175 offset:35840
	ds_read_b128 v[206:209], v175 offset:36864
	ds_read_b128 v[210:213], v175 offset:37888
	ds_read_b128 v[214:217], v175 offset:38912
	ds_read_b128 v[218:221], v175 offset:39936
	global_load_lds_dwordx4 v[228:229], off
	v_lshl_add_u64 v[228:229], s[40:41], 0, v[148:149]
	s_mov_b32 m0, s46
	s_nop 0
	global_load_lds_dwordx4 v[228:229], off
	s_waitcnt vmcnt(8)
	s_waitcnt lgkmcnt(0)
	s_barrier
	s_setprio 1
	s_waitcnt lgkmcnt(0)
	v_mfma_f32_16x16x32_bf16 v[124:127], v[128:131], v[190:193], v[124:127]
	v_mfma_f32_16x16x32_bf16 v[120:123], v[136:139], v[190:193], v[120:123]
	v_mfma_f32_16x16x32_bf16 v[108:111], v[128:131], v[198:201], v[108:111]
	v_mfma_f32_16x16x32_bf16 v[104:107], v[136:139], v[198:201], v[104:107]
	v_mfma_f32_16x16x32_bf16 v[92:95], v[128:131], v[206:209], v[92:95]
	v_mfma_f32_16x16x32_bf16 v[88:91], v[136:139], v[206:209], v[88:91]
	v_mfma_f32_16x16x32_bf16 v[76:79], v[128:131], v[214:217], v[76:79]
	v_mfma_f32_16x16x32_bf16 v[72:75], v[136:139], v[214:217], v[72:75]
	v_mfma_f32_16x16x32_bf16 v[124:127], v[132:135], v[194:197], v[124:127]
	v_mfma_f32_16x16x32_bf16 v[120:123], v[140:143], v[194:197], v[120:123]
	v_mfma_f32_16x16x32_bf16 v[108:111], v[132:135], v[202:205], v[108:111]
	v_mfma_f32_16x16x32_bf16 v[104:107], v[140:143], v[202:205], v[104:107]
	v_mfma_f32_16x16x32_bf16 v[92:95], v[132:135], v[210:213], v[92:95]
	v_mfma_f32_16x16x32_bf16 v[88:91], v[140:143], v[210:213], v[88:91]
	v_mfma_f32_16x16x32_bf16 v[76:79], v[132:135], v[218:221], v[76:79]
	v_mfma_f32_16x16x32_bf16 v[72:75], v[140:143], v[218:221], v[72:75]
	s_setprio 0
	s_setprio 1
	v_mfma_f32_16x16x32_bf16 v[116:119], v[160:163], v[190:193], v[116:119]
	v_mfma_f32_16x16x32_bf16 v[112:115], v[182:185], v[190:193], v[112:115]
	v_mfma_f32_16x16x32_bf16 v[100:103], v[160:163], v[198:201], v[100:103]
	v_mfma_f32_16x16x32_bf16 v[96:99], v[182:185], v[198:201], v[96:99]
	v_mfma_f32_16x16x32_bf16 v[84:87], v[160:163], v[206:209], v[84:87]
	v_mfma_f32_16x16x32_bf16 v[80:83], v[182:185], v[206:209], v[80:83]
	v_mfma_f32_16x16x32_bf16 v[68:71], v[160:163], v[214:217], v[68:71]
	v_mfma_f32_16x16x32_bf16 v[64:67], v[182:185], v[214:217], v[64:67]
	v_mfma_f32_16x16x32_bf16 v[116:119], v[178:181], v[194:197], v[116:119]
	v_mfma_f32_16x16x32_bf16 v[112:115], v[186:189], v[194:197], v[112:115]
	v_mfma_f32_16x16x32_bf16 v[100:103], v[178:181], v[202:205], v[100:103]
	v_mfma_f32_16x16x32_bf16 v[96:99], v[186:189], v[202:205], v[96:99]
	v_mfma_f32_16x16x32_bf16 v[84:87], v[178:181], v[210:213], v[84:87]
	v_mfma_f32_16x16x32_bf16 v[80:83], v[186:189], v[210:213], v[80:83]
	v_mfma_f32_16x16x32_bf16 v[68:71], v[178:181], v[218:221], v[68:71]
	v_mfma_f32_16x16x32_bf16 v[64:67], v[186:189], v[218:221], v[64:67]
	s_setprio 0
	s_barrier
; #define PG8_STAGE(bufoff, gbase, voff) do { _Pragma("unroll") for (int _i = 0; _i < 2; ++_i) \
;         __builtin_amdgcn_global_load_lds((const unsigned*)((const char*)(gbase) + (voff)[_i]), (PG8_LAS unsigned*)(lds + (bufoff) + ldsw + _i * 8192), 16, 0, 0); } while (0)
; #define PG8_WAIT_V(n) asm volatile("s_waitcnt vmcnt(" #n ")" ::: "memory")
; template <class Epi, class Sched, bool ALIGN_EPI = false, bool SP2 = false>
; __device__ __forceinline__ void gemm_phase(PG8_LAS unsigned char* lds, const Gemm g, const Sched& S, const Epi& E) {
;     ...
;             PG8_LDA(At, 1, 1); PG8_STAGE(PG8_SB(1, 0), b3, voffB); PG8_STAGE(PG8_SB(1, 1), b3 + hstep, voffB); PG8_STAGE(PG8_SA(1, 0), a3, voffA);
;             PG8_WAIT_V(8); PG8_WAIT_L(0); PG8_BAR; PG8_MMA(1, 0, At, B0); PG8_MMA(1, 1, At, B1); PG8_BAR; PG8_SCHED;
;             } else {
;             PG8_LDB(B0, 0, 0); PG8_SCHED; PG8_LDA(At, 0, 0); PG8_STAGE(PG8_SA(1, 1), a1 + hstep, voffA);
;             PG8_WAIT_L(8); PG8_BAR; PG8_WAIT_L(0); PG8_MMA(0, 0, At, B0); PG8_BAR; PG8_SCHED;
;             PG8_LDB(B1, 0, 1); PG8_STAGE(PG8_SB(0, 0), b2, voffB);
;             PG8_BAR; PG8_WAIT_L(0); PG8_MMA(0, 1, At, B1); PG8_BAR;
;             PG8_LDA(At, 0, 1); PG8_STAGE(PG8_SA(0, 0), a2, voffA);
;             PG8_BAR; PG8_WAIT_L(0); PG8_MMA(1, 0, At, B0); PG8_BAR; PG8_SCHED;
;             PG8_STAGE(PG8_SB(0, 1), b2 + hstep, voffB);
;             PG8_WAIT_V(6); PG8_BAR; PG8_MMA(1, 1, At, B1); PG8_BAR;
;             PG8_LDB(B0, 1, 0); PG8_SCHED; PG8_LDA(At, 1, 0); PG8_STAGE(PG8_SA(0, 1), a2 + hstep, voffA);
;             PG8_WAIT_L(8); PG8_BAR; PG8_WAIT_L(0); PG8_MMA(0, 0, At, B0); PG8_BAR; PG8_SCHED;
;             PG8_LDB(B1, 1, 1); PG8_STAGE(PG8_SB(1, 0), b3, voffB);
;             PG8_BAR; PG8_WAIT_L(0); PG8_MMA(0, 1, At, B1); PG8_BAR;
;             PG8_LDA(At, 1, 1); PG8_STAGE(PG8_SA(1, 0), a3, voffA);
;             PG8_BAR; PG8_WAIT_L(0); PG8_MMA(1, 0, At, B0); PG8_BAR; PG8_SCHED;
;             PG8_STAGE(PG8_SB(1, 1), b3 + hstep, voffB);
;             PG8_WAIT_V(6); PG8_BAR; PG8_MMA(1, 1, At, B1); PG8_BAR;
;             }
;         }
;         if constexpr (ALIGN_EPI) { if (wr == 0) PG8_BAR; }
;         if constexpr (Epi::HAS_PRE) {
;             if (has_next) { const auto pn_ = E.pre_load(nxt.pm, tid); E(acc, cur, wr, wc, fr, fq, ptab + (ui & 1) * 256); E.pre_store(pn_, ptab + ((ui + 1) & 1) * 256, tid); }
	s_add_i32 s40, s64, s30
	v_lshl_add_u64 v[164:165], v[164:165], 0, s[10:11]
	s_mov_b32 m0, s40
	ds_read_b128 v[190:193], v175 offset:49152
	ds_read_b128 v[194:197], v175 offset:50176
	ds_read_b128 v[198:201], v175 offset:51200
	ds_read_b128 v[202:205], v175 offset:52224
	ds_read_b128 v[206:209], v175 offset:53248
	ds_read_b128 v[210:213], v175 offset:54272
	ds_read_b128 v[214:217], v175 offset:55296
	ds_read_b128 v[218:221], v175 offset:56320
	global_load_lds_dwordx4 v[164:165], off
	s_add_i32 m0, s40, 0x2000
	s_add_u32 s38, s38, 0x10080
	v_lshl_add_u64 v[164:165], v[222:223], 0, s[10:11]
	s_addc_u32 s39, s39, 0
	s_add_i32 s40, s65, s30
	global_load_lds_dwordx4 v[164:165], off
	v_lshl_add_u64 v[164:165], s[38:39], 0, v[146:147]
	s_mov_b32 m0, s40
	s_nop 0
	global_load_lds_dwordx4 v[164:165], off
	v_lshl_add_u64 v[164:165], s[38:39], 0, v[150:151]
	s_add_i32 m0, s40, 0x2000
	s_nop 0
	global_load_lds_dwordx4 v[164:165], off
	v_lshl_add_u64 v[164:165], v[224:225], 0, s[10:11]
	s_mov_b32 m0, s47
	s_nop 0
	global_load_lds_dwordx4 v[164:165], off
	v_lshl_add_u64 v[164:165], v[226:227], 0, s[10:11]
	s_mov_b32 m0, s48
	s_nop 0
	global_load_lds_dwordx4 v[164:165], off
	s_waitcnt vmcnt(8)
	s_waitcnt lgkmcnt(0)
	s_barrier
	s_setprio 1
	s_waitcnt lgkmcnt(0)
	v_mfma_f32_16x16x32_bf16 v[60:63], v[128:131], v[190:193], v[60:63]
	v_mfma_f32_16x16x32_bf16 v[56:59], v[136:139], v[190:193], v[56:59]
	v_mfma_f32_16x16x32_bf16 v[44:47], v[128:131], v[198:201], v[44:47]
	v_mfma_f32_16x16x32_bf16 v[40:43], v[136:139], v[198:201], v[40:43]
	v_mfma_f32_16x16x32_bf16 v[28:31], v[128:131], v[206:209], v[28:31]
	v_mfma_f32_16x16x32_bf16 v[24:27], v[136:139], v[206:209], v[24:27]
	v_mfma_f32_16x16x32_bf16 v[12:15], v[128:131], v[214:217], v[12:15]
	v_mfma_f32_16x16x32_bf16 v[8:11], v[136:139], v[214:217], v[8:11]
	v_mfma_f32_16x16x32_bf16 v[60:63], v[132:135], v[194:197], v[60:63]
	v_mfma_f32_16x16x32_bf16 v[56:59], v[140:143], v[194:197], v[56:59]
	v_mfma_f32_16x16x32_bf16 v[44:47], v[132:135], v[202:205], v[44:47]
	v_mfma_f32_16x16x32_bf16 v[40:43], v[140:143], v[202:205], v[40:43]
	v_mfma_f32_16x16x32_bf16 v[28:31], v[132:135], v[210:213], v[28:31]
	v_mfma_f32_16x16x32_bf16 v[24:27], v[140:143], v[210:213], v[24:27]
	v_mfma_f32_16x16x32_bf16 v[12:15], v[132:135], v[218:221], v[12:15]
	v_mfma_f32_16x16x32_bf16 v[8:11], v[140:143], v[218:221], v[8:11]
	s_setprio 0
	s_setprio 1
	v_mfma_f32_16x16x32_bf16 v[52:55], v[160:163], v[190:193], v[52:55]
	v_mfma_f32_16x16x32_bf16 v[48:51], v[182:185], v[190:193], v[48:51]
	v_mfma_f32_16x16x32_bf16 v[36:39], v[160:163], v[198:201], v[36:39]
	v_mfma_f32_16x16x32_bf16 v[32:35], v[182:185], v[198:201], v[32:35]
	v_mfma_f32_16x16x32_bf16 v[20:23], v[160:163], v[206:209], v[20:23]
	v_mfma_f32_16x16x32_bf16 v[16:19], v[182:185], v[206:209], v[16:19]
	v_mfma_f32_16x16x32_bf16 v[4:7], v[160:163], v[214:217], v[4:7]
	v_mfma_f32_16x16x32_bf16 v[0:3], v[182:185], v[214:217], v[0:3]
	v_mfma_f32_16x16x32_bf16 v[52:55], v[178:181], v[194:197], v[52:55]
	v_mfma_f32_16x16x32_bf16 v[48:51], v[186:189], v[194:197], v[48:51]
	v_mfma_f32_16x16x32_bf16 v[36:39], v[178:181], v[202:205], v[36:39]
	v_mfma_f32_16x16x32_bf16 v[32:35], v[186:189], v[202:205], v[32:35]
	v_mfma_f32_16x16x32_bf16 v[20:23], v[178:181], v[210:213], v[20:23]
	v_mfma_f32_16x16x32_bf16 v[16:19], v[186:189], v[210:213], v[16:19]
	v_mfma_f32_16x16x32_bf16 v[4:7], v[178:181], v[218:221], v[4:7]
	v_mfma_f32_16x16x32_bf16 v[0:3], v[186:189], v[218:221], v[0:3]
	s_setprio 0
	s_barrier
	s_add_i32 s63, s63, 2
	s_add_u32 s36, s36, 0x100
	s_addc_u32 s37, s37, 0
	s_add_u32 s61, s61, 0x100
	s_addc_u32 s62, s62, 0
	s_cmp_gt_u32 s63, 13
	s_cbranch_scc0 .LBB0_755
	v_mbcnt_lo_u32_b32 v234, -1, 0
	v_mbcnt_hi_u32_b32 v234, -1, v234
	v_bfe_u32 v234, v234, 3, 1
	v_sub_u32_e32 v249, 0, v234
	v_and_b32_e32 v248, 0xffff0040, v249
	v_and_b32_e32 v235, 0xffc0, v249
	v_sub_u32_e32 v250, 0x10000, v235
	v_mov_b32_e32 v251, 0
	s_mov_b32 s98, 0xff00ff
	s_mov_b32 s99, 0xff00ff
	s_and_b64 vcc, exec, s[12:13]
	s_cbranch_vccz .LBB0_758
	s_barrier
.LBB0_758:
	s_mov_b64 s[36:37], -1
	s_and_b64 vcc, exec, s[6:7]
	v_lshl_add_u32 v160, s34, 8, v168
	v_lshl_or_b32 v162, s58, 8, v172
	v_add_u32_e32 v162, s100, v162
	s_cbranch_vccnz .LBB0_761
	s_andn2_b64 vcc, exec, s[36:37]
	s_cbranch_vccz .LBB0_762

; __device__ __forceinline__ unsigned cvt_pk_bf16(float lo, float hi) { const f32x2_t v = {lo, hi}; const bf16x2_t b = __builtin_convertvector(v, bf16x2_t); return __builtin_bit_cast(unsigned, b); }
;     __device__ __forceinline__ void operator()(const f32x4 (&acc)[2][2][4][2], const Unit& u, int wr, int wc, int fr, int fq, const PG8_LAS float* tab) const {
;     ...
;             for (int m = 0; m < 4; ++m) { const int row = row0 + ai * HALF + m * 16; bf16_t* rowp = O + (size_t)row * ldc + col0;
;                 const float rstd = tab[rl0 + ai * HALF + m * 16];
; #pragma unroll
;                 for (int bj = 0; bj < 2; ++bj) { f32x4 v0 = acc[ai][bj][m][0] * rstd, v1 = acc[ai][bj][m][1] * rstd;
;                     if (ACT == 1) {
; #pragma unroll
;                         for (int e = 0; e < 4; ++e) { float a = v0[e] > 0.f ? v0[e] : 0.f; v0[e] = a * a; float b = v1[e] > 0.f ? v1[e] : 0.f; v1[e] = b * b; } }
;                     u32x4 w; w.x = cvt_pk_bf16(v0[0], v0[1]); w.y = cvt_pk_bf16(v0[2], v0[3]); w.z = cvt_pk_bf16(v1[0], v1[1]); w.w = cvt_pk_bf16(v1[2], v1[3]);
;                     *(u32x4*)(rowp + bj * HALF) = w; } }
.LBB0_761:
	s_lshl_b32 s6, s31, 10
	s_and_b32 s6, s6, 0x400
	v_add_u32_e32 v132, s6, v170
	ds_read2_b32 v[138:139], v132 offset1:16
	v_ashrrev_i32_e32 v161, 31, v160
	v_ashrrev_i32_e32 v163, 31, v162
	v_lshlrev_b64 v[128:129], 13, v[160:161]
	v_lshl_add_u64 v[128:129], s[92:93], 0, v[128:129]
	s_waitcnt lgkmcnt(0)
	v_pk_mul_f32 v[134:135], v[126:127], v[138:139] op_sel_hi:[1,0]
	v_pk_mul_f32 v[136:137], v[124:125], v[138:139] op_sel_hi:[1,0]
	v_pk_mul_f32 v[140:141], v[122:123], v[138:139] op_sel_hi:[1,0]
	v_pk_mul_f32 v[142:143], v[120:121], v[138:139] op_sel_hi:[1,0]
	v_max_f32_e32 v135, 0, v135
	v_max_f32_e32 v134, 0, v134
	v_max_f32_e32 v137, 0, v137
	v_max_f32_e32 v136, 0, v136
	v_max_f32_e32 v143, 0, v143
	v_max_f32_e32 v142, 0, v142
	v_pk_mul_f32 v[164:165], v[134:135], v[134:135]
	v_max_f32_e32 v135, 0, v141
	v_max_f32_e32 v134, 0, v140
	v_lshlrev_b64 v[130:131], 1, v[162:163]
	v_pk_mul_f32 v[136:137], v[136:137], v[136:137]
	v_pk_mul_f32 v[142:143], v[142:143], v[142:143]
	v_pk_mul_f32 v[140:141], v[134:135], v[134:135]
	v_lshl_add_u64 v[128:129], v[128:129], 0, v[130:131]
	v_cvt_pk_bf16_f32 v134, v136, v137
	v_cvt_pk_bf16_f32 v135, v164, v165
	v_cvt_pk_bf16_f32 v136, v142, v143
	v_cvt_pk_bf16_f32 v137, v140, v141
	v_mov_b32_e32 v236, v134
	v_mov_b32_e32 v237, v135
	v_mov_b32_e32 v238, v136
	v_mov_b32_e32 v239, v137
	v_lshl_add_u64 v[230:231], v[128:129], 0, v[248:249]
	v_lshl_add_u64 v[232:233], v[128:129], 0, v[250:251]
	v_pk_mul_f32 v[140:141], v[114:115], v[138:139] op_sel_hi:[1,0]
	v_pk_mul_f32 v[142:143], v[112:113], v[138:139] op_sel_hi:[1,0]
	v_pk_mul_f32 v[134:135], v[118:119], v[138:139] op_sel_hi:[1,0]
	v_pk_mul_f32 v[136:137], v[116:117], v[138:139] op_sel_hi:[1,0]
	v_max_f32_e32 v135, 0, v135
	v_max_f32_e32 v134, 0, v134
	v_max_f32_e32 v137, 0, v137
	v_max_f32_e32 v136, 0, v136
	v_max_f32_e32 v143, 0, v143
	v_max_f32_e32 v142, 0, v142
	v_pk_mul_f32 v[164:165], v[134:135], v[134:135]
	v_max_f32_e32 v135, 0, v141
	v_max_f32_e32 v134, 0, v140
	v_pk_mul_f32 v[136:137], v[136:137], v[136:137]
	v_pk_mul_f32 v[142:143], v[142:143], v[142:143]
	v_pk_mul_f32 v[140:141], v[134:135], v[134:135]
	v_cvt_pk_bf16_f32 v134, v136, v137
	v_cvt_pk_bf16_f32 v135, v164, v165
	v_cvt_pk_bf16_f32 v136, v142, v143
	v_cvt_pk_bf16_f32 v137, v140, v141
	ds_swizzle_b32 v240, v134 offset:swizzle(SWAP,8)
	ds_swizzle_b32 v241, v135 offset:swizzle(SWAP,8)
	ds_swizzle_b32 v242, v136 offset:swizzle(SWAP,8)
	ds_swizzle_b32 v243, v137 offset:swizzle(SWAP,8)
	ds_swizzle_b32 v244, v236 offset:swizzle(SWAP,8)
	ds_swizzle_b32 v245, v237 offset:swizzle(SWAP,8)
	ds_swizzle_b32 v246, v238 offset:swizzle(SWAP,8)
	ds_swizzle_b32 v247, v239 offset:swizzle(SWAP,8)
	s_waitcnt lgkmcnt(0)
	v_cndmask_b32_e64 v240, v240, v236, s[98:99]
	v_cndmask_b32_e64 v241, v241, v237, s[98:99]
	v_cndmask_b32_e64 v242, v242, v238, s[98:99]
	v_cndmask_b32_e64 v243, v243, v239, s[98:99]
	v_cndmask_b32_e64 v244, v134, v244, s[98:99]
	v_cndmask_b32_e64 v245, v135, v245, s[98:99]
	v_cndmask_b32_e64 v246, v136, v246, s[98:99]
	v_cndmask_b32_e64 v247, v137, v247, s[98:99]
	global_store_dwordx4 v[230:231], v[240:243], off
	global_store_dwordx4 v[232:233], v[244:247], off
	v_mov_b32_e32 v138, v139
	v_pk_mul_f32 v[142:143], v[106:107], v[138:139] op_sel_hi:[1,0]
	v_or_b32_e32 v134, 16, v160
	v_ashrrev_i32_e32 v135, 31, v134
	v_lshlrev_b64 v[134:135], 13, v[134:135]
	v_lshl_add_u64 v[134:135], s[92:93], 0, v[134:135]
	v_lshl_add_u64 v[140:141], v[134:135], 0, v[130:131]
	v_pk_mul_f32 v[134:135], v[110:111], v[138:139] op_sel_hi:[1,0]
	v_pk_mul_f32 v[136:137], v[108:109], v[138:139] op_sel_hi:[1,0]
	v_pk_mul_f32 v[164:165], v[104:105], v[138:139] op_sel_hi:[1,0]
	v_max_f32_e32 v135, 0, v135
	v_max_f32_e32 v134, 0, v134
	v_max_f32_e32 v137, 0, v137
	v_max_f32_e32 v136, 0, v136
	v_max_f32_e32 v165, 0, v165
	v_max_f32_e32 v164, 0, v164
	v_pk_mul_f32 v[178:179], v[134:135], v[134:135]
	v_max_f32_e32 v135, 0, v143
	v_max_f32_e32 v134, 0, v142
	v_pk_mul_f32 v[136:137], v[136:137], v[136:137]
	v_pk_mul_f32 v[164:165], v[164:165], v[164:165]
	v_pk_mul_f32 v[142:143], v[134:135], v[134:135]
	v_cvt_pk_bf16_f32 v134, v136, v137
	v_cvt_pk_bf16_f32 v135, v178, v179
	v_cvt_pk_bf16_f32 v136, v164, v165
	v_cvt_pk_bf16_f32 v137, v142, v143
	v_mov_b32_e32 v236, v134
	v_mov_b32_e32 v237, v135
	v_mov_b32_e32 v238, v136
	v_mov_b32_e32 v239, v137
	v_lshl_add_u64 v[230:231], v[140:141], 0, v[248:249]
	v_lshl_add_u64 v[232:233], v[140:141], 0, v[250:251]
	v_pk_mul_f32 v[142:143], v[98:99], v[138:139] op_sel_hi:[1,0]
	s_nop 0
	v_pk_mul_f32 v[134:135], v[102:103], v[138:139] op_sel_hi:[1,0]
	v_pk_mul_f32 v[136:137], v[100:101], v[138:139] op_sel_hi:[1,0]
	v_pk_mul_f32 v[138:139], v[96:97], v[138:139] op_sel_hi:[1,0]
	v_max_f32_e32 v135, 0, v135
	v_max_f32_e32 v134, 0, v134
	v_max_f32_e32 v137, 0, v137
	v_max_f32_e32 v136, 0, v136
	v_max_f32_e32 v139, 0, v139
	v_max_f32_e32 v138, 0, v138
	v_pk_mul_f32 v[164:165], v[134:135], v[134:135]
	v_max_f32_e32 v135, 0, v143
	v_max_f32_e32 v134, 0, v142
	v_pk_mul_f32 v[136:137], v[136:137], v[136:137]
	v_pk_mul_f32 v[138:139], v[138:139], v[138:139]
	v_pk_mul_f32 v[142:143], v[134:135], v[134:135]
	v_cvt_pk_bf16_f32 v134, v136, v137
	v_cvt_pk_bf16_f32 v135, v164, v165
	v_cvt_pk_bf16_f32 v136, v138, v139
	v_cvt_pk_bf16_f32 v137, v142, v143
	ds_read2_b32 v[138:139], v132 offset0:32 offset1:48
	ds_swizzle_b32 v240, v134 offset:swizzle(SWAP,8)
	ds_swizzle_b32 v241, v135 offset:swizzle(SWAP,8)
	ds_swizzle_b32 v242, v136 offset:swizzle(SWAP,8)
	ds_swizzle_b32 v243, v137 offset:swizzle(SWAP,8)
	ds_swizzle_b32 v244, v236 offset:swizzle(SWAP,8)
	ds_swizzle_b32 v245, v237 offset:swizzle(SWAP,8)
	ds_swizzle_b32 v246, v238 offset:swizzle(SWAP,8)
	ds_swizzle_b32 v247, v239 offset:swizzle(SWAP,8)
	s_waitcnt lgkmcnt(0)
; __device__ __forceinline__ unsigned cvt_pk_bf16(float lo, float hi) { const f32x2_t v = {lo, hi}; const bf16x2_t b = __builtin_convertvector(v, bf16x2_t); return __builtin_bit_cast(unsigned, b); }
;     __device__ __forceinline__ void operator()(const f32x4 (&acc)[2][2][4][2], const Unit& u, int wr, int wc, int fr, int fq, const PG8_LAS float* tab) const {
;     ...
;             for (int m = 0; m < 4; ++m) { const int row = row0 + ai * HALF + m * 16; bf16_t* rowp = O + (size_t)row * ldc + col0;
;                 const float rstd = tab[rl0 + ai * HALF + m * 16];
; #pragma unroll
;                 for (int bj = 0; bj < 2; ++bj) { f32x4 v0 = acc[ai][bj][m][0] * rstd, v1 = acc[ai][bj][m][1] * rstd;
;                     if (ACT == 1) {
; #pragma unroll
;                         for (int e = 0; e < 4; ++e) { float a = v0[e] > 0.f ? v0[e] : 0.f; v0[e] = a * a; float b = v1[e] > 0.f ? v1[e] : 0.f; v1[e] = b * b; } }
;                     u32x4 w; w.x = cvt_pk_bf16(v0[0], v0[1]); w.y = cvt_pk_bf16(v0[2], v0[3]); w.z = cvt_pk_bf16(v1[0], v1[1]); w.w = cvt_pk_bf16(v1[2], v1[3]);
;                     *(u32x4*)(rowp + bj * HALF) = w; } }
	v_cndmask_b32_e64 v240, v240, v236, s[98:99]
	v_cndmask_b32_e64 v241, v241, v237, s[98:99]
	v_cndmask_b32_e64 v242, v242, v238, s[98:99]
	v_cndmask_b32_e64 v243, v243, v239, s[98:99]
	v_cndmask_b32_e64 v244, v134, v244, s[98:99]
	v_cndmask_b32_e64 v245, v135, v245, s[98:99]
	v_cndmask_b32_e64 v246, v136, v246, s[98:99]
	v_cndmask_b32_e64 v247, v137, v247, s[98:99]
	global_store_dwordx4 v[230:231], v[240:243], off
	global_store_dwordx4 v[232:233], v[244:247], off
	s_waitcnt lgkmcnt(0)
	v_pk_mul_f32 v[142:143], v[90:91], v[138:139] op_sel_hi:[1,0]
	v_or_b32_e32 v134, 32, v160
	v_ashrrev_i32_e32 v135, 31, v134
	v_lshlrev_b64 v[134:135], 13, v[134:135]
	v_lshl_add_u64 v[134:135], s[92:93], 0, v[134:135]
	v_lshl_add_u64 v[140:141], v[134:135], 0, v[130:131]
	v_pk_mul_f32 v[134:135], v[94:95], v[138:139] op_sel_hi:[1,0]
	v_pk_mul_f32 v[136:137], v[92:93], v[138:139] op_sel_hi:[1,0]
	v_pk_mul_f32 v[164:165], v[88:89], v[138:139] op_sel_hi:[1,0]
	v_max_f32_e32 v135, 0, v135
	v_max_f32_e32 v134, 0, v134
	v_max_f32_e32 v137, 0, v137
	v_max_f32_e32 v136, 0, v136
	v_max_f32_e32 v165, 0, v165
	v_max_f32_e32 v164, 0, v164
	v_pk_mul_f32 v[178:179], v[134:135], v[134:135]
	v_max_f32_e32 v135, 0, v143
	v_max_f32_e32 v134, 0, v142
	v_pk_mul_f32 v[136:137], v[136:137], v[136:137]
	v_pk_mul_f32 v[164:165], v[164:165], v[164:165]
	v_pk_mul_f32 v[142:143], v[134:135], v[134:135]
	v_cvt_pk_bf16_f32 v134, v136, v137
	v_cvt_pk_bf16_f32 v135, v178, v179
	v_cvt_pk_bf16_f32 v136, v164, v165
	v_cvt_pk_bf16_f32 v137, v142, v143
	v_mov_b32_e32 v236, v134
	v_mov_b32_e32 v237, v135
	v_mov_b32_e32 v238, v136
	v_mov_b32_e32 v239, v137
	v_lshl_add_u64 v[230:231], v[140:141], 0, v[248:249]
	v_lshl_add_u64 v[232:233], v[140:141], 0, v[250:251]
	v_pk_mul_f32 v[142:143], v[82:83], v[138:139] op_sel_hi:[1,0]
	v_pk_mul_f32 v[164:165], v[80:81], v[138:139] op_sel_hi:[1,0]
	v_pk_mul_f32 v[134:135], v[86:87], v[138:139] op_sel_hi:[1,0]
	v_pk_mul_f32 v[136:137], v[84:85], v[138:139] op_sel_hi:[1,0]
	v_max_f32_e32 v135, 0, v135
	v_max_f32_e32 v134, 0, v134
	v_max_f32_e32 v137, 0, v137
	v_max_f32_e32 v136, 0, v136
	v_max_f32_e32 v165, 0, v165
	v_max_f32_e32 v164, 0, v164
	v_pk_mul_f32 v[178:179], v[134:135], v[134:135]
	v_max_f32_e32 v135, 0, v143
	v_max_f32_e32 v134, 0, v142
	v_pk_mul_f32 v[136:137], v[136:137], v[136:137]
	v_pk_mul_f32 v[164:165], v[164:165], v[164:165]
	v_pk_mul_f32 v[142:143], v[134:135], v[134:135]
	v_cvt_pk_bf16_f32 v134, v136, v137
	v_cvt_pk_bf16_f32 v135, v178, v179
	v_cvt_pk_bf16_f32 v136, v164, v165
	v_cvt_pk_bf16_f32 v137, v142, v143
	ds_swizzle_b32 v240, v134 offset:swizzle(SWAP,8)
	ds_swizzle_b32 v241, v135 offset:swizzle(SWAP,8)
	ds_swizzle_b32 v242, v136 offset:swizzle(SWAP,8)
	ds_swizzle_b32 v243, v137 offset:swizzle(SWAP,8)
	ds_swizzle_b32 v244, v236 offset:swizzle(SWAP,8)
	ds_swizzle_b32 v245, v237 offset:swizzle(SWAP,8)
	ds_swizzle_b32 v246, v238 offset:swizzle(SWAP,8)
	ds_swizzle_b32 v247, v239 offset:swizzle(SWAP,8)
	s_waitcnt lgkmcnt(0)
	v_cndmask_b32_e64 v240, v240, v236, s[98:99]
	v_cndmask_b32_e64 v241, v241, v237, s[98:99]
	v_cndmask_b32_e64 v242, v242, v238, s[98:99]
	v_cndmask_b32_e64 v243, v243, v239, s[98:99]
	v_cndmask_b32_e64 v244, v134, v244, s[98:99]
	v_cndmask_b32_e64 v245, v135, v245, s[98:99]
	v_cndmask_b32_e64 v246, v136, v246, s[98:99]
	v_cndmask_b32_e64 v247, v137, v247, s[98:99]
	global_store_dwordx4 v[230:231], v[240:243], off
	global_store_dwordx4 v[232:233], v[244:247], off
	v_mov_b32_e32 v138, v139
	v_pk_mul_f32 v[140:141], v[74:75], v[138:139] op_sel_hi:[1,0]
	v_or_b32_e32 v134, 48, v160
	v_ashrrev_i32_e32 v135, 31, v134
	v_lshlrev_b64 v[134:135], 13, v[134:135]
	v_lshl_add_u64 v[134:135], s[92:93], 0, v[134:135]
	v_lshl_add_u64 v[130:131], v[134:135], 0, v[130:131]
	v_pk_mul_f32 v[134:135], v[78:79], v[138:139] op_sel_hi:[1,0]
	v_pk_mul_f32 v[136:137], v[76:77], v[138:139] op_sel_hi:[1,0]
	v_pk_mul_f32 v[142:143], v[72:73], v[138:139] op_sel_hi:[1,0]
	v_max_f32_e32 v135, 0, v135
	v_max_f32_e32 v134, 0, v134
	v_max_f32_e32 v137, 0, v137
	v_max_f32_e32 v136, 0, v136
	v_max_f32_e32 v143, 0, v143
	v_max_f32_e32 v142, 0, v142
	v_pk_mul_f32 v[164:165], v[134:135], v[134:135]
	v_max_f32_e32 v135, 0, v141
	v_max_f32_e32 v134, 0, v140
	v_pk_mul_f32 v[136:137], v[136:137], v[136:137]
	v_pk_mul_f32 v[142:143], v[142:143], v[142:143]
	v_pk_mul_f32 v[140:141], v[134:135], v[134:135]
	v_cvt_pk_bf16_f32 v134, v136, v137
	v_cvt_pk_bf16_f32 v135, v164, v165
	v_cvt_pk_bf16_f32 v136, v142, v143
	v_cvt_pk_bf16_f32 v137, v140, v141
	v_mov_b32_e32 v236, v134
	v_mov_b32_e32 v237, v135
	v_mov_b32_e32 v238, v136
	v_mov_b32_e32 v239, v137
	v_lshl_add_u64 v[230:231], v[130:131], 0, v[248:249]
	v_lshl_add_u64 v[232:233], v[130:131], 0, v[250:251]
	v_pk_mul_f32 v[140:141], v[66:67], v[138:139] op_sel_hi:[1,0]
	s_nop 0
	v_pk_mul_f32 v[134:135], v[70:71], v[138:139] op_sel_hi:[1,0]
	v_pk_mul_f32 v[136:137], v[68:69], v[138:139] op_sel_hi:[1,0]
	v_max_f32_e32 v135, 0, v135
	v_max_f32_e32 v134, 0, v134
	v_pk_mul_f32 v[142:143], v[134:135], v[134:135]
	v_max_f32_e32 v135, 0, v141
	v_max_f32_e32 v134, 0, v140
	v_pk_mul_f32 v[140:141], v[134:135], v[134:135]
	v_cvt_pk_bf16_f32 v135, v142, v143
	ds_read2_b32 v[142:143], v132 offset0:128 offset1:144
	v_pk_mul_f32 v[138:139], v[64:65], v[138:139] op_sel_hi:[1,0]
	v_max_f32_e32 v137, 0, v137
	v_max_f32_e32 v136, 0, v136
	v_max_f32_e32 v139, 0, v139
	v_max_f32_e32 v138, 0, v138
	v_pk_mul_f32 v[136:137], v[136:137], v[136:137]
	v_pk_mul_f32 v[138:139], v[138:139], v[138:139]
	v_cvt_pk_bf16_f32 v134, v136, v137
	v_cvt_pk_bf16_f32 v136, v138, v139
	v_cvt_pk_bf16_f32 v137, v140, v141
	ds_swizzle_b32 v240, v134 offset:swizzle(SWAP,8)
	ds_swizzle_b32 v241, v135 offset:swizzle(SWAP,8)
	ds_swizzle_b32 v242, v136 offset:swizzle(SWAP,8)
	ds_swizzle_b32 v243, v137 offset:swizzle(SWAP,8)
	ds_swizzle_b32 v244, v236 offset:swizzle(SWAP,8)
	ds_swizzle_b32 v245, v237 offset:swizzle(SWAP,8)
	ds_swizzle_b32 v246, v238 offset:swizzle(SWAP,8)
	ds_swizzle_b32 v247, v239 offset:swizzle(SWAP,8)
	s_waitcnt lgkmcnt(0)
; __device__ __forceinline__ unsigned cvt_pk_bf16(float lo, float hi) { const f32x2_t v = {lo, hi}; const bf16x2_t b = __builtin_convertvector(v, bf16x2_t); return __builtin_bit_cast(unsigned, b); }
;     __device__ __forceinline__ void operator()(const f32x4 (&acc)[2][2][4][2], const Unit& u, int wr, int wc, int fr, int fq, const PG8_LAS float* tab) const {
;     ...
;             for (int m = 0; m < 4; ++m) { const int row = row0 + ai * HALF + m * 16; bf16_t* rowp = O + (size_t)row * ldc + col0;
;                 const float rstd = tab[rl0 + ai * HALF + m * 16];
; #pragma unroll
;                 for (int bj = 0; bj < 2; ++bj) { f32x4 v0 = acc[ai][bj][m][0] * rstd, v1 = acc[ai][bj][m][1] * rstd;
;                     if (ACT == 1) {
; #pragma unroll
;                         for (int e = 0; e < 4; ++e) { float a = v0[e] > 0.f ? v0[e] : 0.f; v0[e] = a * a; float b = v1[e] > 0.f ? v1[e] : 0.f; v1[e] = b * b; } }
;                     u32x4 w; w.x = cvt_pk_bf16(v0[0], v0[1]); w.y = cvt_pk_bf16(v0[2], v0[3]); w.z = cvt_pk_bf16(v1[0], v1[1]); w.w = cvt_pk_bf16(v1[2], v1[3]);
;                     *(u32x4*)(rowp + bj * HALF) = w; } }
	v_cndmask_b32_e64 v240, v240, v236, s[98:99]
	v_cndmask_b32_e64 v241, v241, v237, s[98:99]
	v_cndmask_b32_e64 v242, v242, v238, s[98:99]
	v_cndmask_b32_e64 v243, v243, v239, s[98:99]
	v_cndmask_b32_e64 v244, v134, v244, s[98:99]
	v_cndmask_b32_e64 v245, v135, v245, s[98:99]
	v_cndmask_b32_e64 v246, v136, v246, s[98:99]
	v_cndmask_b32_e64 v247, v137, v247, s[98:99]
	global_store_dwordx4 v[230:231], v[240:243], off
	global_store_dwordx4 v[232:233], v[244:247], off
	s_waitcnt lgkmcnt(0)
	v_pk_mul_f32 v[138:139], v[58:59], v[142:143] op_sel_hi:[1,0]
	v_pk_mul_f32 v[140:141], v[56:57], v[142:143] op_sel_hi:[1,0]
	v_pk_mul_f32 v[134:135], v[62:63], v[142:143] op_sel_hi:[1,0]
	v_pk_mul_f32 v[136:137], v[60:61], v[142:143] op_sel_hi:[1,0]
	v_max_f32_e32 v135, 0, v135
	v_max_f32_e32 v134, 0, v134
	v_max_f32_e32 v137, 0, v137
	v_max_f32_e32 v136, 0, v136
	v_pk_mul_f32 v[164:165], v[134:135], v[134:135]
	v_max_f32_e32 v135, 0, v139
	v_max_f32_e32 v134, 0, v138
	v_pk_mul_f32 v[136:137], v[136:137], v[136:137]
	v_max_f32_e32 v141, 0, v141
	v_max_f32_e32 v140, 0, v140
	v_pk_mul_f32 v[138:139], v[134:135], v[134:135]
	v_pk_mul_f32 v[140:141], v[140:141], v[140:141]
	v_cvt_pk_bf16_f32 v134, v136, v137
	v_cvt_pk_bf16_f32 v137, v138, v139
	v_add_co_u32_e32 v138, vcc, s53, v128
	v_cvt_pk_bf16_f32 v135, v164, v165
	v_cvt_pk_bf16_f32 v136, v140, v141
	v_addc_co_u32_e32 v139, vcc, 0, v129, vcc
	v_mov_b32_e32 v236, v134
	v_mov_b32_e32 v237, v135
	v_mov_b32_e32 v238, v136
	v_mov_b32_e32 v239, v137
	v_lshl_add_u64 v[230:231], v[138:139], 0, v[248:249]
	v_lshl_add_u64 v[232:233], v[138:139], 0, v[250:251]
	v_pk_mul_f32 v[138:139], v[50:51], v[142:143] op_sel_hi:[1,0]
	v_pk_mul_f32 v[140:141], v[48:49], v[142:143] op_sel_hi:[1,0]
	v_pk_mul_f32 v[134:135], v[54:55], v[142:143] op_sel_hi:[1,0]
	v_pk_mul_f32 v[136:137], v[52:53], v[142:143] op_sel_hi:[1,0]
	v_max_f32_e32 v135, 0, v135
	v_max_f32_e32 v134, 0, v134
	v_max_f32_e32 v137, 0, v137
	v_max_f32_e32 v136, 0, v136
	v_max_f32_e32 v141, 0, v141
	v_max_f32_e32 v140, 0, v140
	v_pk_mul_f32 v[164:165], v[134:135], v[134:135]
	v_max_f32_e32 v135, 0, v139
	v_max_f32_e32 v134, 0, v138
	v_pk_mul_f32 v[136:137], v[136:137], v[136:137]
	v_pk_mul_f32 v[140:141], v[140:141], v[140:141]
	v_pk_mul_f32 v[138:139], v[134:135], v[134:135]
	v_lshl_add_u64 v[130:131], v[128:129], 0, s[14:15]
	v_cvt_pk_bf16_f32 v134, v136, v137
	v_cvt_pk_bf16_f32 v135, v164, v165
	v_cvt_pk_bf16_f32 v136, v140, v141
	v_cvt_pk_bf16_f32 v137, v138, v139
	ds_swizzle_b32 v240, v134 offset:swizzle(SWAP,8)
	ds_swizzle_b32 v241, v135 offset:swizzle(SWAP,8)
	ds_swizzle_b32 v242, v136 offset:swizzle(SWAP,8)
	ds_swizzle_b32 v243, v137 offset:swizzle(SWAP,8)
	ds_swizzle_b32 v244, v236 offset:swizzle(SWAP,8)
	ds_swizzle_b32 v245, v237 offset:swizzle(SWAP,8)
	ds_swizzle_b32 v246, v238 offset:swizzle(SWAP,8)
	ds_swizzle_b32 v247, v239 offset:swizzle(SWAP,8)
	s_waitcnt lgkmcnt(0)
	v_cndmask_b32_e64 v240, v240, v236, s[98:99]
	v_cndmask_b32_e64 v241, v241, v237, s[98:99]
	v_cndmask_b32_e64 v242, v242, v238, s[98:99]
	v_cndmask_b32_e64 v243, v243, v239, s[98:99]
	v_cndmask_b32_e64 v244, v134, v244, s[98:99]
	v_cndmask_b32_e64 v245, v135, v245, s[98:99]
	v_cndmask_b32_e64 v246, v136, v246, s[98:99]
	v_cndmask_b32_e64 v247, v137, v247, s[98:99]
	global_store_dwordx4 v[230:231], v[240:243], off
	global_store_dwordx4 v[232:233], v[244:247], off
	v_mov_b32_e32 v130, v143
	v_pk_mul_f32 v[140:141], v[42:43], v[130:131] op_sel_hi:[1,0]
	v_pk_mul_f32 v[134:135], v[46:47], v[130:131] op_sel_hi:[1,0]
	v_pk_mul_f32 v[136:137], v[44:45], v[130:131] op_sel_hi:[1,0]
	v_max_f32_e32 v135, 0, v135
	v_max_f32_e32 v134, 0, v134
	v_pk_mul_f32 v[142:143], v[40:41], v[130:131] op_sel_hi:[1,0]
	v_max_f32_e32 v137, 0, v137
	v_max_f32_e32 v136, 0, v136
	v_pk_mul_f32 v[164:165], v[134:135], v[134:135]
	v_max_f32_e32 v135, 0, v141
	v_max_f32_e32 v134, 0, v140
	v_pk_mul_f32 v[136:137], v[136:137], v[136:137]
	v_max_f32_e32 v143, 0, v143
	v_max_f32_e32 v142, 0, v142
	v_pk_mul_f32 v[140:141], v[134:135], v[134:135]
	v_pk_mul_f32 v[142:143], v[142:143], v[142:143]
	v_cvt_pk_bf16_f32 v134, v136, v137
	v_cvt_pk_bf16_f32 v137, v140, v141
	v_add_co_u32_e32 v140, vcc, s54, v128
	v_cvt_pk_bf16_f32 v135, v164, v165
	v_cvt_pk_bf16_f32 v136, v142, v143
	v_addc_co_u32_e32 v141, vcc, 0, v129, vcc
	v_mov_b32_e32 v236, v134
	v_mov_b32_e32 v237, v135
	v_mov_b32_e32 v238, v136
	v_mov_b32_e32 v239, v137
	v_lshl_add_u64 v[230:231], v[140:141], 0, v[248:249]
	v_lshl_add_u64 v[232:233], v[140:141], 0, v[250:251]
	v_pk_mul_f32 v[140:141], v[34:35], v[130:131] op_sel_hi:[1,0]
	v_lshl_add_u64 v[138:139], v[128:129], 0, s[16:17]
	v_pk_mul_f32 v[134:135], v[38:39], v[130:131] op_sel_hi:[1,0]
	v_pk_mul_f32 v[136:137], v[36:37], v[130:131] op_sel_hi:[1,0]
	v_pk_mul_f32 v[130:131], v[32:33], v[130:131] op_sel_hi:[1,0]
	v_max_f32_e32 v137, 0, v137
	v_max_f32_e32 v131, 0, v131
	v_max_f32_e32 v130, 0, v130
	v_pk_mul_f32 v[142:143], v[130:131], v[130:131]
	v_max_f32_e32 v131, 0, v135
	v_max_f32_e32 v130, 0, v134
	v_pk_mul_f32 v[134:135], v[130:131], v[130:131]
	v_max_f32_e32 v131, 0, v141
	v_max_f32_e32 v130, 0, v140
	v_pk_mul_f32 v[140:141], v[130:131], v[130:131]
	v_cvt_pk_bf16_f32 v131, v134, v135
	ds_read2_b32 v[134:135], v132 offset0:160 offset1:176
	v_max_f32_e32 v136, 0, v136
	v_pk_mul_f32 v[136:137], v[136:137], v[136:137]
	v_cvt_pk_bf16_f32 v132, v142, v143
	v_cvt_pk_bf16_f32 v130, v136, v137
	v_cvt_pk_bf16_f32 v133, v140, v141
	ds_swizzle_b32 v240, v130 offset:swizzle(SWAP,8)
	ds_swizzle_b32 v241, v131 offset:swizzle(SWAP,8)
	ds_swizzle_b32 v242, v132 offset:swizzle(SWAP,8)
	ds_swizzle_b32 v243, v133 offset:swizzle(SWAP,8)
	ds_swizzle_b32 v244, v236 offset:swizzle(SWAP,8)
	ds_swizzle_b32 v245, v237 offset:swizzle(SWAP,8)
	ds_swizzle_b32 v246, v238 offset:swizzle(SWAP,8)
	ds_swizzle_b32 v247, v239 offset:swizzle(SWAP,8)
	s_waitcnt lgkmcnt(0)
; __device__ __forceinline__ unsigned cvt_pk_bf16(float lo, float hi) { const f32x2_t v = {lo, hi}; const bf16x2_t b = __builtin_convertvector(v, bf16x2_t); return __builtin_bit_cast(unsigned, b); }
;     __device__ __forceinline__ void operator()(const f32x4 (&acc)[2][2][4][2], const Unit& u, int wr, int wc, int fr, int fq, const PG8_LAS float* tab) const {
;     ...
;             for (int m = 0; m < 4; ++m) { const int row = row0 + ai * HALF + m * 16; bf16_t* rowp = O + (size_t)row * ldc + col0;
;                 const float rstd = tab[rl0 + ai * HALF + m * 16];
; #pragma unroll
;                 for (int bj = 0; bj < 2; ++bj) { f32x4 v0 = acc[ai][bj][m][0] * rstd, v1 = acc[ai][bj][m][1] * rstd;
;                     if (ACT == 1) {
; #pragma unroll
;                         for (int e = 0; e < 4; ++e) { float a = v0[e] > 0.f ? v0[e] : 0.f; v0[e] = a * a; float b = v1[e] > 0.f ? v1[e] : 0.f; v1[e] = b * b; } }
;                     u32x4 w; w.x = cvt_pk_bf16(v0[0], v0[1]); w.y = cvt_pk_bf16(v0[2], v0[3]); w.z = cvt_pk_bf16(v1[0], v1[1]); w.w = cvt_pk_bf16(v1[2], v1[3]);
;                     *(u32x4*)(rowp + bj * HALF) = w; } }
	v_cndmask_b32_e64 v240, v240, v236, s[98:99]
	v_cndmask_b32_e64 v241, v241, v237, s[98:99]
	v_cndmask_b32_e64 v242, v242, v238, s[98:99]
	v_cndmask_b32_e64 v243, v243, v239, s[98:99]
	v_cndmask_b32_e64 v244, v130, v244, s[98:99]
	v_cndmask_b32_e64 v245, v131, v245, s[98:99]
	v_cndmask_b32_e64 v246, v132, v246, s[98:99]
	v_cndmask_b32_e64 v247, v133, v247, s[98:99]
	global_store_dwordx4 v[230:231], v[240:243], off
	global_store_dwordx4 v[232:233], v[244:247], off
	s_waitcnt lgkmcnt(0)
	v_pk_mul_f32 v[138:139], v[26:27], v[134:135] op_sel_hi:[1,0]
	v_pk_mul_f32 v[140:141], v[24:25], v[134:135] op_sel_hi:[1,0]
	v_pk_mul_f32 v[130:131], v[30:31], v[134:135] op_sel_hi:[1,0]
	v_pk_mul_f32 v[132:133], v[28:29], v[134:135] op_sel_hi:[1,0]
	v_max_f32_e32 v131, 0, v131
	v_max_f32_e32 v130, 0, v130
	v_max_f32_e32 v133, 0, v133
	v_max_f32_e32 v132, 0, v132
	v_pk_mul_f32 v[142:143], v[130:131], v[130:131]
	v_max_f32_e32 v131, 0, v139
	v_max_f32_e32 v130, 0, v138
	v_pk_mul_f32 v[132:133], v[132:133], v[132:133]
	v_max_f32_e32 v141, 0, v141
	v_max_f32_e32 v140, 0, v140
	v_pk_mul_f32 v[138:139], v[130:131], v[130:131]
	v_pk_mul_f32 v[140:141], v[140:141], v[140:141]
	v_cvt_pk_bf16_f32 v130, v132, v133
	v_cvt_pk_bf16_f32 v133, v138, v139
	v_add_co_u32_e32 v138, vcc, s55, v128
	v_cvt_pk_bf16_f32 v131, v142, v143
	v_cvt_pk_bf16_f32 v132, v140, v141
	v_addc_co_u32_e32 v139, vcc, 0, v129, vcc
	v_mov_b32_e32 v236, v130
	v_mov_b32_e32 v237, v131
	v_mov_b32_e32 v238, v132
	v_mov_b32_e32 v239, v133
	v_lshl_add_u64 v[230:231], v[138:139], 0, v[248:249]
	v_lshl_add_u64 v[232:233], v[138:139], 0, v[250:251]
	v_pk_mul_f32 v[138:139], v[18:19], v[134:135] op_sel_hi:[1,0]
	v_pk_mul_f32 v[140:141], v[16:17], v[134:135] op_sel_hi:[1,0]
	v_pk_mul_f32 v[130:131], v[22:23], v[134:135] op_sel_hi:[1,0]
	v_pk_mul_f32 v[132:133], v[20:21], v[134:135] op_sel_hi:[1,0]
	v_max_f32_e32 v131, 0, v131
	v_max_f32_e32 v130, 0, v130
	v_max_f32_e32 v133, 0, v133
	v_max_f32_e32 v132, 0, v132
	v_max_f32_e32 v141, 0, v141
	v_max_f32_e32 v140, 0, v140
	v_pk_mul_f32 v[142:143], v[130:131], v[130:131]
	v_max_f32_e32 v131, 0, v139
	v_max_f32_e32 v130, 0, v138
	v_pk_mul_f32 v[132:133], v[132:133], v[132:133]
	v_pk_mul_f32 v[140:141], v[140:141], v[140:141]
	v_pk_mul_f32 v[138:139], v[130:131], v[130:131]
	v_lshl_add_u64 v[136:137], v[128:129], 0, s[18:19]
	v_cvt_pk_bf16_f32 v130, v132, v133
	v_cvt_pk_bf16_f32 v131, v142, v143
	v_cvt_pk_bf16_f32 v132, v140, v141
	v_cvt_pk_bf16_f32 v133, v138, v139
	v_mov_b32_e32 v134, v135
	ds_swizzle_b32 v240, v130 offset:swizzle(SWAP,8)
	ds_swizzle_b32 v241, v131 offset:swizzle(SWAP,8)
	ds_swizzle_b32 v242, v132 offset:swizzle(SWAP,8)
	ds_swizzle_b32 v243, v133 offset:swizzle(SWAP,8)
	ds_swizzle_b32 v244, v236 offset:swizzle(SWAP,8)
	ds_swizzle_b32 v245, v237 offset:swizzle(SWAP,8)
	ds_swizzle_b32 v246, v238 offset:swizzle(SWAP,8)
	ds_swizzle_b32 v247, v239 offset:swizzle(SWAP,8)
	s_waitcnt lgkmcnt(0)
	v_cndmask_b32_e64 v240, v240, v236, s[98:99]
	v_cndmask_b32_e64 v241, v241, v237, s[98:99]
	v_cndmask_b32_e64 v242, v242, v238, s[98:99]
	v_cndmask_b32_e64 v243, v243, v239, s[98:99]
	v_cndmask_b32_e64 v244, v130, v244, s[98:99]
	v_cndmask_b32_e64 v245, v131, v245, s[98:99]
	v_cndmask_b32_e64 v246, v132, v246, s[98:99]
	v_cndmask_b32_e64 v247, v133, v247, s[98:99]
	global_store_dwordx4 v[230:231], v[240:243], off
	global_store_dwordx4 v[232:233], v[244:247], off
	v_pk_mul_f32 v[138:139], v[10:11], v[134:135] op_sel_hi:[1,0]
	v_pk_mul_f32 v[140:141], v[8:9], v[134:135] op_sel_hi:[1,0]
	v_pk_mul_f32 v[130:131], v[14:15], v[134:135] op_sel_hi:[1,0]
	v_pk_mul_f32 v[132:133], v[12:13], v[134:135] op_sel_hi:[1,0]
	v_max_f32_e32 v131, 0, v131
	v_max_f32_e32 v130, 0, v130
	v_max_f32_e32 v133, 0, v133
	v_max_f32_e32 v132, 0, v132
	v_max_f32_e32 v141, 0, v141
	v_max_f32_e32 v140, 0, v140
	v_pk_mul_f32 v[142:143], v[130:131], v[130:131]
	v_max_f32_e32 v131, 0, v139
	v_max_f32_e32 v130, 0, v138
	v_lshl_add_u64 v[136:137], v[128:129], 0, s[20:21]
	v_pk_mul_f32 v[132:133], v[132:133], v[132:133]
	v_pk_mul_f32 v[140:141], v[140:141], v[140:141]
	v_pk_mul_f32 v[138:139], v[130:131], v[130:131]
	v_add_co_u32_e32 v128, vcc, s56, v128
	v_cvt_pk_bf16_f32 v130, v132, v133
	v_cvt_pk_bf16_f32 v131, v142, v143
	v_cvt_pk_bf16_f32 v132, v140, v141
	v_cvt_pk_bf16_f32 v133, v138, v139
	v_addc_co_u32_e32 v129, vcc, 0, v129, vcc
	v_mov_b32_e32 v236, v130
	v_mov_b32_e32 v237, v131
	v_mov_b32_e32 v238, v132
	v_mov_b32_e32 v239, v133
	v_lshl_add_u64 v[230:231], v[128:129], 0, v[248:249]
	v_lshl_add_u64 v[232:233], v[128:129], 0, v[250:251]
	v_pk_mul_f32 v[128:129], v[6:7], v[134:135] op_sel_hi:[1,0]
	s_nop 0
	v_pk_mul_f32 v[130:131], v[4:5], v[134:135] op_sel_hi:[1,0]
	v_pk_mul_f32 v[132:133], v[2:3], v[134:135] op_sel_hi:[1,0]
	v_pk_mul_f32 v[134:135], v[0:1], v[134:135] op_sel_hi:[1,0]
	v_max_f32_e32 v129, 0, v129
	v_max_f32_e32 v128, 0, v128
	v_max_f32_e32 v131, 0, v131
	v_max_f32_e32 v130, 0, v130
	v_max_f32_e32 v135, 0, v135
	v_max_f32_e32 v134, 0, v134
	v_pk_mul_f32 v[138:139], v[128:129], v[128:129]
	v_max_f32_e32 v129, 0, v133
	v_max_f32_e32 v128, 0, v132
	v_pk_mul_f32 v[130:131], v[130:131], v[130:131]
	v_pk_mul_f32 v[134:135], v[134:135], v[134:135]
	v_pk_mul_f32 v[132:133], v[128:129], v[128:129]
	v_cvt_pk_bf16_f32 v128, v130, v131
	v_cvt_pk_bf16_f32 v129, v138, v139
	v_cvt_pk_bf16_f32 v130, v134, v135
	v_cvt_pk_bf16_f32 v131, v132, v133
	ds_swizzle_b32 v240, v128 offset:swizzle(SWAP,8)
	ds_swizzle_b32 v241, v129 offset:swizzle(SWAP,8)
	ds_swizzle_b32 v242, v130 offset:swizzle(SWAP,8)
	ds_swizzle_b32 v243, v131 offset:swizzle(SWAP,8)
	ds_swizzle_b32 v244, v236 offset:swizzle(SWAP,8)
	ds_swizzle_b32 v245, v237 offset:swizzle(SWAP,8)
	ds_swizzle_b32 v246, v238 offset:swizzle(SWAP,8)
	ds_swizzle_b32 v247, v239 offset:swizzle(SWAP,8)
	s_waitcnt lgkmcnt(0)
	v_cndmask_b32_e64 v240, v240, v236, s[98:99]
	v_cndmask_b32_e64 v241, v241, v237, s[98:99]
	v_cndmask_b32_e64 v242, v242, v238, s[98:99]
	v_cndmask_b32_e64 v243, v243, v239, s[98:99]
	v_cndmask_b32_e64 v244, v128, v244, s[98:99]
	v_cndmask_b32_e64 v245, v129, v245, s[98:99]
	v_cndmask_b32_e64 v246, v130, v246, s[98:99]
	v_cndmask_b32_e64 v247, v131, v247, s[98:99]
	global_store_dwordx4 v[230:231], v[240:243], off
	global_store_dwordx4 v[232:233], v[244:247], off
	s_cbranch_execnz .LBB0_760
; __device__ __forceinline__ unsigned cvt_pk_bf16(float lo, float hi) { const f32x2_t v = {lo, hi}; const bf16x2_t b = __builtin_convertvector(v, bf16x2_t); return __builtin_bit_cast(unsigned, b); }
;     __device__ __forceinline__ void operator()(const f32x4 (&acc)[2][2][4][2], const Unit& u, int wr, int wc, int fr, int fq, const PG8_LAS float* tab) const {
;     ...
;             for (int m = 0; m < 4; ++m) { const int row = row0 + ai * HALF + m * 16; bf16_t* rowp = O + (size_t)row * ldc + col0;
;                 const float rstd = tab[rl0 + ai * HALF + m * 16];
; #pragma unroll
;                 for (int bj = 0; bj < 2; ++bj) { f32x4 v0 = acc[ai][bj][m][0] * rstd, v1 = acc[ai][bj][m][1] * rstd;
;                     if (ACT == 1) {
; #pragma unroll
;                         for (int e = 0; e < 4; ++e) { float a = v0[e] > 0.f ? v0[e] : 0.f; v0[e] = a * a; float b = v1[e] > 0.f ? v1[e] : 0.f; v1[e] = b * b; } }
;                     u32x4 w; w.x = cvt_pk_bf16(v0[0], v0[1]); w.y = cvt_pk_bf16(v0[2], v0[3]); w.z = cvt_pk_bf16(v1[0], v1[1]); w.w = cvt_pk_bf16(v1[2], v1[3]);
;                     *(u32x4*)(rowp + bj * HALF) = w; } }
.LBB0_762:
	s_nop 0
	v_lshl_or_b32 v128, s24, 8, v167
	v_ashrrev_i32_e32 v129, 31, v128
	v_readlane_b32 s6, v254, 41
	v_lshlrev_b64 v[128:129], 6, v[128:129]
	v_readlane_b32 s7, v254, 42
	v_ashrrev_i32_e32 v161, 31, v160
	v_ashrrev_i32_e32 v163, 31, v162
	v_lshl_add_u64 v[140:141], s[6:7], 0, v[128:129]
	s_lshl_b32 s6, s31, 10
	s_and_b32 s6, s6, 0x400
	v_add_u32_e32 v177, s6, v170
	global_load_dwordx4 v[128:131], v[140:141], off offset:48
	global_load_dwordx4 v[132:135], v[140:141], off offset:32
	global_load_dwordx4 v[136:139], v[140:141], off offset:16
	s_nop 0
	global_load_dwordx4 v[140:143], v[140:141], off
	ds_read2_b32 v[178:179], v177 offset1:16
	v_lshlrev_b64 v[164:165], 13, v[160:161]
	v_lshl_add_u64 v[180:181], s[92:93], 0, v[164:165]
	v_lshlrev_b64 v[164:165], 1, v[162:163]
	v_lshl_add_u64 v[162:163], v[180:181], 0, v[164:165]
	s_waitcnt lgkmcnt(0)
	v_pk_mul_f32 v[120:121], v[120:121], v[178:179] op_sel_hi:[1,0]
	v_pk_mul_f32 v[126:127], v[126:127], v[178:179] op_sel_hi:[1,0]
	v_max_f32_e32 v121, 0, v121
	v_max_f32_e32 v120, 0, v120
	v_pk_mul_f32 v[124:125], v[124:125], v[178:179] op_sel_hi:[1,0]
	v_pk_mul_f32 v[122:123], v[122:123], v[178:179] op_sel_hi:[1,0]
	v_pk_mul_f32 v[180:181], v[120:121], v[120:121]
	v_max_f32_e32 v121, 0, v127
	v_max_f32_e32 v120, 0, v126
	v_max_f32_e32 v125, 0, v125
	v_max_f32_e32 v124, 0, v124
	v_pk_mul_f32 v[126:127], v[120:121], v[120:121]
	v_max_f32_e32 v121, 0, v123
	v_max_f32_e32 v120, 0, v122
	v_pk_mul_f32 v[124:125], v[124:125], v[124:125]
	v_pk_mul_f32 v[182:183], v[120:121], v[120:121]
	v_pk_mul_f32 v[112:113], v[112:113], v[178:179] op_sel_hi:[1,0]
	v_cvt_pk_bf16_f32 v120, v124, v125
	v_cvt_pk_bf16_f32 v121, v126, v127
	v_cvt_pk_bf16_f32 v122, v180, v181
	v_cvt_pk_bf16_f32 v123, v182, v183
	v_pk_mul_f32 v[118:119], v[118:119], v[178:179] op_sel_hi:[1,0]
	v_max_f32_e32 v113, 0, v113
	v_max_f32_e32 v112, 0, v112
	v_mov_b32_e32 v236, v120
	v_mov_b32_e32 v237, v121
	v_mov_b32_e32 v238, v122
	v_mov_b32_e32 v239, v123
	v_lshl_add_u64 v[230:231], v[162:163], 0, v[248:249]
	v_lshl_add_u64 v[232:233], v[162:163], 0, v[250:251]
	v_pk_mul_f32 v[116:117], v[116:117], v[178:179] op_sel_hi:[1,0]
	v_pk_mul_f32 v[114:115], v[114:115], v[178:179] op_sel_hi:[1,0]
	v_pk_mul_f32 v[120:121], v[112:113], v[112:113]
	v_max_f32_e32 v113, 0, v119
	v_max_f32_e32 v112, 0, v118
	v_max_f32_e32 v117, 0, v117
	v_max_f32_e32 v116, 0, v116
	v_pk_mul_f32 v[118:119], v[112:113], v[112:113]
	v_max_f32_e32 v113, 0, v115
	v_max_f32_e32 v112, 0, v114
	v_pk_mul_f32 v[116:117], v[116:117], v[116:117]
	v_pk_mul_f32 v[122:123], v[112:113], v[112:113]
	v_cvt_pk_bf16_f32 v112, v116, v117
	v_cvt_pk_bf16_f32 v113, v118, v119
	v_cvt_pk_bf16_f32 v114, v120, v121
	v_cvt_pk_bf16_f32 v115, v122, v123
	ds_swizzle_b32 v240, v112 offset:swizzle(SWAP,8)
	ds_swizzle_b32 v241, v113 offset:swizzle(SWAP,8)
	ds_swizzle_b32 v242, v114 offset:swizzle(SWAP,8)
	ds_swizzle_b32 v243, v115 offset:swizzle(SWAP,8)
	ds_swizzle_b32 v244, v236 offset:swizzle(SWAP,8)
	ds_swizzle_b32 v245, v237 offset:swizzle(SWAP,8)
	ds_swizzle_b32 v246, v238 offset:swizzle(SWAP,8)
	ds_swizzle_b32 v247, v239 offset:swizzle(SWAP,8)
	s_waitcnt lgkmcnt(0)
	v_cndmask_b32_e64 v240, v240, v236, s[98:99]
	v_cndmask_b32_e64 v241, v241, v237, s[98:99]
	v_cndmask_b32_e64 v242, v242, v238, s[98:99]
	v_cndmask_b32_e64 v243, v243, v239, s[98:99]
	v_cndmask_b32_e64 v244, v112, v244, s[98:99]
	v_cndmask_b32_e64 v245, v113, v245, s[98:99]
	v_cndmask_b32_e64 v246, v114, v246, s[98:99]
	v_cndmask_b32_e64 v247, v115, v247, s[98:99]
	global_store_dwordx4 v[230:231], v[240:243], off
	global_store_dwordx4 v[232:233], v[244:247], off
	s_nop 1
	v_mov_b32_e32 v114, v179
	v_pk_mul_f32 v[104:105], v[104:105], v[114:115] op_sel_hi:[1,0]
	v_or_b32_e32 v112, 16, v160
	v_pk_mul_f32 v[110:111], v[110:111], v[114:115] op_sel_hi:[1,0]
	v_max_f32_e32 v105, 0, v105
	v_max_f32_e32 v104, 0, v104
	v_ashrrev_i32_e32 v113, 31, v112
	v_pk_mul_f32 v[108:109], v[108:109], v[114:115] op_sel_hi:[1,0]
	v_pk_mul_f32 v[106:107], v[106:107], v[114:115] op_sel_hi:[1,0]
	v_pk_mul_f32 v[116:117], v[104:105], v[104:105]
	v_max_f32_e32 v105, 0, v111
	v_max_f32_e32 v104, 0, v110
	v_lshlrev_b64 v[112:113], 13, v[112:113]
	v_max_f32_e32 v109, 0, v109
	v_max_f32_e32 v108, 0, v108
	v_pk_mul_f32 v[110:111], v[104:105], v[104:105]
	v_max_f32_e32 v105, 0, v107
	v_max_f32_e32 v104, 0, v106
	v_lshl_add_u64 v[112:113], s[92:93], 0, v[112:113]
	v_pk_mul_f32 v[108:109], v[108:109], v[108:109]
	v_pk_mul_f32 v[118:119], v[104:105], v[104:105]
	v_pk_mul_f32 v[96:97], v[96:97], v[114:115] op_sel_hi:[1,0]
	v_lshl_add_u64 v[112:113], v[112:113], 0, v[164:165]
	v_cvt_pk_bf16_f32 v104, v108, v109
	v_cvt_pk_bf16_f32 v105, v110, v111
	v_cvt_pk_bf16_f32 v106, v116, v117
	v_cvt_pk_bf16_f32 v107, v118, v119
	v_pk_mul_f32 v[102:103], v[102:103], v[114:115] op_sel_hi:[1,0]
	v_max_f32_e32 v97, 0, v97
	v_max_f32_e32 v96, 0, v96
	v_mov_b32_e32 v236, v104
	v_mov_b32_e32 v237, v105
	v_mov_b32_e32 v238, v106
	v_mov_b32_e32 v239, v107
	v_lshl_add_u64 v[230:231], v[112:113], 0, v[248:249]
	v_lshl_add_u64 v[232:233], v[112:113], 0, v[250:251]
	v_pk_mul_f32 v[100:101], v[100:101], v[114:115] op_sel_hi:[1,0]
	v_pk_mul_f32 v[98:99], v[98:99], v[114:115] op_sel_hi:[1,0]
	v_pk_mul_f32 v[104:105], v[96:97], v[96:97]
	v_max_f32_e32 v97, 0, v103
	v_max_f32_e32 v96, 0, v102
	v_max_f32_e32 v101, 0, v101
	v_max_f32_e32 v100, 0, v100
	v_pk_mul_f32 v[102:103], v[96:97], v[96:97]
	v_max_f32_e32 v97, 0, v99
	v_max_f32_e32 v96, 0, v98
	v_pk_mul_f32 v[100:101], v[100:101], v[100:101]
	v_pk_mul_f32 v[106:107], v[96:97], v[96:97]
	v_cvt_pk_bf16_f32 v96, v100, v101
	v_cvt_pk_bf16_f32 v97, v102, v103
	v_cvt_pk_bf16_f32 v98, v104, v105
	v_cvt_pk_bf16_f32 v99, v106, v107
	ds_swizzle_b32 v240, v96 offset:swizzle(SWAP,8)
	ds_swizzle_b32 v241, v97 offset:swizzle(SWAP,8)
	ds_swizzle_b32 v242, v98 offset:swizzle(SWAP,8)
	ds_swizzle_b32 v243, v99 offset:swizzle(SWAP,8)
	ds_swizzle_b32 v244, v236 offset:swizzle(SWAP,8)
	ds_swizzle_b32 v245, v237 offset:swizzle(SWAP,8)
	ds_swizzle_b32 v246, v238 offset:swizzle(SWAP,8)
	ds_swizzle_b32 v247, v239 offset:swizzle(SWAP,8)
	s_waitcnt lgkmcnt(0)
; __device__ __forceinline__ unsigned cvt_pk_bf16(float lo, float hi) { const f32x2_t v = {lo, hi}; const bf16x2_t b = __builtin_convertvector(v, bf16x2_t); return __builtin_bit_cast(unsigned, b); }
;     __device__ __forceinline__ void operator()(const f32x4 (&acc)[2][2][4][2], const Unit& u, int wr, int wc, int fr, int fq, const PG8_LAS float* tab) const {
;     ...
;             for (int m = 0; m < 4; ++m) { const int row = row0 + ai * HALF + m * 16; bf16_t* rowp = O + (size_t)row * ldc + col0;
;                 const float rstd = tab[rl0 + ai * HALF + m * 16];
; #pragma unroll
;                 for (int bj = 0; bj < 2; ++bj) { f32x4 v0 = acc[ai][bj][m][0] * rstd, v1 = acc[ai][bj][m][1] * rstd;
;                     if (ACT == 1) {
; #pragma unroll
;                         for (int e = 0; e < 4; ++e) { float a = v0[e] > 0.f ? v0[e] : 0.f; v0[e] = a * a; float b = v1[e] > 0.f ? v1[e] : 0.f; v1[e] = b * b; } }
;                     u32x4 w; w.x = cvt_pk_bf16(v0[0], v0[1]); w.y = cvt_pk_bf16(v0[2], v0[3]); w.z = cvt_pk_bf16(v1[0], v1[1]); w.w = cvt_pk_bf16(v1[2], v1[3]);
;                     *(u32x4*)(rowp + bj * HALF) = w; } }
	v_cndmask_b32_e64 v240, v240, v236, s[98:99]
	v_cndmask_b32_e64 v241, v241, v237, s[98:99]
	v_cndmask_b32_e64 v242, v242, v238, s[98:99]
	v_cndmask_b32_e64 v243, v243, v239, s[98:99]
	v_cndmask_b32_e64 v244, v96, v244, s[98:99]
	v_cndmask_b32_e64 v245, v97, v245, s[98:99]
	v_cndmask_b32_e64 v246, v98, v246, s[98:99]
	v_cndmask_b32_e64 v247, v99, v247, s[98:99]
	global_store_dwordx4 v[230:231], v[240:243], off
	global_store_dwordx4 v[232:233], v[244:247], off
	ds_read2_b32 v[98:99], v177 offset0:32 offset1:48
	s_waitcnt lgkmcnt(0)
	v_pk_mul_f32 v[88:89], v[88:89], v[98:99] op_sel_hi:[1,0]
	v_or_b32_e32 v96, 32, v160
	v_pk_mul_f32 v[94:95], v[94:95], v[98:99] op_sel_hi:[1,0]
	v_max_f32_e32 v89, 0, v89
	v_max_f32_e32 v88, 0, v88
	v_ashrrev_i32_e32 v97, 31, v96
	v_pk_mul_f32 v[92:93], v[92:93], v[98:99] op_sel_hi:[1,0]
	v_pk_mul_f32 v[90:91], v[90:91], v[98:99] op_sel_hi:[1,0]
	v_pk_mul_f32 v[100:101], v[88:89], v[88:89]
	v_max_f32_e32 v89, 0, v95
	v_max_f32_e32 v88, 0, v94
	v_lshlrev_b64 v[96:97], 13, v[96:97]
	v_max_f32_e32 v93, 0, v93
	v_max_f32_e32 v92, 0, v92
	v_pk_mul_f32 v[94:95], v[88:89], v[88:89]
	v_max_f32_e32 v89, 0, v91
	v_max_f32_e32 v88, 0, v90
	v_lshl_add_u64 v[96:97], s[92:93], 0, v[96:97]
	v_pk_mul_f32 v[92:93], v[92:93], v[92:93]
	v_pk_mul_f32 v[102:103], v[88:89], v[88:89]
	v_pk_mul_f32 v[80:81], v[80:81], v[98:99] op_sel_hi:[1,0]
	v_lshl_add_u64 v[96:97], v[96:97], 0, v[164:165]
	v_cvt_pk_bf16_f32 v88, v92, v93
	v_cvt_pk_bf16_f32 v89, v94, v95
	v_cvt_pk_bf16_f32 v90, v100, v101
	v_cvt_pk_bf16_f32 v91, v102, v103
	v_pk_mul_f32 v[86:87], v[86:87], v[98:99] op_sel_hi:[1,0]
	v_max_f32_e32 v81, 0, v81
	v_max_f32_e32 v80, 0, v80
	v_mov_b32_e32 v236, v88
	v_mov_b32_e32 v237, v89
	v_mov_b32_e32 v238, v90
	v_mov_b32_e32 v239, v91
	v_lshl_add_u64 v[230:231], v[96:97], 0, v[248:249]
	v_lshl_add_u64 v[232:233], v[96:97], 0, v[250:251]
	v_pk_mul_f32 v[84:85], v[84:85], v[98:99] op_sel_hi:[1,0]
	v_pk_mul_f32 v[82:83], v[82:83], v[98:99] op_sel_hi:[1,0]
	v_pk_mul_f32 v[88:89], v[80:81], v[80:81]
	v_max_f32_e32 v81, 0, v87
	v_max_f32_e32 v80, 0, v86
	v_max_f32_e32 v85, 0, v85
	v_max_f32_e32 v84, 0, v84
	v_pk_mul_f32 v[86:87], v[80:81], v[80:81]
	v_max_f32_e32 v81, 0, v83
	v_max_f32_e32 v80, 0, v82
	v_pk_mul_f32 v[84:85], v[84:85], v[84:85]
	v_pk_mul_f32 v[90:91], v[80:81], v[80:81]
	v_cvt_pk_bf16_f32 v80, v84, v85
	v_cvt_pk_bf16_f32 v81, v86, v87
	v_cvt_pk_bf16_f32 v82, v88, v89
	v_cvt_pk_bf16_f32 v83, v90, v91
	ds_swizzle_b32 v240, v80 offset:swizzle(SWAP,8)
	ds_swizzle_b32 v241, v81 offset:swizzle(SWAP,8)
	ds_swizzle_b32 v242, v82 offset:swizzle(SWAP,8)
	ds_swizzle_b32 v243, v83 offset:swizzle(SWAP,8)
	ds_swizzle_b32 v244, v236 offset:swizzle(SWAP,8)
	ds_swizzle_b32 v245, v237 offset:swizzle(SWAP,8)
	ds_swizzle_b32 v246, v238 offset:swizzle(SWAP,8)
	ds_swizzle_b32 v247, v239 offset:swizzle(SWAP,8)
	s_waitcnt lgkmcnt(0)
	v_cndmask_b32_e64 v240, v240, v236, s[98:99]
	v_cndmask_b32_e64 v241, v241, v237, s[98:99]
	v_cndmask_b32_e64 v242, v242, v238, s[98:99]
	v_cndmask_b32_e64 v243, v243, v239, s[98:99]
	v_cndmask_b32_e64 v244, v80, v244, s[98:99]
	v_cndmask_b32_e64 v245, v81, v245, s[98:99]
	v_cndmask_b32_e64 v246, v82, v246, s[98:99]
	v_cndmask_b32_e64 v247, v83, v247, s[98:99]
	global_store_dwordx4 v[230:231], v[240:243], off
	global_store_dwordx4 v[232:233], v[244:247], off
	s_nop 1
	v_mov_b32_e32 v82, v99
	v_pk_mul_f32 v[72:73], v[72:73], v[82:83] op_sel_hi:[1,0]
	v_or_b32_e32 v80, 48, v160
	v_pk_mul_f32 v[78:79], v[78:79], v[82:83] op_sel_hi:[1,0]
	v_max_f32_e32 v73, 0, v73
	v_max_f32_e32 v72, 0, v72
	v_ashrrev_i32_e32 v81, 31, v80
	v_pk_mul_f32 v[76:77], v[76:77], v[82:83] op_sel_hi:[1,0]
	v_pk_mul_f32 v[74:75], v[74:75], v[82:83] op_sel_hi:[1,0]
	v_pk_mul_f32 v[84:85], v[72:73], v[72:73]
	v_max_f32_e32 v73, 0, v79
	v_max_f32_e32 v72, 0, v78
	v_lshlrev_b64 v[80:81], 13, v[80:81]
	v_max_f32_e32 v77, 0, v77
	v_max_f32_e32 v76, 0, v76
	v_pk_mul_f32 v[78:79], v[72:73], v[72:73]
	v_max_f32_e32 v73, 0, v75
	v_max_f32_e32 v72, 0, v74
	v_lshl_add_u64 v[80:81], s[92:93], 0, v[80:81]
	v_pk_mul_f32 v[76:77], v[76:77], v[76:77]
	v_pk_mul_f32 v[86:87], v[72:73], v[72:73]
	v_pk_mul_f32 v[64:65], v[64:65], v[82:83] op_sel_hi:[1,0]
	v_lshl_add_u64 v[80:81], v[80:81], 0, v[164:165]
	v_cvt_pk_bf16_f32 v72, v76, v77
	v_cvt_pk_bf16_f32 v73, v78, v79
	v_cvt_pk_bf16_f32 v74, v84, v85
	v_cvt_pk_bf16_f32 v75, v86, v87
	v_pk_mul_f32 v[70:71], v[70:71], v[82:83] op_sel_hi:[1,0]
	v_pk_mul_f32 v[68:69], v[68:69], v[82:83] op_sel_hi:[1,0]
	v_max_f32_e32 v65, 0, v65
	v_max_f32_e32 v64, 0, v64
	v_mov_b32_e32 v236, v72
	v_mov_b32_e32 v237, v73
	v_mov_b32_e32 v238, v74
	v_mov_b32_e32 v239, v75
	v_lshl_add_u64 v[230:231], v[80:81], 0, v[248:249]
	v_lshl_add_u64 v[232:233], v[80:81], 0, v[250:251]
	v_pk_mul_f32 v[66:67], v[66:67], v[82:83] op_sel_hi:[1,0]
	v_max_f32_e32 v69, 0, v69
	v_max_f32_e32 v68, 0, v68
	v_pk_mul_f32 v[72:73], v[64:65], v[64:65]
	v_max_f32_e32 v65, 0, v71
	v_max_f32_e32 v64, 0, v70
	v_pk_mul_f32 v[68:69], v[68:69], v[68:69]
	v_pk_mul_f32 v[70:71], v[64:65], v[64:65]
	v_max_f32_e32 v65, 0, v67
	v_max_f32_e32 v64, 0, v66
	v_pk_mul_f32 v[74:75], v[64:65], v[64:65]
	v_cvt_pk_bf16_f32 v64, v68, v69
	ds_read2_b32 v[68:69], v177 offset0:128 offset1:144
	v_cvt_pk_bf16_f32 v65, v70, v71
	v_cvt_pk_bf16_f32 v66, v72, v73
	v_cvt_pk_bf16_f32 v67, v74, v75
	ds_swizzle_b32 v240, v64 offset:swizzle(SWAP,8)
	ds_swizzle_b32 v241, v65 offset:swizzle(SWAP,8)
	ds_swizzle_b32 v242, v66 offset:swizzle(SWAP,8)
	ds_swizzle_b32 v243, v67 offset:swizzle(SWAP,8)
	ds_swizzle_b32 v244, v236 offset:swizzle(SWAP,8)
	ds_swizzle_b32 v245, v237 offset:swizzle(SWAP,8)
	ds_swizzle_b32 v246, v238 offset:swizzle(SWAP,8)
	ds_swizzle_b32 v247, v239 offset:swizzle(SWAP,8)
	s_waitcnt lgkmcnt(0)
; __device__ __forceinline__ unsigned cvt_pk_bf16(float lo, float hi) { const f32x2_t v = {lo, hi}; const bf16x2_t b = __builtin_convertvector(v, bf16x2_t); return __builtin_bit_cast(unsigned, b); }
;     __device__ __forceinline__ void operator()(const f32x4 (&acc)[2][2][4][2], const Unit& u, int wr, int wc, int fr, int fq, const PG8_LAS float* tab) const {
;     ...
;             for (int m = 0; m < 4; ++m) { const int row = row0 + ai * HALF + m * 16; bf16_t* rowp = O + (size_t)row * ldc + col0;
;                 const float rstd = tab[rl0 + ai * HALF + m * 16];
; #pragma unroll
;                 for (int bj = 0; bj < 2; ++bj) { f32x4 v0 = acc[ai][bj][m][0] * rstd, v1 = acc[ai][bj][m][1] * rstd;
;                     if (ACT == 1) {
; #pragma unroll
;                         for (int e = 0; e < 4; ++e) { float a = v0[e] > 0.f ? v0[e] : 0.f; v0[e] = a * a; float b = v1[e] > 0.f ? v1[e] : 0.f; v1[e] = b * b; } }
;                     u32x4 w; w.x = cvt_pk_bf16(v0[0], v0[1]); w.y = cvt_pk_bf16(v0[2], v0[3]); w.z = cvt_pk_bf16(v1[0], v1[1]); w.w = cvt_pk_bf16(v1[2], v1[3]);
;                     *(u32x4*)(rowp + bj * HALF) = w; } }
	v_cndmask_b32_e64 v240, v240, v236, s[98:99]
	v_cndmask_b32_e64 v241, v241, v237, s[98:99]
	v_cndmask_b32_e64 v242, v242, v238, s[98:99]
	v_cndmask_b32_e64 v243, v243, v239, s[98:99]
	v_cndmask_b32_e64 v244, v64, v244, s[98:99]
	v_cndmask_b32_e64 v245, v65, v245, s[98:99]
	v_cndmask_b32_e64 v246, v66, v246, s[98:99]
	v_cndmask_b32_e64 v247, v67, v247, s[98:99]
	global_store_dwordx4 v[230:231], v[240:243], off
	global_store_dwordx4 v[232:233], v[244:247], off
	s_waitcnt lgkmcnt(0)
	v_pk_mul_f32 v[56:57], v[56:57], v[68:69] op_sel_hi:[1,0]
	v_pk_mul_f32 v[62:63], v[62:63], v[68:69] op_sel_hi:[1,0]
	v_pk_mul_f32 v[60:61], v[60:61], v[68:69] op_sel_hi:[1,0]
	v_max_f32_e32 v57, 0, v57
	v_max_f32_e32 v56, 0, v56
	v_pk_mul_f32 v[58:59], v[58:59], v[68:69] op_sel_hi:[1,0]
	v_max_f32_e32 v61, 0, v61
	v_max_f32_e32 v60, 0, v60
	v_pk_mul_f32 v[66:67], v[56:57], v[56:57]
	v_max_f32_e32 v57, 0, v63
	v_max_f32_e32 v56, 0, v62
	v_pk_mul_f32 v[60:61], v[60:61], v[60:61]
	v_pk_mul_f32 v[62:63], v[56:57], v[56:57]
	v_max_f32_e32 v57, 0, v59
	v_max_f32_e32 v56, 0, v58
	v_pk_mul_f32 v[70:71], v[56:57], v[56:57]
	v_cvt_pk_bf16_f32 v56, v60, v61
	v_add_co_u32_e32 v60, vcc, s53, v162
	v_pk_mul_f32 v[48:49], v[48:49], v[68:69] op_sel_hi:[1,0]
	v_cvt_pk_bf16_f32 v57, v62, v63
	v_cvt_pk_bf16_f32 v58, v66, v67
	v_cvt_pk_bf16_f32 v59, v70, v71
	v_addc_co_u32_e32 v61, vcc, 0, v163, vcc
	v_pk_mul_f32 v[54:55], v[54:55], v[68:69] op_sel_hi:[1,0]
	v_max_f32_e32 v49, 0, v49
	v_max_f32_e32 v48, 0, v48
	v_mov_b32_e32 v236, v56
	v_mov_b32_e32 v237, v57
	v_mov_b32_e32 v238, v58
	v_mov_b32_e32 v239, v59
	v_lshl_add_u64 v[230:231], v[60:61], 0, v[248:249]
	v_lshl_add_u64 v[232:233], v[60:61], 0, v[250:251]
	v_pk_mul_f32 v[52:53], v[52:53], v[68:69] op_sel_hi:[1,0]
	v_pk_mul_f32 v[50:51], v[50:51], v[68:69] op_sel_hi:[1,0]
	v_pk_mul_f32 v[56:57], v[48:49], v[48:49]
	v_max_f32_e32 v49, 0, v55
	v_max_f32_e32 v48, 0, v54
	v_max_f32_e32 v53, 0, v53
	v_max_f32_e32 v52, 0, v52
	v_pk_mul_f32 v[54:55], v[48:49], v[48:49]
	v_max_f32_e32 v49, 0, v51
	v_max_f32_e32 v48, 0, v50
	v_pk_mul_f32 v[52:53], v[52:53], v[52:53]
	v_pk_mul_f32 v[58:59], v[48:49], v[48:49]
	v_lshl_add_u64 v[64:65], v[162:163], 0, s[14:15]
	v_cvt_pk_bf16_f32 v48, v52, v53
	v_cvt_pk_bf16_f32 v49, v54, v55
	v_cvt_pk_bf16_f32 v50, v56, v57
	v_cvt_pk_bf16_f32 v51, v58, v59
	ds_swizzle_b32 v240, v48 offset:swizzle(SWAP,8)
	ds_swizzle_b32 v241, v49 offset:swizzle(SWAP,8)
	ds_swizzle_b32 v242, v50 offset:swizzle(SWAP,8)
	ds_swizzle_b32 v243, v51 offset:swizzle(SWAP,8)
	ds_swizzle_b32 v244, v236 offset:swizzle(SWAP,8)
	ds_swizzle_b32 v245, v237 offset:swizzle(SWAP,8)
	ds_swizzle_b32 v246, v238 offset:swizzle(SWAP,8)
	ds_swizzle_b32 v247, v239 offset:swizzle(SWAP,8)
	s_waitcnt lgkmcnt(0)
	v_cndmask_b32_e64 v240, v240, v236, s[98:99]
	v_cndmask_b32_e64 v241, v241, v237, s[98:99]
	v_cndmask_b32_e64 v242, v242, v238, s[98:99]
	v_cndmask_b32_e64 v243, v243, v239, s[98:99]
	v_cndmask_b32_e64 v244, v48, v244, s[98:99]
	v_cndmask_b32_e64 v245, v49, v245, s[98:99]
	v_cndmask_b32_e64 v246, v50, v246, s[98:99]
	v_cndmask_b32_e64 v247, v51, v247, s[98:99]
	global_store_dwordx4 v[230:231], v[240:243], off
	global_store_dwordx4 v[232:233], v[244:247], off
	s_nop 1
	v_mov_b32_e32 v50, v69
	v_pk_mul_f32 v[40:41], v[40:41], v[50:51] op_sel_hi:[1,0]
	v_pk_mul_f32 v[46:47], v[46:47], v[50:51] op_sel_hi:[1,0]
	v_pk_mul_f32 v[44:45], v[44:45], v[50:51] op_sel_hi:[1,0]
	v_max_f32_e32 v41, 0, v41
	v_max_f32_e32 v40, 0, v40
	v_pk_mul_f32 v[42:43], v[42:43], v[50:51] op_sel_hi:[1,0]
	v_max_f32_e32 v45, 0, v45
	v_max_f32_e32 v44, 0, v44
	v_pk_mul_f32 v[52:53], v[40:41], v[40:41]
	v_max_f32_e32 v41, 0, v47
	v_max_f32_e32 v40, 0, v46
	v_pk_mul_f32 v[44:45], v[44:45], v[44:45]
	v_pk_mul_f32 v[46:47], v[40:41], v[40:41]
	v_max_f32_e32 v41, 0, v43
	v_max_f32_e32 v40, 0, v42
	v_pk_mul_f32 v[54:55], v[40:41], v[40:41]
	v_cvt_pk_bf16_f32 v40, v44, v45
	v_add_co_u32_e32 v44, vcc, s54, v162
	v_pk_mul_f32 v[32:33], v[32:33], v[50:51] op_sel_hi:[1,0]
	v_cvt_pk_bf16_f32 v41, v46, v47
	v_cvt_pk_bf16_f32 v42, v52, v53
	v_cvt_pk_bf16_f32 v43, v54, v55
	v_addc_co_u32_e32 v45, vcc, 0, v163, vcc
	v_pk_mul_f32 v[38:39], v[38:39], v[50:51] op_sel_hi:[1,0]
	v_pk_mul_f32 v[36:37], v[36:37], v[50:51] op_sel_hi:[1,0]
	v_max_f32_e32 v33, 0, v33
	v_max_f32_e32 v32, 0, v32
	v_mov_b32_e32 v236, v40
	v_mov_b32_e32 v237, v41
	v_mov_b32_e32 v238, v42
	v_mov_b32_e32 v239, v43
	v_lshl_add_u64 v[230:231], v[44:45], 0, v[248:249]
	v_lshl_add_u64 v[232:233], v[44:45], 0, v[250:251]
	v_pk_mul_f32 v[34:35], v[34:35], v[50:51] op_sel_hi:[1,0]
	v_max_f32_e32 v37, 0, v37
	v_max_f32_e32 v36, 0, v36
	v_pk_mul_f32 v[40:41], v[32:33], v[32:33]
	v_max_f32_e32 v33, 0, v39
	v_max_f32_e32 v32, 0, v38
	v_pk_mul_f32 v[36:37], v[36:37], v[36:37]
	v_pk_mul_f32 v[38:39], v[32:33], v[32:33]
	v_max_f32_e32 v33, 0, v35
	v_max_f32_e32 v32, 0, v34
	v_pk_mul_f32 v[42:43], v[32:33], v[32:33]
	v_cvt_pk_bf16_f32 v32, v36, v37
	ds_read2_b32 v[36:37], v177 offset0:160 offset1:176
	v_lshl_add_u64 v[48:49], v[162:163], 0, s[16:17]
	v_cvt_pk_bf16_f32 v33, v38, v39
	v_cvt_pk_bf16_f32 v34, v40, v41
	v_cvt_pk_bf16_f32 v35, v42, v43
	s_waitcnt lgkmcnt(0)
	v_pk_mul_f32 v[24:25], v[24:25], v[36:37] op_sel_hi:[1,0]
	v_pk_mul_f32 v[30:31], v[30:31], v[36:37] op_sel_hi:[1,0]
	v_pk_mul_f32 v[28:29], v[28:29], v[36:37] op_sel_hi:[1,0]
	v_max_f32_e32 v25, 0, v25
	v_max_f32_e32 v24, 0, v24
	ds_swizzle_b32 v240, v32 offset:swizzle(SWAP,8)
	ds_swizzle_b32 v241, v33 offset:swizzle(SWAP,8)
	ds_swizzle_b32 v242, v34 offset:swizzle(SWAP,8)
	ds_swizzle_b32 v243, v35 offset:swizzle(SWAP,8)
	ds_swizzle_b32 v244, v236 offset:swizzle(SWAP,8)
	ds_swizzle_b32 v245, v237 offset:swizzle(SWAP,8)
	ds_swizzle_b32 v246, v238 offset:swizzle(SWAP,8)
	ds_swizzle_b32 v247, v239 offset:swizzle(SWAP,8)
	s_waitcnt lgkmcnt(0)
; #define PG8_LAS __attribute__((address_space(3)))
; __device__ __forceinline__ unsigned cvt_pk_bf16(float lo, float hi) { const f32x2_t v = {lo, hi}; const bf16x2_t b = __builtin_convertvector(v, bf16x2_t); return __builtin_bit_cast(unsigned, b); }
;     __device__ __forceinline__ void pre_store(const Pre& p, PG8_LAS float* tab, int tid) const {
;         const float tot = ((p.s0[0] + p.s0[1]) + (p.s0[2] + p.s0[3])) + ((p.s1[0] + p.s1[1]) + (p.s1[2] + p.s1[3])) + ((p.s2[0] + p.s2[1]) + (p.s2[2] + p.s2[3])) + ((p.s3[0] + p.s3[1]) + (p.s3[2] + p.s3[3]));
;         if (tid < 256) tab[tid] = rsqrtf(tot * (1.0f / 1024.0f) + 1e-6f);
;     __device__ __forceinline__ void operator()(const f32x4 (&acc)[2][2][4][2], const Unit& u, int wr, int wc, int fr, int fq, const PG8_LAS float* tab) const {
;     ...
;             for (int m = 0; m < 4; ++m) { const int row = row0 + ai * HALF + m * 16; bf16_t* rowp = O + (size_t)row * ldc + col0;
;                 const float rstd = tab[rl0 + ai * HALF + m * 16];
; #pragma unroll
;                 for (int bj = 0; bj < 2; ++bj) { f32x4 v0 = acc[ai][bj][m][0] * rstd, v1 = acc[ai][bj][m][1] * rstd;
;                     if (ACT == 1) {
; #pragma unroll
;                         for (int e = 0; e < 4; ++e) { float a = v0[e] > 0.f ? v0[e] : 0.f; v0[e] = a * a; float b = v1[e] > 0.f ? v1[e] : 0.f; v1[e] = b * b; } }
;                     u32x4 w; w.x = cvt_pk_bf16(v0[0], v0[1]); w.y = cvt_pk_bf16(v0[2], v0[3]); w.z = cvt_pk_bf16(v1[0], v1[1]); w.w = cvt_pk_bf16(v1[2], v1[3]);
;                     *(u32x4*)(rowp + bj * HALF) = w; } }
	v_cndmask_b32_e64 v240, v240, v236, s[98:99]
	v_cndmask_b32_e64 v241, v241, v237, s[98:99]
	v_cndmask_b32_e64 v242, v242, v238, s[98:99]
	v_cndmask_b32_e64 v243, v243, v239, s[98:99]
	v_cndmask_b32_e64 v244, v32, v244, s[98:99]
	v_cndmask_b32_e64 v245, v33, v245, s[98:99]
	v_cndmask_b32_e64 v246, v34, v246, s[98:99]
	v_cndmask_b32_e64 v247, v35, v247, s[98:99]
	global_store_dwordx4 v[230:231], v[240:243], off
	global_store_dwordx4 v[232:233], v[244:247], off
	v_pk_mul_f32 v[26:27], v[26:27], v[36:37] op_sel_hi:[1,0]
	v_max_f32_e32 v29, 0, v29
	v_max_f32_e32 v28, 0, v28
	v_pk_mul_f32 v[34:35], v[24:25], v[24:25]
	v_max_f32_e32 v25, 0, v31
	v_max_f32_e32 v24, 0, v30
	v_pk_mul_f32 v[28:29], v[28:29], v[28:29]
	v_pk_mul_f32 v[30:31], v[24:25], v[24:25]
	v_max_f32_e32 v25, 0, v27
	v_max_f32_e32 v24, 0, v26
	v_pk_mul_f32 v[38:39], v[24:25], v[24:25]
	v_cvt_pk_bf16_f32 v24, v28, v29
	v_add_co_u32_e32 v28, vcc, s55, v162
	v_pk_mul_f32 v[16:17], v[16:17], v[36:37] op_sel_hi:[1,0]
	v_cvt_pk_bf16_f32 v25, v30, v31
	v_cvt_pk_bf16_f32 v26, v34, v35
	v_cvt_pk_bf16_f32 v27, v38, v39
	v_addc_co_u32_e32 v29, vcc, 0, v163, vcc
	v_pk_mul_f32 v[22:23], v[22:23], v[36:37] op_sel_hi:[1,0]
	v_max_f32_e32 v17, 0, v17
	v_max_f32_e32 v16, 0, v16
	v_mov_b32_e32 v236, v24
	v_mov_b32_e32 v237, v25
	v_mov_b32_e32 v238, v26
	v_mov_b32_e32 v239, v27
	v_lshl_add_u64 v[230:231], v[28:29], 0, v[248:249]
	v_lshl_add_u64 v[232:233], v[28:29], 0, v[250:251]
	v_pk_mul_f32 v[20:21], v[20:21], v[36:37] op_sel_hi:[1,0]
	v_pk_mul_f32 v[18:19], v[18:19], v[36:37] op_sel_hi:[1,0]
	v_pk_mul_f32 v[24:25], v[16:17], v[16:17]
	v_max_f32_e32 v17, 0, v23
	v_max_f32_e32 v16, 0, v22
	v_max_f32_e32 v21, 0, v21
	v_max_f32_e32 v20, 0, v20
	v_pk_mul_f32 v[22:23], v[16:17], v[16:17]
	v_max_f32_e32 v17, 0, v19
	v_max_f32_e32 v16, 0, v18
	v_pk_mul_f32 v[20:21], v[20:21], v[20:21]
	v_pk_mul_f32 v[26:27], v[16:17], v[16:17]
	v_lshl_add_u64 v[32:33], v[162:163], 0, s[18:19]
	v_cvt_pk_bf16_f32 v16, v20, v21
	v_cvt_pk_bf16_f32 v17, v22, v23
	v_cvt_pk_bf16_f32 v18, v24, v25
	v_cvt_pk_bf16_f32 v19, v26, v27
	ds_swizzle_b32 v240, v16 offset:swizzle(SWAP,8)
	ds_swizzle_b32 v241, v17 offset:swizzle(SWAP,8)
	ds_swizzle_b32 v242, v18 offset:swizzle(SWAP,8)
	ds_swizzle_b32 v243, v19 offset:swizzle(SWAP,8)
	ds_swizzle_b32 v244, v236 offset:swizzle(SWAP,8)
	ds_swizzle_b32 v245, v237 offset:swizzle(SWAP,8)
	ds_swizzle_b32 v246, v238 offset:swizzle(SWAP,8)
	ds_swizzle_b32 v247, v239 offset:swizzle(SWAP,8)
	s_waitcnt lgkmcnt(0)
	v_cndmask_b32_e64 v240, v240, v236, s[98:99]
	v_cndmask_b32_e64 v241, v241, v237, s[98:99]
	v_cndmask_b32_e64 v242, v242, v238, s[98:99]
	v_cndmask_b32_e64 v243, v243, v239, s[98:99]
	v_cndmask_b32_e64 v244, v16, v244, s[98:99]
	v_cndmask_b32_e64 v245, v17, v245, s[98:99]
	v_cndmask_b32_e64 v246, v18, v246, s[98:99]
	v_cndmask_b32_e64 v247, v19, v247, s[98:99]
	global_store_dwordx4 v[230:231], v[240:243], off
	global_store_dwordx4 v[232:233], v[244:247], off
	s_nop 1
	v_mov_b32_e32 v18, v37
	v_pk_mul_f32 v[8:9], v[8:9], v[18:19] op_sel_hi:[1,0]
	v_pk_mul_f32 v[14:15], v[14:15], v[18:19] op_sel_hi:[1,0]
	v_pk_mul_f32 v[12:13], v[12:13], v[18:19] op_sel_hi:[1,0]
	v_max_f32_e32 v9, 0, v9
	v_max_f32_e32 v8, 0, v8
	v_pk_mul_f32 v[10:11], v[10:11], v[18:19] op_sel_hi:[1,0]
	v_max_f32_e32 v13, 0, v13
	v_max_f32_e32 v12, 0, v12
	v_pk_mul_f32 v[20:21], v[8:9], v[8:9]
	v_max_f32_e32 v9, 0, v15
	v_max_f32_e32 v8, 0, v14
	v_pk_mul_f32 v[12:13], v[12:13], v[12:13]
	v_pk_mul_f32 v[14:15], v[8:9], v[8:9]
	v_max_f32_e32 v9, 0, v11
	v_max_f32_e32 v8, 0, v10
	v_pk_mul_f32 v[22:23], v[8:9], v[8:9]
	v_cvt_pk_bf16_f32 v8, v12, v13
	v_add_co_u32_e32 v12, vcc, s56, v162
	v_pk_mul_f32 v[0:1], v[0:1], v[18:19] op_sel_hi:[1,0]
	v_cvt_pk_bf16_f32 v9, v14, v15
	v_cvt_pk_bf16_f32 v10, v20, v21
	v_cvt_pk_bf16_f32 v11, v22, v23
	v_addc_co_u32_e32 v13, vcc, 0, v163, vcc
	v_pk_mul_f32 v[6:7], v[6:7], v[18:19] op_sel_hi:[1,0]
	v_max_f32_e32 v1, 0, v1
	v_max_f32_e32 v0, 0, v0
	v_mov_b32_e32 v236, v8
	v_mov_b32_e32 v237, v9
	v_mov_b32_e32 v238, v10
	v_mov_b32_e32 v239, v11
	v_lshl_add_u64 v[230:231], v[12:13], 0, v[248:249]
	v_lshl_add_u64 v[232:233], v[12:13], 0, v[250:251]
	v_pk_mul_f32 v[4:5], v[4:5], v[18:19] op_sel_hi:[1,0]
	v_pk_mul_f32 v[2:3], v[2:3], v[18:19] op_sel_hi:[1,0]
	v_pk_mul_f32 v[8:9], v[0:1], v[0:1]
	v_max_f32_e32 v1, 0, v7
	v_max_f32_e32 v0, 0, v6
	v_max_f32_e32 v5, 0, v5
	v_max_f32_e32 v4, 0, v4
	v_pk_mul_f32 v[6:7], v[0:1], v[0:1]
	v_max_f32_e32 v1, 0, v3
	v_max_f32_e32 v0, 0, v2
	v_pk_mul_f32 v[4:5], v[4:5], v[4:5]
	v_pk_mul_f32 v[10:11], v[0:1], v[0:1]
	v_lshl_add_u64 v[16:17], v[162:163], 0, s[20:21]
	v_cvt_pk_bf16_f32 v0, v4, v5
	v_cvt_pk_bf16_f32 v1, v6, v7
	v_cvt_pk_bf16_f32 v2, v8, v9
	v_cvt_pk_bf16_f32 v3, v10, v11
	ds_swizzle_b32 v240, v0 offset:swizzle(SWAP,8)
	ds_swizzle_b32 v241, v1 offset:swizzle(SWAP,8)
	ds_swizzle_b32 v242, v2 offset:swizzle(SWAP,8)
	ds_swizzle_b32 v243, v3 offset:swizzle(SWAP,8)
	ds_swizzle_b32 v244, v236 offset:swizzle(SWAP,8)
	ds_swizzle_b32 v245, v237 offset:swizzle(SWAP,8)
	ds_swizzle_b32 v246, v238 offset:swizzle(SWAP,8)
	ds_swizzle_b32 v247, v239 offset:swizzle(SWAP,8)
	s_waitcnt lgkmcnt(0)
	v_cndmask_b32_e64 v240, v240, v236, s[98:99]
	v_cndmask_b32_e64 v241, v241, v237, s[98:99]
	v_cndmask_b32_e64 v242, v242, v238, s[98:99]
	v_cndmask_b32_e64 v243, v243, v239, s[98:99]
	v_cndmask_b32_e64 v244, v0, v244, s[98:99]
	v_cndmask_b32_e64 v245, v1, v245, s[98:99]
	v_cndmask_b32_e64 v246, v2, v246, s[98:99]
	v_cndmask_b32_e64 v247, v3, v247, s[98:99]
	global_store_dwordx4 v[230:231], v[240:243], off
	global_store_dwordx4 v[232:233], v[244:247], off
	s_and_saveexec_b64 s[6:7], s[2:3]
	s_cbranch_execz .LBB0_764
	s_waitcnt vmcnt(0)
	v_mov_b32_e32 v0, v141
	v_mov_b32_e32 v1, v142
	v_mov_b32_e32 v141, v143
	v_mov_b32_e32 v2, v137
	v_mov_b32_e32 v3, v138
	v_mov_b32_e32 v137, v139
	v_pk_add_f32 v[0:1], v[0:1], v[140:141]
	v_pk_add_f32 v[2:3], v[2:3], v[136:137]
	v_pk_add_f32 v[0:1], v[0:1], v[0:1] op_sel:[0,1] op_sel_hi:[1,0]
	v_pk_add_f32 v[2:3], v[2:3], v[2:3] op_sel:[0,1] op_sel_hi:[1,0]
	v_add_f32_e32 v4, v132, v133
	v_add_f32_e32 v6, v134, v135
	v_mov_b32_e32 v1, v128
	v_mov_b32_e32 v3, v129
	v_mov_b32_e32 v5, v130
	v_mov_b32_e32 v7, v131
	v_pk_add_f32 v[0:1], v[0:1], v[2:3]
	v_pk_add_f32 v[2:3], v[4:5], v[6:7]
	s_mov_b32 s23, 0x800000
	v_pk_add_f32 v[0:1], v[0:1], v[2:3]
	s_nop 0
	v_add_f32_e32 v0, v0, v1
	v_fmamk_f32 v0, v0, 0x3a800000, v176
	v_mul_f32_e32 v1, 0x4b800000, v0
	v_cmp_gt_f32_e32 vcc, s23, v0
	s_lshl_b32 s23, s57, 10
	s_and_b32 s23, s23, 0x400
	v_cndmask_b32_e32 v0, v0, v1, vcc
	v_rsq_f32_e32 v0, v0
	s_nop 0
	v_mul_f32_e32 v1, 0x45800000, v0
	v_cndmask_b32_e32 v0, v0, v1, vcc
	v_add_u32_e32 v1, s23, v171
	ds_write_b32 v1, v0

;     __host__ __device__ bool next(int i, Unit& u) const {
;         const long L = (long)i * G + c; if (L >= nwg) return false;
;         int wgid = (int)L; { const int q = nwg / NXCD, r = nwg % NXCD, xcd = wgid % NXCD, off = wgid / NXCD; wgid = (xcd < r ? xcd * (q + 1) : r * (q + 1) + (xcd - r) * q) + off; }
;         const int nig = WGM * nN, gid = wgid / nig, fm = gid * WGM, gsz = (nM - fm) < WGM ? (nM - fm) : WGM;
;         u.pm = fm + ((wgid % nig) % gsz); u.pn = (wgid % nig) / gsz; return true;
; template <class Epi, class Sched, bool ALIGN_EPI = false, bool SP2 = false>
; __device__ __forceinline__ void gemm_phase(PG8_LAS unsigned char* lds, const Gemm g, const Sched& S, const Epi& E) {
;     ...
;     const int tid = tid_, wid = __builtin_amdgcn_readfirstlane(tid >> 6), lane = tid & 63, wr = wid >> 2, wc = wid & 3, fr = lane & 15, fq = lane >> 4;
;     const int K = g.K, nt = K / BK;
;     unsigned voffA[2], voffB[2];
; #pragma unroll
;     for (int i = 0; i < 2; ++i) { int R, C; stage_rc(tid * 16 + i * 8192, R, C); const int Rb = Epi::PERM ? ((R & ~31) + perm32(R & 31)) : R;
;         voffA[i] = (unsigned)(R * K + C) * 2u; voffB[i] = (unsigned)(Rb * K + C) * 2u; }
;     const size_t kstep = (size_t)(BK * 2);
;     const size_t hstep = (size_t)HALF * K * 2;
;     const size_t tstep = 2 * hstep;
;     const unsigned ldsw = (unsigned)wid * 1024u;
;     const int aoff = lds_byte(wr * 64 + fr, fq * 8), boff = lds_byte(wc * 32 + fr, fq * 8);
;     ...
;     Unit cur, nxt; int ui = 0;
;     if (!S.next(0, cur)) return;
;     f32x4 acc[2][2][4][2];
; #pragma unroll
;     for (int a = 0; a < 2; ++a)
; #pragma unroll
;         for (int b = 0; b < 2; ++b)
; #pragma unroll
;             for (int m = 0; m < 4; ++m)
; #pragma unroll
;                 for (int n = 0; n < 2; ++n) acc[a][b][m][n] = (f32x4){0.f, 0.f, 0.f, 0.f};
;     bf16x8 At[4][2], B0[2][2], B1[2][2];
;     const char* cA = (const char*)g.A + (size_t)cur.pm * tstep; const char* cB = (const char*)g.Bt + (size_t)cur.pn * tstep;
;     S.a_ready(cur);
;     PG8_LAS float* ptab = (PG8_LAS float*)(lds + STAGE_BYTES);
;     if constexpr (Epi::HAS_PRE) { const auto p0 = E.pre_load(cur.pm, tid); E.pre_store(p0, ptab, tid); }
;     if constexpr (SP2) {
;         PG8_STAGE(PG8_SB(0, 0), cB, voffB); PG8_STAGE(PG8_SB(0, 1), cB + hstep, voffB); PG8_STAGE(PG8_SA(0, 0), cA, voffA); PG8_STAGE(PG8_SA(0, 1), cA + hstep, voffA);
.LBB0_919:
	s_cmp_lt_i32 s96, 8
	s_cselect_b64 s[0:1], -1, 0
	s_and_b64 s[2:3], s[0:1], s[2:3]
	s_andn2_b64 vcc, exec, s[2:3]
	s_cbranch_vccnz .LBB0_944
	v_readfirstlane_b32 s100, v166
	s_nop 3
	s_lshr_b32 s98, s100, 8
	s_lshl_b32 s98, s98, 16
	s_add_i32 s99, s98, 0x20000
	s_lshr_b32 s100, s100, 6
	s_and_b32 s100, s100, 3
	s_lshl_b32 s100, s100, 5
	v_mov_b32_e32 v8, v166
	s_cmpk_gt_i32 s75, 0xcff
	v_readfirstlane_b32 s6, v8
	s_cbranch_scc1 .LBB0_944
	s_ashr_i32 s33, s75, 31
	s_lshr_b32 s2, s33, 29
	s_add_i32 s2, s75, s2
	s_ashr_i32 s3, s2, 3
	s_and_b32 s2, s2, -8
	s_sub_i32 s2, s75, s2
	s_cmp_lt_i32 s2, 0
	s_movk_i32 s4, 0x1a1
	s_cselect_b32 s4, s4, 0x1a0
	s_mul_i32 s2, s4, s2
	s_add_i32 s2, s2, s3
	s_mul_hi_i32 s3, s2, 0x4ec4ec4f
	s_lshr_b32 s4, s3, 31
	s_ashr_i32 s3, s3, 5
	s_add_i32 s3, s3, s4
	s_lshl_b32 s4, s3, 3
	s_mulk_i32 s3, 0x68
	s_sub_i32 s2, s2, s3
	s_bfe_i32 s3, s2, 0x80000
	s_bfe_u32 s3, s3, 0x3000c
	s_add_i32 s3, s2, s3
	s_bfe_i32 s5, s3, 0x80000
	s_and_b32 s3, s3, 0xf8
	s_sub_i32 s2, s2, s3
	s_sext_i32_i8 s2, s2
	s_sext_i32_i16 s5, s5
	s_add_i32 s24, s4, s2
	s_movk_i32 s2, 0x100
	s_lshr_b32 s7, s5, 3
	v_and_b32_e32 v164, 0xff, v8
	v_cmp_gt_i32_e64 s[2:3], s2, v8
	s_and_saveexec_b64 s[4:5], s[2:3]
	s_cbranch_execz .LBB0_923
	v_lshl_or_b32 v0, s24, 8, v164
	s_waitcnt lgkmcnt(0)
	v_ashrrev_i32_e32 v1, 31, v0
	v_readlane_b32 s8, v254, 41
	v_lshlrev_b64 v[0:1], 6, v[0:1]
	v_readlane_b32 s9, v254, 42
	v_mov_b32_e32 v9, 0x358637bd
	s_nop 0
	v_lshl_add_u64 v[14:15], s[8:9], 0, v[0:1]
	global_load_dwordx4 v[0:3], v[14:15], off
	global_load_dwordx4 v[4:7], v[14:15], off offset:16
	global_load_dwordx4 v[10:13], v[14:15], off offset:32
	s_nop 0
	global_load_dwordx4 v[14:17], v[14:15], off offset:48
	s_mov_b32 s8, 0x800000
	s_waitcnt vmcnt(0)
	v_mov_b32_e32 v18, v1
	v_mov_b32_e32 v19, v2
	v_mov_b32_e32 v1, v3
	v_mov_b32_e32 v2, v5
	v_mov_b32_e32 v3, v6
	v_mov_b32_e32 v5, v7
	v_pk_add_f32 v[0:1], v[18:19], v[0:1]
	v_pk_add_f32 v[2:3], v[2:3], v[4:5]
	v_pk_add_f32 v[0:1], v[0:1], v[0:1] op_sel_hi:[0,1]
	v_pk_add_f32 v[2:3], v[2:3], v[2:3] op_sel_hi:[0,1]
	v_add_f32_e32 v7, v10, v11
	v_add_f32_e32 v11, v12, v13
	v_mov_b32_e32 v6, v14
	v_mov_b32_e32 v10, v15
	v_mov_b32_e32 v2, v16
	v_mov_b32_e32 v0, v17
	v_pk_add_f32 v[4:5], v[6:7], v[10:11]
	v_pk_add_f32 v[0:1], v[2:3], v[0:1]
	s_nop 0
	v_pk_add_f32 v[0:1], v[4:5], v[0:1]
	s_nop 0
	v_add_f32_e32 v0, v0, v1
	v_fmac_f32_e32 v9, 0x3a800000, v0
	v_mul_f32_e32 v0, 0x4b800000, v9
	v_cmp_gt_f32_e32 vcc, s8, v9
	v_lshl_add_u32 v1, v8, 2, 0
	v_add_u32_e32 v1, 0x20000, v1
	v_cndmask_b32_e32 v0, v9, v0, vcc
	v_rsq_f32_e32 v0, v0
	s_nop 0
	v_mul_f32_e32 v2, 0x45800000, v0
	v_cndmask_b32_e32 v0, v0, v2, vcc
	ds_write_b32 v1, v0
.LBB0_923:
	s_or_b64 exec, exec, s[4:5]
	s_waitcnt lgkmcnt(0)
	v_ashrrev_i32_e32 v1, 31, v8
	v_lshrrev_b32_e32 v1, 26, v1
	v_add_u32_e32 v1, v8, v1
	v_mov_b32_e32 v0, s7
	v_ashrrev_i32_e32 v9, 6, v1
	v_bfe_i32 v1, v8, 27, 1
	v_readfirstlane_b32 s22, v0
	v_lshlrev_b32_e32 v0, 4, v8
	v_lshrrev_b32_e32 v1, 22, v1
	v_add_u32_e32 v1, v0, v1
	v_and_b32_e32 v1, 0xfffffc00, v1
	v_sub_u32_e32 v1, v0, v1
	v_lshrrev_b32_e32 v2, 4, v1
	s_add_u32 s34, s70, 0x780000
	v_bitop3_b32 v1, v2, v1, 32 bitop3:0x6c
	s_addc_u32 s35, s71, 0
	s_ashr_i32 s25, s24, 31
	v_ashrrev_i32_e32 v3, 31, v1
	s_lshl_b64 s[4:5], s[24:25], 19
	v_readlane_b32 s8, v254, 39
	v_lshrrev_b32_e32 v3, 26, v3
	v_readlane_b32 s9, v254, 40
	s_add_u32 s26, s8, s4
	s_mov_b32 s23, 0
	v_add_u32_e32 v3, v1, v3
	s_addc_u32 s27, s9, s5
	s_bfe_i64 s[4:5], s[22:23], 0x80000
	v_lshlrev_b32_e32 v2, 3, v9
	v_ashrrev_i32_e32 v10, 6, v3
	v_and_b32_e32 v3, 0xc0, v3
	s_lshl_b64 s[4:5], s[4:5], 19
	v_and_b32_e32 v2, -16, v2
	v_sub_u32_e32 v1, v1, v3
	v_mov_b32_e32 v3, 1
	s_add_u32 s28, s34, s4
	v_add_u32_e32 v2, v10, v2
	v_ashrrev_i16_sdwa v1, v3, sext(v1) dst_sel:DWORD dst_unused:UNUSED_PAD src0_sel:DWORD src1_sel:BYTE_0
	s_addc_u32 s29, s35, s5
	v_lshlrev_b32_e32 v4, 5, v9
	v_bfe_i32 v11, v1, 0, 16
	v_lshlrev_b32_e32 v1, 1, v2
	v_lshrrev_b32_e32 v5, 2, v2
	v_and_b32_e32 v6, 3, v10
	s_mov_b32 s5, 0x1fffe0
	v_and_b32_e32 v4, 32, v4
	v_and_b32_e32 v1, 24, v1
	v_and_b32_e32 v5, 4, v5
	v_and_or_b32 v6, v2, s5, v6
	v_or3_b32 v1, v6, v5, v1
	v_add_lshl_u32 v4, v4, v11, 1
	v_add_u32_e32 v0, 0x2000, v0
	v_lshl_add_u32 v146, v1, 11, v4
	v_add_u32_e32 v146, s98, v146
	v_ashrrev_i32_e32 v1, 31, v0
	v_lshrrev_b32_e32 v1, 22, v1
	v_add_u32_e32 v1, v0, v1
	v_ashrrev_i32_e32 v12, 10, v1
	v_mul_i32_i24_e32 v1, 0x400, v12
	v_sub_u32_e32 v0, v0, v1
	v_lshrrev_b32_e32 v1, 4, v0
	v_bitop3_b32 v0, v1, v0, 32 bitop3:0x6c
	v_lshl_add_u32 v144, v2, 11, v4
	v_ashrrev_i32_e32 v2, 31, v0
	v_lshrrev_b32_e32 v2, 26, v2
	v_add_u32_e32 v2, v0, v2
	v_lshlrev_b32_e32 v1, 3, v12
	v_ashrrev_i32_e32 v13, 6, v2
	v_and_b32_e32 v2, 0xc0, v2
	v_and_b32_e32 v1, -16, v1
	v_sub_u32_e32 v0, v0, v2
	v_add_u32_e32 v1, v13, v1
	v_ashrrev_i16_sdwa v0, v3, sext(v0) dst_sel:DWORD dst_unused:UNUSED_PAD src0_sel:DWORD src1_sel:BYTE_0
	v_and_b32_e32 v3, 3, v13
	v_and_or_b32 v3, v1, s5, v3
	s_ashr_i32 s5, s6, 6
	s_lshl_b32 s22, s5, 10
	v_lshlrev_b32_e32 v4, 5, v12
	v_bfe_i32 v14, v0, 0, 16
	v_lshlrev_b32_e32 v0, 1, v1
	v_lshrrev_b32_e32 v2, 2, v1
	s_add_i32 s25, s22, 0
	v_and_b32_e32 v4, 32, v4
	v_and_b32_e32 v0, 24, v0
	v_and_b32_e32 v2, 4, v2
	s_add_i32 m0, s25, 0x10000
	s_ashr_i32 s4, s6, 8
	v_or3_b32 v0, v3, v2, v0
	v_add_lshl_u32 v2, v4, v14, 1
	global_load_lds_dwordx4 v146, s[28:29]
	s_add_i32 m0, s25, 0x12000
	v_lshl_add_u32 v150, v0, 11, v2
	v_add_u32_e32 v150, s99, v150
	s_add_u32 s8, s28, 0x10000
	global_load_lds_dwordx4 v150, s[28:29]
	s_addc_u32 s9, s29, 0
	s_add_i32 m0, s25, 0x14000
	s_add_i32 s36, s25, 0x2000
	global_load_lds_dwordx4 v146, s[8:9]
	s_add_i32 m0, s25, 0x16000
	v_lshl_add_u32 v148, v1, 11, v2
	global_load_lds_dwordx4 v150, s[8:9]
	s_mov_b32 m0, s25
	s_add_u32 s8, s26, 0x40000
	global_load_lds_dwordx4 v144, s[26:27]
	s_mov_b32 m0, s36
	s_addc_u32 s9, s27, 0
	s_add_i32 s37, s25, 0x4000
	global_load_lds_dwordx4 v148, s[26:27]
	s_mov_b32 m0, s37
	s_add_i32 s38, s25, 0x6000
	global_load_lds_dwordx4 v144, s[8:9]
	s_mov_b32 m0, s38
	v_mov_b32_e32 v147, 0
	global_load_lds_dwordx4 v148, s[8:9]
	v_mov_b32_e32 v151, v147
	v_mov_b32_e32 v145, v147
	v_mov_b32_e32 v149, v147
	s_cmp_eq_u32 s4, 1
	v_lshl_add_u64 v[6:7], s[28:29], 0, v[146:147]
	v_lshl_add_u64 v[4:5], s[28:29], 0, v[150:151]
	v_lshl_add_u64 v[0:1], s[26:27], 0, v[144:145]
	s_cselect_b64 s[8:9], -1, 0
	s_cmp_lg_u32 s4, 1
	v_lshl_add_u64 v[2:3], s[26:27], 0, v[148:149]
	s_cbranch_scc1 .LBB0_925
	s_barrier

; #define PG8_STAGE(bufoff, gbase, voff) do { _Pragma("unroll") for (int _i = 0; _i < 2; ++_i) \
;         __builtin_amdgcn_global_load_lds((const unsigned*)((const char*)(gbase) + (voff)[_i]), (PG8_LAS unsigned*)(lds + (bufoff) + ldsw + _i * 8192), 16, 0, 0); } while (0)
; #define PG8_LDA(dst, b, h) do { _Pragma("unroll") for (int m = 0; m < 4; ++m) _Pragma("unroll") for (int k = 0; k < 2; ++k) dst[m][k] = *(const PG8_LAS bf16x8*)(lds + PG8_SA(b, h) + aoff + m * 2048 + k * 1024); } while (0)
; #define PG8_LDB(dst, b, h) do { _Pragma("unroll") for (int n = 0; n < 2; ++n) _Pragma("unroll") for (int k = 0; k < 2; ++k) dst[n][k] = *(const PG8_LAS bf16x8*)(lds + PG8_SB(b, h) + boff + n * 2048 + k * 1024); } while (0)
; #define PG8_MMA(ai, bj, At, Bt) do { __builtin_amdgcn_s_setprio(1); _Pragma("unroll") for (int m = 0; m < 4; ++m) _Pragma("unroll") for (int n = 0; n < 2; ++n) _Pragma("unroll") for (int k = 0; k < 2; ++k) \
;         acc[ai][bj][m][n] = __builtin_amdgcn_mfma_f32_16x16x32_bf16(Bt[n][k], At[m][k], acc[ai][bj][m][n], 0, 0, 0); __builtin_amdgcn_s_setprio(0); } while (0)
; #define PG8_WAIT_V(n) asm volatile("s_waitcnt vmcnt(" #n ")" ::: "memory")
; #define PG8_WAIT_L(n) asm volatile("s_waitcnt lgkmcnt(" #n ")" ::: "memory")
; #define PG8_BAR __builtin_amdgcn_s_barrier()
; #define PG8_SCHED __builtin_amdgcn_sched_barrier(0)
; template <class Epi, class Sched, bool ALIGN_EPI = false, bool SP2 = false>
; __device__ __forceinline__ void gemm_phase(PG8_LAS unsigned char* lds, const Gemm g, const Sched& S, const Epi& E) {
;     ...
;             PG8_LDB(B0, 0, 0); PG8_LDB(B1, 0, 1); PG8_SCHED; PG8_LDA(At, 0, 0); PG8_STAGE(PG8_SA(1, 1), a1 + hstep, voffA);
;             PG8_WAIT_V(8); PG8_WAIT_L(0); PG8_BAR; PG8_MMA(0, 0, At, B0); PG8_MMA(0, 1, At, B1); PG8_BAR; PG8_SCHED;
;             PG8_LDA(At, 0, 1); PG8_STAGE(PG8_SB(0, 0), b2, voffB); PG8_STAGE(PG8_SB(0, 1), b2 + hstep, voffB); PG8_STAGE(PG8_SA(0, 0), a2, voffA);
;             PG8_WAIT_V(8); PG8_WAIT_L(0); PG8_BAR; PG8_MMA(1, 0, At, B0); PG8_MMA(1, 1, At, B1); PG8_BAR; PG8_SCHED;
.LBB0_931:
	ds_read_b128 v[128:131], v171
	ds_read_b128 v[132:135], v171 offset:1024
	ds_read_b128 v[136:139], v171 offset:2048
	ds_read_b128 v[140:143], v171 offset:3072
	ds_read_b128 v[160:163], v172
	ds_read_b128 v[176:179], v172 offset:1024
	ds_read_b128 v[180:183], v172 offset:2048
	ds_read_b128 v[184:187], v172 offset:3072
	s_add_u32 s28, s26, 0xfffc0080
	s_addc_u32 s29, s27, -1
	s_cmp_eq_u32 s54, 12
	s_cselect_b32 s31, s17, s29
	s_cselect_b32 s30, s50, s28
	s_cselect_b32 s29, s15, s53
	s_cselect_b32 s28, s51, s52
	v_lshl_add_u64 v[220:221], s[26:27], 0, v[152:153]
	s_add_i32 m0, s25, 0xc000
	ds_read_b128 v[188:191], v173
	ds_read_b128 v[192:195], v173 offset:1024
	ds_read_b128 v[196:199], v173 offset:2048
	ds_read_b128 v[200:203], v173 offset:3072
	ds_read_b128 v[204:207], v173 offset:4096
	ds_read_b128 v[208:211], v173 offset:5120
	ds_read_b128 v[212:215], v173 offset:6144
	ds_read_b128 v[216:219], v173 offset:7168
	global_load_lds_dwordx4 v[220:221], off
	v_lshl_add_u64 v[220:221], s[26:27], 0, v[154:155]
	s_add_i32 m0, s25, 0xe000
	s_nop 0
	global_load_lds_dwordx4 v[220:221], off
	s_waitcnt vmcnt(8)
	s_waitcnt lgkmcnt(0)
	s_barrier
	s_setprio 1
	s_waitcnt lgkmcnt(0)
	v_mfma_f32_16x16x32_bf16 v[124:127], v[128:131], v[188:191], v[124:127]
	v_mfma_f32_16x16x32_bf16 v[120:123], v[136:139], v[188:191], v[120:123]
	v_mfma_f32_16x16x32_bf16 v[116:119], v[128:131], v[196:199], v[116:119]
	v_mfma_f32_16x16x32_bf16 v[108:111], v[136:139], v[196:199], v[108:111]
	v_mfma_f32_16x16x32_bf16 v[96:99], v[128:131], v[204:207], v[96:99]
	v_mfma_f32_16x16x32_bf16 v[88:91], v[136:139], v[204:207], v[88:91]
	v_mfma_f32_16x16x32_bf16 v[84:87], v[128:131], v[212:215], v[84:87]
	v_mfma_f32_16x16x32_bf16 v[76:79], v[136:139], v[212:215], v[76:79]
	v_mfma_f32_16x16x32_bf16 v[124:127], v[132:135], v[192:195], v[124:127]
	v_mfma_f32_16x16x32_bf16 v[120:123], v[140:143], v[192:195], v[120:123]
	v_mfma_f32_16x16x32_bf16 v[116:119], v[132:135], v[200:203], v[116:119]
	v_mfma_f32_16x16x32_bf16 v[108:111], v[140:143], v[200:203], v[108:111]
	v_mfma_f32_16x16x32_bf16 v[96:99], v[132:135], v[208:211], v[96:99]
	v_mfma_f32_16x16x32_bf16 v[88:91], v[140:143], v[208:211], v[88:91]
	v_mfma_f32_16x16x32_bf16 v[84:87], v[132:135], v[216:219], v[84:87]
	v_mfma_f32_16x16x32_bf16 v[76:79], v[140:143], v[216:219], v[76:79]
	s_setprio 0
	s_setprio 1
	v_mfma_f32_16x16x32_bf16 v[112:115], v[160:163], v[188:191], v[112:115]
	v_mfma_f32_16x16x32_bf16 v[104:107], v[180:183], v[188:191], v[104:107]
	v_mfma_f32_16x16x32_bf16 v[100:103], v[160:163], v[196:199], v[100:103]
	v_mfma_f32_16x16x32_bf16 v[92:95], v[180:183], v[196:199], v[92:95]
	v_mfma_f32_16x16x32_bf16 v[80:83], v[160:163], v[204:207], v[80:83]
	v_mfma_f32_16x16x32_bf16 v[72:75], v[180:183], v[204:207], v[72:75]
	v_mfma_f32_16x16x32_bf16 v[68:71], v[160:163], v[212:215], v[68:71]
	v_mfma_f32_16x16x32_bf16 v[64:67], v[180:183], v[212:215], v[64:67]
	v_mfma_f32_16x16x32_bf16 v[112:115], v[176:179], v[192:195], v[112:115]
	v_mfma_f32_16x16x32_bf16 v[104:107], v[184:187], v[192:195], v[104:107]
	v_mfma_f32_16x16x32_bf16 v[100:103], v[176:179], v[200:203], v[100:103]
	v_mfma_f32_16x16x32_bf16 v[92:95], v[184:187], v[200:203], v[92:95]
	v_mfma_f32_16x16x32_bf16 v[80:83], v[176:179], v[208:211], v[80:83]
	v_mfma_f32_16x16x32_bf16 v[72:75], v[184:187], v[208:211], v[72:75]
	v_mfma_f32_16x16x32_bf16 v[68:71], v[176:179], v[216:219], v[68:71]
	v_mfma_f32_16x16x32_bf16 v[64:67], v[184:187], v[216:219], v[64:67]
	s_setprio 0
	s_barrier
	s_add_i32 s55, s44, s22
	v_lshl_add_u64 v[220:221], s[28:29], 0, v[146:147]
	s_mov_b32 m0, s55
	ds_read_b128 v[188:191], v173 offset:16384
	ds_read_b128 v[192:195], v173 offset:17408
	ds_read_b128 v[196:199], v173 offset:18432
	ds_read_b128 v[200:203], v173 offset:19456
	ds_read_b128 v[204:207], v173 offset:20480
	ds_read_b128 v[208:211], v173 offset:21504
	ds_read_b128 v[212:215], v173 offset:22528
	ds_read_b128 v[216:219], v173 offset:23552
	global_load_lds_dwordx4 v[220:221], off
	s_add_i32 m0, s55, 0x2000
	s_add_u32 s56, s28, 0x10000
	v_lshl_add_u64 v[222:223], s[28:29], 0, v[150:151]
	s_addc_u32 s57, s29, 0
	s_add_i32 s55, s45, s22
	global_load_lds_dwordx4 v[222:223], off
	v_lshl_add_u64 v[224:225], s[56:57], 0, v[146:147]
	s_mov_b32 m0, s55
	v_lshl_add_u64 v[226:227], s[30:31], 0, v[148:149]
	global_load_lds_dwordx4 v[224:225], off
	v_lshl_add_u64 v[224:225], s[56:57], 0, v[150:151]
	s_add_i32 m0, s55, 0x2000
	s_nop 0
	global_load_lds_dwordx4 v[224:225], off
	v_lshl_add_u64 v[224:225], s[30:31], 0, v[144:145]
	s_mov_b32 m0, s25
	s_nop 0
	global_load_lds_dwordx4 v[224:225], off
	s_mov_b32 m0, s36
	s_nop 0
	global_load_lds_dwordx4 v[226:227], off
	s_waitcnt vmcnt(8)
	s_waitcnt lgkmcnt(0)
	s_barrier
; #define PG8_STAGE(bufoff, gbase, voff) do { _Pragma("unroll") for (int _i = 0; _i < 2; ++_i) \
;         __builtin_amdgcn_global_load_lds((const unsigned*)((const char*)(gbase) + (voff)[_i]), (PG8_LAS unsigned*)(lds + (bufoff) + ldsw + _i * 8192), 16, 0, 0); } while (0)
; #define PG8_LDA(dst, b, h) do { _Pragma("unroll") for (int m = 0; m < 4; ++m) _Pragma("unroll") for (int k = 0; k < 2; ++k) dst[m][k] = *(const PG8_LAS bf16x8*)(lds + PG8_SA(b, h) + aoff + m * 2048 + k * 1024); } while (0)
; #define PG8_LDB(dst, b, h) do { _Pragma("unroll") for (int n = 0; n < 2; ++n) _Pragma("unroll") for (int k = 0; k < 2; ++k) dst[n][k] = *(const PG8_LAS bf16x8*)(lds + PG8_SB(b, h) + boff + n * 2048 + k * 1024); } while (0)
; #define PG8_MMA(ai, bj, At, Bt) do { __builtin_amdgcn_s_setprio(1); _Pragma("unroll") for (int m = 0; m < 4; ++m) _Pragma("unroll") for (int n = 0; n < 2; ++n) _Pragma("unroll") for (int k = 0; k < 2; ++k) \
;         acc[ai][bj][m][n] = __builtin_amdgcn_mfma_f32_16x16x32_bf16(Bt[n][k], At[m][k], acc[ai][bj][m][n], 0, 0, 0); __builtin_amdgcn_s_setprio(0); } while (0)
; #define PG8_WAIT_V(n) asm volatile("s_waitcnt vmcnt(" #n ")" ::: "memory")
; #define PG8_WAIT_L(n) asm volatile("s_waitcnt lgkmcnt(" #n ")" ::: "memory")
; #define PG8_BAR __builtin_amdgcn_s_barrier()
; #define PG8_SCHED __builtin_amdgcn_sched_barrier(0)
; template <class Epi, class Sched, bool ALIGN_EPI = false, bool SP2 = false>
; __device__ __forceinline__ void gemm_phase(PG8_LAS unsigned char* lds, const Gemm g, const Sched& S, const Epi& E) {
;     ...
;             PG8_WAIT_V(8); PG8_WAIT_L(0); PG8_BAR; PG8_MMA(1, 0, At, B0); PG8_MMA(1, 1, At, B1); PG8_BAR; PG8_SCHED;
;             PG8_LDB(B0, 1, 0); PG8_LDB(B1, 1, 1); PG8_SCHED; PG8_LDA(At, 1, 0); PG8_STAGE(PG8_SA(0, 1), a2 + hstep, voffA);
;             PG8_WAIT_V(8); PG8_WAIT_L(0); PG8_BAR; PG8_MMA(0, 0, At, B0); PG8_MMA(0, 1, At, B1); PG8_BAR; PG8_SCHED;
	s_setprio 1
	s_waitcnt lgkmcnt(0)
	v_mfma_f32_16x16x32_bf16 v[60:63], v[128:131], v[188:191], v[60:63]
	v_mfma_f32_16x16x32_bf16 v[56:59], v[136:139], v[188:191], v[56:59]
	v_mfma_f32_16x16x32_bf16 v[52:55], v[128:131], v[196:199], v[52:55]
	v_mfma_f32_16x16x32_bf16 v[44:47], v[136:139], v[196:199], v[44:47]
	v_mfma_f32_16x16x32_bf16 v[32:35], v[128:131], v[204:207], v[32:35]
	v_mfma_f32_16x16x32_bf16 v[24:27], v[136:139], v[204:207], v[24:27]
	v_mfma_f32_16x16x32_bf16 v[20:23], v[128:131], v[212:215], v[20:23]
	v_mfma_f32_16x16x32_bf16 v[12:15], v[136:139], v[212:215], v[12:15]
	v_mfma_f32_16x16x32_bf16 v[60:63], v[132:135], v[192:195], v[60:63]
	v_mfma_f32_16x16x32_bf16 v[56:59], v[140:143], v[192:195], v[56:59]
	v_mfma_f32_16x16x32_bf16 v[52:55], v[132:135], v[200:203], v[52:55]
	v_mfma_f32_16x16x32_bf16 v[44:47], v[140:143], v[200:203], v[44:47]
	v_mfma_f32_16x16x32_bf16 v[32:35], v[132:135], v[208:211], v[32:35]
	v_mfma_f32_16x16x32_bf16 v[24:27], v[140:143], v[208:211], v[24:27]
	v_mfma_f32_16x16x32_bf16 v[20:23], v[132:135], v[216:219], v[20:23]
	v_mfma_f32_16x16x32_bf16 v[12:15], v[140:143], v[216:219], v[12:15]
	s_setprio 0
	s_setprio 1
	v_mfma_f32_16x16x32_bf16 v[48:51], v[160:163], v[188:191], v[48:51]
	v_mfma_f32_16x16x32_bf16 v[40:43], v[180:183], v[188:191], v[40:43]
	v_mfma_f32_16x16x32_bf16 v[36:39], v[160:163], v[196:199], v[36:39]
	v_mfma_f32_16x16x32_bf16 v[28:31], v[180:183], v[196:199], v[28:31]
	v_mfma_f32_16x16x32_bf16 v[16:19], v[160:163], v[204:207], v[16:19]
	v_mfma_f32_16x16x32_bf16 v[8:11], v[180:183], v[204:207], v[8:11]
	v_mfma_f32_16x16x32_bf16 v[4:7], v[160:163], v[212:215], v[4:7]
	v_mfma_f32_16x16x32_bf16 v[0:3], v[180:183], v[212:215], v[0:3]
	v_mfma_f32_16x16x32_bf16 v[48:51], v[176:179], v[192:195], v[48:51]
	v_mfma_f32_16x16x32_bf16 v[40:43], v[184:187], v[192:195], v[40:43]
	v_mfma_f32_16x16x32_bf16 v[36:39], v[176:179], v[200:203], v[36:39]
	v_mfma_f32_16x16x32_bf16 v[28:31], v[184:187], v[200:203], v[28:31]
	v_mfma_f32_16x16x32_bf16 v[16:19], v[176:179], v[208:211], v[16:19]
	v_mfma_f32_16x16x32_bf16 v[8:11], v[184:187], v[208:211], v[8:11]
	v_mfma_f32_16x16x32_bf16 v[4:7], v[176:179], v[216:219], v[4:7]
	v_mfma_f32_16x16x32_bf16 v[0:3], v[184:187], v[216:219], v[0:3]
	s_setprio 0
	s_barrier
	s_add_i32 s55, 0, 0x18000
	s_add_i32 s56, 0, 0x1c000
	v_add_u32_e32 v140, s55, v167
	v_add_u32_e32 v175, s56, v167
	ds_read_b128 v[128:131], v140
	ds_read_b128 v[132:135], v140 offset:1024
	ds_read_b128 v[136:139], v140 offset:2048
	ds_read_b128 v[140:143], v140 offset:3072
	ds_read_b128 v[160:163], v175
	ds_read_b128 v[176:179], v175 offset:1024
	ds_read_b128 v[180:183], v175 offset:2048
	ds_read_b128 v[184:187], v175 offset:3072
	s_add_u32 s30, s30, 0x40000
	s_addc_u32 s31, s31, 0
	s_mov_b32 m0, s37
	v_lshl_add_u64 v[228:229], s[30:31], 0, v[144:145]
	ds_read_b128 v[188:191], v173 offset:32768
	ds_read_b128 v[192:195], v173 offset:33792
	ds_read_b128 v[196:199], v173 offset:34816
	ds_read_b128 v[200:203], v173 offset:35840
	ds_read_b128 v[204:207], v173 offset:36864
	ds_read_b128 v[208:211], v173 offset:37888
	ds_read_b128 v[212:215], v173 offset:38912
	ds_read_b128 v[216:219], v173 offset:39936
	global_load_lds_dwordx4 v[228:229], off
	v_lshl_add_u64 v[228:229], s[30:31], 0, v[148:149]
	s_mov_b32 m0, s38
	s_nop 0
	global_load_lds_dwordx4 v[228:229], off
	s_waitcnt vmcnt(8)
	s_waitcnt lgkmcnt(0)
	s_barrier
	s_setprio 1
	s_waitcnt lgkmcnt(0)
	v_mfma_f32_16x16x32_bf16 v[124:127], v[128:131], v[188:191], v[124:127]
	v_mfma_f32_16x16x32_bf16 v[120:123], v[136:139], v[188:191], v[120:123]
	v_mfma_f32_16x16x32_bf16 v[116:119], v[128:131], v[196:199], v[116:119]
	v_mfma_f32_16x16x32_bf16 v[108:111], v[136:139], v[196:199], v[108:111]
	v_mfma_f32_16x16x32_bf16 v[96:99], v[128:131], v[204:207], v[96:99]
	v_mfma_f32_16x16x32_bf16 v[88:91], v[136:139], v[204:207], v[88:91]
	v_mfma_f32_16x16x32_bf16 v[84:87], v[128:131], v[212:215], v[84:87]
	v_mfma_f32_16x16x32_bf16 v[76:79], v[136:139], v[212:215], v[76:79]
	v_mfma_f32_16x16x32_bf16 v[124:127], v[132:135], v[192:195], v[124:127]
	v_mfma_f32_16x16x32_bf16 v[120:123], v[140:143], v[192:195], v[120:123]
	v_mfma_f32_16x16x32_bf16 v[116:119], v[132:135], v[200:203], v[116:119]
	v_mfma_f32_16x16x32_bf16 v[108:111], v[140:143], v[200:203], v[108:111]
	v_mfma_f32_16x16x32_bf16 v[96:99], v[132:135], v[208:211], v[96:99]
	v_mfma_f32_16x16x32_bf16 v[88:91], v[140:143], v[208:211], v[88:91]
	v_mfma_f32_16x16x32_bf16 v[84:87], v[132:135], v[216:219], v[84:87]
	v_mfma_f32_16x16x32_bf16 v[76:79], v[140:143], v[216:219], v[76:79]
	s_setprio 0
	s_setprio 1
	v_mfma_f32_16x16x32_bf16 v[112:115], v[160:163], v[188:191], v[112:115]
	v_mfma_f32_16x16x32_bf16 v[104:107], v[180:183], v[188:191], v[104:107]
	v_mfma_f32_16x16x32_bf16 v[100:103], v[160:163], v[196:199], v[100:103]
	v_mfma_f32_16x16x32_bf16 v[92:95], v[180:183], v[196:199], v[92:95]
	v_mfma_f32_16x16x32_bf16 v[80:83], v[160:163], v[204:207], v[80:83]
	v_mfma_f32_16x16x32_bf16 v[72:75], v[180:183], v[204:207], v[72:75]
	v_mfma_f32_16x16x32_bf16 v[68:71], v[160:163], v[212:215], v[68:71]
	v_mfma_f32_16x16x32_bf16 v[64:67], v[180:183], v[212:215], v[64:67]
	v_mfma_f32_16x16x32_bf16 v[112:115], v[176:179], v[192:195], v[112:115]
	v_mfma_f32_16x16x32_bf16 v[104:107], v[184:187], v[192:195], v[104:107]
	v_mfma_f32_16x16x32_bf16 v[100:103], v[176:179], v[200:203], v[100:103]
	v_mfma_f32_16x16x32_bf16 v[92:95], v[184:187], v[200:203], v[92:95]
	v_mfma_f32_16x16x32_bf16 v[80:83], v[176:179], v[208:211], v[80:83]
	v_mfma_f32_16x16x32_bf16 v[72:75], v[184:187], v[208:211], v[72:75]
	v_mfma_f32_16x16x32_bf16 v[68:71], v[176:179], v[216:219], v[68:71]
	v_mfma_f32_16x16x32_bf16 v[64:67], v[184:187], v[216:219], v[64:67]
	s_setprio 0
	s_barrier
; __device__ __forceinline__ unsigned cvt_pk_bf16(float lo, float hi) { const f32x2_t v = {lo, hi}; const bf16x2_t b = __builtin_convertvector(v, bf16x2_t); return __builtin_bit_cast(unsigned, b); }
; #define PG8_STAGE(bufoff, gbase, voff) do { _Pragma("unroll") for (int _i = 0; _i < 2; ++_i) \
;         __builtin_amdgcn_global_load_lds((const unsigned*)((const char*)(gbase) + (voff)[_i]), (PG8_LAS unsigned*)(lds + (bufoff) + ldsw + _i * 8192), 16, 0, 0); } while (0)
; #define PG8_LDA(dst, b, h) do { _Pragma("unroll") for (int m = 0; m < 4; ++m) _Pragma("unroll") for (int k = 0; k < 2; ++k) dst[m][k] = *(const PG8_LAS bf16x8*)(lds + PG8_SA(b, h) + aoff + m * 2048 + k * 1024); } while (0)
; #define PG8_WAIT_V(n) asm volatile("s_waitcnt vmcnt(" #n ")" ::: "memory")
; #define PG8_WAIT_L(n) asm volatile("s_waitcnt lgkmcnt(" #n ")" ::: "memory")
; #define PG8_BAR __builtin_amdgcn_s_barrier()
; #define PG8_SCHED __builtin_amdgcn_sched_barrier(0)
;     __device__ __forceinline__ void operator()(const f32x4 (&acc)[2][2][4][2], const Unit& u, int wr, int wc, int fr, int fq, const PG8_LAS float* tab) const {
;     ...
;             for (int m = 0; m < 4; ++m) { const int row = row0 + ai * HALF + m * 16; bf16_t* rowp = O + (size_t)row * ldc + col0;
;                 const float rstd = tab[rl0 + ai * HALF + m * 16];
; #pragma unroll
;                 for (int bj = 0; bj < 2; ++bj) { f32x4 v0 = acc[ai][bj][m][0] * rstd, v1 = acc[ai][bj][m][1] * rstd;
;                     if (ACT == 1) {
; #pragma unroll
;                         for (int e = 0; e < 4; ++e) { float a = v0[e] > 0.f ? v0[e] : 0.f; v0[e] = a * a; float b = v1[e] > 0.f ? v1[e] : 0.f; v1[e] = b * b; } }
;                     u32x4 w; w.x = cvt_pk_bf16(v0[0], v0[1]); w.y = cvt_pk_bf16(v0[2], v0[3]); w.z = cvt_pk_bf16(v1[0], v1[1]); w.w = cvt_pk_bf16(v1[2], v1[3]);
;                     *(u32x4*)(rowp + bj * HALF) = w; } }
; template <class Epi, class Sched, bool ALIGN_EPI = false, bool SP2 = false>
; __device__ __forceinline__ void gemm_phase(PG8_LAS unsigned char* lds, const Gemm g, const Sched& S, const Epi& E) {
;     ...
;             PG8_LDA(At, 1, 1); PG8_STAGE(PG8_SB(1, 0), b3, voffB); PG8_STAGE(PG8_SB(1, 1), b3 + hstep, voffB); PG8_STAGE(PG8_SA(1, 0), a3, voffA);
;             PG8_WAIT_V(8); PG8_WAIT_L(0); PG8_BAR; PG8_MMA(1, 0, At, B0); PG8_MMA(1, 1, At, B1); PG8_BAR; PG8_SCHED;
	s_add_i32 s30, s55, s22
	v_lshl_add_u64 v[220:221], v[220:221], 0, s[10:11]
	s_mov_b32 m0, s30
	ds_read_b128 v[188:191], v173 offset:49152
	ds_read_b128 v[192:195], v173 offset:50176
	ds_read_b128 v[196:199], v173 offset:51200
	ds_read_b128 v[200:203], v173 offset:52224
	ds_read_b128 v[204:207], v173 offset:53248
	ds_read_b128 v[208:211], v173 offset:54272
	ds_read_b128 v[212:215], v173 offset:55296
	ds_read_b128 v[216:219], v173 offset:56320
	global_load_lds_dwordx4 v[220:221], off
	s_add_i32 m0, s30, 0x2000
	s_add_u32 s28, s28, 0x10080
	v_lshl_add_u64 v[220:221], v[222:223], 0, s[10:11]
	s_addc_u32 s29, s29, 0
	s_add_i32 s30, s56, s22
	global_load_lds_dwordx4 v[220:221], off
	v_lshl_add_u64 v[220:221], s[28:29], 0, v[146:147]
	s_mov_b32 m0, s30
	s_nop 0
	global_load_lds_dwordx4 v[220:221], off
	v_lshl_add_u64 v[220:221], s[28:29], 0, v[150:151]
	s_add_i32 m0, s30, 0x2000
	s_nop 0
	global_load_lds_dwordx4 v[220:221], off
	v_lshl_add_u64 v[220:221], v[224:225], 0, s[10:11]
	s_mov_b32 m0, s39
	s_nop 0
	global_load_lds_dwordx4 v[220:221], off
	v_lshl_add_u64 v[220:221], v[226:227], 0, s[10:11]
	s_mov_b32 m0, s40
	s_nop 0
	global_load_lds_dwordx4 v[220:221], off
	s_waitcnt vmcnt(8)
	s_waitcnt lgkmcnt(0)
	s_barrier
	s_setprio 1
	s_waitcnt lgkmcnt(0)
	v_mfma_f32_16x16x32_bf16 v[60:63], v[128:131], v[188:191], v[60:63]
	v_mfma_f32_16x16x32_bf16 v[56:59], v[136:139], v[188:191], v[56:59]
	v_mfma_f32_16x16x32_bf16 v[52:55], v[128:131], v[196:199], v[52:55]
	v_mfma_f32_16x16x32_bf16 v[44:47], v[136:139], v[196:199], v[44:47]
	v_mfma_f32_16x16x32_bf16 v[32:35], v[128:131], v[204:207], v[32:35]
	v_mfma_f32_16x16x32_bf16 v[24:27], v[136:139], v[204:207], v[24:27]
	v_mfma_f32_16x16x32_bf16 v[20:23], v[128:131], v[212:215], v[20:23]
	v_mfma_f32_16x16x32_bf16 v[12:15], v[136:139], v[212:215], v[12:15]
	v_mfma_f32_16x16x32_bf16 v[60:63], v[132:135], v[192:195], v[60:63]
	v_mfma_f32_16x16x32_bf16 v[56:59], v[140:143], v[192:195], v[56:59]
	v_mfma_f32_16x16x32_bf16 v[52:55], v[132:135], v[200:203], v[52:55]
	v_mfma_f32_16x16x32_bf16 v[44:47], v[140:143], v[200:203], v[44:47]
	v_mfma_f32_16x16x32_bf16 v[32:35], v[132:135], v[208:211], v[32:35]
	v_mfma_f32_16x16x32_bf16 v[24:27], v[140:143], v[208:211], v[24:27]
	v_mfma_f32_16x16x32_bf16 v[20:23], v[132:135], v[216:219], v[20:23]
	v_mfma_f32_16x16x32_bf16 v[12:15], v[140:143], v[216:219], v[12:15]
	s_setprio 0
	s_setprio 1
	v_mfma_f32_16x16x32_bf16 v[48:51], v[160:163], v[188:191], v[48:51]
	v_mfma_f32_16x16x32_bf16 v[40:43], v[180:183], v[188:191], v[40:43]
	v_mfma_f32_16x16x32_bf16 v[36:39], v[160:163], v[196:199], v[36:39]
	v_mfma_f32_16x16x32_bf16 v[28:31], v[180:183], v[196:199], v[28:31]
	v_mfma_f32_16x16x32_bf16 v[16:19], v[160:163], v[204:207], v[16:19]
	v_mfma_f32_16x16x32_bf16 v[8:11], v[180:183], v[204:207], v[8:11]
	v_mfma_f32_16x16x32_bf16 v[4:7], v[160:163], v[212:215], v[4:7]
	v_mfma_f32_16x16x32_bf16 v[0:3], v[180:183], v[212:215], v[0:3]
	v_mfma_f32_16x16x32_bf16 v[48:51], v[176:179], v[192:195], v[48:51]
	v_mfma_f32_16x16x32_bf16 v[40:43], v[184:187], v[192:195], v[40:43]
	v_mfma_f32_16x16x32_bf16 v[36:39], v[176:179], v[200:203], v[36:39]
	v_mfma_f32_16x16x32_bf16 v[28:31], v[184:187], v[200:203], v[28:31]
	v_mfma_f32_16x16x32_bf16 v[16:19], v[176:179], v[208:211], v[16:19]
	v_mfma_f32_16x16x32_bf16 v[8:11], v[184:187], v[208:211], v[8:11]
	v_mfma_f32_16x16x32_bf16 v[4:7], v[176:179], v[216:219], v[4:7]
	v_mfma_f32_16x16x32_bf16 v[0:3], v[184:187], v[216:219], v[0:3]
	s_setprio 0
	s_barrier
	s_add_i32 s54, s54, 2
	s_add_u32 s26, s26, 0x100
	s_addc_u32 s27, s27, 0
	s_add_u32 s52, s52, 0x100
	s_addc_u32 s53, s53, 0
	s_cmp_gt_u32 s54, 13
	s_cbranch_scc0 .LBB0_931
	v_mbcnt_lo_u32_b32 v234, -1, 0
	v_mbcnt_hi_u32_b32 v234, -1, v234
	v_bfe_u32 v234, v234, 3, 1
	v_sub_u32_e32 v249, 0, v234
	v_and_b32_e32 v248, 0xffff3040, v249
	v_and_b32_e32 v235, 0xcfc0, v249
	v_sub_u32_e32 v250, 0xd000, v235
	v_mov_b32_e32 v251, 0
	s_mov_b32 s98, 0xff00ff
	s_mov_b32 s99, 0xff00ff
	s_and_b64 vcc, exec, s[12:13]
	s_cbranch_vccz .LBB0_934
	s_barrier

;     __host__ __device__ bool next(int i, Unit& u) const {
;         const long L = (long)i * G + c; if (L >= nwg) return false;
;         int wgid = (int)L; { const int q = nwg / NXCD, r = nwg % NXCD, xcd = wgid % NXCD, off = wgid / NXCD; wgid = (xcd < r ? xcd * (q + 1) : r * (q + 1) + (xcd - r) * q) + off; }
;         const int nig = WGM * nN, gid = wgid / nig, fm = gid * WGM, gsz = (nM - fm) < WGM ? (nM - fm) : WGM;
;         u.pm = fm + ((wgid % nig) % gsz); u.pn = (wgid % nig) / gsz; return true;
; template <int L> __device__ __forceinline__ void layer_phases(const KArgs& a, LAS unsigned char* lds, const XcdBarrier& xbar, int lo, int hi) {
;     ...
;     if (PH_IN(P0 + 4)) {
;         pg8::Gemm g{XB, (const bf16_t*)(ws + WS_WUP) + (size_t)l * FF * DM, MTOK, FF, DM}; pg8::StaticOrder S; S.init(MTOK, FF, G, (int)blockIdx.x);
;         pg8::EpiBf16<1> E{Hb, FF, SSQ};
;         pg8::gemm_phase<pg8::EpiBf16<1>, pg8::StaticOrder, true, true>(lds, g, S, E);
.LBB0_1536:
	s_cmp_lt_i32 s96, 12
	s_cselect_b64 s[0:1], -1, 0
	s_and_b64 s[2:3], s[0:1], s[2:3]
	s_andn2_b64 vcc, exec, s[2:3]
	s_cbranch_vccnz .LBB0_1569
	v_readfirstlane_b32 s100, v166
	s_nop 3
	s_lshr_b32 s98, s100, 8
	s_lshl_b32 s98, s98, 16
	s_add_i32 s99, s98, 0x20000
	s_lshr_b32 s100, s100, 6
	s_and_b32 s100, s100, 3
	s_lshl_b32 s100, s100, 5
	v_mov_b32_e32 v8, v166
	s_cmpk_gt_i32 s75, 0xfff
	v_readfirstlane_b32 s6, v8
	s_cbranch_scc1 .LBB0_1569
	s_ashr_i32 s33, s75, 31
	s_lshr_b32 s2, s33, 29
	s_add_i32 s4, s75, s2
	s_and_b32 s2, s4, -8
	s_sub_i32 s5, s75, s2
	s_cmp_gt_i32 s5, -1
	s_cbranch_scc0 .LBB0_1540
	s_lshl_b32 s7, s5, 9
	s_cbranch_execz .LBB0_1541
	s_branch .LBB0_1542

; #define PG8_LAS __attribute__((address_space(3)))
; #define PG8_WAIT_V(n) asm volatile("s_waitcnt vmcnt(" #n ")" ::: "memory")
; #define PG8_BAR __builtin_amdgcn_s_barrier()
; template <class Epi, class Sched, bool ALIGN_EPI = false, bool SP2 = false>
; __device__ __forceinline__ void gemm_phase(PG8_LAS unsigned char* lds, const Gemm g, const Sched& S, const Epi& E) {
;     ...
;     const int tid = tid_, wid = __builtin_amdgcn_readfirstlane(tid >> 6), lane = tid & 63, wr = wid >> 2, wc = wid & 3, fr = lane & 15, fq = lane >> 4;
;     const int K = g.K, nt = K / BK;
;     unsigned voffA[2], voffB[2];
; #pragma unroll
;     for (int i = 0; i < 2; ++i) { int R, C; stage_rc(tid * 16 + i * 8192, R, C); const int Rb = Epi::PERM ? ((R & ~31) + perm32(R & 31)) : R;
;         voffA[i] = (unsigned)(R * K + C) * 2u; voffB[i] = (unsigned)(Rb * K + C) * 2u; }
;     const size_t kstep = (size_t)(BK * 2);
;     const size_t hstep = (size_t)HALF * K * 2;
;     const size_t tstep = 2 * hstep;
;     const unsigned ldsw = (unsigned)wid * 1024u;
;     const int aoff = lds_byte(wr * 64 + fr, fq * 8), boff = lds_byte(wc * 32 + fr, fq * 8);
;     ...
;     Unit cur, nxt; int ui = 0;
;     if (!S.next(0, cur)) return;
;     f32x4 acc[2][2][4][2];
; #pragma unroll
;     for (int a = 0; a < 2; ++a)
; #pragma unroll
;         for (int b = 0; b < 2; ++b)
; #pragma unroll
;             for (int m = 0; m < 4; ++m)
; #pragma unroll
;                 for (int n = 0; n < 2; ++n) acc[a][b][m][n] = (f32x4){0.f, 0.f, 0.f, 0.f};
;     bf16x8 At[4][2], B0[2][2], B1[2][2];
;     const char* cA = (const char*)g.A + (size_t)cur.pm * tstep; const char* cB = (const char*)g.Bt + (size_t)cur.pn * tstep;
;     S.a_ready(cur);
;     PG8_LAS float* ptab = (PG8_LAS float*)(lds + STAGE_BYTES);
;     if constexpr (Epi::HAS_PRE) { const auto p0 = E.pre_load(cur.pm, tid); E.pre_store(p0, ptab, tid); }
;     if constexpr (SP2) {
;         PG8_STAGE(PG8_SB(0, 0), cB, voffB); PG8_STAGE(PG8_SB(0, 1), cB + hstep, voffB); PG8_STAGE(PG8_SA(0, 0), cA, voffA); PG8_STAGE(PG8_SA(0, 1), cA + hstep, voffA);
;         if (wr == 1) PG8_BAR;
;         PG8_WAIT_V(2); PG8_BAR;
;         PG8_STAGE(PG8_SB(1, 0), cB + kstep, voffB); PG8_STAGE(PG8_SA(1, 0), cA + kstep, voffA); PG8_STAGE(PG8_SB(1, 1), cB + hstep + kstep, voffB);
;         PG8_WAIT_V(6); PG8_BAR;
.LBB0_1544:
	s_or_b64 exec, exec, s[4:5]
	s_waitcnt lgkmcnt(0)
	v_ashrrev_i32_e32 v1, 31, v8
	v_lshrrev_b32_e32 v1, 26, v1
	v_add_u32_e32 v1, v8, v1
	v_mov_b32_e32 v0, s7
	v_ashrrev_i32_e32 v9, 6, v1
	v_bfe_i32 v1, v8, 27, 1
	v_readfirstlane_b32 s30, v0
	v_lshlrev_b32_e32 v0, 4, v8
	v_lshrrev_b32_e32 v1, 22, v1
	v_add_u32_e32 v1, v0, v1
	v_and_b32_e32 v1, 0xfffffc00, v1
	v_sub_u32_e32 v1, v0, v1
	v_lshrrev_b32_e32 v2, 4, v1
	s_add_u32 s42, s70, 0x1a00000
	v_bitop3_b32 v1, v2, v1, 32 bitop3:0x6c
	s_addc_u32 s43, s71, 0
	s_ashr_i32 s35, s34, 31
	v_ashrrev_i32_e32 v3, 31, v1
	s_lshl_b64 s[4:5], s[34:35], 19
	v_readlane_b32 s8, v254, 39
	v_lshrrev_b32_e32 v3, 26, v3
	v_readlane_b32 s9, v254, 40
	s_add_u32 s36, s8, s4
	s_mov_b32 s31, 0
	v_add_u32_e32 v3, v1, v3
	s_addc_u32 s37, s9, s5
	s_bfe_i64 s[4:5], s[30:31], 0x80000
	v_lshlrev_b32_e32 v2, 3, v9
	v_ashrrev_i32_e32 v10, 6, v3
	v_and_b32_e32 v3, 0xc0, v3
	s_lshl_b64 s[4:5], s[4:5], 19
	v_and_b32_e32 v2, -16, v2
	v_sub_u32_e32 v1, v1, v3
	v_mov_b32_e32 v3, 1
	s_add_u32 s38, s42, s4
	v_add_u32_e32 v2, v10, v2
	v_ashrrev_i16_sdwa v1, v3, sext(v1) dst_sel:DWORD dst_unused:UNUSED_PAD src0_sel:DWORD src1_sel:BYTE_0
	s_addc_u32 s39, s43, s5
	v_lshlrev_b32_e32 v4, 5, v9
	v_bfe_i32 v11, v1, 0, 16
	v_lshlrev_b32_e32 v1, 1, v2
	v_lshrrev_b32_e32 v5, 2, v2
	v_and_b32_e32 v6, 3, v10
	s_mov_b32 s5, 0x1fffe0
	v_and_b32_e32 v4, 32, v4
	v_and_b32_e32 v1, 24, v1
	v_and_b32_e32 v5, 4, v5
	v_and_or_b32 v6, v2, s5, v6
	v_or3_b32 v1, v6, v5, v1
	v_add_lshl_u32 v4, v4, v11, 1
	v_add_u32_e32 v0, 0x2000, v0
	v_lshl_add_u32 v146, v1, 11, v4
	v_add_u32_e32 v146, s98, v146
	v_ashrrev_i32_e32 v1, 31, v0
	v_lshrrev_b32_e32 v1, 22, v1
	v_add_u32_e32 v1, v0, v1
	v_ashrrev_i32_e32 v12, 10, v1
	v_mul_i32_i24_e32 v1, 0x400, v12
	v_sub_u32_e32 v0, v0, v1
	v_lshrrev_b32_e32 v1, 4, v0
	v_bitop3_b32 v0, v1, v0, 32 bitop3:0x6c
	v_lshl_add_u32 v144, v2, 11, v4
	v_ashrrev_i32_e32 v2, 31, v0
	v_lshrrev_b32_e32 v2, 26, v2
	v_add_u32_e32 v2, v0, v2
	v_lshlrev_b32_e32 v1, 3, v12
	v_ashrrev_i32_e32 v13, 6, v2
	v_and_b32_e32 v2, 0xc0, v2
	v_and_b32_e32 v1, -16, v1
	v_sub_u32_e32 v0, v0, v2
	v_add_u32_e32 v1, v13, v1
	v_ashrrev_i16_sdwa v0, v3, sext(v0) dst_sel:DWORD dst_unused:UNUSED_PAD src0_sel:DWORD src1_sel:BYTE_0
	v_and_b32_e32 v3, 3, v13
	v_and_or_b32 v3, v1, s5, v3
	s_ashr_i32 s5, s6, 6
	s_lshl_b32 s30, s5, 10
	v_lshlrev_b32_e32 v4, 5, v12
	v_bfe_i32 v14, v0, 0, 16
	v_lshlrev_b32_e32 v0, 1, v1
	v_lshrrev_b32_e32 v2, 2, v1
	s_add_i32 s35, s30, 0
	v_and_b32_e32 v4, 32, v4
	v_and_b32_e32 v0, 24, v0
	v_and_b32_e32 v2, 4, v2
	s_add_i32 m0, s35, 0x10000
	s_ashr_i32 s4, s6, 8
	v_or3_b32 v0, v3, v2, v0
	v_add_lshl_u32 v2, v4, v14, 1
	global_load_lds_dwordx4 v146, s[38:39]
	s_add_i32 m0, s35, 0x12000
	v_lshl_add_u32 v150, v0, 11, v2
	v_add_u32_e32 v150, s99, v150
	s_add_u32 s8, s38, 0x10000
	global_load_lds_dwordx4 v150, s[38:39]
	s_addc_u32 s9, s39, 0
	s_add_i32 m0, s35, 0x14000
	s_add_i32 s44, s35, 0x2000
	global_load_lds_dwordx4 v146, s[8:9]
	s_add_i32 m0, s35, 0x16000
	v_lshl_add_u32 v148, v1, 11, v2
	global_load_lds_dwordx4 v150, s[8:9]
	s_mov_b32 m0, s35
	s_add_u32 s8, s36, 0x40000
	global_load_lds_dwordx4 v144, s[36:37]
	s_mov_b32 m0, s44
	s_addc_u32 s9, s37, 0
	s_add_i32 s45, s35, 0x4000
	global_load_lds_dwordx4 v148, s[36:37]
	s_mov_b32 m0, s45
	s_add_i32 s46, s35, 0x6000
	global_load_lds_dwordx4 v144, s[8:9]
	s_mov_b32 m0, s46
	v_mov_b32_e32 v147, 0
	global_load_lds_dwordx4 v148, s[8:9]
	v_mov_b32_e32 v151, v147
	v_mov_b32_e32 v145, v147
	v_mov_b32_e32 v149, v147
	s_cmp_eq_u32 s4, 1
	v_lshl_add_u64 v[6:7], s[38:39], 0, v[146:147]
	v_lshl_add_u64 v[4:5], s[38:39], 0, v[150:151]
	v_lshl_add_u64 v[0:1], s[36:37], 0, v[144:145]
	s_cselect_b64 s[8:9], -1, 0
	s_cmp_lg_u32 s4, 1
	v_lshl_add_u64 v[2:3], s[36:37], 0, v[148:149]
	s_cbranch_scc1 .LBB0_1546
	s_barrier
.LBB0_1546:
	s_lshl_b32 s5, s5, 5
	s_mov_b64 s[10:11], 0x80
	s_and_b32 s5, s5, 0x60
	s_add_i32 m0, s35, 0x18000
	v_lshl_add_u64 v[6:7], v[6:7], 0, s[10:11]
	s_lshl_b32 s14, s4, 13
	s_lshl_b32 s15, s5, 7
	s_waitcnt vmcnt(2)
	s_barrier
	global_load_lds_dwordx4 v[6:7], off
	v_lshl_add_u64 v[4:5], v[4:5], 0, s[10:11]
	s_add_i32 m0, s35, 0x1a000
	s_add_i32 s47, s35, 0x8000
	s_add_i32 s48, s35, 0xa000
	global_load_lds_dwordx4 v[4:5], off
	v_lshl_add_u64 v[0:1], v[0:1], 0, s[10:11]
	s_mov_b32 m0, s47
	s_add_u32 s12, s38, 0x10080
	global_load_lds_dwordx4 v[0:1], off
	v_lshl_add_u64 v[0:1], v[2:3], 0, s[10:11]
	s_mov_b32 m0, s48
	s_addc_u32 s13, s39, 0
	global_load_lds_dwordx4 v[0:1], off
	s_add_i32 m0, s35, 0x1c000
	v_lshl_add_u64 v[0:1], s[12:13], 0, v[146:147]
	global_load_lds_dwordx4 v[0:1], off
	v_lshl_add_u64 v[0:1], s[12:13], 0, v[150:151]
	s_add_i32 m0, s35, 0x1e000
	v_lshlrev_b32_e32 v4, 2, v8
	global_load_lds_dwordx4 v[0:1], off
	v_lshrrev_b32_e32 v1, 1, v8
	v_and_b32_e32 v0, 15, v8
	v_and_b32_e32 v1, 24, v1
	v_lshl_or_b32 v168, s4, 6, v0
	v_lshlrev_b32_e32 v2, 1, v1
	v_lshl_or_b32 v0, v0, 6, v2
	v_lshlrev_b32_e32 v2, 2, v168
	v_and_b32_e32 v3, 32, v2
	v_and_b32_e32 v5, 32, v4
	v_bitop3_b32 v3, v0, s14, v3 bitop3:0xde
	v_bitop3_b32 v169, v0, s15, v5 bitop3:0xde
	v_lshlrev_b32_e32 v0, 14, v9
	v_and_b32_e32 v0, 0xffff8000, v0
	v_or_b32_e32 v172, s5, v1
	v_lshl_add_u32 v0, v10, 11, v0
	v_and_b32_e32 v1, 1, v9
	v_lshl_or_b32 v0, v1, 6, v0
	v_lshl_add_u32 v152, v11, 1, v0
	v_lshlrev_b32_e32 v0, 14, v12
	s_add_i32 s4, 0, 0x20000
	v_and_b32_e32 v0, 0xffff8000, v0
	s_waitcnt vmcnt(6)
	s_cmpk_lt_u32 s6, 0x100
	v_lshl_add_u32 v0, v13, 11, v0
	v_and_b32_e32 v1, 1, v12
	s_cselect_b64 s[12:13], -1, 0
	v_lshl_or_b32 v0, v1, 6, v0
	s_add_i32 s51, 0, 0x10000
	s_add_i32 s52, 0, 0x14000
	s_sext_i32_i8 s59, s7
	v_add_u32_e32 v170, s4, v2
	v_add_u32_e32 v171, s4, v4
	s_ashr_i32 s49, s94, 31
	s_mov_b32 s50, s94
	v_mov_b32_e32 v153, v147
	v_lshl_add_u32 v154, v14, 1, v0
	v_mov_b32_e32 v155, v147
	v_mov_b64_e32 v[156:157], 0x1000
	v_mov_b64_e32 v[158:159], 0xfff
	v_add_u32_e32 v173, s51, v169
	v_add_u32_e32 v174, s52, v169
	v_add_u32_e32 v175, 0, v3
	s_mov_b64 s[14:15], 0x100000
	s_mov_b32 s53, 0x100000
	s_mov_b64 s[16:17], 0x120000
	s_mov_b32 s54, 0x120000
	s_mov_b64 s[18:19], 0x140000
	s_mov_b32 s55, 0x140000
	s_mov_b64 s[20:21], 0x160000
	s_mov_b32 s56, 0x160000
	v_mov_b32_e32 v176, 0x358637bd
	s_mov_b32 s57, 0x800000
	s_barrier
	s_branch .LBB0_1549

; #define PG8_STAGE(bufoff, gbase, voff) do { _Pragma("unroll") for (int _i = 0; _i < 2; ++_i) \
;         __builtin_amdgcn_global_load_lds((const unsigned*)((const char*)(gbase) + (voff)[_i]), (PG8_LAS unsigned*)(lds + (bufoff) + ldsw + _i * 8192), 16, 0, 0); } while (0)
; #define PG8_LDA(dst, b, h) do { _Pragma("unroll") for (int m = 0; m < 4; ++m) _Pragma("unroll") for (int k = 0; k < 2; ++k) dst[m][k] = *(const PG8_LAS bf16x8*)(lds + PG8_SA(b, h) + aoff + m * 2048 + k * 1024); } while (0)
; #define PG8_LDB(dst, b, h) do { _Pragma("unroll") for (int n = 0; n < 2; ++n) _Pragma("unroll") for (int k = 0; k < 2; ++k) dst[n][k] = *(const PG8_LAS bf16x8*)(lds + PG8_SB(b, h) + boff + n * 2048 + k * 1024); } while (0)
; #define PG8_MMA(ai, bj, At, Bt) do { __builtin_amdgcn_s_setprio(1); _Pragma("unroll") for (int m = 0; m < 4; ++m) _Pragma("unroll") for (int n = 0; n < 2; ++n) _Pragma("unroll") for (int k = 0; k < 2; ++k) \
;         acc[ai][bj][m][n] = __builtin_amdgcn_mfma_f32_16x16x32_bf16(Bt[n][k], At[m][k], acc[ai][bj][m][n], 0, 0, 0); __builtin_amdgcn_s_setprio(0); } while (0)
; #define PG8_WAIT_V(n) asm volatile("s_waitcnt vmcnt(" #n ")" ::: "memory")
; #define PG8_WAIT_L(n) asm volatile("s_waitcnt lgkmcnt(" #n ")" ::: "memory")
; #define PG8_BAR __builtin_amdgcn_s_barrier()
; #define PG8_SCHED __builtin_amdgcn_sched_barrier(0)
; template <class Epi, class Sched, bool ALIGN_EPI = false, bool SP2 = false>
; __device__ __forceinline__ void gemm_phase(PG8_LAS unsigned char* lds, const Gemm g, const Sched& S, const Epi& E) {
;     ...
;             PG8_LDB(B0, 0, 0); PG8_LDB(B1, 0, 1); PG8_SCHED; PG8_LDA(At, 0, 0); PG8_STAGE(PG8_SA(1, 1), a1 + hstep, voffA);
;             PG8_WAIT_V(8); PG8_WAIT_L(0); PG8_BAR; PG8_MMA(0, 0, At, B0); PG8_MMA(0, 1, At, B1); PG8_BAR; PG8_SCHED;
;             PG8_LDA(At, 0, 1); PG8_STAGE(PG8_SB(0, 0), b2, voffB); PG8_STAGE(PG8_SB(0, 1), b2 + hstep, voffB); PG8_STAGE(PG8_SA(0, 0), a2, voffA);
;             PG8_WAIT_V(8); PG8_WAIT_L(0); PG8_BAR; PG8_MMA(1, 0, At, B0); PG8_MMA(1, 1, At, B1); PG8_BAR; PG8_SCHED;
.LBB0_1556:
	ds_read_b128 v[128:131], v173
	ds_read_b128 v[132:135], v173 offset:1024
	ds_read_b128 v[136:139], v173 offset:2048
	ds_read_b128 v[140:143], v173 offset:3072
	ds_read_b128 v[160:163], v174
	ds_read_b128 v[178:181], v174 offset:1024
	ds_read_b128 v[182:185], v174 offset:2048
	ds_read_b128 v[186:189], v174 offset:3072
	s_add_u32 s38, s36, 0xfffc0080
	s_addc_u32 s39, s37, -1
	s_cmp_eq_u32 s64, 12
	s_cselect_b32 s41, s25, s39
	s_cselect_b32 s40, s60, s38
	s_cselect_b32 s39, s23, s63
	s_cselect_b32 s38, s61, s62
	v_lshl_add_u64 v[164:165], s[36:37], 0, v[152:153]
	s_add_i32 m0, s35, 0xc000
	ds_read_b128 v[190:193], v175
	ds_read_b128 v[194:197], v175 offset:1024
	ds_read_b128 v[198:201], v175 offset:2048
	ds_read_b128 v[202:205], v175 offset:3072
	ds_read_b128 v[206:209], v175 offset:4096
	ds_read_b128 v[210:213], v175 offset:5120
	ds_read_b128 v[214:217], v175 offset:6144
	ds_read_b128 v[218:221], v175 offset:7168
	global_load_lds_dwordx4 v[164:165], off
	v_lshl_add_u64 v[164:165], s[36:37], 0, v[154:155]
	s_add_i32 m0, s35, 0xe000
	s_nop 0
	global_load_lds_dwordx4 v[164:165], off
	s_waitcnt vmcnt(8)
	s_waitcnt lgkmcnt(0)
	s_barrier
	s_setprio 1
	s_waitcnt lgkmcnt(0)
	v_mfma_f32_16x16x32_bf16 v[124:127], v[128:131], v[190:193], v[124:127]
	v_mfma_f32_16x16x32_bf16 v[120:123], v[136:139], v[190:193], v[120:123]
	v_mfma_f32_16x16x32_bf16 v[108:111], v[128:131], v[198:201], v[108:111]
	v_mfma_f32_16x16x32_bf16 v[104:107], v[136:139], v[198:201], v[104:107]
	v_mfma_f32_16x16x32_bf16 v[92:95], v[128:131], v[206:209], v[92:95]
	v_mfma_f32_16x16x32_bf16 v[88:91], v[136:139], v[206:209], v[88:91]
	v_mfma_f32_16x16x32_bf16 v[76:79], v[128:131], v[214:217], v[76:79]
	v_mfma_f32_16x16x32_bf16 v[72:75], v[136:139], v[214:217], v[72:75]
	v_mfma_f32_16x16x32_bf16 v[124:127], v[132:135], v[194:197], v[124:127]
	v_mfma_f32_16x16x32_bf16 v[120:123], v[140:143], v[194:197], v[120:123]
	v_mfma_f32_16x16x32_bf16 v[108:111], v[132:135], v[202:205], v[108:111]
	v_mfma_f32_16x16x32_bf16 v[104:107], v[140:143], v[202:205], v[104:107]
	v_mfma_f32_16x16x32_bf16 v[92:95], v[132:135], v[210:213], v[92:95]
	v_mfma_f32_16x16x32_bf16 v[88:91], v[140:143], v[210:213], v[88:91]
	v_mfma_f32_16x16x32_bf16 v[76:79], v[132:135], v[218:221], v[76:79]
	v_mfma_f32_16x16x32_bf16 v[72:75], v[140:143], v[218:221], v[72:75]
	s_setprio 0
	s_setprio 1
	v_mfma_f32_16x16x32_bf16 v[116:119], v[160:163], v[190:193], v[116:119]
	v_mfma_f32_16x16x32_bf16 v[112:115], v[182:185], v[190:193], v[112:115]
	v_mfma_f32_16x16x32_bf16 v[100:103], v[160:163], v[198:201], v[100:103]
	v_mfma_f32_16x16x32_bf16 v[96:99], v[182:185], v[198:201], v[96:99]
	v_mfma_f32_16x16x32_bf16 v[84:87], v[160:163], v[206:209], v[84:87]
	v_mfma_f32_16x16x32_bf16 v[80:83], v[182:185], v[206:209], v[80:83]
	v_mfma_f32_16x16x32_bf16 v[68:71], v[160:163], v[214:217], v[68:71]
	v_mfma_f32_16x16x32_bf16 v[64:67], v[182:185], v[214:217], v[64:67]
	v_mfma_f32_16x16x32_bf16 v[116:119], v[178:181], v[194:197], v[116:119]
	v_mfma_f32_16x16x32_bf16 v[112:115], v[186:189], v[194:197], v[112:115]
	v_mfma_f32_16x16x32_bf16 v[100:103], v[178:181], v[202:205], v[100:103]
	v_mfma_f32_16x16x32_bf16 v[96:99], v[186:189], v[202:205], v[96:99]
	v_mfma_f32_16x16x32_bf16 v[84:87], v[178:181], v[210:213], v[84:87]
	v_mfma_f32_16x16x32_bf16 v[80:83], v[186:189], v[210:213], v[80:83]
	v_mfma_f32_16x16x32_bf16 v[68:71], v[178:181], v[218:221], v[68:71]
	v_mfma_f32_16x16x32_bf16 v[64:67], v[186:189], v[218:221], v[64:67]
	s_setprio 0
	s_barrier
	s_add_i32 s65, s51, s30
	v_lshl_add_u64 v[164:165], s[38:39], 0, v[146:147]
	s_mov_b32 m0, s65
	ds_read_b128 v[190:193], v175 offset:16384
	ds_read_b128 v[194:197], v175 offset:17408
	ds_read_b128 v[198:201], v175 offset:18432
	ds_read_b128 v[202:205], v175 offset:19456
	ds_read_b128 v[206:209], v175 offset:20480
	ds_read_b128 v[210:213], v175 offset:21504
	ds_read_b128 v[214:217], v175 offset:22528
	ds_read_b128 v[218:221], v175 offset:23552
	global_load_lds_dwordx4 v[164:165], off
	s_add_i32 m0, s65, 0x2000
	s_add_u32 s66, s38, 0x10000
	v_lshl_add_u64 v[222:223], s[38:39], 0, v[150:151]
	s_addc_u32 s67, s39, 0
	s_add_i32 s65, s52, s30
	global_load_lds_dwordx4 v[222:223], off
	v_lshl_add_u64 v[224:225], s[66:67], 0, v[146:147]
	s_mov_b32 m0, s65
	v_lshl_add_u64 v[226:227], s[40:41], 0, v[148:149]
	global_load_lds_dwordx4 v[224:225], off
	v_lshl_add_u64 v[224:225], s[66:67], 0, v[150:151]
	s_add_i32 m0, s65, 0x2000
	s_nop 0
	global_load_lds_dwordx4 v[224:225], off
	v_lshl_add_u64 v[224:225], s[40:41], 0, v[144:145]
	s_mov_b32 m0, s35
	s_nop 0
	global_load_lds_dwordx4 v[224:225], off
	s_mov_b32 m0, s44
	s_nop 0
	global_load_lds_dwordx4 v[226:227], off
	s_waitcnt vmcnt(8)
	s_waitcnt lgkmcnt(0)
	s_barrier
; #define PG8_STAGE(bufoff, gbase, voff) do { _Pragma("unroll") for (int _i = 0; _i < 2; ++_i) \
;         __builtin_amdgcn_global_load_lds((const unsigned*)((const char*)(gbase) + (voff)[_i]), (PG8_LAS unsigned*)(lds + (bufoff) + ldsw + _i * 8192), 16, 0, 0); } while (0)
; #define PG8_LDA(dst, b, h) do { _Pragma("unroll") for (int m = 0; m < 4; ++m) _Pragma("unroll") for (int k = 0; k < 2; ++k) dst[m][k] = *(const PG8_LAS bf16x8*)(lds + PG8_SA(b, h) + aoff + m * 2048 + k * 1024); } while (0)
; #define PG8_LDB(dst, b, h) do { _Pragma("unroll") for (int n = 0; n < 2; ++n) _Pragma("unroll") for (int k = 0; k < 2; ++k) dst[n][k] = *(const PG8_LAS bf16x8*)(lds + PG8_SB(b, h) + boff + n * 2048 + k * 1024); } while (0)
; #define PG8_MMA(ai, bj, At, Bt) do { __builtin_amdgcn_s_setprio(1); _Pragma("unroll") for (int m = 0; m < 4; ++m) _Pragma("unroll") for (int n = 0; n < 2; ++n) _Pragma("unroll") for (int k = 0; k < 2; ++k) \
;         acc[ai][bj][m][n] = __builtin_amdgcn_mfma_f32_16x16x32_bf16(Bt[n][k], At[m][k], acc[ai][bj][m][n], 0, 0, 0); __builtin_amdgcn_s_setprio(0); } while (0)
; #define PG8_WAIT_V(n) asm volatile("s_waitcnt vmcnt(" #n ")" ::: "memory")
; #define PG8_WAIT_L(n) asm volatile("s_waitcnt lgkmcnt(" #n ")" ::: "memory")
; #define PG8_BAR __builtin_amdgcn_s_barrier()
; #define PG8_SCHED __builtin_amdgcn_sched_barrier(0)
; template <class Epi, class Sched, bool ALIGN_EPI = false, bool SP2 = false>
; __device__ __forceinline__ void gemm_phase(PG8_LAS unsigned char* lds, const Gemm g, const Sched& S, const Epi& E) {
;     ...
;             PG8_WAIT_V(8); PG8_WAIT_L(0); PG8_BAR; PG8_MMA(1, 0, At, B0); PG8_MMA(1, 1, At, B1); PG8_BAR; PG8_SCHED;
;             PG8_LDB(B0, 1, 0); PG8_LDB(B1, 1, 1); PG8_SCHED; PG8_LDA(At, 1, 0); PG8_STAGE(PG8_SA(0, 1), a2 + hstep, voffA);
;             PG8_WAIT_V(8); PG8_WAIT_L(0); PG8_BAR; PG8_MMA(0, 0, At, B0); PG8_MMA(0, 1, At, B1); PG8_BAR; PG8_SCHED;
	s_setprio 1
	s_waitcnt lgkmcnt(0)
	v_mfma_f32_16x16x32_bf16 v[60:63], v[128:131], v[190:193], v[60:63]
	v_mfma_f32_16x16x32_bf16 v[56:59], v[136:139], v[190:193], v[56:59]
	v_mfma_f32_16x16x32_bf16 v[44:47], v[128:131], v[198:201], v[44:47]
	v_mfma_f32_16x16x32_bf16 v[40:43], v[136:139], v[198:201], v[40:43]
	v_mfma_f32_16x16x32_bf16 v[28:31], v[128:131], v[206:209], v[28:31]
	v_mfma_f32_16x16x32_bf16 v[24:27], v[136:139], v[206:209], v[24:27]
	v_mfma_f32_16x16x32_bf16 v[12:15], v[128:131], v[214:217], v[12:15]
	v_mfma_f32_16x16x32_bf16 v[8:11], v[136:139], v[214:217], v[8:11]
	v_mfma_f32_16x16x32_bf16 v[60:63], v[132:135], v[194:197], v[60:63]
	v_mfma_f32_16x16x32_bf16 v[56:59], v[140:143], v[194:197], v[56:59]
	v_mfma_f32_16x16x32_bf16 v[44:47], v[132:135], v[202:205], v[44:47]
	v_mfma_f32_16x16x32_bf16 v[40:43], v[140:143], v[202:205], v[40:43]
	v_mfma_f32_16x16x32_bf16 v[28:31], v[132:135], v[210:213], v[28:31]
	v_mfma_f32_16x16x32_bf16 v[24:27], v[140:143], v[210:213], v[24:27]
	v_mfma_f32_16x16x32_bf16 v[12:15], v[132:135], v[218:221], v[12:15]
	v_mfma_f32_16x16x32_bf16 v[8:11], v[140:143], v[218:221], v[8:11]
	s_setprio 0
	s_setprio 1
	v_mfma_f32_16x16x32_bf16 v[52:55], v[160:163], v[190:193], v[52:55]
	v_mfma_f32_16x16x32_bf16 v[48:51], v[182:185], v[190:193], v[48:51]
	v_mfma_f32_16x16x32_bf16 v[36:39], v[160:163], v[198:201], v[36:39]
	v_mfma_f32_16x16x32_bf16 v[32:35], v[182:185], v[198:201], v[32:35]
	v_mfma_f32_16x16x32_bf16 v[20:23], v[160:163], v[206:209], v[20:23]
	v_mfma_f32_16x16x32_bf16 v[16:19], v[182:185], v[206:209], v[16:19]
	v_mfma_f32_16x16x32_bf16 v[4:7], v[160:163], v[214:217], v[4:7]
	v_mfma_f32_16x16x32_bf16 v[0:3], v[182:185], v[214:217], v[0:3]
	v_mfma_f32_16x16x32_bf16 v[52:55], v[178:181], v[194:197], v[52:55]
	v_mfma_f32_16x16x32_bf16 v[48:51], v[186:189], v[194:197], v[48:51]
	v_mfma_f32_16x16x32_bf16 v[36:39], v[178:181], v[202:205], v[36:39]
	v_mfma_f32_16x16x32_bf16 v[32:35], v[186:189], v[202:205], v[32:35]
	v_mfma_f32_16x16x32_bf16 v[20:23], v[178:181], v[210:213], v[20:23]
	v_mfma_f32_16x16x32_bf16 v[16:19], v[186:189], v[210:213], v[16:19]
	v_mfma_f32_16x16x32_bf16 v[4:7], v[178:181], v[218:221], v[4:7]
	v_mfma_f32_16x16x32_bf16 v[0:3], v[186:189], v[218:221], v[0:3]
	s_setprio 0
	s_barrier
	s_add_i32 s65, 0, 0x18000
	s_add_i32 s66, 0, 0x1c000
	v_add_u32_e32 v140, s65, v169
	v_add_u32_e32 v177, s66, v169
	ds_read_b128 v[128:131], v140
	ds_read_b128 v[132:135], v140 offset:1024
	ds_read_b128 v[136:139], v140 offset:2048
	ds_read_b128 v[140:143], v140 offset:3072
	ds_read_b128 v[160:163], v177
	ds_read_b128 v[178:181], v177 offset:1024
	ds_read_b128 v[182:185], v177 offset:2048
	ds_read_b128 v[186:189], v177 offset:3072
	s_add_u32 s40, s40, 0x40000
	s_addc_u32 s41, s41, 0
	s_mov_b32 m0, s45
	v_lshl_add_u64 v[228:229], s[40:41], 0, v[144:145]
	ds_read_b128 v[190:193], v175 offset:32768
	ds_read_b128 v[194:197], v175 offset:33792
	ds_read_b128 v[198:201], v175 offset:34816
	ds_read_b128 v[202:205], v175 offset:35840
	ds_read_b128 v[206:209], v175 offset:36864
	ds_read_b128 v[210:213], v175 offset:37888
	ds_read_b128 v[214:217], v175 offset:38912
	ds_read_b128 v[218:221], v175 offset:39936
	global_load_lds_dwordx4 v[228:229], off
	v_lshl_add_u64 v[228:229], s[40:41], 0, v[148:149]
	s_mov_b32 m0, s46
	s_nop 0
	global_load_lds_dwordx4 v[228:229], off
	s_waitcnt vmcnt(8)
	s_waitcnt lgkmcnt(0)
	s_barrier
	s_setprio 1
	s_waitcnt lgkmcnt(0)
	v_mfma_f32_16x16x32_bf16 v[124:127], v[128:131], v[190:193], v[124:127]
	v_mfma_f32_16x16x32_bf16 v[120:123], v[136:139], v[190:193], v[120:123]
	v_mfma_f32_16x16x32_bf16 v[108:111], v[128:131], v[198:201], v[108:111]
	v_mfma_f32_16x16x32_bf16 v[104:107], v[136:139], v[198:201], v[104:107]
	v_mfma_f32_16x16x32_bf16 v[92:95], v[128:131], v[206:209], v[92:95]
	v_mfma_f32_16x16x32_bf16 v[88:91], v[136:139], v[206:209], v[88:91]
	v_mfma_f32_16x16x32_bf16 v[76:79], v[128:131], v[214:217], v[76:79]
	v_mfma_f32_16x16x32_bf16 v[72:75], v[136:139], v[214:217], v[72:75]
	v_mfma_f32_16x16x32_bf16 v[124:127], v[132:135], v[194:197], v[124:127]
	v_mfma_f32_16x16x32_bf16 v[120:123], v[140:143], v[194:197], v[120:123]
	v_mfma_f32_16x16x32_bf16 v[108:111], v[132:135], v[202:205], v[108:111]
	v_mfma_f32_16x16x32_bf16 v[104:107], v[140:143], v[202:205], v[104:107]
	v_mfma_f32_16x16x32_bf16 v[92:95], v[132:135], v[210:213], v[92:95]
	v_mfma_f32_16x16x32_bf16 v[88:91], v[140:143], v[210:213], v[88:91]
	v_mfma_f32_16x16x32_bf16 v[76:79], v[132:135], v[218:221], v[76:79]
	v_mfma_f32_16x16x32_bf16 v[72:75], v[140:143], v[218:221], v[72:75]
	s_setprio 0
	s_setprio 1
	v_mfma_f32_16x16x32_bf16 v[116:119], v[160:163], v[190:193], v[116:119]
	v_mfma_f32_16x16x32_bf16 v[112:115], v[182:185], v[190:193], v[112:115]
	v_mfma_f32_16x16x32_bf16 v[100:103], v[160:163], v[198:201], v[100:103]
	v_mfma_f32_16x16x32_bf16 v[96:99], v[182:185], v[198:201], v[96:99]
	v_mfma_f32_16x16x32_bf16 v[84:87], v[160:163], v[206:209], v[84:87]
	v_mfma_f32_16x16x32_bf16 v[80:83], v[182:185], v[206:209], v[80:83]
	v_mfma_f32_16x16x32_bf16 v[68:71], v[160:163], v[214:217], v[68:71]
	v_mfma_f32_16x16x32_bf16 v[64:67], v[182:185], v[214:217], v[64:67]
	v_mfma_f32_16x16x32_bf16 v[116:119], v[178:181], v[194:197], v[116:119]
	v_mfma_f32_16x16x32_bf16 v[112:115], v[186:189], v[194:197], v[112:115]
	v_mfma_f32_16x16x32_bf16 v[100:103], v[178:181], v[202:205], v[100:103]
	v_mfma_f32_16x16x32_bf16 v[96:99], v[186:189], v[202:205], v[96:99]
	v_mfma_f32_16x16x32_bf16 v[84:87], v[178:181], v[210:213], v[84:87]
	v_mfma_f32_16x16x32_bf16 v[80:83], v[186:189], v[210:213], v[80:83]
	v_mfma_f32_16x16x32_bf16 v[68:71], v[178:181], v[218:221], v[68:71]
	v_mfma_f32_16x16x32_bf16 v[64:67], v[186:189], v[218:221], v[64:67]
	s_setprio 0
	s_barrier
; #define PG8_STAGE(bufoff, gbase, voff) do { _Pragma("unroll") for (int _i = 0; _i < 2; ++_i) \
;         __builtin_amdgcn_global_load_lds((const unsigned*)((const char*)(gbase) + (voff)[_i]), (PG8_LAS unsigned*)(lds + (bufoff) + ldsw + _i * 8192), 16, 0, 0); } while (0)
; #define PG8_LDA(dst, b, h) do { _Pragma("unroll") for (int m = 0; m < 4; ++m) _Pragma("unroll") for (int k = 0; k < 2; ++k) dst[m][k] = *(const PG8_LAS bf16x8*)(lds + PG8_SA(b, h) + aoff + m * 2048 + k * 1024); } while (0)
; #define PG8_MMA(ai, bj, At, Bt) do { __builtin_amdgcn_s_setprio(1); _Pragma("unroll") for (int m = 0; m < 4; ++m) _Pragma("unroll") for (int n = 0; n < 2; ++n) _Pragma("unroll") for (int k = 0; k < 2; ++k) \
;         acc[ai][bj][m][n] = __builtin_amdgcn_mfma_f32_16x16x32_bf16(Bt[n][k], At[m][k], acc[ai][bj][m][n], 0, 0, 0); __builtin_amdgcn_s_setprio(0); } while (0)
; #define PG8_WAIT_V(n) asm volatile("s_waitcnt vmcnt(" #n ")" ::: "memory")
; #define PG8_WAIT_L(n) asm volatile("s_waitcnt lgkmcnt(" #n ")" ::: "memory")
; #define PG8_BAR __builtin_amdgcn_s_barrier()
; #define PG8_SCHED __builtin_amdgcn_sched_barrier(0)
;     __device__ __forceinline__ void operator()(const f32x4 (&acc)[2][2][4][2], const Unit& u, int wr, int wc, int fr, int fq, const PG8_LAS float* tab) const {
;         const int rl0 = wr * 64 + fr; const int row0 = u.pm * BM + rl0; const int col0 = u.pn * BM + wc * 32 + 8 * fq;
; template <class Epi, class Sched, bool ALIGN_EPI = false, bool SP2 = false>
; __device__ __forceinline__ void gemm_phase(PG8_LAS unsigned char* lds, const Gemm g, const Sched& S, const Epi& E) {
;     ...
;             PG8_LDA(At, 1, 1); PG8_STAGE(PG8_SB(1, 0), b3, voffB); PG8_STAGE(PG8_SB(1, 1), b3 + hstep, voffB); PG8_STAGE(PG8_SA(1, 0), a3, voffA);
;             PG8_WAIT_V(8); PG8_WAIT_L(0); PG8_BAR; PG8_MMA(1, 0, At, B0); PG8_MMA(1, 1, At, B1); PG8_BAR; PG8_SCHED;
	s_add_i32 s40, s65, s30
	v_lshl_add_u64 v[164:165], v[164:165], 0, s[10:11]
	s_mov_b32 m0, s40
	ds_read_b128 v[190:193], v175 offset:49152
	ds_read_b128 v[194:197], v175 offset:50176
	ds_read_b128 v[198:201], v175 offset:51200
	ds_read_b128 v[202:205], v175 offset:52224
	ds_read_b128 v[206:209], v175 offset:53248
	ds_read_b128 v[210:213], v175 offset:54272
	ds_read_b128 v[214:217], v175 offset:55296
	ds_read_b128 v[218:221], v175 offset:56320
	global_load_lds_dwordx4 v[164:165], off
	s_add_i32 m0, s40, 0x2000
	s_add_u32 s38, s38, 0x10080
	v_lshl_add_u64 v[164:165], v[222:223], 0, s[10:11]
	s_addc_u32 s39, s39, 0
	s_add_i32 s40, s66, s30
	global_load_lds_dwordx4 v[164:165], off
	v_lshl_add_u64 v[164:165], s[38:39], 0, v[146:147]
	s_mov_b32 m0, s40
	s_nop 0
	global_load_lds_dwordx4 v[164:165], off
	v_lshl_add_u64 v[164:165], s[38:39], 0, v[150:151]
	s_add_i32 m0, s40, 0x2000
	s_nop 0
	global_load_lds_dwordx4 v[164:165], off
	v_lshl_add_u64 v[164:165], v[224:225], 0, s[10:11]
	s_mov_b32 m0, s47
	s_nop 0
	global_load_lds_dwordx4 v[164:165], off
	v_lshl_add_u64 v[164:165], v[226:227], 0, s[10:11]
	s_mov_b32 m0, s48
	s_nop 0
	global_load_lds_dwordx4 v[164:165], off
	s_waitcnt vmcnt(8)
	s_waitcnt lgkmcnt(0)
	s_barrier
	s_setprio 1
	s_waitcnt lgkmcnt(0)
	v_mfma_f32_16x16x32_bf16 v[60:63], v[128:131], v[190:193], v[60:63]
	v_mfma_f32_16x16x32_bf16 v[56:59], v[136:139], v[190:193], v[56:59]
	v_mfma_f32_16x16x32_bf16 v[44:47], v[128:131], v[198:201], v[44:47]
	v_mfma_f32_16x16x32_bf16 v[40:43], v[136:139], v[198:201], v[40:43]
	v_mfma_f32_16x16x32_bf16 v[28:31], v[128:131], v[206:209], v[28:31]
	v_mfma_f32_16x16x32_bf16 v[24:27], v[136:139], v[206:209], v[24:27]
	v_mfma_f32_16x16x32_bf16 v[12:15], v[128:131], v[214:217], v[12:15]
	v_mfma_f32_16x16x32_bf16 v[8:11], v[136:139], v[214:217], v[8:11]
	v_mfma_f32_16x16x32_bf16 v[60:63], v[132:135], v[194:197], v[60:63]
	v_mfma_f32_16x16x32_bf16 v[56:59], v[140:143], v[194:197], v[56:59]
	v_mfma_f32_16x16x32_bf16 v[44:47], v[132:135], v[202:205], v[44:47]
	v_mfma_f32_16x16x32_bf16 v[40:43], v[140:143], v[202:205], v[40:43]
	v_mfma_f32_16x16x32_bf16 v[28:31], v[132:135], v[210:213], v[28:31]
	v_mfma_f32_16x16x32_bf16 v[24:27], v[140:143], v[210:213], v[24:27]
	v_mfma_f32_16x16x32_bf16 v[12:15], v[132:135], v[218:221], v[12:15]
	v_mfma_f32_16x16x32_bf16 v[8:11], v[140:143], v[218:221], v[8:11]
	s_setprio 0
	s_setprio 1
	v_mfma_f32_16x16x32_bf16 v[52:55], v[160:163], v[190:193], v[52:55]
	v_mfma_f32_16x16x32_bf16 v[48:51], v[182:185], v[190:193], v[48:51]
	v_mfma_f32_16x16x32_bf16 v[36:39], v[160:163], v[198:201], v[36:39]
	v_mfma_f32_16x16x32_bf16 v[32:35], v[182:185], v[198:201], v[32:35]
	v_mfma_f32_16x16x32_bf16 v[20:23], v[160:163], v[206:209], v[20:23]
	v_mfma_f32_16x16x32_bf16 v[16:19], v[182:185], v[206:209], v[16:19]
	v_mfma_f32_16x16x32_bf16 v[4:7], v[160:163], v[214:217], v[4:7]
	v_mfma_f32_16x16x32_bf16 v[0:3], v[182:185], v[214:217], v[0:3]
	v_mfma_f32_16x16x32_bf16 v[52:55], v[178:181], v[194:197], v[52:55]
	v_mfma_f32_16x16x32_bf16 v[48:51], v[186:189], v[194:197], v[48:51]
	v_mfma_f32_16x16x32_bf16 v[36:39], v[178:181], v[202:205], v[36:39]
	v_mfma_f32_16x16x32_bf16 v[32:35], v[186:189], v[202:205], v[32:35]
	v_mfma_f32_16x16x32_bf16 v[20:23], v[178:181], v[210:213], v[20:23]
	v_mfma_f32_16x16x32_bf16 v[16:19], v[186:189], v[210:213], v[16:19]
	v_mfma_f32_16x16x32_bf16 v[4:7], v[178:181], v[218:221], v[4:7]
	v_mfma_f32_16x16x32_bf16 v[0:3], v[186:189], v[218:221], v[0:3]
	s_setprio 0
	s_barrier
	s_add_i32 s64, s64, 2
	s_add_u32 s36, s36, 0x100
	s_addc_u32 s37, s37, 0
	s_add_u32 s62, s62, 0x100
	s_addc_u32 s63, s63, 0
	s_cmp_gt_u32 s64, 13
	s_cbranch_scc0 .LBB0_1556
	v_mbcnt_lo_u32_b32 v234, -1, 0
	v_mbcnt_hi_u32_b32 v234, -1, v234
	v_bfe_u32 v234, v234, 3, 1
	v_sub_u32_e32 v249, 0, v234
	v_and_b32_e32 v248, 0xffff0040, v249
	v_and_b32_e32 v235, 0xffc0, v249
	v_sub_u32_e32 v250, 0x10000, v235
	v_mov_b32_e32 v251, 0
	s_mov_b32 s98, 0xff00ff
	s_mov_b32 s99, 0xff00ff
	s_and_b64 vcc, exec, s[12:13]
	s_cbranch_vccz .LBB0_1559
	s_barrier
.LBB0_1559:
	s_mov_b64 s[36:37], -1
	s_and_b64 vcc, exec, s[6:7]
	v_lshl_add_u32 v160, s34, 8, v168
	v_lshl_or_b32 v162, s59, 8, v172
	v_add_u32_e32 v162, s100, v162
	s_cbranch_vccnz .LBB0_1562
	s_andn2_b64 vcc, exec, s[36:37]
	s_cbranch_vccz .LBB0_1563

; __device__ __forceinline__ unsigned cvt_pk_bf16(float lo, float hi) { const f32x2_t v = {lo, hi}; const bf16x2_t b = __builtin_convertvector(v, bf16x2_t); return __builtin_bit_cast(unsigned, b); }
;     __device__ __forceinline__ void operator()(const f32x4 (&acc)[2][2][4][2], const Unit& u, int wr, int wc, int fr, int fq, const PG8_LAS float* tab) const {
;     ...
;             for (int m = 0; m < 4; ++m) { const int row = row0 + ai * HALF + m * 16; bf16_t* rowp = O + (size_t)row * ldc + col0;
;                 const float rstd = tab[rl0 + ai * HALF + m * 16];
; #pragma unroll
;                 for (int bj = 0; bj < 2; ++bj) { f32x4 v0 = acc[ai][bj][m][0] * rstd, v1 = acc[ai][bj][m][1] * rstd;
;                     if (ACT == 1) {
; #pragma unroll
;                         for (int e = 0; e < 4; ++e) { float a = v0[e] > 0.f ? v0[e] : 0.f; v0[e] = a * a; float b = v1[e] > 0.f ? v1[e] : 0.f; v1[e] = b * b; } }
;                     u32x4 w; w.x = cvt_pk_bf16(v0[0], v0[1]); w.y = cvt_pk_bf16(v0[2], v0[3]); w.z = cvt_pk_bf16(v1[0], v1[1]); w.w = cvt_pk_bf16(v1[2], v1[3]);
;                     *(u32x4*)(rowp + bj * HALF) = w; } }
.LBB0_1563:
	s_nop 0
	v_lshl_or_b32 v128, s24, 8, v167
	v_ashrrev_i32_e32 v129, 31, v128
	v_readlane_b32 s6, v254, 41
	v_lshlrev_b64 v[128:129], 6, v[128:129]
	v_readlane_b32 s7, v254, 42
	v_ashrrev_i32_e32 v161, 31, v160
	v_ashrrev_i32_e32 v163, 31, v162
	v_lshl_add_u64 v[140:141], s[6:7], 0, v[128:129]
	s_lshl_b32 s6, s31, 10
	s_and_b32 s6, s6, 0x400
	v_add_u32_e32 v177, s6, v170
	global_load_dwordx4 v[128:131], v[140:141], off offset:48
	global_load_dwordx4 v[132:135], v[140:141], off offset:32
	global_load_dwordx4 v[136:139], v[140:141], off offset:16
	s_nop 0
	global_load_dwordx4 v[140:143], v[140:141], off
	ds_read2_b32 v[178:179], v177 offset1:16
	v_lshlrev_b64 v[164:165], 13, v[160:161]
	v_lshl_add_u64 v[180:181], s[92:93], 0, v[164:165]
	v_lshlrev_b64 v[164:165], 1, v[162:163]
	v_lshl_add_u64 v[162:163], v[180:181], 0, v[164:165]
	s_waitcnt lgkmcnt(0)
	v_pk_mul_f32 v[120:121], v[120:121], v[178:179] op_sel_hi:[1,0]
	v_pk_mul_f32 v[126:127], v[126:127], v[178:179] op_sel_hi:[1,0]
	v_max_f32_e32 v121, 0, v121
	v_max_f32_e32 v120, 0, v120
	v_pk_mul_f32 v[124:125], v[124:125], v[178:179] op_sel_hi:[1,0]
	v_pk_mul_f32 v[122:123], v[122:123], v[178:179] op_sel_hi:[1,0]
	v_pk_mul_f32 v[180:181], v[120:121], v[120:121]
	v_max_f32_e32 v121, 0, v127
	v_max_f32_e32 v120, 0, v126
	v_max_f32_e32 v125, 0, v125
	v_max_f32_e32 v124, 0, v124
	v_pk_mul_f32 v[126:127], v[120:121], v[120:121]
	v_max_f32_e32 v121, 0, v123
	v_max_f32_e32 v120, 0, v122
	v_pk_mul_f32 v[124:125], v[124:125], v[124:125]
	v_pk_mul_f32 v[182:183], v[120:121], v[120:121]
	v_pk_mul_f32 v[112:113], v[112:113], v[178:179] op_sel_hi:[1,0]
	v_cvt_pk_bf16_f32 v120, v124, v125
	v_cvt_pk_bf16_f32 v121, v126, v127
	v_cvt_pk_bf16_f32 v122, v180, v181
	v_cvt_pk_bf16_f32 v123, v182, v183
	v_pk_mul_f32 v[118:119], v[118:119], v[178:179] op_sel_hi:[1,0]
	v_max_f32_e32 v113, 0, v113
	v_max_f32_e32 v112, 0, v112
	v_mov_b32_e32 v236, v120
	v_mov_b32_e32 v237, v121
	v_mov_b32_e32 v238, v122
	v_mov_b32_e32 v239, v123
	v_lshl_add_u64 v[230:231], v[162:163], 0, v[248:249]
	v_lshl_add_u64 v[232:233], v[162:163], 0, v[250:251]
	v_pk_mul_f32 v[116:117], v[116:117], v[178:179] op_sel_hi:[1,0]
	v_pk_mul_f32 v[114:115], v[114:115], v[178:179] op_sel_hi:[1,0]
	v_pk_mul_f32 v[120:121], v[112:113], v[112:113]
	v_max_f32_e32 v113, 0, v119
	v_max_f32_e32 v112, 0, v118
	v_max_f32_e32 v117, 0, v117
	v_max_f32_e32 v116, 0, v116
	v_pk_mul_f32 v[118:119], v[112:113], v[112:113]
	v_max_f32_e32 v113, 0, v115
	v_max_f32_e32 v112, 0, v114
	v_pk_mul_f32 v[116:117], v[116:117], v[116:117]
	v_pk_mul_f32 v[122:123], v[112:113], v[112:113]
	v_cvt_pk_bf16_f32 v112, v116, v117
	v_cvt_pk_bf16_f32 v113, v118, v119
	v_cvt_pk_bf16_f32 v114, v120, v121
	v_cvt_pk_bf16_f32 v115, v122, v123
	ds_swizzle_b32 v240, v112 offset:swizzle(SWAP,8)
	ds_swizzle_b32 v241, v113 offset:swizzle(SWAP,8)
	ds_swizzle_b32 v242, v114 offset:swizzle(SWAP,8)
	ds_swizzle_b32 v243, v115 offset:swizzle(SWAP,8)
	ds_swizzle_b32 v244, v236 offset:swizzle(SWAP,8)
	ds_swizzle_b32 v245, v237 offset:swizzle(SWAP,8)
	ds_swizzle_b32 v246, v238 offset:swizzle(SWAP,8)
	ds_swizzle_b32 v247, v239 offset:swizzle(SWAP,8)
	s_waitcnt lgkmcnt(0)
	v_cndmask_b32_e64 v240, v240, v236, s[98:99]
	v_cndmask_b32_e64 v241, v241, v237, s[98:99]
	v_cndmask_b32_e64 v242, v242, v238, s[98:99]
	v_cndmask_b32_e64 v243, v243, v239, s[98:99]
	v_cndmask_b32_e64 v244, v112, v244, s[98:99]
	v_cndmask_b32_e64 v245, v113, v245, s[98:99]
	v_cndmask_b32_e64 v246, v114, v246, s[98:99]
	v_cndmask_b32_e64 v247, v115, v247, s[98:99]
	global_store_dwordx4 v[230:231], v[240:243], off
	global_store_dwordx4 v[232:233], v[244:247], off
	s_nop 1
	v_mov_b32_e32 v114, v179
	v_pk_mul_f32 v[104:105], v[104:105], v[114:115] op_sel_hi:[1,0]
	v_or_b32_e32 v112, 16, v160
	v_pk_mul_f32 v[110:111], v[110:111], v[114:115] op_sel_hi:[1,0]
	v_max_f32_e32 v105, 0, v105
	v_max_f32_e32 v104, 0, v104
	v_ashrrev_i32_e32 v113, 31, v112
	v_pk_mul_f32 v[108:109], v[108:109], v[114:115] op_sel_hi:[1,0]
	v_pk_mul_f32 v[106:107], v[106:107], v[114:115] op_sel_hi:[1,0]
	v_pk_mul_f32 v[116:117], v[104:105], v[104:105]
	v_max_f32_e32 v105, 0, v111
	v_max_f32_e32 v104, 0, v110
	v_lshlrev_b64 v[112:113], 13, v[112:113]
	v_max_f32_e32 v109, 0, v109
	v_max_f32_e32 v108, 0, v108
	v_pk_mul_f32 v[110:111], v[104:105], v[104:105]
	v_max_f32_e32 v105, 0, v107
	v_max_f32_e32 v104, 0, v106
	v_lshl_add_u64 v[112:113], s[92:93], 0, v[112:113]
	v_pk_mul_f32 v[108:109], v[108:109], v[108:109]
	v_pk_mul_f32 v[118:119], v[104:105], v[104:105]
	v_pk_mul_f32 v[96:97], v[96:97], v[114:115] op_sel_hi:[1,0]
	v_lshl_add_u64 v[112:113], v[112:113], 0, v[164:165]
	v_cvt_pk_bf16_f32 v104, v108, v109
	v_cvt_pk_bf16_f32 v105, v110, v111
	v_cvt_pk_bf16_f32 v106, v116, v117
	v_cvt_pk_bf16_f32 v107, v118, v119
	v_pk_mul_f32 v[102:103], v[102:103], v[114:115] op_sel_hi:[1,0]
	v_max_f32_e32 v97, 0, v97
	v_max_f32_e32 v96, 0, v96
	v_mov_b32_e32 v236, v104
	v_mov_b32_e32 v237, v105
	v_mov_b32_e32 v238, v106
	v_mov_b32_e32 v239, v107
	v_lshl_add_u64 v[230:231], v[112:113], 0, v[248:249]
	v_lshl_add_u64 v[232:233], v[112:113], 0, v[250:251]
	v_pk_mul_f32 v[100:101], v[100:101], v[114:115] op_sel_hi:[1,0]
	v_pk_mul_f32 v[98:99], v[98:99], v[114:115] op_sel_hi:[1,0]
	v_pk_mul_f32 v[104:105], v[96:97], v[96:97]
	v_max_f32_e32 v97, 0, v103
	v_max_f32_e32 v96, 0, v102
	v_max_f32_e32 v101, 0, v101
	v_max_f32_e32 v100, 0, v100
	v_pk_mul_f32 v[102:103], v[96:97], v[96:97]
	v_max_f32_e32 v97, 0, v99
	v_max_f32_e32 v96, 0, v98
	v_pk_mul_f32 v[100:101], v[100:101], v[100:101]
	v_pk_mul_f32 v[106:107], v[96:97], v[96:97]
	v_cvt_pk_bf16_f32 v96, v100, v101
	v_cvt_pk_bf16_f32 v97, v102, v103
	v_cvt_pk_bf16_f32 v98, v104, v105
	v_cvt_pk_bf16_f32 v99, v106, v107
	ds_swizzle_b32 v240, v96 offset:swizzle(SWAP,8)
	ds_swizzle_b32 v241, v97 offset:swizzle(SWAP,8)
	ds_swizzle_b32 v242, v98 offset:swizzle(SWAP,8)
	ds_swizzle_b32 v243, v99 offset:swizzle(SWAP,8)
	ds_swizzle_b32 v244, v236 offset:swizzle(SWAP,8)
	ds_swizzle_b32 v245, v237 offset:swizzle(SWAP,8)
	ds_swizzle_b32 v246, v238 offset:swizzle(SWAP,8)
	ds_swizzle_b32 v247, v239 offset:swizzle(SWAP,8)
	s_waitcnt lgkmcnt(0)
; __device__ __forceinline__ unsigned cvt_pk_bf16(float lo, float hi) { const f32x2_t v = {lo, hi}; const bf16x2_t b = __builtin_convertvector(v, bf16x2_t); return __builtin_bit_cast(unsigned, b); }
;     __device__ __forceinline__ void operator()(const f32x4 (&acc)[2][2][4][2], const Unit& u, int wr, int wc, int fr, int fq, const PG8_LAS float* tab) const {
;     ...
;             for (int m = 0; m < 4; ++m) { const int row = row0 + ai * HALF + m * 16; bf16_t* rowp = O + (size_t)row * ldc + col0;
;                 const float rstd = tab[rl0 + ai * HALF + m * 16];
; #pragma unroll
;                 for (int bj = 0; bj < 2; ++bj) { f32x4 v0 = acc[ai][bj][m][0] * rstd, v1 = acc[ai][bj][m][1] * rstd;
;                     if (ACT == 1) {
; #pragma unroll
;                         for (int e = 0; e < 4; ++e) { float a = v0[e] > 0.f ? v0[e] : 0.f; v0[e] = a * a; float b = v1[e] > 0.f ? v1[e] : 0.f; v1[e] = b * b; } }
;                     u32x4 w; w.x = cvt_pk_bf16(v0[0], v0[1]); w.y = cvt_pk_bf16(v0[2], v0[3]); w.z = cvt_pk_bf16(v1[0], v1[1]); w.w = cvt_pk_bf16(v1[2], v1[3]);
;                     *(u32x4*)(rowp + bj * HALF) = w; } }
	v_cndmask_b32_e64 v240, v240, v236, s[98:99]
	v_cndmask_b32_e64 v241, v241, v237, s[98:99]
	v_cndmask_b32_e64 v242, v242, v238, s[98:99]
	v_cndmask_b32_e64 v243, v243, v239, s[98:99]
	v_cndmask_b32_e64 v244, v96, v244, s[98:99]
	v_cndmask_b32_e64 v245, v97, v245, s[98:99]
	v_cndmask_b32_e64 v246, v98, v246, s[98:99]
	v_cndmask_b32_e64 v247, v99, v247, s[98:99]
	global_store_dwordx4 v[230:231], v[240:243], off
	global_store_dwordx4 v[232:233], v[244:247], off
	ds_read2_b32 v[98:99], v177 offset0:32 offset1:48
	s_waitcnt lgkmcnt(0)
	v_pk_mul_f32 v[88:89], v[88:89], v[98:99] op_sel_hi:[1,0]
	v_or_b32_e32 v96, 32, v160
	v_pk_mul_f32 v[94:95], v[94:95], v[98:99] op_sel_hi:[1,0]
	v_max_f32_e32 v89, 0, v89
	v_max_f32_e32 v88, 0, v88
	v_ashrrev_i32_e32 v97, 31, v96
	v_pk_mul_f32 v[92:93], v[92:93], v[98:99] op_sel_hi:[1,0]
	v_pk_mul_f32 v[90:91], v[90:91], v[98:99] op_sel_hi:[1,0]
	v_pk_mul_f32 v[100:101], v[88:89], v[88:89]
	v_max_f32_e32 v89, 0, v95
	v_max_f32_e32 v88, 0, v94
	v_lshlrev_b64 v[96:97], 13, v[96:97]
	v_max_f32_e32 v93, 0, v93
	v_max_f32_e32 v92, 0, v92
	v_pk_mul_f32 v[94:95], v[88:89], v[88:89]
	v_max_f32_e32 v89, 0, v91
	v_max_f32_e32 v88, 0, v90
	v_lshl_add_u64 v[96:97], s[92:93], 0, v[96:97]
	v_pk_mul_f32 v[92:93], v[92:93], v[92:93]
	v_pk_mul_f32 v[102:103], v[88:89], v[88:89]
	v_pk_mul_f32 v[80:81], v[80:81], v[98:99] op_sel_hi:[1,0]
	v_lshl_add_u64 v[96:97], v[96:97], 0, v[164:165]
	v_cvt_pk_bf16_f32 v88, v92, v93
	v_cvt_pk_bf16_f32 v89, v94, v95
	v_cvt_pk_bf16_f32 v90, v100, v101
	v_cvt_pk_bf16_f32 v91, v102, v103
	v_pk_mul_f32 v[86:87], v[86:87], v[98:99] op_sel_hi:[1,0]
	v_max_f32_e32 v81, 0, v81
	v_max_f32_e32 v80, 0, v80
	v_mov_b32_e32 v236, v88
	v_mov_b32_e32 v237, v89
	v_mov_b32_e32 v238, v90
	v_mov_b32_e32 v239, v91
	v_lshl_add_u64 v[230:231], v[96:97], 0, v[248:249]
	v_lshl_add_u64 v[232:233], v[96:97], 0, v[250:251]
	v_pk_mul_f32 v[84:85], v[84:85], v[98:99] op_sel_hi:[1,0]
	v_pk_mul_f32 v[82:83], v[82:83], v[98:99] op_sel_hi:[1,0]
	v_pk_mul_f32 v[88:89], v[80:81], v[80:81]
	v_max_f32_e32 v81, 0, v87
	v_max_f32_e32 v80, 0, v86
	v_max_f32_e32 v85, 0, v85
	v_max_f32_e32 v84, 0, v84
	v_pk_mul_f32 v[86:87], v[80:81], v[80:81]
	v_max_f32_e32 v81, 0, v83
	v_max_f32_e32 v80, 0, v82
	v_pk_mul_f32 v[84:85], v[84:85], v[84:85]
	v_pk_mul_f32 v[90:91], v[80:81], v[80:81]
	v_cvt_pk_bf16_f32 v80, v84, v85
	v_cvt_pk_bf16_f32 v81, v86, v87
	v_cvt_pk_bf16_f32 v82, v88, v89
	v_cvt_pk_bf16_f32 v83, v90, v91
	ds_swizzle_b32 v240, v80 offset:swizzle(SWAP,8)
	ds_swizzle_b32 v241, v81 offset:swizzle(SWAP,8)
	ds_swizzle_b32 v242, v82 offset:swizzle(SWAP,8)
	ds_swizzle_b32 v243, v83 offset:swizzle(SWAP,8)
	ds_swizzle_b32 v244, v236 offset:swizzle(SWAP,8)
	ds_swizzle_b32 v245, v237 offset:swizzle(SWAP,8)
	ds_swizzle_b32 v246, v238 offset:swizzle(SWAP,8)
	ds_swizzle_b32 v247, v239 offset:swizzle(SWAP,8)
	s_waitcnt lgkmcnt(0)
	v_cndmask_b32_e64 v240, v240, v236, s[98:99]
	v_cndmask_b32_e64 v241, v241, v237, s[98:99]
	v_cndmask_b32_e64 v242, v242, v238, s[98:99]
	v_cndmask_b32_e64 v243, v243, v239, s[98:99]
	v_cndmask_b32_e64 v244, v80, v244, s[98:99]
	v_cndmask_b32_e64 v245, v81, v245, s[98:99]
	v_cndmask_b32_e64 v246, v82, v246, s[98:99]
	v_cndmask_b32_e64 v247, v83, v247, s[98:99]
	global_store_dwordx4 v[230:231], v[240:243], off
	global_store_dwordx4 v[232:233], v[244:247], off
	s_nop 1
	v_mov_b32_e32 v82, v99
	v_pk_mul_f32 v[72:73], v[72:73], v[82:83] op_sel_hi:[1,0]
	v_or_b32_e32 v80, 48, v160
	v_pk_mul_f32 v[78:79], v[78:79], v[82:83] op_sel_hi:[1,0]
	v_max_f32_e32 v73, 0, v73
	v_max_f32_e32 v72, 0, v72
	v_ashrrev_i32_e32 v81, 31, v80
	v_pk_mul_f32 v[76:77], v[76:77], v[82:83] op_sel_hi:[1,0]
	v_pk_mul_f32 v[74:75], v[74:75], v[82:83] op_sel_hi:[1,0]
	v_pk_mul_f32 v[84:85], v[72:73], v[72:73]
	v_max_f32_e32 v73, 0, v79
	v_max_f32_e32 v72, 0, v78
	v_lshlrev_b64 v[80:81], 13, v[80:81]
	v_max_f32_e32 v77, 0, v77
	v_max_f32_e32 v76, 0, v76
	v_pk_mul_f32 v[78:79], v[72:73], v[72:73]
	v_max_f32_e32 v73, 0, v75
	v_max_f32_e32 v72, 0, v74
	v_lshl_add_u64 v[80:81], s[92:93], 0, v[80:81]
	v_pk_mul_f32 v[76:77], v[76:77], v[76:77]
	v_pk_mul_f32 v[86:87], v[72:73], v[72:73]
	v_pk_mul_f32 v[64:65], v[64:65], v[82:83] op_sel_hi:[1,0]
	v_lshl_add_u64 v[80:81], v[80:81], 0, v[164:165]
	v_cvt_pk_bf16_f32 v72, v76, v77
	v_cvt_pk_bf16_f32 v73, v78, v79
	v_cvt_pk_bf16_f32 v74, v84, v85
	v_cvt_pk_bf16_f32 v75, v86, v87
	v_pk_mul_f32 v[70:71], v[70:71], v[82:83] op_sel_hi:[1,0]
	v_pk_mul_f32 v[68:69], v[68:69], v[82:83] op_sel_hi:[1,0]
	v_max_f32_e32 v65, 0, v65
	v_max_f32_e32 v64, 0, v64
	v_mov_b32_e32 v236, v72
	v_mov_b32_e32 v237, v73
	v_mov_b32_e32 v238, v74
	v_mov_b32_e32 v239, v75
	v_lshl_add_u64 v[230:231], v[80:81], 0, v[248:249]
	v_lshl_add_u64 v[232:233], v[80:81], 0, v[250:251]
	v_pk_mul_f32 v[66:67], v[66:67], v[82:83] op_sel_hi:[1,0]
	v_max_f32_e32 v69, 0, v69
	v_max_f32_e32 v68, 0, v68
	v_pk_mul_f32 v[72:73], v[64:65], v[64:65]
	v_max_f32_e32 v65, 0, v71
	v_max_f32_e32 v64, 0, v70
	v_pk_mul_f32 v[68:69], v[68:69], v[68:69]
	v_pk_mul_f32 v[70:71], v[64:65], v[64:65]
	v_max_f32_e32 v65, 0, v67
	v_max_f32_e32 v64, 0, v66
	v_pk_mul_f32 v[74:75], v[64:65], v[64:65]
	v_cvt_pk_bf16_f32 v64, v68, v69
	ds_read2_b32 v[68:69], v177 offset0:128 offset1:144
	v_cvt_pk_bf16_f32 v65, v70, v71
	v_cvt_pk_bf16_f32 v66, v72, v73
	v_cvt_pk_bf16_f32 v67, v74, v75
	ds_swizzle_b32 v240, v64 offset:swizzle(SWAP,8)
	ds_swizzle_b32 v241, v65 offset:swizzle(SWAP,8)
	ds_swizzle_b32 v242, v66 offset:swizzle(SWAP,8)
	ds_swizzle_b32 v243, v67 offset:swizzle(SWAP,8)
	ds_swizzle_b32 v244, v236 offset:swizzle(SWAP,8)
	ds_swizzle_b32 v245, v237 offset:swizzle(SWAP,8)
	ds_swizzle_b32 v246, v238 offset:swizzle(SWAP,8)
	ds_swizzle_b32 v247, v239 offset:swizzle(SWAP,8)
	s_waitcnt lgkmcnt(0)
; __device__ __forceinline__ unsigned cvt_pk_bf16(float lo, float hi) { const f32x2_t v = {lo, hi}; const bf16x2_t b = __builtin_convertvector(v, bf16x2_t); return __builtin_bit_cast(unsigned, b); }
;     __device__ __forceinline__ void operator()(const f32x4 (&acc)[2][2][4][2], const Unit& u, int wr, int wc, int fr, int fq, const PG8_LAS float* tab) const {
;     ...
;             for (int m = 0; m < 4; ++m) { const int row = row0 + ai * HALF + m * 16; bf16_t* rowp = O + (size_t)row * ldc + col0;
;                 const float rstd = tab[rl0 + ai * HALF + m * 16];
; #pragma unroll
;                 for (int bj = 0; bj < 2; ++bj) { f32x4 v0 = acc[ai][bj][m][0] * rstd, v1 = acc[ai][bj][m][1] * rstd;
;                     if (ACT == 1) {
; #pragma unroll
;                         for (int e = 0; e < 4; ++e) { float a = v0[e] > 0.f ? v0[e] : 0.f; v0[e] = a * a; float b = v1[e] > 0.f ? v1[e] : 0.f; v1[e] = b * b; } }
;                     u32x4 w; w.x = cvt_pk_bf16(v0[0], v0[1]); w.y = cvt_pk_bf16(v0[2], v0[3]); w.z = cvt_pk_bf16(v1[0], v1[1]); w.w = cvt_pk_bf16(v1[2], v1[3]);
;                     *(u32x4*)(rowp + bj * HALF) = w; } }
	v_cndmask_b32_e64 v240, v240, v236, s[98:99]
	v_cndmask_b32_e64 v241, v241, v237, s[98:99]
	v_cndmask_b32_e64 v242, v242, v238, s[98:99]
	v_cndmask_b32_e64 v243, v243, v239, s[98:99]
	v_cndmask_b32_e64 v244, v64, v244, s[98:99]
	v_cndmask_b32_e64 v245, v65, v245, s[98:99]
	v_cndmask_b32_e64 v246, v66, v246, s[98:99]
	v_cndmask_b32_e64 v247, v67, v247, s[98:99]
	global_store_dwordx4 v[230:231], v[240:243], off
	global_store_dwordx4 v[232:233], v[244:247], off
	s_waitcnt lgkmcnt(0)
	v_pk_mul_f32 v[56:57], v[56:57], v[68:69] op_sel_hi:[1,0]
	v_pk_mul_f32 v[62:63], v[62:63], v[68:69] op_sel_hi:[1,0]
	v_pk_mul_f32 v[60:61], v[60:61], v[68:69] op_sel_hi:[1,0]
	v_max_f32_e32 v57, 0, v57
	v_max_f32_e32 v56, 0, v56
	v_pk_mul_f32 v[58:59], v[58:59], v[68:69] op_sel_hi:[1,0]
	v_max_f32_e32 v61, 0, v61
	v_max_f32_e32 v60, 0, v60
	v_pk_mul_f32 v[66:67], v[56:57], v[56:57]
	v_max_f32_e32 v57, 0, v63
	v_max_f32_e32 v56, 0, v62
	v_pk_mul_f32 v[60:61], v[60:61], v[60:61]
	v_pk_mul_f32 v[62:63], v[56:57], v[56:57]
	v_max_f32_e32 v57, 0, v59
	v_max_f32_e32 v56, 0, v58
	v_pk_mul_f32 v[70:71], v[56:57], v[56:57]
	v_cvt_pk_bf16_f32 v56, v60, v61
	v_add_co_u32_e32 v60, vcc, s53, v162
	v_pk_mul_f32 v[48:49], v[48:49], v[68:69] op_sel_hi:[1,0]
	v_cvt_pk_bf16_f32 v57, v62, v63
	v_cvt_pk_bf16_f32 v58, v66, v67
	v_cvt_pk_bf16_f32 v59, v70, v71
	v_addc_co_u32_e32 v61, vcc, 0, v163, vcc
	v_pk_mul_f32 v[54:55], v[54:55], v[68:69] op_sel_hi:[1,0]
	v_max_f32_e32 v49, 0, v49
	v_max_f32_e32 v48, 0, v48
	v_mov_b32_e32 v236, v56
	v_mov_b32_e32 v237, v57
	v_mov_b32_e32 v238, v58
	v_mov_b32_e32 v239, v59
	v_lshl_add_u64 v[230:231], v[60:61], 0, v[248:249]
	v_lshl_add_u64 v[232:233], v[60:61], 0, v[250:251]
	v_pk_mul_f32 v[52:53], v[52:53], v[68:69] op_sel_hi:[1,0]
	v_pk_mul_f32 v[50:51], v[50:51], v[68:69] op_sel_hi:[1,0]
	v_pk_mul_f32 v[56:57], v[48:49], v[48:49]
	v_max_f32_e32 v49, 0, v55
	v_max_f32_e32 v48, 0, v54
	v_max_f32_e32 v53, 0, v53
	v_max_f32_e32 v52, 0, v52
	v_pk_mul_f32 v[54:55], v[48:49], v[48:49]
	v_max_f32_e32 v49, 0, v51
	v_max_f32_e32 v48, 0, v50
	v_pk_mul_f32 v[52:53], v[52:53], v[52:53]
	v_pk_mul_f32 v[58:59], v[48:49], v[48:49]
	v_lshl_add_u64 v[64:65], v[162:163], 0, s[14:15]
	v_cvt_pk_bf16_f32 v48, v52, v53
	v_cvt_pk_bf16_f32 v49, v54, v55
	v_cvt_pk_bf16_f32 v50, v56, v57
	v_cvt_pk_bf16_f32 v51, v58, v59
	ds_swizzle_b32 v240, v48 offset:swizzle(SWAP,8)
	ds_swizzle_b32 v241, v49 offset:swizzle(SWAP,8)
	ds_swizzle_b32 v242, v50 offset:swizzle(SWAP,8)
	ds_swizzle_b32 v243, v51 offset:swizzle(SWAP,8)
	ds_swizzle_b32 v244, v236 offset:swizzle(SWAP,8)
	ds_swizzle_b32 v245, v237 offset:swizzle(SWAP,8)
	ds_swizzle_b32 v246, v238 offset:swizzle(SWAP,8)
	ds_swizzle_b32 v247, v239 offset:swizzle(SWAP,8)
	s_waitcnt lgkmcnt(0)
	v_cndmask_b32_e64 v240, v240, v236, s[98:99]
	v_cndmask_b32_e64 v241, v241, v237, s[98:99]
	v_cndmask_b32_e64 v242, v242, v238, s[98:99]
	v_cndmask_b32_e64 v243, v243, v239, s[98:99]
	v_cndmask_b32_e64 v244, v48, v244, s[98:99]
	v_cndmask_b32_e64 v245, v49, v245, s[98:99]
	v_cndmask_b32_e64 v246, v50, v246, s[98:99]
	v_cndmask_b32_e64 v247, v51, v247, s[98:99]
	global_store_dwordx4 v[230:231], v[240:243], off
	global_store_dwordx4 v[232:233], v[244:247], off
	s_nop 1
	v_mov_b32_e32 v50, v69
	v_pk_mul_f32 v[40:41], v[40:41], v[50:51] op_sel_hi:[1,0]
	v_pk_mul_f32 v[46:47], v[46:47], v[50:51] op_sel_hi:[1,0]
	v_pk_mul_f32 v[44:45], v[44:45], v[50:51] op_sel_hi:[1,0]
	v_max_f32_e32 v41, 0, v41
	v_max_f32_e32 v40, 0, v40
	v_pk_mul_f32 v[42:43], v[42:43], v[50:51] op_sel_hi:[1,0]
	v_max_f32_e32 v45, 0, v45
	v_max_f32_e32 v44, 0, v44
	v_pk_mul_f32 v[52:53], v[40:41], v[40:41]
	v_max_f32_e32 v41, 0, v47
	v_max_f32_e32 v40, 0, v46
	v_pk_mul_f32 v[44:45], v[44:45], v[44:45]
	v_pk_mul_f32 v[46:47], v[40:41], v[40:41]
	v_max_f32_e32 v41, 0, v43
	v_max_f32_e32 v40, 0, v42
	v_pk_mul_f32 v[54:55], v[40:41], v[40:41]
	v_cvt_pk_bf16_f32 v40, v44, v45
	v_add_co_u32_e32 v44, vcc, s54, v162
	v_pk_mul_f32 v[32:33], v[32:33], v[50:51] op_sel_hi:[1,0]
	v_cvt_pk_bf16_f32 v41, v46, v47
	v_cvt_pk_bf16_f32 v42, v52, v53
	v_cvt_pk_bf16_f32 v43, v54, v55
	v_addc_co_u32_e32 v45, vcc, 0, v163, vcc
	v_pk_mul_f32 v[38:39], v[38:39], v[50:51] op_sel_hi:[1,0]
	v_pk_mul_f32 v[36:37], v[36:37], v[50:51] op_sel_hi:[1,0]
	v_max_f32_e32 v33, 0, v33
	v_max_f32_e32 v32, 0, v32
	v_mov_b32_e32 v236, v40
	v_mov_b32_e32 v237, v41
	v_mov_b32_e32 v238, v42
	v_mov_b32_e32 v239, v43
	v_lshl_add_u64 v[230:231], v[44:45], 0, v[248:249]
	v_lshl_add_u64 v[232:233], v[44:45], 0, v[250:251]
	v_pk_mul_f32 v[34:35], v[34:35], v[50:51] op_sel_hi:[1,0]
	v_max_f32_e32 v37, 0, v37
	v_max_f32_e32 v36, 0, v36
	v_pk_mul_f32 v[40:41], v[32:33], v[32:33]
	v_max_f32_e32 v33, 0, v39
	v_max_f32_e32 v32, 0, v38
	v_pk_mul_f32 v[36:37], v[36:37], v[36:37]
	v_pk_mul_f32 v[38:39], v[32:33], v[32:33]
	v_max_f32_e32 v33, 0, v35
	v_max_f32_e32 v32, 0, v34
	v_pk_mul_f32 v[42:43], v[32:33], v[32:33]
	v_cvt_pk_bf16_f32 v32, v36, v37
	ds_read2_b32 v[36:37], v177 offset0:160 offset1:176
	v_lshl_add_u64 v[48:49], v[162:163], 0, s[16:17]
	v_cvt_pk_bf16_f32 v33, v38, v39
	v_cvt_pk_bf16_f32 v34, v40, v41
	v_cvt_pk_bf16_f32 v35, v42, v43
	s_waitcnt lgkmcnt(0)
	v_pk_mul_f32 v[24:25], v[24:25], v[36:37] op_sel_hi:[1,0]
	v_pk_mul_f32 v[30:31], v[30:31], v[36:37] op_sel_hi:[1,0]
	v_pk_mul_f32 v[28:29], v[28:29], v[36:37] op_sel_hi:[1,0]
	v_max_f32_e32 v25, 0, v25
	v_max_f32_e32 v24, 0, v24
	ds_swizzle_b32 v240, v32 offset:swizzle(SWAP,8)
	ds_swizzle_b32 v241, v33 offset:swizzle(SWAP,8)
	ds_swizzle_b32 v242, v34 offset:swizzle(SWAP,8)
	ds_swizzle_b32 v243, v35 offset:swizzle(SWAP,8)
	ds_swizzle_b32 v244, v236 offset:swizzle(SWAP,8)
	ds_swizzle_b32 v245, v237 offset:swizzle(SWAP,8)
	ds_swizzle_b32 v246, v238 offset:swizzle(SWAP,8)
	ds_swizzle_b32 v247, v239 offset:swizzle(SWAP,8)
	s_waitcnt lgkmcnt(0)
; #define PG8_LAS __attribute__((address_space(3)))
; __device__ __forceinline__ unsigned cvt_pk_bf16(float lo, float hi) { const f32x2_t v = {lo, hi}; const bf16x2_t b = __builtin_convertvector(v, bf16x2_t); return __builtin_bit_cast(unsigned, b); }
;     __device__ __forceinline__ void pre_store(const Pre& p, PG8_LAS float* tab, int tid) const {
;         const float tot = ((p.s0[0] + p.s0[1]) + (p.s0[2] + p.s0[3])) + ((p.s1[0] + p.s1[1]) + (p.s1[2] + p.s1[3])) + ((p.s2[0] + p.s2[1]) + (p.s2[2] + p.s2[3])) + ((p.s3[0] + p.s3[1]) + (p.s3[2] + p.s3[3]));
;         if (tid < 256) tab[tid] = rsqrtf(tot * (1.0f / 1024.0f) + 1e-6f);
;     __device__ __forceinline__ void operator()(const f32x4 (&acc)[2][2][4][2], const Unit& u, int wr, int wc, int fr, int fq, const PG8_LAS float* tab) const {
;     ...
;             for (int m = 0; m < 4; ++m) { const int row = row0 + ai * HALF + m * 16; bf16_t* rowp = O + (size_t)row * ldc + col0;
;                 const float rstd = tab[rl0 + ai * HALF + m * 16];
; #pragma unroll
;                 for (int bj = 0; bj < 2; ++bj) { f32x4 v0 = acc[ai][bj][m][0] * rstd, v1 = acc[ai][bj][m][1] * rstd;
;                     if (ACT == 1) {
; #pragma unroll
;                         for (int e = 0; e < 4; ++e) { float a = v0[e] > 0.f ? v0[e] : 0.f; v0[e] = a * a; float b = v1[e] > 0.f ? v1[e] : 0.f; v1[e] = b * b; } }
;                     u32x4 w; w.x = cvt_pk_bf16(v0[0], v0[1]); w.y = cvt_pk_bf16(v0[2], v0[3]); w.z = cvt_pk_bf16(v1[0], v1[1]); w.w = cvt_pk_bf16(v1[2], v1[3]);
;                     *(u32x4*)(rowp + bj * HALF) = w; } }
	v_cndmask_b32_e64 v240, v240, v236, s[98:99]
	v_cndmask_b32_e64 v241, v241, v237, s[98:99]
	v_cndmask_b32_e64 v242, v242, v238, s[98:99]
	v_cndmask_b32_e64 v243, v243, v239, s[98:99]
	v_cndmask_b32_e64 v244, v32, v244, s[98:99]
	v_cndmask_b32_e64 v245, v33, v245, s[98:99]
	v_cndmask_b32_e64 v246, v34, v246, s[98:99]
	v_cndmask_b32_e64 v247, v35, v247, s[98:99]
	global_store_dwordx4 v[230:231], v[240:243], off
	global_store_dwordx4 v[232:233], v[244:247], off
	v_pk_mul_f32 v[26:27], v[26:27], v[36:37] op_sel_hi:[1,0]
	v_max_f32_e32 v29, 0, v29
	v_max_f32_e32 v28, 0, v28
	v_pk_mul_f32 v[34:35], v[24:25], v[24:25]
	v_max_f32_e32 v25, 0, v31
	v_max_f32_e32 v24, 0, v30
	v_pk_mul_f32 v[28:29], v[28:29], v[28:29]
	v_pk_mul_f32 v[30:31], v[24:25], v[24:25]
	v_max_f32_e32 v25, 0, v27
	v_max_f32_e32 v24, 0, v26
	v_pk_mul_f32 v[38:39], v[24:25], v[24:25]
	v_cvt_pk_bf16_f32 v24, v28, v29
	v_add_co_u32_e32 v28, vcc, s55, v162
	v_pk_mul_f32 v[16:17], v[16:17], v[36:37] op_sel_hi:[1,0]
	v_cvt_pk_bf16_f32 v25, v30, v31
	v_cvt_pk_bf16_f32 v26, v34, v35
	v_cvt_pk_bf16_f32 v27, v38, v39
	v_addc_co_u32_e32 v29, vcc, 0, v163, vcc
	v_pk_mul_f32 v[22:23], v[22:23], v[36:37] op_sel_hi:[1,0]
	v_max_f32_e32 v17, 0, v17
	v_max_f32_e32 v16, 0, v16
	v_mov_b32_e32 v236, v24
	v_mov_b32_e32 v237, v25
	v_mov_b32_e32 v238, v26
	v_mov_b32_e32 v239, v27
	v_lshl_add_u64 v[230:231], v[28:29], 0, v[248:249]
	v_lshl_add_u64 v[232:233], v[28:29], 0, v[250:251]
	v_pk_mul_f32 v[20:21], v[20:21], v[36:37] op_sel_hi:[1,0]
	v_pk_mul_f32 v[18:19], v[18:19], v[36:37] op_sel_hi:[1,0]
	v_pk_mul_f32 v[24:25], v[16:17], v[16:17]
	v_max_f32_e32 v17, 0, v23
	v_max_f32_e32 v16, 0, v22
	v_max_f32_e32 v21, 0, v21
	v_max_f32_e32 v20, 0, v20
	v_pk_mul_f32 v[22:23], v[16:17], v[16:17]
	v_max_f32_e32 v17, 0, v19
	v_max_f32_e32 v16, 0, v18
	v_pk_mul_f32 v[20:21], v[20:21], v[20:21]
	v_pk_mul_f32 v[26:27], v[16:17], v[16:17]
	v_lshl_add_u64 v[32:33], v[162:163], 0, s[18:19]
	v_cvt_pk_bf16_f32 v16, v20, v21
	v_cvt_pk_bf16_f32 v17, v22, v23
	v_cvt_pk_bf16_f32 v18, v24, v25
	v_cvt_pk_bf16_f32 v19, v26, v27
	ds_swizzle_b32 v240, v16 offset:swizzle(SWAP,8)
	ds_swizzle_b32 v241, v17 offset:swizzle(SWAP,8)
	ds_swizzle_b32 v242, v18 offset:swizzle(SWAP,8)
	ds_swizzle_b32 v243, v19 offset:swizzle(SWAP,8)
	ds_swizzle_b32 v244, v236 offset:swizzle(SWAP,8)
	ds_swizzle_b32 v245, v237 offset:swizzle(SWAP,8)
	ds_swizzle_b32 v246, v238 offset:swizzle(SWAP,8)
	ds_swizzle_b32 v247, v239 offset:swizzle(SWAP,8)
	s_waitcnt lgkmcnt(0)
	v_cndmask_b32_e64 v240, v240, v236, s[98:99]
	v_cndmask_b32_e64 v241, v241, v237, s[98:99]
	v_cndmask_b32_e64 v242, v242, v238, s[98:99]
	v_cndmask_b32_e64 v243, v243, v239, s[98:99]
	v_cndmask_b32_e64 v244, v16, v244, s[98:99]
	v_cndmask_b32_e64 v245, v17, v245, s[98:99]
	v_cndmask_b32_e64 v246, v18, v246, s[98:99]
	v_cndmask_b32_e64 v247, v19, v247, s[98:99]
	global_store_dwordx4 v[230:231], v[240:243], off
	global_store_dwordx4 v[232:233], v[244:247], off
	s_nop 1
	v_mov_b32_e32 v18, v37
	v_pk_mul_f32 v[8:9], v[8:9], v[18:19] op_sel_hi:[1,0]
	v_pk_mul_f32 v[14:15], v[14:15], v[18:19] op_sel_hi:[1,0]
	v_pk_mul_f32 v[12:13], v[12:13], v[18:19] op_sel_hi:[1,0]
	v_max_f32_e32 v9, 0, v9
	v_max_f32_e32 v8, 0, v8
	v_pk_mul_f32 v[10:11], v[10:11], v[18:19] op_sel_hi:[1,0]
	v_max_f32_e32 v13, 0, v13
	v_max_f32_e32 v12, 0, v12
	v_pk_mul_f32 v[20:21], v[8:9], v[8:9]
	v_max_f32_e32 v9, 0, v15
	v_max_f32_e32 v8, 0, v14
	v_pk_mul_f32 v[12:13], v[12:13], v[12:13]
	v_pk_mul_f32 v[14:15], v[8:9], v[8:9]
	v_max_f32_e32 v9, 0, v11
	v_max_f32_e32 v8, 0, v10
	v_pk_mul_f32 v[22:23], v[8:9], v[8:9]
	v_cvt_pk_bf16_f32 v8, v12, v13
	v_add_co_u32_e32 v12, vcc, s56, v162
	v_pk_mul_f32 v[0:1], v[0:1], v[18:19] op_sel_hi:[1,0]
	v_cvt_pk_bf16_f32 v9, v14, v15
	v_cvt_pk_bf16_f32 v10, v20, v21
	v_cvt_pk_bf16_f32 v11, v22, v23
	v_addc_co_u32_e32 v13, vcc, 0, v163, vcc
	v_pk_mul_f32 v[6:7], v[6:7], v[18:19] op_sel_hi:[1,0]
	v_max_f32_e32 v1, 0, v1
	v_max_f32_e32 v0, 0, v0
	v_mov_b32_e32 v236, v8
	v_mov_b32_e32 v237, v9
	v_mov_b32_e32 v238, v10
	v_mov_b32_e32 v239, v11
	v_lshl_add_u64 v[230:231], v[12:13], 0, v[248:249]
	v_lshl_add_u64 v[232:233], v[12:13], 0, v[250:251]
	v_pk_mul_f32 v[4:5], v[4:5], v[18:19] op_sel_hi:[1,0]
	v_pk_mul_f32 v[2:3], v[2:3], v[18:19] op_sel_hi:[1,0]
	v_pk_mul_f32 v[8:9], v[0:1], v[0:1]
	v_max_f32_e32 v1, 0, v7
	v_max_f32_e32 v0, 0, v6
	v_max_f32_e32 v5, 0, v5
	v_max_f32_e32 v4, 0, v4
	v_pk_mul_f32 v[6:7], v[0:1], v[0:1]
	v_max_f32_e32 v1, 0, v3
	v_max_f32_e32 v0, 0, v2
	v_pk_mul_f32 v[4:5], v[4:5], v[4:5]
	v_pk_mul_f32 v[10:11], v[0:1], v[0:1]
	v_lshl_add_u64 v[16:17], v[162:163], 0, s[20:21]
	v_cvt_pk_bf16_f32 v0, v4, v5
	v_cvt_pk_bf16_f32 v1, v6, v7
	v_cvt_pk_bf16_f32 v2, v8, v9
	v_cvt_pk_bf16_f32 v3, v10, v11
	ds_swizzle_b32 v240, v0 offset:swizzle(SWAP,8)
	ds_swizzle_b32 v241, v1 offset:swizzle(SWAP,8)
	ds_swizzle_b32 v242, v2 offset:swizzle(SWAP,8)
	ds_swizzle_b32 v243, v3 offset:swizzle(SWAP,8)
	ds_swizzle_b32 v244, v236 offset:swizzle(SWAP,8)
	ds_swizzle_b32 v245, v237 offset:swizzle(SWAP,8)
	ds_swizzle_b32 v246, v238 offset:swizzle(SWAP,8)
	ds_swizzle_b32 v247, v239 offset:swizzle(SWAP,8)
	s_waitcnt lgkmcnt(0)
	v_cndmask_b32_e64 v240, v240, v236, s[98:99]
	v_cndmask_b32_e64 v241, v241, v237, s[98:99]
	v_cndmask_b32_e64 v242, v242, v238, s[98:99]
	v_cndmask_b32_e64 v243, v243, v239, s[98:99]
	v_cndmask_b32_e64 v244, v0, v244, s[98:99]
	v_cndmask_b32_e64 v245, v1, v245, s[98:99]
	v_cndmask_b32_e64 v246, v2, v246, s[98:99]
	v_cndmask_b32_e64 v247, v3, v247, s[98:99]
	global_store_dwordx4 v[230:231], v[240:243], off
	global_store_dwordx4 v[232:233], v[244:247], off
	s_and_saveexec_b64 s[6:7], s[2:3]
	s_cbranch_execz .LBB0_1565
	s_waitcnt vmcnt(0)
	v_mov_b32_e32 v0, v141
	v_mov_b32_e32 v1, v142
	v_mov_b32_e32 v141, v143
	v_mov_b32_e32 v2, v137
	v_mov_b32_e32 v3, v138
	v_mov_b32_e32 v137, v139
	v_pk_add_f32 v[0:1], v[0:1], v[140:141]
	v_pk_add_f32 v[2:3], v[2:3], v[136:137]
	v_pk_add_f32 v[0:1], v[0:1], v[0:1] op_sel:[0,1] op_sel_hi:[1,0]
	v_pk_add_f32 v[2:3], v[2:3], v[2:3] op_sel:[0,1] op_sel_hi:[1,0]
	v_add_f32_e32 v4, v132, v133
	v_add_f32_e32 v6, v134, v135
	v_mov_b32_e32 v1, v128
	v_mov_b32_e32 v3, v129
	v_mov_b32_e32 v5, v130
	v_mov_b32_e32 v7, v131
	v_pk_add_f32 v[0:1], v[0:1], v[2:3]
	v_pk_add_f32 v[2:3], v[4:5], v[6:7]
	s_lshl_b32 s23, s58, 10
	v_pk_add_f32 v[0:1], v[0:1], v[2:3]
	s_and_b32 s23, s23, 0x400
	v_add_f32_e32 v0, v0, v1
	v_fmamk_f32 v0, v0, 0x3a800000, v176
	v_mul_f32_e32 v1, 0x4b800000, v0
	v_cmp_gt_f32_e32 vcc, s57, v0
	s_nop 1
	v_cndmask_b32_e32 v0, v0, v1, vcc
	v_rsq_f32_e32 v0, v0
	s_nop 0
	v_mul_f32_e32 v1, 0x45800000, v0
	v_cndmask_b32_e32 v0, v0, v1, vcc
	v_add_u32_e32 v1, s23, v171
	ds_write_b32 v1, v0
